# norm phases: the first five row loads are issued before the wait for the per-lane parameter vectors (one load round trip less at phase start)
# speedup vs baseline: 1.0027x; 1.0027x over previous
.LBB0_94:
	s_cmp_gt_i32 s44, 1
	s_cselect_b64 s[2:3], -1, 0
	s_cmp_lt_i32 s45, 2
	s_cselect_b64 s[4:5], -1, 0
	s_or_b64 s[2:3], s[2:3], s[4:5]
	s_and_b64 vcc, exec, s[2:3]
	s_cbranch_vccnz .LBB0_295
	s_lshl_b32 s96, s22, 3
	s_lshr_b32 s97, s70, 6
	s_add_u32 s96, s96, s97
	s_lshl_b32 s97, s96, 4
	s_cmpk_ge_u32 s97, 0x8000
	s_cbranch_scc1 .Lnp1_done
	s_load_dwordx2 s[88:89], s[0:1], 0x0
	s_load_dwordx2 s[90:91], s[0:1], 0x18
	s_load_dwordx2 s[92:93], s[0:1], 0x140
	s_load_dwordx2 s[94:95], s[0:1], 0x158
	v_mbcnt_hi_u32_b32 v0, -1, v210
	v_lshlrev_b32_e32 v1, 4, v0
	s_waitcnt lgkmcnt(0)
	s_add_u32 s90, s90, 0
	s_addc_u32 s91, s91, 0
	global_load_dwordx4 v[112:115], v1, s[90:91] nt
	global_load_dwordx4 v[116:119], v1, s[90:91] offset:1024 nt
	global_load_dwordx4 v[120:123], v1, s[90:91] offset:2048 nt
	global_load_dwordx4 v[124:127], v1, s[90:91] offset:3072 nt
	s_lshr_b32 s98, s97, 12
	s_add_u32 s98, s98, 0
	s_mul_i32 s98, s98, 0x3000
	s_add_u32 s92, s92, s98
	s_addc_u32 s93, s93, 0
	global_load_dwordx4 v[144:147], v1, s[92:93] nt
	global_load_dwordx4 v[148:151], v1, s[92:93] offset:1024 nt
	global_load_dwordx4 v[152:155], v1, s[92:93] offset:2048 nt
	global_load_dwordx4 v[156:159], v1, s[92:93] offset:3072 nt
	s_add_u32 s92, s92, 0x1000
	s_addc_u32 s93, s93, 0
	global_load_dwordx4 v[128:131], v1, s[92:93] nt
	global_load_dwordx4 v[132:135], v1, s[92:93] offset:1024 nt
	global_load_dwordx4 v[136:139], v1, s[92:93] offset:2048 nt
	global_load_dwordx4 v[140:143], v1, s[92:93] offset:3072 nt
	s_load_dwordx2 s[90:91], s[0:1], 0x210
	s_load_dwordx2 s[92:93], s[0:1], 0x218
	s_add_u32 s98, s97, 0
	s_lshl_b32 s98, s98, 12
	v_add_u32_e32 v3, s98, v1
	global_load_dwordx4 v[16:19], v3, s[88:89] nt
	global_load_dwordx4 v[20:23], v3, s[88:89] offset:1024 nt
	global_load_dwordx4 v[24:27], v3, s[88:89] offset:2048 nt
	global_load_dwordx4 v[28:31], v3, s[88:89] offset:3072 nt
	s_add_u32 s98, s97, 1
	s_lshl_b32 s98, s98, 12
	v_add_u32_e32 v3, s98, v1
	global_load_dwordx4 v[32:35], v3, s[88:89] nt
	global_load_dwordx4 v[36:39], v3, s[88:89] offset:1024 nt
	global_load_dwordx4 v[40:43], v3, s[88:89] offset:2048 nt
	global_load_dwordx4 v[44:47], v3, s[88:89] offset:3072 nt
	s_add_u32 s98, s97, 2
	s_lshl_b32 s98, s98, 12
	v_add_u32_e32 v3, s98, v1
	global_load_dwordx4 v[48:51], v3, s[88:89] nt
	global_load_dwordx4 v[52:55], v3, s[88:89] offset:1024 nt
	global_load_dwordx4 v[56:59], v3, s[88:89] offset:2048 nt
	global_load_dwordx4 v[60:63], v3, s[88:89] offset:3072 nt
	s_add_u32 s98, s97, 3
	s_lshl_b32 s98, s98, 12
	v_add_u32_e32 v3, s98, v1
	global_load_dwordx4 v[64:67], v3, s[88:89] nt
	global_load_dwordx4 v[68:71], v3, s[88:89] offset:1024 nt
	global_load_dwordx4 v[72:75], v3, s[88:89] offset:2048 nt
	global_load_dwordx4 v[76:79], v3, s[88:89] offset:3072 nt
	s_add_u32 s98, s97, 4
	s_lshl_b32 s98, s98, 12
	v_add_u32_e32 v3, s98, v1
	global_load_dwordx4 v[80:83], v3, s[88:89] nt
	global_load_dwordx4 v[84:87], v3, s[88:89] offset:1024 nt
	global_load_dwordx4 v[88:91], v3, s[88:89] offset:2048 nt
	global_load_dwordx4 v[92:95], v3, s[88:89] offset:3072 nt
	s_waitcnt vmcnt(0) lgkmcnt(0)
	v_pk_add_f32 v[128:129], v[128:129], 1.0 op_sel_hi:[1,0]
	v_pk_add_f32 v[130:131], v[130:131], 1.0 op_sel_hi:[1,0]
	v_pk_add_f32 v[132:133], v[132:133], 1.0 op_sel_hi:[1,0]
	v_pk_add_f32 v[134:135], v[134:135], 1.0 op_sel_hi:[1,0]
	v_pk_add_f32 v[136:137], v[136:137], 1.0 op_sel_hi:[1,0]
	v_pk_add_f32 v[138:139], v[138:139], 1.0 op_sel_hi:[1,0]
	v_pk_add_f32 v[140:141], v[140:141], 1.0 op_sel_hi:[1,0]
	v_pk_add_f32 v[142:143], v[142:143], 1.0 op_sel_hi:[1,0]
	s_add_u32 s98, s97, 5
	s_lshl_b32 s98, s98, 12
	v_add_u32_e32 v3, s98, v1
	global_load_dwordx4 v[96:99], v3, s[88:89] nt
	global_load_dwordx4 v[100:103], v3, s[88:89] offset:1024 nt
	global_load_dwordx4 v[104:107], v3, s[88:89] offset:2048 nt
	global_load_dwordx4 v[108:111], v3, s[88:89] offset:3072 nt
	s_waitcnt vmcnt(20)
	v_mul_f32_e32 v4, v16, v16
	v_fma_f32 v4, v17, v17, v4
	v_fma_f32 v4, v18, v18, v4
	v_fma_f32 v4, v19, v19, v4
	v_fma_f32 v4, v20, v20, v4
	v_fma_f32 v4, v21, v21, v4
	v_fma_f32 v4, v22, v22, v4
	v_fma_f32 v4, v23, v23, v4
	v_fma_f32 v4, v24, v24, v4
	v_fma_f32 v4, v25, v25, v4
	v_fma_f32 v4, v26, v26, v4
	v_fma_f32 v4, v27, v27, v4
	v_fma_f32 v4, v28, v28, v4
	v_fma_f32 v4, v29, v29, v4
	v_fma_f32 v4, v30, v30, v4
	v_fma_f32 v4, v31, v31, v4
	s_nop 1
	v_add_f32_dpp v5, v4, v4 quad_perm:[1,0,3,2] row_mask:0xf bank_mask:0xf
	s_nop 1
	v_add_f32_dpp v4, v5, v5 quad_perm:[2,3,0,1] row_mask:0xf bank_mask:0xf
	s_nop 1
	v_add_f32_dpp v5, v4, v4 row_half_mirror row_mask:0xf bank_mask:0xf
	s_nop 1
	v_add_f32_dpp v4, v5, v5 row_mirror row_mask:0xf bank_mask:0xf
	s_nop 1
	v_readlane_b32 s98, v4, 0
	v_readlane_b32 s99, v4, 16
	s_nop 3
	v_mov_b32_e32 v5, s98
	v_add_f32_e32 v5, s99, v5
	v_readlane_b32 s98, v4, 32
	v_readlane_b32 s99, v4, 48
	s_nop 3
	v_add_f32_e32 v5, s98, v5
	v_add_f32_e32 v5, s99, v5
	v_mul_f32_e32 v5, 0x3a800000, v5
	v_add_f32_e32 v5, 0x358637bd, v5
	v_rsq_f32_e32 v6, v5
	s_nop 0
	s_add_u32 s98, s97, 0
	v_pk_mul_f32 v[16:17], v[16:17], v[6:7] op_sel_hi:[1,0]
	v_pk_mul_f32 v[18:19], v[18:19], v[6:7] op_sel_hi:[1,0]
	v_pk_mul_f32 v[20:21], v[20:21], v[6:7] op_sel_hi:[1,0]
	v_pk_mul_f32 v[22:23], v[22:23], v[6:7] op_sel_hi:[1,0]
	v_pk_mul_f32 v[24:25], v[24:25], v[6:7] op_sel_hi:[1,0]
	v_pk_mul_f32 v[26:27], v[26:27], v[6:7] op_sel_hi:[1,0]
	v_pk_mul_f32 v[28:29], v[28:29], v[6:7] op_sel_hi:[1,0]
	v_pk_mul_f32 v[30:31], v[30:31], v[6:7] op_sel_hi:[1,0]
	v_pk_mul_f32 v[16:17], v[16:17], v[112:113]
	v_pk_mul_f32 v[18:19], v[18:19], v[114:115]
	v_pk_mul_f32 v[20:21], v[20:21], v[116:117]
	v_pk_mul_f32 v[22:23], v[22:23], v[118:119]
	v_pk_mul_f32 v[24:25], v[24:25], v[120:121]
	v_pk_mul_f32 v[26:27], v[26:27], v[122:123]
	v_pk_mul_f32 v[28:29], v[28:29], v[124:125]
	v_pk_mul_f32 v[30:31], v[30:31], v[126:127]
	v_pk_fma_f32 v[16:17], v[16:17], v[128:129], v[144:145]
	v_pk_fma_f32 v[18:19], v[18:19], v[130:131], v[146:147]
	v_pk_fma_f32 v[20:21], v[20:21], v[132:133], v[148:149]
	v_pk_fma_f32 v[22:23], v[22:23], v[134:135], v[150:151]
	v_pk_fma_f32 v[24:25], v[24:25], v[136:137], v[152:153]
	v_pk_fma_f32 v[26:27], v[26:27], v[138:139], v[154:155]
	v_pk_fma_f32 v[28:29], v[28:29], v[140:141], v[156:157]
	v_pk_fma_f32 v[30:31], v[30:31], v[142:143], v[158:159]
	v_cvt_pk_bf16_f32 v16, v16, v17
	v_cvt_pk_bf16_f32 v17, v18, v19
	v_cvt_pk_bf16_f32 v18, v20, v21
	v_cvt_pk_bf16_f32 v19, v22, v23
	v_cvt_pk_bf16_f32 v20, v24, v25
	v_cvt_pk_bf16_f32 v21, v26, v27
	v_cvt_pk_bf16_f32 v22, v28, v29
	v_cvt_pk_bf16_f32 v23, v30, v31
	s_lshl_b32 s99, s98, 11
	v_lshl_add_u32 v8, v0, 3, s99
	global_store_dwordx2 v8, v[16:17], s[94:95]
	global_store_dwordx2 v8, v[18:19], s[94:95] offset:512
	global_store_dwordx2 v8, v[20:21], s[94:95] offset:1024
	global_store_dwordx2 v8, v[22:23], s[94:95] offset:1536
	s_lshl_b32 s99, s98, 2
	v_mov_b32_e32 v9, s99
	v_mov_b32_e32 v10, 0
	v_cmp_eq_u32_e32 vcc, 0, v0
	s_and_saveexec_b64 s[98:99], vcc
	global_store_dword v9, v10, s[90:91]
	global_store_dword v9, v10, s[92:93]
	s_or_b64 exec, exec, s[98:99]
	s_add_u32 s98, s97, 6
	s_lshl_b32 s98, s98, 12
	v_add_u32_e32 v3, s98, v1
	global_load_dwordx4 v[16:19], v3, s[88:89] nt
	global_load_dwordx4 v[20:23], v3, s[88:89] offset:1024 nt
	global_load_dwordx4 v[24:27], v3, s[88:89] offset:2048 nt
	global_load_dwordx4 v[28:31], v3, s[88:89] offset:3072 nt
	s_waitcnt vmcnt(26)
	v_mul_f32_e32 v4, v32, v32
	v_fma_f32 v4, v33, v33, v4
	v_fma_f32 v4, v34, v34, v4
	v_fma_f32 v4, v35, v35, v4
	v_fma_f32 v4, v36, v36, v4
	v_fma_f32 v4, v37, v37, v4
	v_fma_f32 v4, v38, v38, v4
	v_fma_f32 v4, v39, v39, v4
	v_fma_f32 v4, v40, v40, v4
	v_fma_f32 v4, v41, v41, v4
	v_fma_f32 v4, v42, v42, v4
	v_fma_f32 v4, v43, v43, v4
	v_fma_f32 v4, v44, v44, v4
	v_fma_f32 v4, v45, v45, v4
	v_fma_f32 v4, v46, v46, v4
	v_fma_f32 v4, v47, v47, v4
	s_nop 1
	v_add_f32_dpp v5, v4, v4 quad_perm:[1,0,3,2] row_mask:0xf bank_mask:0xf
	s_nop 1
	v_add_f32_dpp v4, v5, v5 quad_perm:[2,3,0,1] row_mask:0xf bank_mask:0xf
	s_nop 1
	v_add_f32_dpp v5, v4, v4 row_half_mirror row_mask:0xf bank_mask:0xf
	s_nop 1
	v_add_f32_dpp v4, v5, v5 row_mirror row_mask:0xf bank_mask:0xf
	s_nop 1
	v_readlane_b32 s98, v4, 0
	v_readlane_b32 s99, v4, 16
	s_nop 3
	v_mov_b32_e32 v5, s98
	v_add_f32_e32 v5, s99, v5
	v_readlane_b32 s98, v4, 32
	v_readlane_b32 s99, v4, 48
	s_nop 3
	v_add_f32_e32 v5, s98, v5
	v_add_f32_e32 v5, s99, v5
	v_mul_f32_e32 v5, 0x3a800000, v5
	v_add_f32_e32 v5, 0x358637bd, v5
	v_rsq_f32_e32 v6, v5
	s_nop 0
	s_add_u32 s98, s97, 1
	v_pk_mul_f32 v[32:33], v[32:33], v[6:7] op_sel_hi:[1,0]
	v_pk_mul_f32 v[34:35], v[34:35], v[6:7] op_sel_hi:[1,0]
	v_pk_mul_f32 v[36:37], v[36:37], v[6:7] op_sel_hi:[1,0]
	v_pk_mul_f32 v[38:39], v[38:39], v[6:7] op_sel_hi:[1,0]
	v_pk_mul_f32 v[40:41], v[40:41], v[6:7] op_sel_hi:[1,0]
	v_pk_mul_f32 v[42:43], v[42:43], v[6:7] op_sel_hi:[1,0]
	v_pk_mul_f32 v[44:45], v[44:45], v[6:7] op_sel_hi:[1,0]
	v_pk_mul_f32 v[46:47], v[46:47], v[6:7] op_sel_hi:[1,0]
	v_pk_mul_f32 v[32:33], v[32:33], v[112:113]
	v_pk_mul_f32 v[34:35], v[34:35], v[114:115]
	v_pk_mul_f32 v[36:37], v[36:37], v[116:117]
	v_pk_mul_f32 v[38:39], v[38:39], v[118:119]
	v_pk_mul_f32 v[40:41], v[40:41], v[120:121]
	v_pk_mul_f32 v[42:43], v[42:43], v[122:123]
	v_pk_mul_f32 v[44:45], v[44:45], v[124:125]
	v_pk_mul_f32 v[46:47], v[46:47], v[126:127]
	v_pk_fma_f32 v[32:33], v[32:33], v[128:129], v[144:145]
	v_pk_fma_f32 v[34:35], v[34:35], v[130:131], v[146:147]
	v_pk_fma_f32 v[36:37], v[36:37], v[132:133], v[148:149]
	v_pk_fma_f32 v[38:39], v[38:39], v[134:135], v[150:151]
	v_pk_fma_f32 v[40:41], v[40:41], v[136:137], v[152:153]
	v_pk_fma_f32 v[42:43], v[42:43], v[138:139], v[154:155]
	v_pk_fma_f32 v[44:45], v[44:45], v[140:141], v[156:157]
	v_pk_fma_f32 v[46:47], v[46:47], v[142:143], v[158:159]
	v_cvt_pk_bf16_f32 v32, v32, v33
	v_cvt_pk_bf16_f32 v33, v34, v35
	v_cvt_pk_bf16_f32 v34, v36, v37
	v_cvt_pk_bf16_f32 v35, v38, v39
	v_cvt_pk_bf16_f32 v36, v40, v41
	v_cvt_pk_bf16_f32 v37, v42, v43
	v_cvt_pk_bf16_f32 v38, v44, v45
	v_cvt_pk_bf16_f32 v39, v46, v47
	s_lshl_b32 s99, s98, 11
	v_lshl_add_u32 v8, v0, 3, s99
	global_store_dwordx2 v8, v[32:33], s[94:95]
	global_store_dwordx2 v8, v[34:35], s[94:95] offset:512
	global_store_dwordx2 v8, v[36:37], s[94:95] offset:1024
	global_store_dwordx2 v8, v[38:39], s[94:95] offset:1536
	s_lshl_b32 s99, s98, 2
	v_mov_b32_e32 v9, s99
	v_mov_b32_e32 v10, 0
	v_cmp_eq_u32_e32 vcc, 0, v0
	s_and_saveexec_b64 s[98:99], vcc
	global_store_dword v9, v10, s[90:91]
	global_store_dword v9, v10, s[92:93]
	s_or_b64 exec, exec, s[98:99]
	s_add_u32 s98, s97, 7
	s_lshl_b32 s98, s98, 12
	v_add_u32_e32 v3, s98, v1
	global_load_dwordx4 v[32:35], v3, s[88:89] nt
	global_load_dwordx4 v[36:39], v3, s[88:89] offset:1024 nt
	global_load_dwordx4 v[40:43], v3, s[88:89] offset:2048 nt
	global_load_dwordx4 v[44:47], v3, s[88:89] offset:3072 nt
	s_waitcnt vmcnt(32)
	v_mul_f32_e32 v4, v48, v48
	v_fma_f32 v4, v49, v49, v4
	v_fma_f32 v4, v50, v50, v4
	v_fma_f32 v4, v51, v51, v4
	v_fma_f32 v4, v52, v52, v4
	v_fma_f32 v4, v53, v53, v4
	v_fma_f32 v4, v54, v54, v4
	v_fma_f32 v4, v55, v55, v4
	v_fma_f32 v4, v56, v56, v4
	v_fma_f32 v4, v57, v57, v4
	v_fma_f32 v4, v58, v58, v4
	v_fma_f32 v4, v59, v59, v4
	v_fma_f32 v4, v60, v60, v4
	v_fma_f32 v4, v61, v61, v4
	v_fma_f32 v4, v62, v62, v4
	v_fma_f32 v4, v63, v63, v4
	s_nop 1
	v_add_f32_dpp v5, v4, v4 quad_perm:[1,0,3,2] row_mask:0xf bank_mask:0xf
	s_nop 1
	v_add_f32_dpp v4, v5, v5 quad_perm:[2,3,0,1] row_mask:0xf bank_mask:0xf
	s_nop 1
	v_add_f32_dpp v5, v4, v4 row_half_mirror row_mask:0xf bank_mask:0xf
	s_nop 1
	v_add_f32_dpp v4, v5, v5 row_mirror row_mask:0xf bank_mask:0xf
	s_nop 1
	v_readlane_b32 s98, v4, 0
	v_readlane_b32 s99, v4, 16
	s_nop 3
	v_mov_b32_e32 v5, s98
	v_add_f32_e32 v5, s99, v5
	v_readlane_b32 s98, v4, 32
	v_readlane_b32 s99, v4, 48
	s_nop 3
	v_add_f32_e32 v5, s98, v5
	v_add_f32_e32 v5, s99, v5
	v_mul_f32_e32 v5, 0x3a800000, v5
	v_add_f32_e32 v5, 0x358637bd, v5
	v_rsq_f32_e32 v6, v5
	s_nop 0
	s_add_u32 s98, s97, 2
	v_pk_mul_f32 v[48:49], v[48:49], v[6:7] op_sel_hi:[1,0]
	v_pk_mul_f32 v[50:51], v[50:51], v[6:7] op_sel_hi:[1,0]
	v_pk_mul_f32 v[52:53], v[52:53], v[6:7] op_sel_hi:[1,0]
	v_pk_mul_f32 v[54:55], v[54:55], v[6:7] op_sel_hi:[1,0]
	v_pk_mul_f32 v[56:57], v[56:57], v[6:7] op_sel_hi:[1,0]
	v_pk_mul_f32 v[58:59], v[58:59], v[6:7] op_sel_hi:[1,0]
	v_pk_mul_f32 v[60:61], v[60:61], v[6:7] op_sel_hi:[1,0]
	v_pk_mul_f32 v[62:63], v[62:63], v[6:7] op_sel_hi:[1,0]
	v_pk_mul_f32 v[48:49], v[48:49], v[112:113]
	v_pk_mul_f32 v[50:51], v[50:51], v[114:115]
	v_pk_mul_f32 v[52:53], v[52:53], v[116:117]
	v_pk_mul_f32 v[54:55], v[54:55], v[118:119]
	v_pk_mul_f32 v[56:57], v[56:57], v[120:121]
	v_pk_mul_f32 v[58:59], v[58:59], v[122:123]
	v_pk_mul_f32 v[60:61], v[60:61], v[124:125]
	v_pk_mul_f32 v[62:63], v[62:63], v[126:127]
	v_pk_fma_f32 v[48:49], v[48:49], v[128:129], v[144:145]
	v_pk_fma_f32 v[50:51], v[50:51], v[130:131], v[146:147]
	v_pk_fma_f32 v[52:53], v[52:53], v[132:133], v[148:149]
	v_pk_fma_f32 v[54:55], v[54:55], v[134:135], v[150:151]
	v_pk_fma_f32 v[56:57], v[56:57], v[136:137], v[152:153]
	v_pk_fma_f32 v[58:59], v[58:59], v[138:139], v[154:155]
	v_pk_fma_f32 v[60:61], v[60:61], v[140:141], v[156:157]
	v_pk_fma_f32 v[62:63], v[62:63], v[142:143], v[158:159]
	v_cvt_pk_bf16_f32 v48, v48, v49
	v_cvt_pk_bf16_f32 v49, v50, v51
	v_cvt_pk_bf16_f32 v50, v52, v53
	v_cvt_pk_bf16_f32 v51, v54, v55
	v_cvt_pk_bf16_f32 v52, v56, v57
	v_cvt_pk_bf16_f32 v53, v58, v59
	v_cvt_pk_bf16_f32 v54, v60, v61
	v_cvt_pk_bf16_f32 v55, v62, v63
	s_lshl_b32 s99, s98, 11
	v_lshl_add_u32 v8, v0, 3, s99
	global_store_dwordx2 v8, v[48:49], s[94:95]
	global_store_dwordx2 v8, v[50:51], s[94:95] offset:512
	global_store_dwordx2 v8, v[52:53], s[94:95] offset:1024
	global_store_dwordx2 v8, v[54:55], s[94:95] offset:1536
	s_lshl_b32 s99, s98, 2
	v_mov_b32_e32 v9, s99
	v_mov_b32_e32 v10, 0
	v_cmp_eq_u32_e32 vcc, 0, v0
	s_and_saveexec_b64 s[98:99], vcc
	global_store_dword v9, v10, s[90:91]
	global_store_dword v9, v10, s[92:93]
	s_or_b64 exec, exec, s[98:99]
	s_add_u32 s98, s97, 8
	s_lshl_b32 s98, s98, 12
	v_add_u32_e32 v3, s98, v1
	global_load_dwordx4 v[48:51], v3, s[88:89] nt
	global_load_dwordx4 v[52:55], v3, s[88:89] offset:1024 nt
	global_load_dwordx4 v[56:59], v3, s[88:89] offset:2048 nt
	global_load_dwordx4 v[60:63], v3, s[88:89] offset:3072 nt
	s_waitcnt vmcnt(38)
	v_mul_f32_e32 v4, v64, v64
	v_fma_f32 v4, v65, v65, v4
	v_fma_f32 v4, v66, v66, v4
	v_fma_f32 v4, v67, v67, v4
	v_fma_f32 v4, v68, v68, v4
	v_fma_f32 v4, v69, v69, v4
	v_fma_f32 v4, v70, v70, v4
	v_fma_f32 v4, v71, v71, v4
	v_fma_f32 v4, v72, v72, v4
	v_fma_f32 v4, v73, v73, v4
	v_fma_f32 v4, v74, v74, v4
	v_fma_f32 v4, v75, v75, v4
	v_fma_f32 v4, v76, v76, v4
	v_fma_f32 v4, v77, v77, v4
	v_fma_f32 v4, v78, v78, v4
	v_fma_f32 v4, v79, v79, v4
	s_nop 1
	v_add_f32_dpp v5, v4, v4 quad_perm:[1,0,3,2] row_mask:0xf bank_mask:0xf
	s_nop 1
	v_add_f32_dpp v4, v5, v5 quad_perm:[2,3,0,1] row_mask:0xf bank_mask:0xf
	s_nop 1
	v_add_f32_dpp v5, v4, v4 row_half_mirror row_mask:0xf bank_mask:0xf
	s_nop 1
	v_add_f32_dpp v4, v5, v5 row_mirror row_mask:0xf bank_mask:0xf
	s_nop 1
	v_readlane_b32 s98, v4, 0
	v_readlane_b32 s99, v4, 16
	s_nop 3
	v_mov_b32_e32 v5, s98
	v_add_f32_e32 v5, s99, v5
	v_readlane_b32 s98, v4, 32
	v_readlane_b32 s99, v4, 48
	s_nop 3
	v_add_f32_e32 v5, s98, v5
	v_add_f32_e32 v5, s99, v5
	v_mul_f32_e32 v5, 0x3a800000, v5
	v_add_f32_e32 v5, 0x358637bd, v5
	v_rsq_f32_e32 v6, v5
	s_nop 0
	s_add_u32 s98, s97, 3
	v_pk_mul_f32 v[64:65], v[64:65], v[6:7] op_sel_hi:[1,0]
	v_pk_mul_f32 v[66:67], v[66:67], v[6:7] op_sel_hi:[1,0]
	v_pk_mul_f32 v[68:69], v[68:69], v[6:7] op_sel_hi:[1,0]
	v_pk_mul_f32 v[70:71], v[70:71], v[6:7] op_sel_hi:[1,0]
	v_pk_mul_f32 v[72:73], v[72:73], v[6:7] op_sel_hi:[1,0]
	v_pk_mul_f32 v[74:75], v[74:75], v[6:7] op_sel_hi:[1,0]
	v_pk_mul_f32 v[76:77], v[76:77], v[6:7] op_sel_hi:[1,0]
	v_pk_mul_f32 v[78:79], v[78:79], v[6:7] op_sel_hi:[1,0]
	v_pk_mul_f32 v[64:65], v[64:65], v[112:113]
	v_pk_mul_f32 v[66:67], v[66:67], v[114:115]
	v_pk_mul_f32 v[68:69], v[68:69], v[116:117]
	v_pk_mul_f32 v[70:71], v[70:71], v[118:119]
	v_pk_mul_f32 v[72:73], v[72:73], v[120:121]
	v_pk_mul_f32 v[74:75], v[74:75], v[122:123]
	v_pk_mul_f32 v[76:77], v[76:77], v[124:125]
	v_pk_mul_f32 v[78:79], v[78:79], v[126:127]
	v_pk_fma_f32 v[64:65], v[64:65], v[128:129], v[144:145]
	v_pk_fma_f32 v[66:67], v[66:67], v[130:131], v[146:147]
	v_pk_fma_f32 v[68:69], v[68:69], v[132:133], v[148:149]
	v_pk_fma_f32 v[70:71], v[70:71], v[134:135], v[150:151]
	v_pk_fma_f32 v[72:73], v[72:73], v[136:137], v[152:153]
	v_pk_fma_f32 v[74:75], v[74:75], v[138:139], v[154:155]
	v_pk_fma_f32 v[76:77], v[76:77], v[140:141], v[156:157]
	v_pk_fma_f32 v[78:79], v[78:79], v[142:143], v[158:159]
	v_cvt_pk_bf16_f32 v64, v64, v65
	v_cvt_pk_bf16_f32 v65, v66, v67
	v_cvt_pk_bf16_f32 v66, v68, v69
	v_cvt_pk_bf16_f32 v67, v70, v71
	v_cvt_pk_bf16_f32 v68, v72, v73
	v_cvt_pk_bf16_f32 v69, v74, v75
	v_cvt_pk_bf16_f32 v70, v76, v77
	v_cvt_pk_bf16_f32 v71, v78, v79
	s_lshl_b32 s99, s98, 11
	v_lshl_add_u32 v8, v0, 3, s99
	global_store_dwordx2 v8, v[64:65], s[94:95]
	global_store_dwordx2 v8, v[66:67], s[94:95] offset:512
	global_store_dwordx2 v8, v[68:69], s[94:95] offset:1024
	global_store_dwordx2 v8, v[70:71], s[94:95] offset:1536
	s_lshl_b32 s99, s98, 2
	v_mov_b32_e32 v9, s99
	v_mov_b32_e32 v10, 0
	v_cmp_eq_u32_e32 vcc, 0, v0
	s_and_saveexec_b64 s[98:99], vcc
	global_store_dword v9, v10, s[90:91]
	global_store_dword v9, v10, s[92:93]
	s_or_b64 exec, exec, s[98:99]
	s_add_u32 s98, s97, 9
	s_lshl_b32 s98, s98, 12
	v_add_u32_e32 v3, s98, v1
	global_load_dwordx4 v[64:67], v3, s[88:89] nt
	global_load_dwordx4 v[68:71], v3, s[88:89] offset:1024 nt
	global_load_dwordx4 v[72:75], v3, s[88:89] offset:2048 nt
	global_load_dwordx4 v[76:79], v3, s[88:89] offset:3072 nt
	s_waitcnt vmcnt(44)
	v_mul_f32_e32 v4, v80, v80
	v_fma_f32 v4, v81, v81, v4
	v_fma_f32 v4, v82, v82, v4
	v_fma_f32 v4, v83, v83, v4
	v_fma_f32 v4, v84, v84, v4
	v_fma_f32 v4, v85, v85, v4
	v_fma_f32 v4, v86, v86, v4
	v_fma_f32 v4, v87, v87, v4
	v_fma_f32 v4, v88, v88, v4
	v_fma_f32 v4, v89, v89, v4
	v_fma_f32 v4, v90, v90, v4
	v_fma_f32 v4, v91, v91, v4
	v_fma_f32 v4, v92, v92, v4
	v_fma_f32 v4, v93, v93, v4
	v_fma_f32 v4, v94, v94, v4
	v_fma_f32 v4, v95, v95, v4
	s_nop 1
	v_add_f32_dpp v5, v4, v4 quad_perm:[1,0,3,2] row_mask:0xf bank_mask:0xf
	s_nop 1
	v_add_f32_dpp v4, v5, v5 quad_perm:[2,3,0,1] row_mask:0xf bank_mask:0xf
	s_nop 1
	v_add_f32_dpp v5, v4, v4 row_half_mirror row_mask:0xf bank_mask:0xf
	s_nop 1
	v_add_f32_dpp v4, v5, v5 row_mirror row_mask:0xf bank_mask:0xf
	s_nop 1
	v_readlane_b32 s98, v4, 0
	v_readlane_b32 s99, v4, 16
	s_nop 3
	v_mov_b32_e32 v5, s98
	v_add_f32_e32 v5, s99, v5
	v_readlane_b32 s98, v4, 32
	v_readlane_b32 s99, v4, 48
	s_nop 3
	v_add_f32_e32 v5, s98, v5
	v_add_f32_e32 v5, s99, v5
	v_mul_f32_e32 v5, 0x3a800000, v5
	v_add_f32_e32 v5, 0x358637bd, v5
	v_rsq_f32_e32 v6, v5
	s_nop 0
	s_add_u32 s98, s97, 4
	v_pk_mul_f32 v[80:81], v[80:81], v[6:7] op_sel_hi:[1,0]
	v_pk_mul_f32 v[82:83], v[82:83], v[6:7] op_sel_hi:[1,0]
	v_pk_mul_f32 v[84:85], v[84:85], v[6:7] op_sel_hi:[1,0]
	v_pk_mul_f32 v[86:87], v[86:87], v[6:7] op_sel_hi:[1,0]
	v_pk_mul_f32 v[88:89], v[88:89], v[6:7] op_sel_hi:[1,0]
	v_pk_mul_f32 v[90:91], v[90:91], v[6:7] op_sel_hi:[1,0]
	v_pk_mul_f32 v[92:93], v[92:93], v[6:7] op_sel_hi:[1,0]
	v_pk_mul_f32 v[94:95], v[94:95], v[6:7] op_sel_hi:[1,0]
	v_pk_mul_f32 v[80:81], v[80:81], v[112:113]
	v_pk_mul_f32 v[82:83], v[82:83], v[114:115]
	v_pk_mul_f32 v[84:85], v[84:85], v[116:117]
	v_pk_mul_f32 v[86:87], v[86:87], v[118:119]
	v_pk_mul_f32 v[88:89], v[88:89], v[120:121]
	v_pk_mul_f32 v[90:91], v[90:91], v[122:123]
	v_pk_mul_f32 v[92:93], v[92:93], v[124:125]
	v_pk_mul_f32 v[94:95], v[94:95], v[126:127]
	v_pk_fma_f32 v[80:81], v[80:81], v[128:129], v[144:145]
	v_pk_fma_f32 v[82:83], v[82:83], v[130:131], v[146:147]
	v_pk_fma_f32 v[84:85], v[84:85], v[132:133], v[148:149]
	v_pk_fma_f32 v[86:87], v[86:87], v[134:135], v[150:151]
	v_pk_fma_f32 v[88:89], v[88:89], v[136:137], v[152:153]
	v_pk_fma_f32 v[90:91], v[90:91], v[138:139], v[154:155]
	v_pk_fma_f32 v[92:93], v[92:93], v[140:141], v[156:157]
	v_pk_fma_f32 v[94:95], v[94:95], v[142:143], v[158:159]
	v_cvt_pk_bf16_f32 v80, v80, v81
	v_cvt_pk_bf16_f32 v81, v82, v83
	v_cvt_pk_bf16_f32 v82, v84, v85
	v_cvt_pk_bf16_f32 v83, v86, v87
	v_cvt_pk_bf16_f32 v84, v88, v89
	v_cvt_pk_bf16_f32 v85, v90, v91
	v_cvt_pk_bf16_f32 v86, v92, v93
	v_cvt_pk_bf16_f32 v87, v94, v95
	s_lshl_b32 s99, s98, 11
	v_lshl_add_u32 v8, v0, 3, s99
	global_store_dwordx2 v8, v[80:81], s[94:95]
	global_store_dwordx2 v8, v[82:83], s[94:95] offset:512
	global_store_dwordx2 v8, v[84:85], s[94:95] offset:1024
	global_store_dwordx2 v8, v[86:87], s[94:95] offset:1536
	s_lshl_b32 s99, s98, 2
	v_mov_b32_e32 v9, s99
	v_mov_b32_e32 v10, 0
	v_cmp_eq_u32_e32 vcc, 0, v0
	s_and_saveexec_b64 s[98:99], vcc
	global_store_dword v9, v10, s[90:91]
	global_store_dword v9, v10, s[92:93]
	s_or_b64 exec, exec, s[98:99]
	s_add_u32 s98, s97, 10
	s_lshl_b32 s98, s98, 12
	v_add_u32_e32 v3, s98, v1
	global_load_dwordx4 v[80:83], v3, s[88:89] nt
	global_load_dwordx4 v[84:87], v3, s[88:89] offset:1024 nt
	global_load_dwordx4 v[88:91], v3, s[88:89] offset:2048 nt
	global_load_dwordx4 v[92:95], v3, s[88:89] offset:3072 nt
	s_waitcnt vmcnt(50)
	v_mul_f32_e32 v4, v96, v96
	v_fma_f32 v4, v97, v97, v4
	v_fma_f32 v4, v98, v98, v4
	v_fma_f32 v4, v99, v99, v4
	v_fma_f32 v4, v100, v100, v4
	v_fma_f32 v4, v101, v101, v4
	v_fma_f32 v4, v102, v102, v4
	v_fma_f32 v4, v103, v103, v4
	v_fma_f32 v4, v104, v104, v4
	v_fma_f32 v4, v105, v105, v4
	v_fma_f32 v4, v106, v106, v4
	v_fma_f32 v4, v107, v107, v4
	v_fma_f32 v4, v108, v108, v4
	v_fma_f32 v4, v109, v109, v4
	v_fma_f32 v4, v110, v110, v4
	v_fma_f32 v4, v111, v111, v4
	s_nop 1
	v_add_f32_dpp v5, v4, v4 quad_perm:[1,0,3,2] row_mask:0xf bank_mask:0xf
	s_nop 1
	v_add_f32_dpp v4, v5, v5 quad_perm:[2,3,0,1] row_mask:0xf bank_mask:0xf
	s_nop 1
	v_add_f32_dpp v5, v4, v4 row_half_mirror row_mask:0xf bank_mask:0xf
	s_nop 1
	v_add_f32_dpp v4, v5, v5 row_mirror row_mask:0xf bank_mask:0xf
	s_nop 1
	v_readlane_b32 s98, v4, 0
	v_readlane_b32 s99, v4, 16
	s_nop 3
	v_mov_b32_e32 v5, s98
	v_add_f32_e32 v5, s99, v5
	v_readlane_b32 s98, v4, 32
	v_readlane_b32 s99, v4, 48
	s_nop 3
	v_add_f32_e32 v5, s98, v5
	v_add_f32_e32 v5, s99, v5
	v_mul_f32_e32 v5, 0x3a800000, v5
	v_add_f32_e32 v5, 0x358637bd, v5
	v_rsq_f32_e32 v6, v5
	s_nop 0
	s_add_u32 s98, s97, 5
	v_pk_mul_f32 v[96:97], v[96:97], v[6:7] op_sel_hi:[1,0]
	v_pk_mul_f32 v[98:99], v[98:99], v[6:7] op_sel_hi:[1,0]
	v_pk_mul_f32 v[100:101], v[100:101], v[6:7] op_sel_hi:[1,0]
	v_pk_mul_f32 v[102:103], v[102:103], v[6:7] op_sel_hi:[1,0]
	v_pk_mul_f32 v[104:105], v[104:105], v[6:7] op_sel_hi:[1,0]
	v_pk_mul_f32 v[106:107], v[106:107], v[6:7] op_sel_hi:[1,0]
	v_pk_mul_f32 v[108:109], v[108:109], v[6:7] op_sel_hi:[1,0]
	v_pk_mul_f32 v[110:111], v[110:111], v[6:7] op_sel_hi:[1,0]
	v_pk_mul_f32 v[96:97], v[96:97], v[112:113]
	v_pk_mul_f32 v[98:99], v[98:99], v[114:115]
	v_pk_mul_f32 v[100:101], v[100:101], v[116:117]
	v_pk_mul_f32 v[102:103], v[102:103], v[118:119]
	v_pk_mul_f32 v[104:105], v[104:105], v[120:121]
	v_pk_mul_f32 v[106:107], v[106:107], v[122:123]
	v_pk_mul_f32 v[108:109], v[108:109], v[124:125]
	v_pk_mul_f32 v[110:111], v[110:111], v[126:127]
	v_pk_fma_f32 v[96:97], v[96:97], v[128:129], v[144:145]
	v_pk_fma_f32 v[98:99], v[98:99], v[130:131], v[146:147]
	v_pk_fma_f32 v[100:101], v[100:101], v[132:133], v[148:149]
	v_pk_fma_f32 v[102:103], v[102:103], v[134:135], v[150:151]
	v_pk_fma_f32 v[104:105], v[104:105], v[136:137], v[152:153]
	v_pk_fma_f32 v[106:107], v[106:107], v[138:139], v[154:155]
	v_pk_fma_f32 v[108:109], v[108:109], v[140:141], v[156:157]
	v_pk_fma_f32 v[110:111], v[110:111], v[142:143], v[158:159]
	v_cvt_pk_bf16_f32 v96, v96, v97
	v_cvt_pk_bf16_f32 v97, v98, v99
	v_cvt_pk_bf16_f32 v98, v100, v101
	v_cvt_pk_bf16_f32 v99, v102, v103
	v_cvt_pk_bf16_f32 v100, v104, v105
	v_cvt_pk_bf16_f32 v101, v106, v107
	v_cvt_pk_bf16_f32 v102, v108, v109
	v_cvt_pk_bf16_f32 v103, v110, v111
	s_lshl_b32 s99, s98, 11
	v_lshl_add_u32 v8, v0, 3, s99
	global_store_dwordx2 v8, v[96:97], s[94:95]
	global_store_dwordx2 v8, v[98:99], s[94:95] offset:512
	global_store_dwordx2 v8, v[100:101], s[94:95] offset:1024
	global_store_dwordx2 v8, v[102:103], s[94:95] offset:1536
	s_lshl_b32 s99, s98, 2
	v_mov_b32_e32 v9, s99
	v_mov_b32_e32 v10, 0
	v_cmp_eq_u32_e32 vcc, 0, v0
	s_and_saveexec_b64 s[98:99], vcc
	global_store_dword v9, v10, s[90:91]
	global_store_dword v9, v10, s[92:93]
	s_or_b64 exec, exec, s[98:99]
	s_add_u32 s98, s97, 11
	s_lshl_b32 s98, s98, 12
	v_add_u32_e32 v3, s98, v1
	global_load_dwordx4 v[96:99], v3, s[88:89] nt
	global_load_dwordx4 v[100:103], v3, s[88:89] offset:1024 nt
	global_load_dwordx4 v[104:107], v3, s[88:89] offset:2048 nt
	global_load_dwordx4 v[108:111], v3, s[88:89] offset:3072 nt
	s_waitcnt vmcnt(50)
	v_mul_f32_e32 v4, v16, v16
	v_fma_f32 v4, v17, v17, v4
	v_fma_f32 v4, v18, v18, v4
	v_fma_f32 v4, v19, v19, v4
	v_fma_f32 v4, v20, v20, v4
	v_fma_f32 v4, v21, v21, v4
	v_fma_f32 v4, v22, v22, v4
	v_fma_f32 v4, v23, v23, v4
	v_fma_f32 v4, v24, v24, v4
	v_fma_f32 v4, v25, v25, v4
	v_fma_f32 v4, v26, v26, v4
	v_fma_f32 v4, v27, v27, v4
	v_fma_f32 v4, v28, v28, v4
	v_fma_f32 v4, v29, v29, v4
	v_fma_f32 v4, v30, v30, v4
	v_fma_f32 v4, v31, v31, v4
	s_nop 1
	v_add_f32_dpp v5, v4, v4 quad_perm:[1,0,3,2] row_mask:0xf bank_mask:0xf
	s_nop 1
	v_add_f32_dpp v4, v5, v5 quad_perm:[2,3,0,1] row_mask:0xf bank_mask:0xf
	s_nop 1
	v_add_f32_dpp v5, v4, v4 row_half_mirror row_mask:0xf bank_mask:0xf
	s_nop 1
	v_add_f32_dpp v4, v5, v5 row_mirror row_mask:0xf bank_mask:0xf
	s_nop 1
	v_readlane_b32 s98, v4, 0
	v_readlane_b32 s99, v4, 16
	s_nop 3
	v_mov_b32_e32 v5, s98
	v_add_f32_e32 v5, s99, v5
	v_readlane_b32 s98, v4, 32
	v_readlane_b32 s99, v4, 48
	s_nop 3
	v_add_f32_e32 v5, s98, v5
	v_add_f32_e32 v5, s99, v5
	v_mul_f32_e32 v5, 0x3a800000, v5
	v_add_f32_e32 v5, 0x358637bd, v5
	v_rsq_f32_e32 v6, v5
	s_nop 0
	s_add_u32 s98, s97, 6
	v_pk_mul_f32 v[16:17], v[16:17], v[6:7] op_sel_hi:[1,0]
	v_pk_mul_f32 v[18:19], v[18:19], v[6:7] op_sel_hi:[1,0]
	v_pk_mul_f32 v[20:21], v[20:21], v[6:7] op_sel_hi:[1,0]
	v_pk_mul_f32 v[22:23], v[22:23], v[6:7] op_sel_hi:[1,0]
	v_pk_mul_f32 v[24:25], v[24:25], v[6:7] op_sel_hi:[1,0]
	v_pk_mul_f32 v[26:27], v[26:27], v[6:7] op_sel_hi:[1,0]
	v_pk_mul_f32 v[28:29], v[28:29], v[6:7] op_sel_hi:[1,0]
	v_pk_mul_f32 v[30:31], v[30:31], v[6:7] op_sel_hi:[1,0]
	v_pk_mul_f32 v[16:17], v[16:17], v[112:113]
	v_pk_mul_f32 v[18:19], v[18:19], v[114:115]
	v_pk_mul_f32 v[20:21], v[20:21], v[116:117]
	v_pk_mul_f32 v[22:23], v[22:23], v[118:119]
	v_pk_mul_f32 v[24:25], v[24:25], v[120:121]
	v_pk_mul_f32 v[26:27], v[26:27], v[122:123]
	v_pk_mul_f32 v[28:29], v[28:29], v[124:125]
	v_pk_mul_f32 v[30:31], v[30:31], v[126:127]
	v_pk_fma_f32 v[16:17], v[16:17], v[128:129], v[144:145]
	v_pk_fma_f32 v[18:19], v[18:19], v[130:131], v[146:147]
	v_pk_fma_f32 v[20:21], v[20:21], v[132:133], v[148:149]
	v_pk_fma_f32 v[22:23], v[22:23], v[134:135], v[150:151]
	v_pk_fma_f32 v[24:25], v[24:25], v[136:137], v[152:153]
	v_pk_fma_f32 v[26:27], v[26:27], v[138:139], v[154:155]
	v_pk_fma_f32 v[28:29], v[28:29], v[140:141], v[156:157]
	v_pk_fma_f32 v[30:31], v[30:31], v[142:143], v[158:159]
	v_cvt_pk_bf16_f32 v16, v16, v17
	v_cvt_pk_bf16_f32 v17, v18, v19
	v_cvt_pk_bf16_f32 v18, v20, v21
	v_cvt_pk_bf16_f32 v19, v22, v23
	v_cvt_pk_bf16_f32 v20, v24, v25
	v_cvt_pk_bf16_f32 v21, v26, v27
	v_cvt_pk_bf16_f32 v22, v28, v29
	v_cvt_pk_bf16_f32 v23, v30, v31
	s_lshl_b32 s99, s98, 11
	v_lshl_add_u32 v8, v0, 3, s99
	global_store_dwordx2 v8, v[16:17], s[94:95]
	global_store_dwordx2 v8, v[18:19], s[94:95] offset:512
	global_store_dwordx2 v8, v[20:21], s[94:95] offset:1024
	global_store_dwordx2 v8, v[22:23], s[94:95] offset:1536
	s_lshl_b32 s99, s98, 2
	v_mov_b32_e32 v9, s99
	v_mov_b32_e32 v10, 0
	v_cmp_eq_u32_e32 vcc, 0, v0
	s_and_saveexec_b64 s[98:99], vcc
	global_store_dword v9, v10, s[90:91]
	global_store_dword v9, v10, s[92:93]
	s_or_b64 exec, exec, s[98:99]
	s_add_u32 s98, s97, 12
	s_lshl_b32 s98, s98, 12
	v_add_u32_e32 v3, s98, v1
	global_load_dwordx4 v[16:19], v3, s[88:89] nt
	global_load_dwordx4 v[20:23], v3, s[88:89] offset:1024 nt
	global_load_dwordx4 v[24:27], v3, s[88:89] offset:2048 nt
	global_load_dwordx4 v[28:31], v3, s[88:89] offset:3072 nt
	s_waitcnt vmcnt(50)
	v_mul_f32_e32 v4, v32, v32
	v_fma_f32 v4, v33, v33, v4
	v_fma_f32 v4, v34, v34, v4
	v_fma_f32 v4, v35, v35, v4
	v_fma_f32 v4, v36, v36, v4
	v_fma_f32 v4, v37, v37, v4
	v_fma_f32 v4, v38, v38, v4
	v_fma_f32 v4, v39, v39, v4
	v_fma_f32 v4, v40, v40, v4
	v_fma_f32 v4, v41, v41, v4
	v_fma_f32 v4, v42, v42, v4
	v_fma_f32 v4, v43, v43, v4
	v_fma_f32 v4, v44, v44, v4
	v_fma_f32 v4, v45, v45, v4
	v_fma_f32 v4, v46, v46, v4
	v_fma_f32 v4, v47, v47, v4
	s_nop 1
	v_add_f32_dpp v5, v4, v4 quad_perm:[1,0,3,2] row_mask:0xf bank_mask:0xf
	s_nop 1
	v_add_f32_dpp v4, v5, v5 quad_perm:[2,3,0,1] row_mask:0xf bank_mask:0xf
	s_nop 1
	v_add_f32_dpp v5, v4, v4 row_half_mirror row_mask:0xf bank_mask:0xf
	s_nop 1
	v_add_f32_dpp v4, v5, v5 row_mirror row_mask:0xf bank_mask:0xf
	s_nop 1
	v_readlane_b32 s98, v4, 0
	v_readlane_b32 s99, v4, 16
	s_nop 3
	v_mov_b32_e32 v5, s98
	v_add_f32_e32 v5, s99, v5
	v_readlane_b32 s98, v4, 32
	v_readlane_b32 s99, v4, 48
	s_nop 3
	v_add_f32_e32 v5, s98, v5
	v_add_f32_e32 v5, s99, v5
	v_mul_f32_e32 v5, 0x3a800000, v5
	v_add_f32_e32 v5, 0x358637bd, v5
	v_rsq_f32_e32 v6, v5
	s_nop 0
	s_add_u32 s98, s97, 7
	v_pk_mul_f32 v[32:33], v[32:33], v[6:7] op_sel_hi:[1,0]
	v_pk_mul_f32 v[34:35], v[34:35], v[6:7] op_sel_hi:[1,0]
	v_pk_mul_f32 v[36:37], v[36:37], v[6:7] op_sel_hi:[1,0]
	v_pk_mul_f32 v[38:39], v[38:39], v[6:7] op_sel_hi:[1,0]
	v_pk_mul_f32 v[40:41], v[40:41], v[6:7] op_sel_hi:[1,0]
	v_pk_mul_f32 v[42:43], v[42:43], v[6:7] op_sel_hi:[1,0]
	v_pk_mul_f32 v[44:45], v[44:45], v[6:7] op_sel_hi:[1,0]
	v_pk_mul_f32 v[46:47], v[46:47], v[6:7] op_sel_hi:[1,0]
	v_pk_mul_f32 v[32:33], v[32:33], v[112:113]
	v_pk_mul_f32 v[34:35], v[34:35], v[114:115]
	v_pk_mul_f32 v[36:37], v[36:37], v[116:117]
	v_pk_mul_f32 v[38:39], v[38:39], v[118:119]
	v_pk_mul_f32 v[40:41], v[40:41], v[120:121]
	v_pk_mul_f32 v[42:43], v[42:43], v[122:123]
	v_pk_mul_f32 v[44:45], v[44:45], v[124:125]
	v_pk_mul_f32 v[46:47], v[46:47], v[126:127]
	v_pk_fma_f32 v[32:33], v[32:33], v[128:129], v[144:145]
	v_pk_fma_f32 v[34:35], v[34:35], v[130:131], v[146:147]
	v_pk_fma_f32 v[36:37], v[36:37], v[132:133], v[148:149]
	v_pk_fma_f32 v[38:39], v[38:39], v[134:135], v[150:151]
	v_pk_fma_f32 v[40:41], v[40:41], v[136:137], v[152:153]
	v_pk_fma_f32 v[42:43], v[42:43], v[138:139], v[154:155]
	v_pk_fma_f32 v[44:45], v[44:45], v[140:141], v[156:157]
	v_pk_fma_f32 v[46:47], v[46:47], v[142:143], v[158:159]
	v_cvt_pk_bf16_f32 v32, v32, v33
	v_cvt_pk_bf16_f32 v33, v34, v35
	v_cvt_pk_bf16_f32 v34, v36, v37
	v_cvt_pk_bf16_f32 v35, v38, v39
	v_cvt_pk_bf16_f32 v36, v40, v41
	v_cvt_pk_bf16_f32 v37, v42, v43
	v_cvt_pk_bf16_f32 v38, v44, v45
	v_cvt_pk_bf16_f32 v39, v46, v47
	s_lshl_b32 s99, s98, 11
	v_lshl_add_u32 v8, v0, 3, s99
	global_store_dwordx2 v8, v[32:33], s[94:95]
	global_store_dwordx2 v8, v[34:35], s[94:95] offset:512
	global_store_dwordx2 v8, v[36:37], s[94:95] offset:1024
	global_store_dwordx2 v8, v[38:39], s[94:95] offset:1536
	s_lshl_b32 s99, s98, 2
	v_mov_b32_e32 v9, s99
	v_mov_b32_e32 v10, 0
	v_cmp_eq_u32_e32 vcc, 0, v0
	s_and_saveexec_b64 s[98:99], vcc
	global_store_dword v9, v10, s[90:91]
	global_store_dword v9, v10, s[92:93]
	s_or_b64 exec, exec, s[98:99]
	s_add_u32 s98, s97, 13
	s_lshl_b32 s98, s98, 12
	v_add_u32_e32 v3, s98, v1
	global_load_dwordx4 v[32:35], v3, s[88:89] nt
	global_load_dwordx4 v[36:39], v3, s[88:89] offset:1024 nt
	global_load_dwordx4 v[40:43], v3, s[88:89] offset:2048 nt
	global_load_dwordx4 v[44:47], v3, s[88:89] offset:3072 nt
	s_waitcnt vmcnt(50)
	v_mul_f32_e32 v4, v48, v48
	v_fma_f32 v4, v49, v49, v4
	v_fma_f32 v4, v50, v50, v4
	v_fma_f32 v4, v51, v51, v4
	v_fma_f32 v4, v52, v52, v4
	v_fma_f32 v4, v53, v53, v4
	v_fma_f32 v4, v54, v54, v4
	v_fma_f32 v4, v55, v55, v4
	v_fma_f32 v4, v56, v56, v4
	v_fma_f32 v4, v57, v57, v4
	v_fma_f32 v4, v58, v58, v4
	v_fma_f32 v4, v59, v59, v4
	v_fma_f32 v4, v60, v60, v4
	v_fma_f32 v4, v61, v61, v4
	v_fma_f32 v4, v62, v62, v4
	v_fma_f32 v4, v63, v63, v4
	s_nop 1
	v_add_f32_dpp v5, v4, v4 quad_perm:[1,0,3,2] row_mask:0xf bank_mask:0xf
	s_nop 1
	v_add_f32_dpp v4, v5, v5 quad_perm:[2,3,0,1] row_mask:0xf bank_mask:0xf
	s_nop 1
	v_add_f32_dpp v5, v4, v4 row_half_mirror row_mask:0xf bank_mask:0xf
	s_nop 1
	v_add_f32_dpp v4, v5, v5 row_mirror row_mask:0xf bank_mask:0xf
	s_nop 1
	v_readlane_b32 s98, v4, 0
	v_readlane_b32 s99, v4, 16
	s_nop 3
	v_mov_b32_e32 v5, s98
	v_add_f32_e32 v5, s99, v5
	v_readlane_b32 s98, v4, 32
	v_readlane_b32 s99, v4, 48
	s_nop 3
	v_add_f32_e32 v5, s98, v5
	v_add_f32_e32 v5, s99, v5
	v_mul_f32_e32 v5, 0x3a800000, v5
	v_add_f32_e32 v5, 0x358637bd, v5
	v_rsq_f32_e32 v6, v5
	s_nop 0
	s_add_u32 s98, s97, 8
	v_pk_mul_f32 v[48:49], v[48:49], v[6:7] op_sel_hi:[1,0]
	v_pk_mul_f32 v[50:51], v[50:51], v[6:7] op_sel_hi:[1,0]
	v_pk_mul_f32 v[52:53], v[52:53], v[6:7] op_sel_hi:[1,0]
	v_pk_mul_f32 v[54:55], v[54:55], v[6:7] op_sel_hi:[1,0]
	v_pk_mul_f32 v[56:57], v[56:57], v[6:7] op_sel_hi:[1,0]
	v_pk_mul_f32 v[58:59], v[58:59], v[6:7] op_sel_hi:[1,0]
	v_pk_mul_f32 v[60:61], v[60:61], v[6:7] op_sel_hi:[1,0]
	v_pk_mul_f32 v[62:63], v[62:63], v[6:7] op_sel_hi:[1,0]
	v_pk_mul_f32 v[48:49], v[48:49], v[112:113]
	v_pk_mul_f32 v[50:51], v[50:51], v[114:115]
	v_pk_mul_f32 v[52:53], v[52:53], v[116:117]
	v_pk_mul_f32 v[54:55], v[54:55], v[118:119]
	v_pk_mul_f32 v[56:57], v[56:57], v[120:121]
	v_pk_mul_f32 v[58:59], v[58:59], v[122:123]
	v_pk_mul_f32 v[60:61], v[60:61], v[124:125]
	v_pk_mul_f32 v[62:63], v[62:63], v[126:127]
	v_pk_fma_f32 v[48:49], v[48:49], v[128:129], v[144:145]
	v_pk_fma_f32 v[50:51], v[50:51], v[130:131], v[146:147]
	v_pk_fma_f32 v[52:53], v[52:53], v[132:133], v[148:149]
	v_pk_fma_f32 v[54:55], v[54:55], v[134:135], v[150:151]
	v_pk_fma_f32 v[56:57], v[56:57], v[136:137], v[152:153]
	v_pk_fma_f32 v[58:59], v[58:59], v[138:139], v[154:155]
	v_pk_fma_f32 v[60:61], v[60:61], v[140:141], v[156:157]
	v_pk_fma_f32 v[62:63], v[62:63], v[142:143], v[158:159]
	v_cvt_pk_bf16_f32 v48, v48, v49
	v_cvt_pk_bf16_f32 v49, v50, v51
	v_cvt_pk_bf16_f32 v50, v52, v53
	v_cvt_pk_bf16_f32 v51, v54, v55
	v_cvt_pk_bf16_f32 v52, v56, v57
	v_cvt_pk_bf16_f32 v53, v58, v59
	v_cvt_pk_bf16_f32 v54, v60, v61
	v_cvt_pk_bf16_f32 v55, v62, v63
	s_lshl_b32 s99, s98, 11
	v_lshl_add_u32 v8, v0, 3, s99
	global_store_dwordx2 v8, v[48:49], s[94:95]
	global_store_dwordx2 v8, v[50:51], s[94:95] offset:512
	global_store_dwordx2 v8, v[52:53], s[94:95] offset:1024
	global_store_dwordx2 v8, v[54:55], s[94:95] offset:1536
	s_lshl_b32 s99, s98, 2
	v_mov_b32_e32 v9, s99
	v_mov_b32_e32 v10, 0
	v_cmp_eq_u32_e32 vcc, 0, v0
	s_and_saveexec_b64 s[98:99], vcc
	global_store_dword v9, v10, s[90:91]
	global_store_dword v9, v10, s[92:93]
	s_or_b64 exec, exec, s[98:99]
	s_add_u32 s98, s97, 14
	s_lshl_b32 s98, s98, 12
	v_add_u32_e32 v3, s98, v1
	global_load_dwordx4 v[48:51], v3, s[88:89] nt
	global_load_dwordx4 v[52:55], v3, s[88:89] offset:1024 nt
	global_load_dwordx4 v[56:59], v3, s[88:89] offset:2048 nt
	global_load_dwordx4 v[60:63], v3, s[88:89] offset:3072 nt
	s_waitcnt vmcnt(50)
	v_mul_f32_e32 v4, v64, v64
	v_fma_f32 v4, v65, v65, v4
	v_fma_f32 v4, v66, v66, v4
	v_fma_f32 v4, v67, v67, v4
	v_fma_f32 v4, v68, v68, v4
	v_fma_f32 v4, v69, v69, v4
	v_fma_f32 v4, v70, v70, v4
	v_fma_f32 v4, v71, v71, v4
	v_fma_f32 v4, v72, v72, v4
	v_fma_f32 v4, v73, v73, v4
	v_fma_f32 v4, v74, v74, v4
	v_fma_f32 v4, v75, v75, v4
	v_fma_f32 v4, v76, v76, v4
	v_fma_f32 v4, v77, v77, v4
	v_fma_f32 v4, v78, v78, v4
	v_fma_f32 v4, v79, v79, v4
	s_nop 1
	v_add_f32_dpp v5, v4, v4 quad_perm:[1,0,3,2] row_mask:0xf bank_mask:0xf
	s_nop 1
	v_add_f32_dpp v4, v5, v5 quad_perm:[2,3,0,1] row_mask:0xf bank_mask:0xf
	s_nop 1
	v_add_f32_dpp v5, v4, v4 row_half_mirror row_mask:0xf bank_mask:0xf
	s_nop 1
	v_add_f32_dpp v4, v5, v5 row_mirror row_mask:0xf bank_mask:0xf
	s_nop 1
	v_readlane_b32 s98, v4, 0
	v_readlane_b32 s99, v4, 16
	s_nop 3
	v_mov_b32_e32 v5, s98
	v_add_f32_e32 v5, s99, v5
	v_readlane_b32 s98, v4, 32
	v_readlane_b32 s99, v4, 48
	s_nop 3
	v_add_f32_e32 v5, s98, v5
	v_add_f32_e32 v5, s99, v5
	v_mul_f32_e32 v5, 0x3a800000, v5
	v_add_f32_e32 v5, 0x358637bd, v5
	v_rsq_f32_e32 v6, v5
	s_nop 0
	s_add_u32 s98, s97, 9
	v_pk_mul_f32 v[64:65], v[64:65], v[6:7] op_sel_hi:[1,0]
	v_pk_mul_f32 v[66:67], v[66:67], v[6:7] op_sel_hi:[1,0]
	v_pk_mul_f32 v[68:69], v[68:69], v[6:7] op_sel_hi:[1,0]
	v_pk_mul_f32 v[70:71], v[70:71], v[6:7] op_sel_hi:[1,0]
	v_pk_mul_f32 v[72:73], v[72:73], v[6:7] op_sel_hi:[1,0]
	v_pk_mul_f32 v[74:75], v[74:75], v[6:7] op_sel_hi:[1,0]
	v_pk_mul_f32 v[76:77], v[76:77], v[6:7] op_sel_hi:[1,0]
	v_pk_mul_f32 v[78:79], v[78:79], v[6:7] op_sel_hi:[1,0]
	v_pk_mul_f32 v[64:65], v[64:65], v[112:113]
	v_pk_mul_f32 v[66:67], v[66:67], v[114:115]
	v_pk_mul_f32 v[68:69], v[68:69], v[116:117]
	v_pk_mul_f32 v[70:71], v[70:71], v[118:119]
	v_pk_mul_f32 v[72:73], v[72:73], v[120:121]
	v_pk_mul_f32 v[74:75], v[74:75], v[122:123]
	v_pk_mul_f32 v[76:77], v[76:77], v[124:125]
	v_pk_mul_f32 v[78:79], v[78:79], v[126:127]
	v_pk_fma_f32 v[64:65], v[64:65], v[128:129], v[144:145]
	v_pk_fma_f32 v[66:67], v[66:67], v[130:131], v[146:147]
	v_pk_fma_f32 v[68:69], v[68:69], v[132:133], v[148:149]
	v_pk_fma_f32 v[70:71], v[70:71], v[134:135], v[150:151]
	v_pk_fma_f32 v[72:73], v[72:73], v[136:137], v[152:153]
	v_pk_fma_f32 v[74:75], v[74:75], v[138:139], v[154:155]
	v_pk_fma_f32 v[76:77], v[76:77], v[140:141], v[156:157]
	v_pk_fma_f32 v[78:79], v[78:79], v[142:143], v[158:159]
	v_cvt_pk_bf16_f32 v64, v64, v65
	v_cvt_pk_bf16_f32 v65, v66, v67
	v_cvt_pk_bf16_f32 v66, v68, v69
	v_cvt_pk_bf16_f32 v67, v70, v71
	v_cvt_pk_bf16_f32 v68, v72, v73
	v_cvt_pk_bf16_f32 v69, v74, v75
	v_cvt_pk_bf16_f32 v70, v76, v77
	v_cvt_pk_bf16_f32 v71, v78, v79
	s_lshl_b32 s99, s98, 11
	v_lshl_add_u32 v8, v0, 3, s99
	global_store_dwordx2 v8, v[64:65], s[94:95]
	global_store_dwordx2 v8, v[66:67], s[94:95] offset:512
	global_store_dwordx2 v8, v[68:69], s[94:95] offset:1024
	global_store_dwordx2 v8, v[70:71], s[94:95] offset:1536
	s_lshl_b32 s99, s98, 2
	v_mov_b32_e32 v9, s99
	v_mov_b32_e32 v10, 0
	v_cmp_eq_u32_e32 vcc, 0, v0
	s_and_saveexec_b64 s[98:99], vcc
	global_store_dword v9, v10, s[90:91]
	global_store_dword v9, v10, s[92:93]
	s_or_b64 exec, exec, s[98:99]
	s_add_u32 s98, s97, 15
	s_lshl_b32 s98, s98, 12
	v_add_u32_e32 v3, s98, v1
	global_load_dwordx4 v[64:67], v3, s[88:89] nt
	global_load_dwordx4 v[68:71], v3, s[88:89] offset:1024 nt
	global_load_dwordx4 v[72:75], v3, s[88:89] offset:2048 nt
	global_load_dwordx4 v[76:79], v3, s[88:89] offset:3072 nt
	s_waitcnt vmcnt(50)
	v_mul_f32_e32 v4, v80, v80
	v_fma_f32 v4, v81, v81, v4
	v_fma_f32 v4, v82, v82, v4
	v_fma_f32 v4, v83, v83, v4
	v_fma_f32 v4, v84, v84, v4
	v_fma_f32 v4, v85, v85, v4
	v_fma_f32 v4, v86, v86, v4
	v_fma_f32 v4, v87, v87, v4
	v_fma_f32 v4, v88, v88, v4
	v_fma_f32 v4, v89, v89, v4
	v_fma_f32 v4, v90, v90, v4
	v_fma_f32 v4, v91, v91, v4
	v_fma_f32 v4, v92, v92, v4
	v_fma_f32 v4, v93, v93, v4
	v_fma_f32 v4, v94, v94, v4
	v_fma_f32 v4, v95, v95, v4
	s_nop 1
	v_add_f32_dpp v5, v4, v4 quad_perm:[1,0,3,2] row_mask:0xf bank_mask:0xf
	s_nop 1
	v_add_f32_dpp v4, v5, v5 quad_perm:[2,3,0,1] row_mask:0xf bank_mask:0xf
	s_nop 1
	v_add_f32_dpp v5, v4, v4 row_half_mirror row_mask:0xf bank_mask:0xf
	s_nop 1
	v_add_f32_dpp v4, v5, v5 row_mirror row_mask:0xf bank_mask:0xf
	s_nop 1
	v_readlane_b32 s98, v4, 0
	v_readlane_b32 s99, v4, 16
	s_nop 3
	v_mov_b32_e32 v5, s98
	v_add_f32_e32 v5, s99, v5
	v_readlane_b32 s98, v4, 32
	v_readlane_b32 s99, v4, 48
	s_nop 3
	v_add_f32_e32 v5, s98, v5
	v_add_f32_e32 v5, s99, v5
	v_mul_f32_e32 v5, 0x3a800000, v5
	v_add_f32_e32 v5, 0x358637bd, v5
	v_rsq_f32_e32 v6, v5
	s_nop 0
	s_add_u32 s98, s97, 10
	v_pk_mul_f32 v[80:81], v[80:81], v[6:7] op_sel_hi:[1,0]
	v_pk_mul_f32 v[82:83], v[82:83], v[6:7] op_sel_hi:[1,0]
	v_pk_mul_f32 v[84:85], v[84:85], v[6:7] op_sel_hi:[1,0]
	v_pk_mul_f32 v[86:87], v[86:87], v[6:7] op_sel_hi:[1,0]
	v_pk_mul_f32 v[88:89], v[88:89], v[6:7] op_sel_hi:[1,0]
	v_pk_mul_f32 v[90:91], v[90:91], v[6:7] op_sel_hi:[1,0]
	v_pk_mul_f32 v[92:93], v[92:93], v[6:7] op_sel_hi:[1,0]
	v_pk_mul_f32 v[94:95], v[94:95], v[6:7] op_sel_hi:[1,0]
	v_pk_mul_f32 v[80:81], v[80:81], v[112:113]
	v_pk_mul_f32 v[82:83], v[82:83], v[114:115]
	v_pk_mul_f32 v[84:85], v[84:85], v[116:117]
	v_pk_mul_f32 v[86:87], v[86:87], v[118:119]
	v_pk_mul_f32 v[88:89], v[88:89], v[120:121]
	v_pk_mul_f32 v[90:91], v[90:91], v[122:123]
	v_pk_mul_f32 v[92:93], v[92:93], v[124:125]
	v_pk_mul_f32 v[94:95], v[94:95], v[126:127]
	v_pk_fma_f32 v[80:81], v[80:81], v[128:129], v[144:145]
	v_pk_fma_f32 v[82:83], v[82:83], v[130:131], v[146:147]
	v_pk_fma_f32 v[84:85], v[84:85], v[132:133], v[148:149]
	v_pk_fma_f32 v[86:87], v[86:87], v[134:135], v[150:151]
	v_pk_fma_f32 v[88:89], v[88:89], v[136:137], v[152:153]
	v_pk_fma_f32 v[90:91], v[90:91], v[138:139], v[154:155]
	v_pk_fma_f32 v[92:93], v[92:93], v[140:141], v[156:157]
	v_pk_fma_f32 v[94:95], v[94:95], v[142:143], v[158:159]
	v_cvt_pk_bf16_f32 v80, v80, v81
	v_cvt_pk_bf16_f32 v81, v82, v83
	v_cvt_pk_bf16_f32 v82, v84, v85
	v_cvt_pk_bf16_f32 v83, v86, v87
	v_cvt_pk_bf16_f32 v84, v88, v89
	v_cvt_pk_bf16_f32 v85, v90, v91
	v_cvt_pk_bf16_f32 v86, v92, v93
	v_cvt_pk_bf16_f32 v87, v94, v95
	s_lshl_b32 s99, s98, 11
	v_lshl_add_u32 v8, v0, 3, s99
	global_store_dwordx2 v8, v[80:81], s[94:95]
	global_store_dwordx2 v8, v[82:83], s[94:95] offset:512
	global_store_dwordx2 v8, v[84:85], s[94:95] offset:1024
	global_store_dwordx2 v8, v[86:87], s[94:95] offset:1536
	s_lshl_b32 s99, s98, 2
	v_mov_b32_e32 v9, s99
	v_mov_b32_e32 v10, 0
	v_cmp_eq_u32_e32 vcc, 0, v0
	s_and_saveexec_b64 s[98:99], vcc
	global_store_dword v9, v10, s[90:91]
	global_store_dword v9, v10, s[92:93]
	s_or_b64 exec, exec, s[98:99]
	s_waitcnt vmcnt(46)
	v_mul_f32_e32 v4, v96, v96
	v_fma_f32 v4, v97, v97, v4
	v_fma_f32 v4, v98, v98, v4
	v_fma_f32 v4, v99, v99, v4
	v_fma_f32 v4, v100, v100, v4
	v_fma_f32 v4, v101, v101, v4
	v_fma_f32 v4, v102, v102, v4
	v_fma_f32 v4, v103, v103, v4
	v_fma_f32 v4, v104, v104, v4
	v_fma_f32 v4, v105, v105, v4
	v_fma_f32 v4, v106, v106, v4
	v_fma_f32 v4, v107, v107, v4
	v_fma_f32 v4, v108, v108, v4
	v_fma_f32 v4, v109, v109, v4
	v_fma_f32 v4, v110, v110, v4
	v_fma_f32 v4, v111, v111, v4
	s_nop 1
	v_add_f32_dpp v5, v4, v4 quad_perm:[1,0,3,2] row_mask:0xf bank_mask:0xf
	s_nop 1
	v_add_f32_dpp v4, v5, v5 quad_perm:[2,3,0,1] row_mask:0xf bank_mask:0xf
	s_nop 1
	v_add_f32_dpp v5, v4, v4 row_half_mirror row_mask:0xf bank_mask:0xf
	s_nop 1
	v_add_f32_dpp v4, v5, v5 row_mirror row_mask:0xf bank_mask:0xf
	s_nop 1
	v_readlane_b32 s98, v4, 0
	v_readlane_b32 s99, v4, 16
	s_nop 3
	v_mov_b32_e32 v5, s98
	v_add_f32_e32 v5, s99, v5
	v_readlane_b32 s98, v4, 32
	v_readlane_b32 s99, v4, 48
	s_nop 3
	v_add_f32_e32 v5, s98, v5
	v_add_f32_e32 v5, s99, v5
	v_mul_f32_e32 v5, 0x3a800000, v5
	v_add_f32_e32 v5, 0x358637bd, v5
	v_rsq_f32_e32 v6, v5
	s_nop 0
	s_add_u32 s98, s97, 11
	v_pk_mul_f32 v[96:97], v[96:97], v[6:7] op_sel_hi:[1,0]
	v_pk_mul_f32 v[98:99], v[98:99], v[6:7] op_sel_hi:[1,0]
	v_pk_mul_f32 v[100:101], v[100:101], v[6:7] op_sel_hi:[1,0]
	v_pk_mul_f32 v[102:103], v[102:103], v[6:7] op_sel_hi:[1,0]
	v_pk_mul_f32 v[104:105], v[104:105], v[6:7] op_sel_hi:[1,0]
	v_pk_mul_f32 v[106:107], v[106:107], v[6:7] op_sel_hi:[1,0]
	v_pk_mul_f32 v[108:109], v[108:109], v[6:7] op_sel_hi:[1,0]
	v_pk_mul_f32 v[110:111], v[110:111], v[6:7] op_sel_hi:[1,0]
	v_pk_mul_f32 v[96:97], v[96:97], v[112:113]
	v_pk_mul_f32 v[98:99], v[98:99], v[114:115]
	v_pk_mul_f32 v[100:101], v[100:101], v[116:117]
	v_pk_mul_f32 v[102:103], v[102:103], v[118:119]
	v_pk_mul_f32 v[104:105], v[104:105], v[120:121]
	v_pk_mul_f32 v[106:107], v[106:107], v[122:123]
	v_pk_mul_f32 v[108:109], v[108:109], v[124:125]
	v_pk_mul_f32 v[110:111], v[110:111], v[126:127]
	v_pk_fma_f32 v[96:97], v[96:97], v[128:129], v[144:145]
	v_pk_fma_f32 v[98:99], v[98:99], v[130:131], v[146:147]
	v_pk_fma_f32 v[100:101], v[100:101], v[132:133], v[148:149]
	v_pk_fma_f32 v[102:103], v[102:103], v[134:135], v[150:151]
	v_pk_fma_f32 v[104:105], v[104:105], v[136:137], v[152:153]
	v_pk_fma_f32 v[106:107], v[106:107], v[138:139], v[154:155]
	v_pk_fma_f32 v[108:109], v[108:109], v[140:141], v[156:157]
	v_pk_fma_f32 v[110:111], v[110:111], v[142:143], v[158:159]
	v_cvt_pk_bf16_f32 v96, v96, v97
	v_cvt_pk_bf16_f32 v97, v98, v99
	v_cvt_pk_bf16_f32 v98, v100, v101
	v_cvt_pk_bf16_f32 v99, v102, v103
	v_cvt_pk_bf16_f32 v100, v104, v105
	v_cvt_pk_bf16_f32 v101, v106, v107
	v_cvt_pk_bf16_f32 v102, v108, v109
	v_cvt_pk_bf16_f32 v103, v110, v111
	s_lshl_b32 s99, s98, 11
	v_lshl_add_u32 v8, v0, 3, s99
	global_store_dwordx2 v8, v[96:97], s[94:95]
	global_store_dwordx2 v8, v[98:99], s[94:95] offset:512
	global_store_dwordx2 v8, v[100:101], s[94:95] offset:1024
	global_store_dwordx2 v8, v[102:103], s[94:95] offset:1536
	s_lshl_b32 s99, s98, 2
	v_mov_b32_e32 v9, s99
	v_mov_b32_e32 v10, 0
	v_cmp_eq_u32_e32 vcc, 0, v0
	s_and_saveexec_b64 s[98:99], vcc
	global_store_dword v9, v10, s[90:91]
	global_store_dword v9, v10, s[92:93]
	s_or_b64 exec, exec, s[98:99]
	s_waitcnt vmcnt(42)
	v_mul_f32_e32 v4, v16, v16
	v_fma_f32 v4, v17, v17, v4
	v_fma_f32 v4, v18, v18, v4
	v_fma_f32 v4, v19, v19, v4
	v_fma_f32 v4, v20, v20, v4
	v_fma_f32 v4, v21, v21, v4
	v_fma_f32 v4, v22, v22, v4
	v_fma_f32 v4, v23, v23, v4
	v_fma_f32 v4, v24, v24, v4
	v_fma_f32 v4, v25, v25, v4
	v_fma_f32 v4, v26, v26, v4
	v_fma_f32 v4, v27, v27, v4
	v_fma_f32 v4, v28, v28, v4
	v_fma_f32 v4, v29, v29, v4
	v_fma_f32 v4, v30, v30, v4
	v_fma_f32 v4, v31, v31, v4
	s_nop 1
	v_add_f32_dpp v5, v4, v4 quad_perm:[1,0,3,2] row_mask:0xf bank_mask:0xf
	s_nop 1
	v_add_f32_dpp v4, v5, v5 quad_perm:[2,3,0,1] row_mask:0xf bank_mask:0xf
	s_nop 1
	v_add_f32_dpp v5, v4, v4 row_half_mirror row_mask:0xf bank_mask:0xf
	s_nop 1
	v_add_f32_dpp v4, v5, v5 row_mirror row_mask:0xf bank_mask:0xf
	s_nop 1
	v_readlane_b32 s98, v4, 0
	v_readlane_b32 s99, v4, 16
	s_nop 3
	v_mov_b32_e32 v5, s98
	v_add_f32_e32 v5, s99, v5
	v_readlane_b32 s98, v4, 32
	v_readlane_b32 s99, v4, 48
	s_nop 3
	v_add_f32_e32 v5, s98, v5
	v_add_f32_e32 v5, s99, v5
	v_mul_f32_e32 v5, 0x3a800000, v5
	v_add_f32_e32 v5, 0x358637bd, v5
	v_rsq_f32_e32 v6, v5
	s_nop 0
	s_add_u32 s98, s97, 12
	v_pk_mul_f32 v[16:17], v[16:17], v[6:7] op_sel_hi:[1,0]
	v_pk_mul_f32 v[18:19], v[18:19], v[6:7] op_sel_hi:[1,0]
	v_pk_mul_f32 v[20:21], v[20:21], v[6:7] op_sel_hi:[1,0]
	v_pk_mul_f32 v[22:23], v[22:23], v[6:7] op_sel_hi:[1,0]
	v_pk_mul_f32 v[24:25], v[24:25], v[6:7] op_sel_hi:[1,0]
	v_pk_mul_f32 v[26:27], v[26:27], v[6:7] op_sel_hi:[1,0]
	v_pk_mul_f32 v[28:29], v[28:29], v[6:7] op_sel_hi:[1,0]
	v_pk_mul_f32 v[30:31], v[30:31], v[6:7] op_sel_hi:[1,0]
	v_pk_mul_f32 v[16:17], v[16:17], v[112:113]
	v_pk_mul_f32 v[18:19], v[18:19], v[114:115]
	v_pk_mul_f32 v[20:21], v[20:21], v[116:117]
	v_pk_mul_f32 v[22:23], v[22:23], v[118:119]
	v_pk_mul_f32 v[24:25], v[24:25], v[120:121]
	v_pk_mul_f32 v[26:27], v[26:27], v[122:123]
	v_pk_mul_f32 v[28:29], v[28:29], v[124:125]
	v_pk_mul_f32 v[30:31], v[30:31], v[126:127]
	v_pk_fma_f32 v[16:17], v[16:17], v[128:129], v[144:145]
	v_pk_fma_f32 v[18:19], v[18:19], v[130:131], v[146:147]
	v_pk_fma_f32 v[20:21], v[20:21], v[132:133], v[148:149]
	v_pk_fma_f32 v[22:23], v[22:23], v[134:135], v[150:151]
	v_pk_fma_f32 v[24:25], v[24:25], v[136:137], v[152:153]
	v_pk_fma_f32 v[26:27], v[26:27], v[138:139], v[154:155]
	v_pk_fma_f32 v[28:29], v[28:29], v[140:141], v[156:157]
	v_pk_fma_f32 v[30:31], v[30:31], v[142:143], v[158:159]
	v_cvt_pk_bf16_f32 v16, v16, v17
	v_cvt_pk_bf16_f32 v17, v18, v19
	v_cvt_pk_bf16_f32 v18, v20, v21
	v_cvt_pk_bf16_f32 v19, v22, v23
	v_cvt_pk_bf16_f32 v20, v24, v25
	v_cvt_pk_bf16_f32 v21, v26, v27
	v_cvt_pk_bf16_f32 v22, v28, v29
	v_cvt_pk_bf16_f32 v23, v30, v31
	s_lshl_b32 s99, s98, 11
	v_lshl_add_u32 v8, v0, 3, s99
	global_store_dwordx2 v8, v[16:17], s[94:95]
	global_store_dwordx2 v8, v[18:19], s[94:95] offset:512
	global_store_dwordx2 v8, v[20:21], s[94:95] offset:1024
	global_store_dwordx2 v8, v[22:23], s[94:95] offset:1536
	s_lshl_b32 s99, s98, 2
	v_mov_b32_e32 v9, s99
	v_mov_b32_e32 v10, 0
	v_cmp_eq_u32_e32 vcc, 0, v0
	s_and_saveexec_b64 s[98:99], vcc
	global_store_dword v9, v10, s[90:91]
	global_store_dword v9, v10, s[92:93]
	s_or_b64 exec, exec, s[98:99]
	s_waitcnt vmcnt(38)
	v_mul_f32_e32 v4, v32, v32
	v_fma_f32 v4, v33, v33, v4
	v_fma_f32 v4, v34, v34, v4
	v_fma_f32 v4, v35, v35, v4
	v_fma_f32 v4, v36, v36, v4
	v_fma_f32 v4, v37, v37, v4
	v_fma_f32 v4, v38, v38, v4
	v_fma_f32 v4, v39, v39, v4
	v_fma_f32 v4, v40, v40, v4
	v_fma_f32 v4, v41, v41, v4
	v_fma_f32 v4, v42, v42, v4
	v_fma_f32 v4, v43, v43, v4
	v_fma_f32 v4, v44, v44, v4
	v_fma_f32 v4, v45, v45, v4
	v_fma_f32 v4, v46, v46, v4
	v_fma_f32 v4, v47, v47, v4
	s_nop 1
	v_add_f32_dpp v5, v4, v4 quad_perm:[1,0,3,2] row_mask:0xf bank_mask:0xf
	s_nop 1
	v_add_f32_dpp v4, v5, v5 quad_perm:[2,3,0,1] row_mask:0xf bank_mask:0xf
	s_nop 1
	v_add_f32_dpp v5, v4, v4 row_half_mirror row_mask:0xf bank_mask:0xf
	s_nop 1
	v_add_f32_dpp v4, v5, v5 row_mirror row_mask:0xf bank_mask:0xf
	s_nop 1
	v_readlane_b32 s98, v4, 0
	v_readlane_b32 s99, v4, 16
	s_nop 3
	v_mov_b32_e32 v5, s98
	v_add_f32_e32 v5, s99, v5
	v_readlane_b32 s98, v4, 32
	v_readlane_b32 s99, v4, 48
	s_nop 3
	v_add_f32_e32 v5, s98, v5
	v_add_f32_e32 v5, s99, v5
	v_mul_f32_e32 v5, 0x3a800000, v5
	v_add_f32_e32 v5, 0x358637bd, v5
	v_rsq_f32_e32 v6, v5
	s_nop 0
	s_add_u32 s98, s97, 13
	v_pk_mul_f32 v[32:33], v[32:33], v[6:7] op_sel_hi:[1,0]
	v_pk_mul_f32 v[34:35], v[34:35], v[6:7] op_sel_hi:[1,0]
	v_pk_mul_f32 v[36:37], v[36:37], v[6:7] op_sel_hi:[1,0]
	v_pk_mul_f32 v[38:39], v[38:39], v[6:7] op_sel_hi:[1,0]
	v_pk_mul_f32 v[40:41], v[40:41], v[6:7] op_sel_hi:[1,0]
	v_pk_mul_f32 v[42:43], v[42:43], v[6:7] op_sel_hi:[1,0]
	v_pk_mul_f32 v[44:45], v[44:45], v[6:7] op_sel_hi:[1,0]
	v_pk_mul_f32 v[46:47], v[46:47], v[6:7] op_sel_hi:[1,0]
	v_pk_mul_f32 v[32:33], v[32:33], v[112:113]
	v_pk_mul_f32 v[34:35], v[34:35], v[114:115]
	v_pk_mul_f32 v[36:37], v[36:37], v[116:117]
	v_pk_mul_f32 v[38:39], v[38:39], v[118:119]
	v_pk_mul_f32 v[40:41], v[40:41], v[120:121]
	v_pk_mul_f32 v[42:43], v[42:43], v[122:123]
	v_pk_mul_f32 v[44:45], v[44:45], v[124:125]
	v_pk_mul_f32 v[46:47], v[46:47], v[126:127]
	v_pk_fma_f32 v[32:33], v[32:33], v[128:129], v[144:145]
	v_pk_fma_f32 v[34:35], v[34:35], v[130:131], v[146:147]
	v_pk_fma_f32 v[36:37], v[36:37], v[132:133], v[148:149]
	v_pk_fma_f32 v[38:39], v[38:39], v[134:135], v[150:151]
	v_pk_fma_f32 v[40:41], v[40:41], v[136:137], v[152:153]
	v_pk_fma_f32 v[42:43], v[42:43], v[138:139], v[154:155]
	v_pk_fma_f32 v[44:45], v[44:45], v[140:141], v[156:157]
	v_pk_fma_f32 v[46:47], v[46:47], v[142:143], v[158:159]
	v_cvt_pk_bf16_f32 v32, v32, v33
	v_cvt_pk_bf16_f32 v33, v34, v35
	v_cvt_pk_bf16_f32 v34, v36, v37
	v_cvt_pk_bf16_f32 v35, v38, v39
	v_cvt_pk_bf16_f32 v36, v40, v41
	v_cvt_pk_bf16_f32 v37, v42, v43
	v_cvt_pk_bf16_f32 v38, v44, v45
	v_cvt_pk_bf16_f32 v39, v46, v47
	s_lshl_b32 s99, s98, 11
	v_lshl_add_u32 v8, v0, 3, s99
	global_store_dwordx2 v8, v[32:33], s[94:95]
	global_store_dwordx2 v8, v[34:35], s[94:95] offset:512
	global_store_dwordx2 v8, v[36:37], s[94:95] offset:1024
	global_store_dwordx2 v8, v[38:39], s[94:95] offset:1536
	s_lshl_b32 s99, s98, 2
	v_mov_b32_e32 v9, s99
	v_mov_b32_e32 v10, 0
	v_cmp_eq_u32_e32 vcc, 0, v0
	s_and_saveexec_b64 s[98:99], vcc
	global_store_dword v9, v10, s[90:91]
	global_store_dword v9, v10, s[92:93]
	s_or_b64 exec, exec, s[98:99]
	s_waitcnt vmcnt(34)
	v_mul_f32_e32 v4, v48, v48
	v_fma_f32 v4, v49, v49, v4
	v_fma_f32 v4, v50, v50, v4
	v_fma_f32 v4, v51, v51, v4
	v_fma_f32 v4, v52, v52, v4
	v_fma_f32 v4, v53, v53, v4
	v_fma_f32 v4, v54, v54, v4
	v_fma_f32 v4, v55, v55, v4
	v_fma_f32 v4, v56, v56, v4
	v_fma_f32 v4, v57, v57, v4
	v_fma_f32 v4, v58, v58, v4
	v_fma_f32 v4, v59, v59, v4
	v_fma_f32 v4, v60, v60, v4
	v_fma_f32 v4, v61, v61, v4
	v_fma_f32 v4, v62, v62, v4
	v_fma_f32 v4, v63, v63, v4
	s_nop 1
	v_add_f32_dpp v5, v4, v4 quad_perm:[1,0,3,2] row_mask:0xf bank_mask:0xf
	s_nop 1
	v_add_f32_dpp v4, v5, v5 quad_perm:[2,3,0,1] row_mask:0xf bank_mask:0xf
	s_nop 1
	v_add_f32_dpp v5, v4, v4 row_half_mirror row_mask:0xf bank_mask:0xf
	s_nop 1
	v_add_f32_dpp v4, v5, v5 row_mirror row_mask:0xf bank_mask:0xf
	s_nop 1
	v_readlane_b32 s98, v4, 0
	v_readlane_b32 s99, v4, 16
	s_nop 3
	v_mov_b32_e32 v5, s98
	v_add_f32_e32 v5, s99, v5
	v_readlane_b32 s98, v4, 32
	v_readlane_b32 s99, v4, 48
	s_nop 3
	v_add_f32_e32 v5, s98, v5
	v_add_f32_e32 v5, s99, v5
	v_mul_f32_e32 v5, 0x3a800000, v5
	v_add_f32_e32 v5, 0x358637bd, v5
	v_rsq_f32_e32 v6, v5
	s_nop 0
	s_add_u32 s98, s97, 14
	v_pk_mul_f32 v[48:49], v[48:49], v[6:7] op_sel_hi:[1,0]
	v_pk_mul_f32 v[50:51], v[50:51], v[6:7] op_sel_hi:[1,0]
	v_pk_mul_f32 v[52:53], v[52:53], v[6:7] op_sel_hi:[1,0]
	v_pk_mul_f32 v[54:55], v[54:55], v[6:7] op_sel_hi:[1,0]
	v_pk_mul_f32 v[56:57], v[56:57], v[6:7] op_sel_hi:[1,0]
	v_pk_mul_f32 v[58:59], v[58:59], v[6:7] op_sel_hi:[1,0]
	v_pk_mul_f32 v[60:61], v[60:61], v[6:7] op_sel_hi:[1,0]
	v_pk_mul_f32 v[62:63], v[62:63], v[6:7] op_sel_hi:[1,0]
	v_pk_mul_f32 v[48:49], v[48:49], v[112:113]
	v_pk_mul_f32 v[50:51], v[50:51], v[114:115]
	v_pk_mul_f32 v[52:53], v[52:53], v[116:117]
	v_pk_mul_f32 v[54:55], v[54:55], v[118:119]
	v_pk_mul_f32 v[56:57], v[56:57], v[120:121]
	v_pk_mul_f32 v[58:59], v[58:59], v[122:123]
	v_pk_mul_f32 v[60:61], v[60:61], v[124:125]
	v_pk_mul_f32 v[62:63], v[62:63], v[126:127]
	v_pk_fma_f32 v[48:49], v[48:49], v[128:129], v[144:145]
	v_pk_fma_f32 v[50:51], v[50:51], v[130:131], v[146:147]
	v_pk_fma_f32 v[52:53], v[52:53], v[132:133], v[148:149]
	v_pk_fma_f32 v[54:55], v[54:55], v[134:135], v[150:151]
	v_pk_fma_f32 v[56:57], v[56:57], v[136:137], v[152:153]
	v_pk_fma_f32 v[58:59], v[58:59], v[138:139], v[154:155]
	v_pk_fma_f32 v[60:61], v[60:61], v[140:141], v[156:157]
	v_pk_fma_f32 v[62:63], v[62:63], v[142:143], v[158:159]
	v_cvt_pk_bf16_f32 v48, v48, v49
	v_cvt_pk_bf16_f32 v49, v50, v51
	v_cvt_pk_bf16_f32 v50, v52, v53
	v_cvt_pk_bf16_f32 v51, v54, v55
	v_cvt_pk_bf16_f32 v52, v56, v57
	v_cvt_pk_bf16_f32 v53, v58, v59
	v_cvt_pk_bf16_f32 v54, v60, v61
	v_cvt_pk_bf16_f32 v55, v62, v63
	s_lshl_b32 s99, s98, 11
	v_lshl_add_u32 v8, v0, 3, s99
	global_store_dwordx2 v8, v[48:49], s[94:95]
	global_store_dwordx2 v8, v[50:51], s[94:95] offset:512
	global_store_dwordx2 v8, v[52:53], s[94:95] offset:1024
	global_store_dwordx2 v8, v[54:55], s[94:95] offset:1536
	s_lshl_b32 s99, s98, 2
	v_mov_b32_e32 v9, s99
	v_mov_b32_e32 v10, 0
	v_cmp_eq_u32_e32 vcc, 0, v0
	s_and_saveexec_b64 s[98:99], vcc
	global_store_dword v9, v10, s[90:91]
	global_store_dword v9, v10, s[92:93]
	s_or_b64 exec, exec, s[98:99]
	s_waitcnt vmcnt(30)
	v_mul_f32_e32 v4, v64, v64
	v_fma_f32 v4, v65, v65, v4
	v_fma_f32 v4, v66, v66, v4
	v_fma_f32 v4, v67, v67, v4
	v_fma_f32 v4, v68, v68, v4
	v_fma_f32 v4, v69, v69, v4
	v_fma_f32 v4, v70, v70, v4
	v_fma_f32 v4, v71, v71, v4
	v_fma_f32 v4, v72, v72, v4
	v_fma_f32 v4, v73, v73, v4
	v_fma_f32 v4, v74, v74, v4
	v_fma_f32 v4, v75, v75, v4
	v_fma_f32 v4, v76, v76, v4
	v_fma_f32 v4, v77, v77, v4
	v_fma_f32 v4, v78, v78, v4
	v_fma_f32 v4, v79, v79, v4
	s_nop 1
	v_add_f32_dpp v5, v4, v4 quad_perm:[1,0,3,2] row_mask:0xf bank_mask:0xf
	s_nop 1
	v_add_f32_dpp v4, v5, v5 quad_perm:[2,3,0,1] row_mask:0xf bank_mask:0xf
	s_nop 1
	v_add_f32_dpp v5, v4, v4 row_half_mirror row_mask:0xf bank_mask:0xf
	s_nop 1
	v_add_f32_dpp v4, v5, v5 row_mirror row_mask:0xf bank_mask:0xf
	s_nop 1
	v_readlane_b32 s98, v4, 0
	v_readlane_b32 s99, v4, 16
	s_nop 3
	v_mov_b32_e32 v5, s98
	v_add_f32_e32 v5, s99, v5
	v_readlane_b32 s98, v4, 32
	v_readlane_b32 s99, v4, 48
	s_nop 3
	v_add_f32_e32 v5, s98, v5
	v_add_f32_e32 v5, s99, v5
	v_mul_f32_e32 v5, 0x3a800000, v5
	v_add_f32_e32 v5, 0x358637bd, v5
	v_rsq_f32_e32 v6, v5
	s_nop 0
	s_add_u32 s98, s97, 15
	v_pk_mul_f32 v[64:65], v[64:65], v[6:7] op_sel_hi:[1,0]
	v_pk_mul_f32 v[66:67], v[66:67], v[6:7] op_sel_hi:[1,0]
	v_pk_mul_f32 v[68:69], v[68:69], v[6:7] op_sel_hi:[1,0]
	v_pk_mul_f32 v[70:71], v[70:71], v[6:7] op_sel_hi:[1,0]
	v_pk_mul_f32 v[72:73], v[72:73], v[6:7] op_sel_hi:[1,0]
	v_pk_mul_f32 v[74:75], v[74:75], v[6:7] op_sel_hi:[1,0]
	v_pk_mul_f32 v[76:77], v[76:77], v[6:7] op_sel_hi:[1,0]
	v_pk_mul_f32 v[78:79], v[78:79], v[6:7] op_sel_hi:[1,0]
	v_pk_mul_f32 v[64:65], v[64:65], v[112:113]
	v_pk_mul_f32 v[66:67], v[66:67], v[114:115]
	v_pk_mul_f32 v[68:69], v[68:69], v[116:117]
	v_pk_mul_f32 v[70:71], v[70:71], v[118:119]
	v_pk_mul_f32 v[72:73], v[72:73], v[120:121]
	v_pk_mul_f32 v[74:75], v[74:75], v[122:123]
	v_pk_mul_f32 v[76:77], v[76:77], v[124:125]
	v_pk_mul_f32 v[78:79], v[78:79], v[126:127]
	v_pk_fma_f32 v[64:65], v[64:65], v[128:129], v[144:145]
	v_pk_fma_f32 v[66:67], v[66:67], v[130:131], v[146:147]
	v_pk_fma_f32 v[68:69], v[68:69], v[132:133], v[148:149]
	v_pk_fma_f32 v[70:71], v[70:71], v[134:135], v[150:151]
	v_pk_fma_f32 v[72:73], v[72:73], v[136:137], v[152:153]
	v_pk_fma_f32 v[74:75], v[74:75], v[138:139], v[154:155]
	v_pk_fma_f32 v[76:77], v[76:77], v[140:141], v[156:157]
	v_pk_fma_f32 v[78:79], v[78:79], v[142:143], v[158:159]
	v_cvt_pk_bf16_f32 v64, v64, v65
	v_cvt_pk_bf16_f32 v65, v66, v67
	v_cvt_pk_bf16_f32 v66, v68, v69
	v_cvt_pk_bf16_f32 v67, v70, v71
	v_cvt_pk_bf16_f32 v68, v72, v73
	v_cvt_pk_bf16_f32 v69, v74, v75
	v_cvt_pk_bf16_f32 v70, v76, v77
	v_cvt_pk_bf16_f32 v71, v78, v79
	s_lshl_b32 s99, s98, 11
	v_lshl_add_u32 v8, v0, 3, s99
	global_store_dwordx2 v8, v[64:65], s[94:95]
	global_store_dwordx2 v8, v[66:67], s[94:95] offset:512
	global_store_dwordx2 v8, v[68:69], s[94:95] offset:1024
	global_store_dwordx2 v8, v[70:71], s[94:95] offset:1536
	s_lshl_b32 s99, s98, 2
	v_mov_b32_e32 v9, s99
	v_mov_b32_e32 v10, 0
	v_cmp_eq_u32_e32 vcc, 0, v0
	s_and_saveexec_b64 s[98:99], vcc
	global_store_dword v9, v10, s[90:91]
	global_store_dword v9, v10, s[92:93]
	s_or_b64 exec, exec, s[98:99]
	s_waitcnt vmcnt(0)

.LBB0_1397:
	s_cmp_gt_i32 s44, 6
	s_waitcnt lgkmcnt(0)
	s_cselect_b64 s[2:3], -1, 0
	s_cmp_lt_i32 s45, 7
	s_cselect_b64 s[4:5], -1, 0
	s_or_b64 s[2:3], s[2:3], s[4:5]
	s_and_b64 vcc, exec, s[2:3]
	s_cbranch_vccnz .LBB0_1457
	s_lshl_b32 s96, s22, 3
	s_lshr_b32 s97, s70, 6
	s_add_u32 s96, s96, s97
	s_lshl_b32 s97, s96, 4
	s_cmpk_ge_u32 s97, 0x8000
	s_cbranch_scc1 .Lnp6_done
	s_load_dwordx2 s[88:89], s[0:1], 0xb8
	s_load_dwordx2 s[90:91], s[0:1], 0x18
	s_load_dwordx2 s[92:93], s[0:1], 0x140
	s_load_dwordx2 s[94:95], s[0:1], 0x158
	v_mbcnt_hi_u32_b32 v0, -1, v210
	v_lshlrev_b32_e32 v1, 4, v0
	s_waitcnt lgkmcnt(0)
	s_add_u32 s90, s90, 4096
	s_addc_u32 s91, s91, 0
	global_load_dwordx4 v[112:115], v1, s[90:91] nt
	global_load_dwordx4 v[116:119], v1, s[90:91] offset:1024 nt
	global_load_dwordx4 v[120:123], v1, s[90:91] offset:2048 nt
	global_load_dwordx4 v[124:127], v1, s[90:91] offset:3072 nt
	s_lshr_b32 s98, s97, 12
	s_add_u32 s98, s98, 8
	s_mul_i32 s98, s98, 0x3000
	s_add_u32 s92, s92, s98
	s_addc_u32 s93, s93, 0
	global_load_dwordx4 v[144:147], v1, s[92:93] nt
	global_load_dwordx4 v[148:151], v1, s[92:93] offset:1024 nt
	global_load_dwordx4 v[152:155], v1, s[92:93] offset:2048 nt
	global_load_dwordx4 v[156:159], v1, s[92:93] offset:3072 nt
	s_add_u32 s92, s92, 0x1000
	s_addc_u32 s93, s93, 0
	global_load_dwordx4 v[128:131], v1, s[92:93] nt
	global_load_dwordx4 v[132:135], v1, s[92:93] offset:1024 nt
	global_load_dwordx4 v[136:139], v1, s[92:93] offset:2048 nt
	global_load_dwordx4 v[140:143], v1, s[92:93] offset:3072 nt
	s_load_dwordx2 s[90:91], s[0:1], 0x210
	s_load_dwordx2 s[92:93], s[0:1], 0x218
	s_add_u32 s98, s97, 0
	s_lshl_b32 s98, s98, 12
	v_add_u32_e32 v3, s98, v1
	global_load_dwordx4 v[16:19], v3, s[88:89] nt
	global_load_dwordx4 v[20:23], v3, s[88:89] offset:1024 nt
	global_load_dwordx4 v[24:27], v3, s[88:89] offset:2048 nt
	global_load_dwordx4 v[28:31], v3, s[88:89] offset:3072 nt
	s_add_u32 s98, s97, 1
	s_lshl_b32 s98, s98, 12
	v_add_u32_e32 v3, s98, v1
	global_load_dwordx4 v[32:35], v3, s[88:89] nt
	global_load_dwordx4 v[36:39], v3, s[88:89] offset:1024 nt
	global_load_dwordx4 v[40:43], v3, s[88:89] offset:2048 nt
	global_load_dwordx4 v[44:47], v3, s[88:89] offset:3072 nt
	s_add_u32 s98, s97, 2
	s_lshl_b32 s98, s98, 12
	v_add_u32_e32 v3, s98, v1
	global_load_dwordx4 v[48:51], v3, s[88:89] nt
	global_load_dwordx4 v[52:55], v3, s[88:89] offset:1024 nt
	global_load_dwordx4 v[56:59], v3, s[88:89] offset:2048 nt
	global_load_dwordx4 v[60:63], v3, s[88:89] offset:3072 nt
	s_add_u32 s98, s97, 3
	s_lshl_b32 s98, s98, 12
	v_add_u32_e32 v3, s98, v1
	global_load_dwordx4 v[64:67], v3, s[88:89] nt
	global_load_dwordx4 v[68:71], v3, s[88:89] offset:1024 nt
	global_load_dwordx4 v[72:75], v3, s[88:89] offset:2048 nt
	global_load_dwordx4 v[76:79], v3, s[88:89] offset:3072 nt
	s_add_u32 s98, s97, 4
	s_lshl_b32 s98, s98, 12
	v_add_u32_e32 v3, s98, v1
	global_load_dwordx4 v[80:83], v3, s[88:89] nt
	global_load_dwordx4 v[84:87], v3, s[88:89] offset:1024 nt
	global_load_dwordx4 v[88:91], v3, s[88:89] offset:2048 nt
	global_load_dwordx4 v[92:95], v3, s[88:89] offset:3072 nt
	s_waitcnt vmcnt(0) lgkmcnt(0)
	v_pk_add_f32 v[128:129], v[128:129], 1.0 op_sel_hi:[1,0]
	v_pk_add_f32 v[130:131], v[130:131], 1.0 op_sel_hi:[1,0]
	v_pk_add_f32 v[132:133], v[132:133], 1.0 op_sel_hi:[1,0]
	v_pk_add_f32 v[134:135], v[134:135], 1.0 op_sel_hi:[1,0]
	v_pk_add_f32 v[136:137], v[136:137], 1.0 op_sel_hi:[1,0]
	v_pk_add_f32 v[138:139], v[138:139], 1.0 op_sel_hi:[1,0]
	v_pk_add_f32 v[140:141], v[140:141], 1.0 op_sel_hi:[1,0]
	v_pk_add_f32 v[142:143], v[142:143], 1.0 op_sel_hi:[1,0]
	s_add_u32 s98, s97, 5
	s_lshl_b32 s98, s98, 12
	v_add_u32_e32 v3, s98, v1
	global_load_dwordx4 v[96:99], v3, s[88:89] nt
	global_load_dwordx4 v[100:103], v3, s[88:89] offset:1024 nt
	global_load_dwordx4 v[104:107], v3, s[88:89] offset:2048 nt
	global_load_dwordx4 v[108:111], v3, s[88:89] offset:3072 nt
	s_waitcnt vmcnt(20)
	v_mul_f32_e32 v4, v16, v16
	v_fma_f32 v4, v17, v17, v4
	v_fma_f32 v4, v18, v18, v4
	v_fma_f32 v4, v19, v19, v4
	v_fma_f32 v4, v20, v20, v4
	v_fma_f32 v4, v21, v21, v4
	v_fma_f32 v4, v22, v22, v4
	v_fma_f32 v4, v23, v23, v4
	v_fma_f32 v4, v24, v24, v4
	v_fma_f32 v4, v25, v25, v4
	v_fma_f32 v4, v26, v26, v4
	v_fma_f32 v4, v27, v27, v4
	v_fma_f32 v4, v28, v28, v4
	v_fma_f32 v4, v29, v29, v4
	v_fma_f32 v4, v30, v30, v4
	v_fma_f32 v4, v31, v31, v4
	s_nop 1
	v_add_f32_dpp v5, v4, v4 quad_perm:[1,0,3,2] row_mask:0xf bank_mask:0xf
	s_nop 1
	v_add_f32_dpp v4, v5, v5 quad_perm:[2,3,0,1] row_mask:0xf bank_mask:0xf
	s_nop 1
	v_add_f32_dpp v5, v4, v4 row_half_mirror row_mask:0xf bank_mask:0xf
	s_nop 1
	v_add_f32_dpp v4, v5, v5 row_mirror row_mask:0xf bank_mask:0xf
	s_nop 1
	v_readlane_b32 s98, v4, 0
	v_readlane_b32 s99, v4, 16
	s_nop 3
	v_mov_b32_e32 v5, s98
	v_add_f32_e32 v5, s99, v5
	v_readlane_b32 s98, v4, 32
	v_readlane_b32 s99, v4, 48
	s_nop 3
	v_add_f32_e32 v5, s98, v5
	v_add_f32_e32 v5, s99, v5
	v_mul_f32_e32 v5, 0x3a800000, v5
	v_add_f32_e32 v5, 0x358637bd, v5
	v_rsq_f32_e32 v6, v5
	s_nop 0
	s_add_u32 s98, s97, 0
	v_pk_mul_f32 v[16:17], v[16:17], v[6:7] op_sel_hi:[1,0]
	v_pk_mul_f32 v[18:19], v[18:19], v[6:7] op_sel_hi:[1,0]
	v_pk_mul_f32 v[20:21], v[20:21], v[6:7] op_sel_hi:[1,0]
	v_pk_mul_f32 v[22:23], v[22:23], v[6:7] op_sel_hi:[1,0]
	v_pk_mul_f32 v[24:25], v[24:25], v[6:7] op_sel_hi:[1,0]
	v_pk_mul_f32 v[26:27], v[26:27], v[6:7] op_sel_hi:[1,0]
	v_pk_mul_f32 v[28:29], v[28:29], v[6:7] op_sel_hi:[1,0]
	v_pk_mul_f32 v[30:31], v[30:31], v[6:7] op_sel_hi:[1,0]
	v_pk_mul_f32 v[16:17], v[16:17], v[112:113]
	v_pk_mul_f32 v[18:19], v[18:19], v[114:115]
	v_pk_mul_f32 v[20:21], v[20:21], v[116:117]
	v_pk_mul_f32 v[22:23], v[22:23], v[118:119]
	v_pk_mul_f32 v[24:25], v[24:25], v[120:121]
	v_pk_mul_f32 v[26:27], v[26:27], v[122:123]
	v_pk_mul_f32 v[28:29], v[28:29], v[124:125]
	v_pk_mul_f32 v[30:31], v[30:31], v[126:127]
	v_pk_fma_f32 v[16:17], v[16:17], v[128:129], v[144:145]
	v_pk_fma_f32 v[18:19], v[18:19], v[130:131], v[146:147]
	v_pk_fma_f32 v[20:21], v[20:21], v[132:133], v[148:149]
	v_pk_fma_f32 v[22:23], v[22:23], v[134:135], v[150:151]
	v_pk_fma_f32 v[24:25], v[24:25], v[136:137], v[152:153]
	v_pk_fma_f32 v[26:27], v[26:27], v[138:139], v[154:155]
	v_pk_fma_f32 v[28:29], v[28:29], v[140:141], v[156:157]
	v_pk_fma_f32 v[30:31], v[30:31], v[142:143], v[158:159]
	v_cvt_pk_bf16_f32 v16, v16, v17
	v_cvt_pk_bf16_f32 v17, v18, v19
	v_cvt_pk_bf16_f32 v18, v20, v21
	v_cvt_pk_bf16_f32 v19, v22, v23
	v_cvt_pk_bf16_f32 v20, v24, v25
	v_cvt_pk_bf16_f32 v21, v26, v27
	v_cvt_pk_bf16_f32 v22, v28, v29
	v_cvt_pk_bf16_f32 v23, v30, v31
	s_lshl_b32 s99, s98, 11
	v_lshl_add_u32 v8, v0, 3, s99
	global_store_dwordx2 v8, v[16:17], s[94:95]
	global_store_dwordx2 v8, v[18:19], s[94:95] offset:512
	global_store_dwordx2 v8, v[20:21], s[94:95] offset:1024
	global_store_dwordx2 v8, v[22:23], s[94:95] offset:1536
	s_lshl_b32 s99, s98, 2
	v_mov_b32_e32 v9, s99
	v_mov_b32_e32 v10, 0
	v_cmp_eq_u32_e32 vcc, 0, v0
	s_and_saveexec_b64 s[98:99], vcc
	global_store_dword v9, v10, s[90:91]
	global_store_dword v9, v10, s[92:93]
	s_or_b64 exec, exec, s[98:99]
	s_add_u32 s98, s97, 6
	s_lshl_b32 s98, s98, 12
	v_add_u32_e32 v3, s98, v1
	global_load_dwordx4 v[16:19], v3, s[88:89] nt
	global_load_dwordx4 v[20:23], v3, s[88:89] offset:1024 nt
	global_load_dwordx4 v[24:27], v3, s[88:89] offset:2048 nt
	global_load_dwordx4 v[28:31], v3, s[88:89] offset:3072 nt
	s_waitcnt vmcnt(26)
	v_mul_f32_e32 v4, v32, v32
	v_fma_f32 v4, v33, v33, v4
	v_fma_f32 v4, v34, v34, v4
	v_fma_f32 v4, v35, v35, v4
	v_fma_f32 v4, v36, v36, v4
	v_fma_f32 v4, v37, v37, v4
	v_fma_f32 v4, v38, v38, v4
	v_fma_f32 v4, v39, v39, v4
	v_fma_f32 v4, v40, v40, v4
	v_fma_f32 v4, v41, v41, v4
	v_fma_f32 v4, v42, v42, v4
	v_fma_f32 v4, v43, v43, v4
	v_fma_f32 v4, v44, v44, v4
	v_fma_f32 v4, v45, v45, v4
	v_fma_f32 v4, v46, v46, v4
	v_fma_f32 v4, v47, v47, v4
	s_nop 1
	v_add_f32_dpp v5, v4, v4 quad_perm:[1,0,3,2] row_mask:0xf bank_mask:0xf
	s_nop 1
	v_add_f32_dpp v4, v5, v5 quad_perm:[2,3,0,1] row_mask:0xf bank_mask:0xf
	s_nop 1
	v_add_f32_dpp v5, v4, v4 row_half_mirror row_mask:0xf bank_mask:0xf
	s_nop 1
	v_add_f32_dpp v4, v5, v5 row_mirror row_mask:0xf bank_mask:0xf
	s_nop 1
	v_readlane_b32 s98, v4, 0
	v_readlane_b32 s99, v4, 16
	s_nop 3
	v_mov_b32_e32 v5, s98
	v_add_f32_e32 v5, s99, v5
	v_readlane_b32 s98, v4, 32
	v_readlane_b32 s99, v4, 48
	s_nop 3
	v_add_f32_e32 v5, s98, v5
	v_add_f32_e32 v5, s99, v5
	v_mul_f32_e32 v5, 0x3a800000, v5
	v_add_f32_e32 v5, 0x358637bd, v5
	v_rsq_f32_e32 v6, v5
	s_nop 0
	s_add_u32 s98, s97, 1
	v_pk_mul_f32 v[32:33], v[32:33], v[6:7] op_sel_hi:[1,0]
	v_pk_mul_f32 v[34:35], v[34:35], v[6:7] op_sel_hi:[1,0]
	v_pk_mul_f32 v[36:37], v[36:37], v[6:7] op_sel_hi:[1,0]
	v_pk_mul_f32 v[38:39], v[38:39], v[6:7] op_sel_hi:[1,0]
	v_pk_mul_f32 v[40:41], v[40:41], v[6:7] op_sel_hi:[1,0]
	v_pk_mul_f32 v[42:43], v[42:43], v[6:7] op_sel_hi:[1,0]
	v_pk_mul_f32 v[44:45], v[44:45], v[6:7] op_sel_hi:[1,0]
	v_pk_mul_f32 v[46:47], v[46:47], v[6:7] op_sel_hi:[1,0]
	v_pk_mul_f32 v[32:33], v[32:33], v[112:113]
	v_pk_mul_f32 v[34:35], v[34:35], v[114:115]
	v_pk_mul_f32 v[36:37], v[36:37], v[116:117]
	v_pk_mul_f32 v[38:39], v[38:39], v[118:119]
	v_pk_mul_f32 v[40:41], v[40:41], v[120:121]
	v_pk_mul_f32 v[42:43], v[42:43], v[122:123]
	v_pk_mul_f32 v[44:45], v[44:45], v[124:125]
	v_pk_mul_f32 v[46:47], v[46:47], v[126:127]
	v_pk_fma_f32 v[32:33], v[32:33], v[128:129], v[144:145]
	v_pk_fma_f32 v[34:35], v[34:35], v[130:131], v[146:147]
	v_pk_fma_f32 v[36:37], v[36:37], v[132:133], v[148:149]
	v_pk_fma_f32 v[38:39], v[38:39], v[134:135], v[150:151]
	v_pk_fma_f32 v[40:41], v[40:41], v[136:137], v[152:153]
	v_pk_fma_f32 v[42:43], v[42:43], v[138:139], v[154:155]
	v_pk_fma_f32 v[44:45], v[44:45], v[140:141], v[156:157]
	v_pk_fma_f32 v[46:47], v[46:47], v[142:143], v[158:159]
	v_cvt_pk_bf16_f32 v32, v32, v33
	v_cvt_pk_bf16_f32 v33, v34, v35
	v_cvt_pk_bf16_f32 v34, v36, v37
	v_cvt_pk_bf16_f32 v35, v38, v39
	v_cvt_pk_bf16_f32 v36, v40, v41
	v_cvt_pk_bf16_f32 v37, v42, v43
	v_cvt_pk_bf16_f32 v38, v44, v45
	v_cvt_pk_bf16_f32 v39, v46, v47
	s_lshl_b32 s99, s98, 11
	v_lshl_add_u32 v8, v0, 3, s99
	global_store_dwordx2 v8, v[32:33], s[94:95]
	global_store_dwordx2 v8, v[34:35], s[94:95] offset:512
	global_store_dwordx2 v8, v[36:37], s[94:95] offset:1024
	global_store_dwordx2 v8, v[38:39], s[94:95] offset:1536
	s_lshl_b32 s99, s98, 2
	v_mov_b32_e32 v9, s99
	v_mov_b32_e32 v10, 0
	v_cmp_eq_u32_e32 vcc, 0, v0
	s_and_saveexec_b64 s[98:99], vcc
	global_store_dword v9, v10, s[90:91]
	global_store_dword v9, v10, s[92:93]
	s_or_b64 exec, exec, s[98:99]
	s_add_u32 s98, s97, 7
	s_lshl_b32 s98, s98, 12
	v_add_u32_e32 v3, s98, v1
	global_load_dwordx4 v[32:35], v3, s[88:89] nt
	global_load_dwordx4 v[36:39], v3, s[88:89] offset:1024 nt
	global_load_dwordx4 v[40:43], v3, s[88:89] offset:2048 nt
	global_load_dwordx4 v[44:47], v3, s[88:89] offset:3072 nt
	s_waitcnt vmcnt(32)
	v_mul_f32_e32 v4, v48, v48
	v_fma_f32 v4, v49, v49, v4
	v_fma_f32 v4, v50, v50, v4
	v_fma_f32 v4, v51, v51, v4
	v_fma_f32 v4, v52, v52, v4
	v_fma_f32 v4, v53, v53, v4
	v_fma_f32 v4, v54, v54, v4
	v_fma_f32 v4, v55, v55, v4
	v_fma_f32 v4, v56, v56, v4
	v_fma_f32 v4, v57, v57, v4
	v_fma_f32 v4, v58, v58, v4
	v_fma_f32 v4, v59, v59, v4
	v_fma_f32 v4, v60, v60, v4
	v_fma_f32 v4, v61, v61, v4
	v_fma_f32 v4, v62, v62, v4
	v_fma_f32 v4, v63, v63, v4
	s_nop 1
	v_add_f32_dpp v5, v4, v4 quad_perm:[1,0,3,2] row_mask:0xf bank_mask:0xf
	s_nop 1
	v_add_f32_dpp v4, v5, v5 quad_perm:[2,3,0,1] row_mask:0xf bank_mask:0xf
	s_nop 1
	v_add_f32_dpp v5, v4, v4 row_half_mirror row_mask:0xf bank_mask:0xf
	s_nop 1
	v_add_f32_dpp v4, v5, v5 row_mirror row_mask:0xf bank_mask:0xf
	s_nop 1
	v_readlane_b32 s98, v4, 0
	v_readlane_b32 s99, v4, 16
	s_nop 3
	v_mov_b32_e32 v5, s98
	v_add_f32_e32 v5, s99, v5
	v_readlane_b32 s98, v4, 32
	v_readlane_b32 s99, v4, 48
	s_nop 3
	v_add_f32_e32 v5, s98, v5
	v_add_f32_e32 v5, s99, v5
	v_mul_f32_e32 v5, 0x3a800000, v5
	v_add_f32_e32 v5, 0x358637bd, v5
	v_rsq_f32_e32 v6, v5
	s_nop 0
	s_add_u32 s98, s97, 2
	v_pk_mul_f32 v[48:49], v[48:49], v[6:7] op_sel_hi:[1,0]
	v_pk_mul_f32 v[50:51], v[50:51], v[6:7] op_sel_hi:[1,0]
	v_pk_mul_f32 v[52:53], v[52:53], v[6:7] op_sel_hi:[1,0]
	v_pk_mul_f32 v[54:55], v[54:55], v[6:7] op_sel_hi:[1,0]
	v_pk_mul_f32 v[56:57], v[56:57], v[6:7] op_sel_hi:[1,0]
	v_pk_mul_f32 v[58:59], v[58:59], v[6:7] op_sel_hi:[1,0]
	v_pk_mul_f32 v[60:61], v[60:61], v[6:7] op_sel_hi:[1,0]
	v_pk_mul_f32 v[62:63], v[62:63], v[6:7] op_sel_hi:[1,0]
	v_pk_mul_f32 v[48:49], v[48:49], v[112:113]
	v_pk_mul_f32 v[50:51], v[50:51], v[114:115]
	v_pk_mul_f32 v[52:53], v[52:53], v[116:117]
	v_pk_mul_f32 v[54:55], v[54:55], v[118:119]
	v_pk_mul_f32 v[56:57], v[56:57], v[120:121]
	v_pk_mul_f32 v[58:59], v[58:59], v[122:123]
	v_pk_mul_f32 v[60:61], v[60:61], v[124:125]
	v_pk_mul_f32 v[62:63], v[62:63], v[126:127]
	v_pk_fma_f32 v[48:49], v[48:49], v[128:129], v[144:145]
	v_pk_fma_f32 v[50:51], v[50:51], v[130:131], v[146:147]
	v_pk_fma_f32 v[52:53], v[52:53], v[132:133], v[148:149]
	v_pk_fma_f32 v[54:55], v[54:55], v[134:135], v[150:151]
	v_pk_fma_f32 v[56:57], v[56:57], v[136:137], v[152:153]
	v_pk_fma_f32 v[58:59], v[58:59], v[138:139], v[154:155]
	v_pk_fma_f32 v[60:61], v[60:61], v[140:141], v[156:157]
	v_pk_fma_f32 v[62:63], v[62:63], v[142:143], v[158:159]
	v_cvt_pk_bf16_f32 v48, v48, v49
	v_cvt_pk_bf16_f32 v49, v50, v51
	v_cvt_pk_bf16_f32 v50, v52, v53
	v_cvt_pk_bf16_f32 v51, v54, v55
	v_cvt_pk_bf16_f32 v52, v56, v57
	v_cvt_pk_bf16_f32 v53, v58, v59
	v_cvt_pk_bf16_f32 v54, v60, v61
	v_cvt_pk_bf16_f32 v55, v62, v63
	s_lshl_b32 s99, s98, 11
	v_lshl_add_u32 v8, v0, 3, s99
	global_store_dwordx2 v8, v[48:49], s[94:95]
	global_store_dwordx2 v8, v[50:51], s[94:95] offset:512
	global_store_dwordx2 v8, v[52:53], s[94:95] offset:1024
	global_store_dwordx2 v8, v[54:55], s[94:95] offset:1536
	s_lshl_b32 s99, s98, 2
	v_mov_b32_e32 v9, s99
	v_mov_b32_e32 v10, 0
	v_cmp_eq_u32_e32 vcc, 0, v0
	s_and_saveexec_b64 s[98:99], vcc
	global_store_dword v9, v10, s[90:91]
	global_store_dword v9, v10, s[92:93]
	s_or_b64 exec, exec, s[98:99]
	s_add_u32 s98, s97, 8
	s_lshl_b32 s98, s98, 12
	v_add_u32_e32 v3, s98, v1
	global_load_dwordx4 v[48:51], v3, s[88:89] nt
	global_load_dwordx4 v[52:55], v3, s[88:89] offset:1024 nt
	global_load_dwordx4 v[56:59], v3, s[88:89] offset:2048 nt
	global_load_dwordx4 v[60:63], v3, s[88:89] offset:3072 nt
	s_waitcnt vmcnt(38)
	v_mul_f32_e32 v4, v64, v64
	v_fma_f32 v4, v65, v65, v4
	v_fma_f32 v4, v66, v66, v4
	v_fma_f32 v4, v67, v67, v4
	v_fma_f32 v4, v68, v68, v4
	v_fma_f32 v4, v69, v69, v4
	v_fma_f32 v4, v70, v70, v4
	v_fma_f32 v4, v71, v71, v4
	v_fma_f32 v4, v72, v72, v4
	v_fma_f32 v4, v73, v73, v4
	v_fma_f32 v4, v74, v74, v4
	v_fma_f32 v4, v75, v75, v4
	v_fma_f32 v4, v76, v76, v4
	v_fma_f32 v4, v77, v77, v4
	v_fma_f32 v4, v78, v78, v4
	v_fma_f32 v4, v79, v79, v4
	s_nop 1
	v_add_f32_dpp v5, v4, v4 quad_perm:[1,0,3,2] row_mask:0xf bank_mask:0xf
	s_nop 1
	v_add_f32_dpp v4, v5, v5 quad_perm:[2,3,0,1] row_mask:0xf bank_mask:0xf
	s_nop 1
	v_add_f32_dpp v5, v4, v4 row_half_mirror row_mask:0xf bank_mask:0xf
	s_nop 1
	v_add_f32_dpp v4, v5, v5 row_mirror row_mask:0xf bank_mask:0xf
	s_nop 1
	v_readlane_b32 s98, v4, 0
	v_readlane_b32 s99, v4, 16
	s_nop 3
	v_mov_b32_e32 v5, s98
	v_add_f32_e32 v5, s99, v5
	v_readlane_b32 s98, v4, 32
	v_readlane_b32 s99, v4, 48
	s_nop 3
	v_add_f32_e32 v5, s98, v5
	v_add_f32_e32 v5, s99, v5
	v_mul_f32_e32 v5, 0x3a800000, v5
	v_add_f32_e32 v5, 0x358637bd, v5
	v_rsq_f32_e32 v6, v5
	s_nop 0
	s_add_u32 s98, s97, 3
	v_pk_mul_f32 v[64:65], v[64:65], v[6:7] op_sel_hi:[1,0]
	v_pk_mul_f32 v[66:67], v[66:67], v[6:7] op_sel_hi:[1,0]
	v_pk_mul_f32 v[68:69], v[68:69], v[6:7] op_sel_hi:[1,0]
	v_pk_mul_f32 v[70:71], v[70:71], v[6:7] op_sel_hi:[1,0]
	v_pk_mul_f32 v[72:73], v[72:73], v[6:7] op_sel_hi:[1,0]
	v_pk_mul_f32 v[74:75], v[74:75], v[6:7] op_sel_hi:[1,0]
	v_pk_mul_f32 v[76:77], v[76:77], v[6:7] op_sel_hi:[1,0]
	v_pk_mul_f32 v[78:79], v[78:79], v[6:7] op_sel_hi:[1,0]
	v_pk_mul_f32 v[64:65], v[64:65], v[112:113]
	v_pk_mul_f32 v[66:67], v[66:67], v[114:115]
	v_pk_mul_f32 v[68:69], v[68:69], v[116:117]
	v_pk_mul_f32 v[70:71], v[70:71], v[118:119]
	v_pk_mul_f32 v[72:73], v[72:73], v[120:121]
	v_pk_mul_f32 v[74:75], v[74:75], v[122:123]
	v_pk_mul_f32 v[76:77], v[76:77], v[124:125]
	v_pk_mul_f32 v[78:79], v[78:79], v[126:127]
	v_pk_fma_f32 v[64:65], v[64:65], v[128:129], v[144:145]
	v_pk_fma_f32 v[66:67], v[66:67], v[130:131], v[146:147]
	v_pk_fma_f32 v[68:69], v[68:69], v[132:133], v[148:149]
	v_pk_fma_f32 v[70:71], v[70:71], v[134:135], v[150:151]
	v_pk_fma_f32 v[72:73], v[72:73], v[136:137], v[152:153]
	v_pk_fma_f32 v[74:75], v[74:75], v[138:139], v[154:155]
	v_pk_fma_f32 v[76:77], v[76:77], v[140:141], v[156:157]
	v_pk_fma_f32 v[78:79], v[78:79], v[142:143], v[158:159]
	v_cvt_pk_bf16_f32 v64, v64, v65
	v_cvt_pk_bf16_f32 v65, v66, v67
	v_cvt_pk_bf16_f32 v66, v68, v69
	v_cvt_pk_bf16_f32 v67, v70, v71
	v_cvt_pk_bf16_f32 v68, v72, v73
	v_cvt_pk_bf16_f32 v69, v74, v75
	v_cvt_pk_bf16_f32 v70, v76, v77
	v_cvt_pk_bf16_f32 v71, v78, v79
	s_lshl_b32 s99, s98, 11
	v_lshl_add_u32 v8, v0, 3, s99
	global_store_dwordx2 v8, v[64:65], s[94:95]
	global_store_dwordx2 v8, v[66:67], s[94:95] offset:512
	global_store_dwordx2 v8, v[68:69], s[94:95] offset:1024
	global_store_dwordx2 v8, v[70:71], s[94:95] offset:1536
	s_lshl_b32 s99, s98, 2
	v_mov_b32_e32 v9, s99
	v_mov_b32_e32 v10, 0
	v_cmp_eq_u32_e32 vcc, 0, v0
	s_and_saveexec_b64 s[98:99], vcc
	global_store_dword v9, v10, s[90:91]
	global_store_dword v9, v10, s[92:93]
	s_or_b64 exec, exec, s[98:99]
	s_add_u32 s98, s97, 9
	s_lshl_b32 s98, s98, 12
	v_add_u32_e32 v3, s98, v1
	global_load_dwordx4 v[64:67], v3, s[88:89] nt
	global_load_dwordx4 v[68:71], v3, s[88:89] offset:1024 nt
	global_load_dwordx4 v[72:75], v3, s[88:89] offset:2048 nt
	global_load_dwordx4 v[76:79], v3, s[88:89] offset:3072 nt
	s_waitcnt vmcnt(44)
	v_mul_f32_e32 v4, v80, v80
	v_fma_f32 v4, v81, v81, v4
	v_fma_f32 v4, v82, v82, v4
	v_fma_f32 v4, v83, v83, v4
	v_fma_f32 v4, v84, v84, v4
	v_fma_f32 v4, v85, v85, v4
	v_fma_f32 v4, v86, v86, v4
	v_fma_f32 v4, v87, v87, v4
	v_fma_f32 v4, v88, v88, v4
	v_fma_f32 v4, v89, v89, v4
	v_fma_f32 v4, v90, v90, v4
	v_fma_f32 v4, v91, v91, v4
	v_fma_f32 v4, v92, v92, v4
	v_fma_f32 v4, v93, v93, v4
	v_fma_f32 v4, v94, v94, v4
	v_fma_f32 v4, v95, v95, v4
	s_nop 1
	v_add_f32_dpp v5, v4, v4 quad_perm:[1,0,3,2] row_mask:0xf bank_mask:0xf
	s_nop 1
	v_add_f32_dpp v4, v5, v5 quad_perm:[2,3,0,1] row_mask:0xf bank_mask:0xf
	s_nop 1
	v_add_f32_dpp v5, v4, v4 row_half_mirror row_mask:0xf bank_mask:0xf
	s_nop 1
	v_add_f32_dpp v4, v5, v5 row_mirror row_mask:0xf bank_mask:0xf
	s_nop 1
	v_readlane_b32 s98, v4, 0
	v_readlane_b32 s99, v4, 16
	s_nop 3
	v_mov_b32_e32 v5, s98
	v_add_f32_e32 v5, s99, v5
	v_readlane_b32 s98, v4, 32
	v_readlane_b32 s99, v4, 48
	s_nop 3
	v_add_f32_e32 v5, s98, v5
	v_add_f32_e32 v5, s99, v5
	v_mul_f32_e32 v5, 0x3a800000, v5
	v_add_f32_e32 v5, 0x358637bd, v5
	v_rsq_f32_e32 v6, v5
	s_nop 0
	s_add_u32 s98, s97, 4
	v_pk_mul_f32 v[80:81], v[80:81], v[6:7] op_sel_hi:[1,0]
	v_pk_mul_f32 v[82:83], v[82:83], v[6:7] op_sel_hi:[1,0]
	v_pk_mul_f32 v[84:85], v[84:85], v[6:7] op_sel_hi:[1,0]
	v_pk_mul_f32 v[86:87], v[86:87], v[6:7] op_sel_hi:[1,0]
	v_pk_mul_f32 v[88:89], v[88:89], v[6:7] op_sel_hi:[1,0]
	v_pk_mul_f32 v[90:91], v[90:91], v[6:7] op_sel_hi:[1,0]
	v_pk_mul_f32 v[92:93], v[92:93], v[6:7] op_sel_hi:[1,0]
	v_pk_mul_f32 v[94:95], v[94:95], v[6:7] op_sel_hi:[1,0]
	v_pk_mul_f32 v[80:81], v[80:81], v[112:113]
	v_pk_mul_f32 v[82:83], v[82:83], v[114:115]
	v_pk_mul_f32 v[84:85], v[84:85], v[116:117]
	v_pk_mul_f32 v[86:87], v[86:87], v[118:119]
	v_pk_mul_f32 v[88:89], v[88:89], v[120:121]
	v_pk_mul_f32 v[90:91], v[90:91], v[122:123]
	v_pk_mul_f32 v[92:93], v[92:93], v[124:125]
	v_pk_mul_f32 v[94:95], v[94:95], v[126:127]
	v_pk_fma_f32 v[80:81], v[80:81], v[128:129], v[144:145]
	v_pk_fma_f32 v[82:83], v[82:83], v[130:131], v[146:147]
	v_pk_fma_f32 v[84:85], v[84:85], v[132:133], v[148:149]
	v_pk_fma_f32 v[86:87], v[86:87], v[134:135], v[150:151]
	v_pk_fma_f32 v[88:89], v[88:89], v[136:137], v[152:153]
	v_pk_fma_f32 v[90:91], v[90:91], v[138:139], v[154:155]
	v_pk_fma_f32 v[92:93], v[92:93], v[140:141], v[156:157]
	v_pk_fma_f32 v[94:95], v[94:95], v[142:143], v[158:159]
	v_cvt_pk_bf16_f32 v80, v80, v81
	v_cvt_pk_bf16_f32 v81, v82, v83
	v_cvt_pk_bf16_f32 v82, v84, v85
	v_cvt_pk_bf16_f32 v83, v86, v87
	v_cvt_pk_bf16_f32 v84, v88, v89
	v_cvt_pk_bf16_f32 v85, v90, v91
	v_cvt_pk_bf16_f32 v86, v92, v93
	v_cvt_pk_bf16_f32 v87, v94, v95
	s_lshl_b32 s99, s98, 11
	v_lshl_add_u32 v8, v0, 3, s99
	global_store_dwordx2 v8, v[80:81], s[94:95]
	global_store_dwordx2 v8, v[82:83], s[94:95] offset:512
	global_store_dwordx2 v8, v[84:85], s[94:95] offset:1024
	global_store_dwordx2 v8, v[86:87], s[94:95] offset:1536
	s_lshl_b32 s99, s98, 2
	v_mov_b32_e32 v9, s99
	v_mov_b32_e32 v10, 0
	v_cmp_eq_u32_e32 vcc, 0, v0
	s_and_saveexec_b64 s[98:99], vcc
	global_store_dword v9, v10, s[90:91]
	global_store_dword v9, v10, s[92:93]
	s_or_b64 exec, exec, s[98:99]
	s_add_u32 s98, s97, 10
	s_lshl_b32 s98, s98, 12
	v_add_u32_e32 v3, s98, v1
	global_load_dwordx4 v[80:83], v3, s[88:89] nt
	global_load_dwordx4 v[84:87], v3, s[88:89] offset:1024 nt
	global_load_dwordx4 v[88:91], v3, s[88:89] offset:2048 nt
	global_load_dwordx4 v[92:95], v3, s[88:89] offset:3072 nt
	s_waitcnt vmcnt(50)
	v_mul_f32_e32 v4, v96, v96
	v_fma_f32 v4, v97, v97, v4
	v_fma_f32 v4, v98, v98, v4
	v_fma_f32 v4, v99, v99, v4
	v_fma_f32 v4, v100, v100, v4
	v_fma_f32 v4, v101, v101, v4
	v_fma_f32 v4, v102, v102, v4
	v_fma_f32 v4, v103, v103, v4
	v_fma_f32 v4, v104, v104, v4
	v_fma_f32 v4, v105, v105, v4
	v_fma_f32 v4, v106, v106, v4
	v_fma_f32 v4, v107, v107, v4
	v_fma_f32 v4, v108, v108, v4
	v_fma_f32 v4, v109, v109, v4
	v_fma_f32 v4, v110, v110, v4
	v_fma_f32 v4, v111, v111, v4
	s_nop 1
	v_add_f32_dpp v5, v4, v4 quad_perm:[1,0,3,2] row_mask:0xf bank_mask:0xf
	s_nop 1
	v_add_f32_dpp v4, v5, v5 quad_perm:[2,3,0,1] row_mask:0xf bank_mask:0xf
	s_nop 1
	v_add_f32_dpp v5, v4, v4 row_half_mirror row_mask:0xf bank_mask:0xf
	s_nop 1
	v_add_f32_dpp v4, v5, v5 row_mirror row_mask:0xf bank_mask:0xf
	s_nop 1
	v_readlane_b32 s98, v4, 0
	v_readlane_b32 s99, v4, 16
	s_nop 3
	v_mov_b32_e32 v5, s98
	v_add_f32_e32 v5, s99, v5
	v_readlane_b32 s98, v4, 32
	v_readlane_b32 s99, v4, 48
	s_nop 3
	v_add_f32_e32 v5, s98, v5
	v_add_f32_e32 v5, s99, v5
	v_mul_f32_e32 v5, 0x3a800000, v5
	v_add_f32_e32 v5, 0x358637bd, v5
	v_rsq_f32_e32 v6, v5
	s_nop 0
	s_add_u32 s98, s97, 5
	v_pk_mul_f32 v[96:97], v[96:97], v[6:7] op_sel_hi:[1,0]
	v_pk_mul_f32 v[98:99], v[98:99], v[6:7] op_sel_hi:[1,0]
	v_pk_mul_f32 v[100:101], v[100:101], v[6:7] op_sel_hi:[1,0]
	v_pk_mul_f32 v[102:103], v[102:103], v[6:7] op_sel_hi:[1,0]
	v_pk_mul_f32 v[104:105], v[104:105], v[6:7] op_sel_hi:[1,0]
	v_pk_mul_f32 v[106:107], v[106:107], v[6:7] op_sel_hi:[1,0]
	v_pk_mul_f32 v[108:109], v[108:109], v[6:7] op_sel_hi:[1,0]
	v_pk_mul_f32 v[110:111], v[110:111], v[6:7] op_sel_hi:[1,0]
	v_pk_mul_f32 v[96:97], v[96:97], v[112:113]
	v_pk_mul_f32 v[98:99], v[98:99], v[114:115]
	v_pk_mul_f32 v[100:101], v[100:101], v[116:117]
	v_pk_mul_f32 v[102:103], v[102:103], v[118:119]
	v_pk_mul_f32 v[104:105], v[104:105], v[120:121]
	v_pk_mul_f32 v[106:107], v[106:107], v[122:123]
	v_pk_mul_f32 v[108:109], v[108:109], v[124:125]
	v_pk_mul_f32 v[110:111], v[110:111], v[126:127]
	v_pk_fma_f32 v[96:97], v[96:97], v[128:129], v[144:145]
	v_pk_fma_f32 v[98:99], v[98:99], v[130:131], v[146:147]
	v_pk_fma_f32 v[100:101], v[100:101], v[132:133], v[148:149]
	v_pk_fma_f32 v[102:103], v[102:103], v[134:135], v[150:151]
	v_pk_fma_f32 v[104:105], v[104:105], v[136:137], v[152:153]
	v_pk_fma_f32 v[106:107], v[106:107], v[138:139], v[154:155]
	v_pk_fma_f32 v[108:109], v[108:109], v[140:141], v[156:157]
	v_pk_fma_f32 v[110:111], v[110:111], v[142:143], v[158:159]
	v_cvt_pk_bf16_f32 v96, v96, v97
	v_cvt_pk_bf16_f32 v97, v98, v99
	v_cvt_pk_bf16_f32 v98, v100, v101
	v_cvt_pk_bf16_f32 v99, v102, v103
	v_cvt_pk_bf16_f32 v100, v104, v105
	v_cvt_pk_bf16_f32 v101, v106, v107
	v_cvt_pk_bf16_f32 v102, v108, v109
	v_cvt_pk_bf16_f32 v103, v110, v111
	s_lshl_b32 s99, s98, 11
	v_lshl_add_u32 v8, v0, 3, s99
	global_store_dwordx2 v8, v[96:97], s[94:95]
	global_store_dwordx2 v8, v[98:99], s[94:95] offset:512
	global_store_dwordx2 v8, v[100:101], s[94:95] offset:1024
	global_store_dwordx2 v8, v[102:103], s[94:95] offset:1536
	s_lshl_b32 s99, s98, 2
	v_mov_b32_e32 v9, s99
	v_mov_b32_e32 v10, 0
	v_cmp_eq_u32_e32 vcc, 0, v0
	s_and_saveexec_b64 s[98:99], vcc
	global_store_dword v9, v10, s[90:91]
	global_store_dword v9, v10, s[92:93]
	s_or_b64 exec, exec, s[98:99]
	s_add_u32 s98, s97, 11
	s_lshl_b32 s98, s98, 12
	v_add_u32_e32 v3, s98, v1
	global_load_dwordx4 v[96:99], v3, s[88:89] nt
	global_load_dwordx4 v[100:103], v3, s[88:89] offset:1024 nt
	global_load_dwordx4 v[104:107], v3, s[88:89] offset:2048 nt
	global_load_dwordx4 v[108:111], v3, s[88:89] offset:3072 nt
	s_waitcnt vmcnt(50)
	v_mul_f32_e32 v4, v16, v16
	v_fma_f32 v4, v17, v17, v4
	v_fma_f32 v4, v18, v18, v4
	v_fma_f32 v4, v19, v19, v4
	v_fma_f32 v4, v20, v20, v4
	v_fma_f32 v4, v21, v21, v4
	v_fma_f32 v4, v22, v22, v4
	v_fma_f32 v4, v23, v23, v4
	v_fma_f32 v4, v24, v24, v4
	v_fma_f32 v4, v25, v25, v4
	v_fma_f32 v4, v26, v26, v4
	v_fma_f32 v4, v27, v27, v4
	v_fma_f32 v4, v28, v28, v4
	v_fma_f32 v4, v29, v29, v4
	v_fma_f32 v4, v30, v30, v4
	v_fma_f32 v4, v31, v31, v4
	s_nop 1
	v_add_f32_dpp v5, v4, v4 quad_perm:[1,0,3,2] row_mask:0xf bank_mask:0xf
	s_nop 1
	v_add_f32_dpp v4, v5, v5 quad_perm:[2,3,0,1] row_mask:0xf bank_mask:0xf
	s_nop 1
	v_add_f32_dpp v5, v4, v4 row_half_mirror row_mask:0xf bank_mask:0xf
	s_nop 1
	v_add_f32_dpp v4, v5, v5 row_mirror row_mask:0xf bank_mask:0xf
	s_nop 1
	v_readlane_b32 s98, v4, 0
	v_readlane_b32 s99, v4, 16
	s_nop 3
	v_mov_b32_e32 v5, s98
	v_add_f32_e32 v5, s99, v5
	v_readlane_b32 s98, v4, 32
	v_readlane_b32 s99, v4, 48
	s_nop 3
	v_add_f32_e32 v5, s98, v5
	v_add_f32_e32 v5, s99, v5
	v_mul_f32_e32 v5, 0x3a800000, v5
	v_add_f32_e32 v5, 0x358637bd, v5
	v_rsq_f32_e32 v6, v5
	s_nop 0
	s_add_u32 s98, s97, 6
	v_pk_mul_f32 v[16:17], v[16:17], v[6:7] op_sel_hi:[1,0]
	v_pk_mul_f32 v[18:19], v[18:19], v[6:7] op_sel_hi:[1,0]
	v_pk_mul_f32 v[20:21], v[20:21], v[6:7] op_sel_hi:[1,0]
	v_pk_mul_f32 v[22:23], v[22:23], v[6:7] op_sel_hi:[1,0]
	v_pk_mul_f32 v[24:25], v[24:25], v[6:7] op_sel_hi:[1,0]
	v_pk_mul_f32 v[26:27], v[26:27], v[6:7] op_sel_hi:[1,0]
	v_pk_mul_f32 v[28:29], v[28:29], v[6:7] op_sel_hi:[1,0]
	v_pk_mul_f32 v[30:31], v[30:31], v[6:7] op_sel_hi:[1,0]
	v_pk_mul_f32 v[16:17], v[16:17], v[112:113]
	v_pk_mul_f32 v[18:19], v[18:19], v[114:115]
	v_pk_mul_f32 v[20:21], v[20:21], v[116:117]
	v_pk_mul_f32 v[22:23], v[22:23], v[118:119]
	v_pk_mul_f32 v[24:25], v[24:25], v[120:121]
	v_pk_mul_f32 v[26:27], v[26:27], v[122:123]
	v_pk_mul_f32 v[28:29], v[28:29], v[124:125]
	v_pk_mul_f32 v[30:31], v[30:31], v[126:127]
	v_pk_fma_f32 v[16:17], v[16:17], v[128:129], v[144:145]
	v_pk_fma_f32 v[18:19], v[18:19], v[130:131], v[146:147]
	v_pk_fma_f32 v[20:21], v[20:21], v[132:133], v[148:149]
	v_pk_fma_f32 v[22:23], v[22:23], v[134:135], v[150:151]
	v_pk_fma_f32 v[24:25], v[24:25], v[136:137], v[152:153]
	v_pk_fma_f32 v[26:27], v[26:27], v[138:139], v[154:155]
	v_pk_fma_f32 v[28:29], v[28:29], v[140:141], v[156:157]
	v_pk_fma_f32 v[30:31], v[30:31], v[142:143], v[158:159]
	v_cvt_pk_bf16_f32 v16, v16, v17
	v_cvt_pk_bf16_f32 v17, v18, v19
	v_cvt_pk_bf16_f32 v18, v20, v21
	v_cvt_pk_bf16_f32 v19, v22, v23
	v_cvt_pk_bf16_f32 v20, v24, v25
	v_cvt_pk_bf16_f32 v21, v26, v27
	v_cvt_pk_bf16_f32 v22, v28, v29
	v_cvt_pk_bf16_f32 v23, v30, v31
	s_lshl_b32 s99, s98, 11
	v_lshl_add_u32 v8, v0, 3, s99
	global_store_dwordx2 v8, v[16:17], s[94:95]
	global_store_dwordx2 v8, v[18:19], s[94:95] offset:512
	global_store_dwordx2 v8, v[20:21], s[94:95] offset:1024
	global_store_dwordx2 v8, v[22:23], s[94:95] offset:1536
	s_lshl_b32 s99, s98, 2
	v_mov_b32_e32 v9, s99
	v_mov_b32_e32 v10, 0
	v_cmp_eq_u32_e32 vcc, 0, v0
	s_and_saveexec_b64 s[98:99], vcc
	global_store_dword v9, v10, s[90:91]
	global_store_dword v9, v10, s[92:93]
	s_or_b64 exec, exec, s[98:99]
	s_add_u32 s98, s97, 12
	s_lshl_b32 s98, s98, 12
	v_add_u32_e32 v3, s98, v1
	global_load_dwordx4 v[16:19], v3, s[88:89] nt
	global_load_dwordx4 v[20:23], v3, s[88:89] offset:1024 nt
	global_load_dwordx4 v[24:27], v3, s[88:89] offset:2048 nt
	global_load_dwordx4 v[28:31], v3, s[88:89] offset:3072 nt
	s_waitcnt vmcnt(50)
	v_mul_f32_e32 v4, v32, v32
	v_fma_f32 v4, v33, v33, v4
	v_fma_f32 v4, v34, v34, v4
	v_fma_f32 v4, v35, v35, v4
	v_fma_f32 v4, v36, v36, v4
	v_fma_f32 v4, v37, v37, v4
	v_fma_f32 v4, v38, v38, v4
	v_fma_f32 v4, v39, v39, v4
	v_fma_f32 v4, v40, v40, v4
	v_fma_f32 v4, v41, v41, v4
	v_fma_f32 v4, v42, v42, v4
	v_fma_f32 v4, v43, v43, v4
	v_fma_f32 v4, v44, v44, v4
	v_fma_f32 v4, v45, v45, v4
	v_fma_f32 v4, v46, v46, v4
	v_fma_f32 v4, v47, v47, v4
	s_nop 1
	v_add_f32_dpp v5, v4, v4 quad_perm:[1,0,3,2] row_mask:0xf bank_mask:0xf
	s_nop 1
	v_add_f32_dpp v4, v5, v5 quad_perm:[2,3,0,1] row_mask:0xf bank_mask:0xf
	s_nop 1
	v_add_f32_dpp v5, v4, v4 row_half_mirror row_mask:0xf bank_mask:0xf
	s_nop 1
	v_add_f32_dpp v4, v5, v5 row_mirror row_mask:0xf bank_mask:0xf
	s_nop 1
	v_readlane_b32 s98, v4, 0
	v_readlane_b32 s99, v4, 16
	s_nop 3
	v_mov_b32_e32 v5, s98
	v_add_f32_e32 v5, s99, v5
	v_readlane_b32 s98, v4, 32
	v_readlane_b32 s99, v4, 48
	s_nop 3
	v_add_f32_e32 v5, s98, v5
	v_add_f32_e32 v5, s99, v5
	v_mul_f32_e32 v5, 0x3a800000, v5
	v_add_f32_e32 v5, 0x358637bd, v5
	v_rsq_f32_e32 v6, v5
	s_nop 0
	s_add_u32 s98, s97, 7
	v_pk_mul_f32 v[32:33], v[32:33], v[6:7] op_sel_hi:[1,0]
	v_pk_mul_f32 v[34:35], v[34:35], v[6:7] op_sel_hi:[1,0]
	v_pk_mul_f32 v[36:37], v[36:37], v[6:7] op_sel_hi:[1,0]
	v_pk_mul_f32 v[38:39], v[38:39], v[6:7] op_sel_hi:[1,0]
	v_pk_mul_f32 v[40:41], v[40:41], v[6:7] op_sel_hi:[1,0]
	v_pk_mul_f32 v[42:43], v[42:43], v[6:7] op_sel_hi:[1,0]
	v_pk_mul_f32 v[44:45], v[44:45], v[6:7] op_sel_hi:[1,0]
	v_pk_mul_f32 v[46:47], v[46:47], v[6:7] op_sel_hi:[1,0]
	v_pk_mul_f32 v[32:33], v[32:33], v[112:113]
	v_pk_mul_f32 v[34:35], v[34:35], v[114:115]
	v_pk_mul_f32 v[36:37], v[36:37], v[116:117]
	v_pk_mul_f32 v[38:39], v[38:39], v[118:119]
	v_pk_mul_f32 v[40:41], v[40:41], v[120:121]
	v_pk_mul_f32 v[42:43], v[42:43], v[122:123]
	v_pk_mul_f32 v[44:45], v[44:45], v[124:125]
	v_pk_mul_f32 v[46:47], v[46:47], v[126:127]
	v_pk_fma_f32 v[32:33], v[32:33], v[128:129], v[144:145]
	v_pk_fma_f32 v[34:35], v[34:35], v[130:131], v[146:147]
	v_pk_fma_f32 v[36:37], v[36:37], v[132:133], v[148:149]
	v_pk_fma_f32 v[38:39], v[38:39], v[134:135], v[150:151]
	v_pk_fma_f32 v[40:41], v[40:41], v[136:137], v[152:153]
	v_pk_fma_f32 v[42:43], v[42:43], v[138:139], v[154:155]
	v_pk_fma_f32 v[44:45], v[44:45], v[140:141], v[156:157]
	v_pk_fma_f32 v[46:47], v[46:47], v[142:143], v[158:159]
	v_cvt_pk_bf16_f32 v32, v32, v33
	v_cvt_pk_bf16_f32 v33, v34, v35
	v_cvt_pk_bf16_f32 v34, v36, v37
	v_cvt_pk_bf16_f32 v35, v38, v39
	v_cvt_pk_bf16_f32 v36, v40, v41
	v_cvt_pk_bf16_f32 v37, v42, v43
	v_cvt_pk_bf16_f32 v38, v44, v45
	v_cvt_pk_bf16_f32 v39, v46, v47
	s_lshl_b32 s99, s98, 11
	v_lshl_add_u32 v8, v0, 3, s99
	global_store_dwordx2 v8, v[32:33], s[94:95]
	global_store_dwordx2 v8, v[34:35], s[94:95] offset:512
	global_store_dwordx2 v8, v[36:37], s[94:95] offset:1024
	global_store_dwordx2 v8, v[38:39], s[94:95] offset:1536
	s_lshl_b32 s99, s98, 2
	v_mov_b32_e32 v9, s99
	v_mov_b32_e32 v10, 0
	v_cmp_eq_u32_e32 vcc, 0, v0
	s_and_saveexec_b64 s[98:99], vcc
	global_store_dword v9, v10, s[90:91]
	global_store_dword v9, v10, s[92:93]
	s_or_b64 exec, exec, s[98:99]
	s_add_u32 s98, s97, 13
	s_lshl_b32 s98, s98, 12
	v_add_u32_e32 v3, s98, v1
	global_load_dwordx4 v[32:35], v3, s[88:89] nt
	global_load_dwordx4 v[36:39], v3, s[88:89] offset:1024 nt
	global_load_dwordx4 v[40:43], v3, s[88:89] offset:2048 nt
	global_load_dwordx4 v[44:47], v3, s[88:89] offset:3072 nt
	s_waitcnt vmcnt(50)
	v_mul_f32_e32 v4, v48, v48
	v_fma_f32 v4, v49, v49, v4
	v_fma_f32 v4, v50, v50, v4
	v_fma_f32 v4, v51, v51, v4
	v_fma_f32 v4, v52, v52, v4
	v_fma_f32 v4, v53, v53, v4
	v_fma_f32 v4, v54, v54, v4
	v_fma_f32 v4, v55, v55, v4
	v_fma_f32 v4, v56, v56, v4
	v_fma_f32 v4, v57, v57, v4
	v_fma_f32 v4, v58, v58, v4
	v_fma_f32 v4, v59, v59, v4
	v_fma_f32 v4, v60, v60, v4
	v_fma_f32 v4, v61, v61, v4
	v_fma_f32 v4, v62, v62, v4
	v_fma_f32 v4, v63, v63, v4
	s_nop 1
	v_add_f32_dpp v5, v4, v4 quad_perm:[1,0,3,2] row_mask:0xf bank_mask:0xf
	s_nop 1
	v_add_f32_dpp v4, v5, v5 quad_perm:[2,3,0,1] row_mask:0xf bank_mask:0xf
	s_nop 1
	v_add_f32_dpp v5, v4, v4 row_half_mirror row_mask:0xf bank_mask:0xf
	s_nop 1
	v_add_f32_dpp v4, v5, v5 row_mirror row_mask:0xf bank_mask:0xf
	s_nop 1
	v_readlane_b32 s98, v4, 0
	v_readlane_b32 s99, v4, 16
	s_nop 3
	v_mov_b32_e32 v5, s98
	v_add_f32_e32 v5, s99, v5
	v_readlane_b32 s98, v4, 32
	v_readlane_b32 s99, v4, 48
	s_nop 3
	v_add_f32_e32 v5, s98, v5
	v_add_f32_e32 v5, s99, v5
	v_mul_f32_e32 v5, 0x3a800000, v5
	v_add_f32_e32 v5, 0x358637bd, v5
	v_rsq_f32_e32 v6, v5
	s_nop 0
	s_add_u32 s98, s97, 8
	v_pk_mul_f32 v[48:49], v[48:49], v[6:7] op_sel_hi:[1,0]
	v_pk_mul_f32 v[50:51], v[50:51], v[6:7] op_sel_hi:[1,0]
	v_pk_mul_f32 v[52:53], v[52:53], v[6:7] op_sel_hi:[1,0]
	v_pk_mul_f32 v[54:55], v[54:55], v[6:7] op_sel_hi:[1,0]
	v_pk_mul_f32 v[56:57], v[56:57], v[6:7] op_sel_hi:[1,0]
	v_pk_mul_f32 v[58:59], v[58:59], v[6:7] op_sel_hi:[1,0]
	v_pk_mul_f32 v[60:61], v[60:61], v[6:7] op_sel_hi:[1,0]
	v_pk_mul_f32 v[62:63], v[62:63], v[6:7] op_sel_hi:[1,0]
	v_pk_mul_f32 v[48:49], v[48:49], v[112:113]
	v_pk_mul_f32 v[50:51], v[50:51], v[114:115]
	v_pk_mul_f32 v[52:53], v[52:53], v[116:117]
	v_pk_mul_f32 v[54:55], v[54:55], v[118:119]
	v_pk_mul_f32 v[56:57], v[56:57], v[120:121]
	v_pk_mul_f32 v[58:59], v[58:59], v[122:123]
	v_pk_mul_f32 v[60:61], v[60:61], v[124:125]
	v_pk_mul_f32 v[62:63], v[62:63], v[126:127]
	v_pk_fma_f32 v[48:49], v[48:49], v[128:129], v[144:145]
	v_pk_fma_f32 v[50:51], v[50:51], v[130:131], v[146:147]
	v_pk_fma_f32 v[52:53], v[52:53], v[132:133], v[148:149]
	v_pk_fma_f32 v[54:55], v[54:55], v[134:135], v[150:151]
	v_pk_fma_f32 v[56:57], v[56:57], v[136:137], v[152:153]
	v_pk_fma_f32 v[58:59], v[58:59], v[138:139], v[154:155]
	v_pk_fma_f32 v[60:61], v[60:61], v[140:141], v[156:157]
	v_pk_fma_f32 v[62:63], v[62:63], v[142:143], v[158:159]
	v_cvt_pk_bf16_f32 v48, v48, v49
	v_cvt_pk_bf16_f32 v49, v50, v51
	v_cvt_pk_bf16_f32 v50, v52, v53
	v_cvt_pk_bf16_f32 v51, v54, v55
	v_cvt_pk_bf16_f32 v52, v56, v57
	v_cvt_pk_bf16_f32 v53, v58, v59
	v_cvt_pk_bf16_f32 v54, v60, v61
	v_cvt_pk_bf16_f32 v55, v62, v63
	s_lshl_b32 s99, s98, 11
	v_lshl_add_u32 v8, v0, 3, s99
	global_store_dwordx2 v8, v[48:49], s[94:95]
	global_store_dwordx2 v8, v[50:51], s[94:95] offset:512
	global_store_dwordx2 v8, v[52:53], s[94:95] offset:1024
	global_store_dwordx2 v8, v[54:55], s[94:95] offset:1536
	s_lshl_b32 s99, s98, 2
	v_mov_b32_e32 v9, s99
	v_mov_b32_e32 v10, 0
	v_cmp_eq_u32_e32 vcc, 0, v0
	s_and_saveexec_b64 s[98:99], vcc
	global_store_dword v9, v10, s[90:91]
	global_store_dword v9, v10, s[92:93]
	s_or_b64 exec, exec, s[98:99]
	s_add_u32 s98, s97, 14
	s_lshl_b32 s98, s98, 12
	v_add_u32_e32 v3, s98, v1
	global_load_dwordx4 v[48:51], v3, s[88:89] nt
	global_load_dwordx4 v[52:55], v3, s[88:89] offset:1024 nt
	global_load_dwordx4 v[56:59], v3, s[88:89] offset:2048 nt
	global_load_dwordx4 v[60:63], v3, s[88:89] offset:3072 nt
	s_waitcnt vmcnt(50)
	v_mul_f32_e32 v4, v64, v64
	v_fma_f32 v4, v65, v65, v4
	v_fma_f32 v4, v66, v66, v4
	v_fma_f32 v4, v67, v67, v4
	v_fma_f32 v4, v68, v68, v4
	v_fma_f32 v4, v69, v69, v4
	v_fma_f32 v4, v70, v70, v4
	v_fma_f32 v4, v71, v71, v4
	v_fma_f32 v4, v72, v72, v4
	v_fma_f32 v4, v73, v73, v4
	v_fma_f32 v4, v74, v74, v4
	v_fma_f32 v4, v75, v75, v4
	v_fma_f32 v4, v76, v76, v4
	v_fma_f32 v4, v77, v77, v4
	v_fma_f32 v4, v78, v78, v4
	v_fma_f32 v4, v79, v79, v4
	s_nop 1
	v_add_f32_dpp v5, v4, v4 quad_perm:[1,0,3,2] row_mask:0xf bank_mask:0xf
	s_nop 1
	v_add_f32_dpp v4, v5, v5 quad_perm:[2,3,0,1] row_mask:0xf bank_mask:0xf
	s_nop 1
	v_add_f32_dpp v5, v4, v4 row_half_mirror row_mask:0xf bank_mask:0xf
	s_nop 1
	v_add_f32_dpp v4, v5, v5 row_mirror row_mask:0xf bank_mask:0xf
	s_nop 1
	v_readlane_b32 s98, v4, 0
	v_readlane_b32 s99, v4, 16
	s_nop 3
	v_mov_b32_e32 v5, s98
	v_add_f32_e32 v5, s99, v5
	v_readlane_b32 s98, v4, 32
	v_readlane_b32 s99, v4, 48
	s_nop 3
	v_add_f32_e32 v5, s98, v5
	v_add_f32_e32 v5, s99, v5
	v_mul_f32_e32 v5, 0x3a800000, v5
	v_add_f32_e32 v5, 0x358637bd, v5
	v_rsq_f32_e32 v6, v5
	s_nop 0
	s_add_u32 s98, s97, 9
	v_pk_mul_f32 v[64:65], v[64:65], v[6:7] op_sel_hi:[1,0]
	v_pk_mul_f32 v[66:67], v[66:67], v[6:7] op_sel_hi:[1,0]
	v_pk_mul_f32 v[68:69], v[68:69], v[6:7] op_sel_hi:[1,0]
	v_pk_mul_f32 v[70:71], v[70:71], v[6:7] op_sel_hi:[1,0]
	v_pk_mul_f32 v[72:73], v[72:73], v[6:7] op_sel_hi:[1,0]
	v_pk_mul_f32 v[74:75], v[74:75], v[6:7] op_sel_hi:[1,0]
	v_pk_mul_f32 v[76:77], v[76:77], v[6:7] op_sel_hi:[1,0]
	v_pk_mul_f32 v[78:79], v[78:79], v[6:7] op_sel_hi:[1,0]
	v_pk_mul_f32 v[64:65], v[64:65], v[112:113]
	v_pk_mul_f32 v[66:67], v[66:67], v[114:115]
	v_pk_mul_f32 v[68:69], v[68:69], v[116:117]
	v_pk_mul_f32 v[70:71], v[70:71], v[118:119]
	v_pk_mul_f32 v[72:73], v[72:73], v[120:121]
	v_pk_mul_f32 v[74:75], v[74:75], v[122:123]
	v_pk_mul_f32 v[76:77], v[76:77], v[124:125]
	v_pk_mul_f32 v[78:79], v[78:79], v[126:127]
	v_pk_fma_f32 v[64:65], v[64:65], v[128:129], v[144:145]
	v_pk_fma_f32 v[66:67], v[66:67], v[130:131], v[146:147]
	v_pk_fma_f32 v[68:69], v[68:69], v[132:133], v[148:149]
	v_pk_fma_f32 v[70:71], v[70:71], v[134:135], v[150:151]
	v_pk_fma_f32 v[72:73], v[72:73], v[136:137], v[152:153]
	v_pk_fma_f32 v[74:75], v[74:75], v[138:139], v[154:155]
	v_pk_fma_f32 v[76:77], v[76:77], v[140:141], v[156:157]
	v_pk_fma_f32 v[78:79], v[78:79], v[142:143], v[158:159]
	v_cvt_pk_bf16_f32 v64, v64, v65
	v_cvt_pk_bf16_f32 v65, v66, v67
	v_cvt_pk_bf16_f32 v66, v68, v69
	v_cvt_pk_bf16_f32 v67, v70, v71
	v_cvt_pk_bf16_f32 v68, v72, v73
	v_cvt_pk_bf16_f32 v69, v74, v75
	v_cvt_pk_bf16_f32 v70, v76, v77
	v_cvt_pk_bf16_f32 v71, v78, v79
	s_lshl_b32 s99, s98, 11
	v_lshl_add_u32 v8, v0, 3, s99
	global_store_dwordx2 v8, v[64:65], s[94:95]
	global_store_dwordx2 v8, v[66:67], s[94:95] offset:512
	global_store_dwordx2 v8, v[68:69], s[94:95] offset:1024
	global_store_dwordx2 v8, v[70:71], s[94:95] offset:1536
	s_lshl_b32 s99, s98, 2
	v_mov_b32_e32 v9, s99
	v_mov_b32_e32 v10, 0
	v_cmp_eq_u32_e32 vcc, 0, v0
	s_and_saveexec_b64 s[98:99], vcc
	global_store_dword v9, v10, s[90:91]
	global_store_dword v9, v10, s[92:93]
	s_or_b64 exec, exec, s[98:99]
	s_add_u32 s98, s97, 15
	s_lshl_b32 s98, s98, 12
	v_add_u32_e32 v3, s98, v1
	global_load_dwordx4 v[64:67], v3, s[88:89] nt
	global_load_dwordx4 v[68:71], v3, s[88:89] offset:1024 nt
	global_load_dwordx4 v[72:75], v3, s[88:89] offset:2048 nt
	global_load_dwordx4 v[76:79], v3, s[88:89] offset:3072 nt
	s_waitcnt vmcnt(50)
	v_mul_f32_e32 v4, v80, v80
	v_fma_f32 v4, v81, v81, v4
	v_fma_f32 v4, v82, v82, v4
	v_fma_f32 v4, v83, v83, v4
	v_fma_f32 v4, v84, v84, v4
	v_fma_f32 v4, v85, v85, v4
	v_fma_f32 v4, v86, v86, v4
	v_fma_f32 v4, v87, v87, v4
	v_fma_f32 v4, v88, v88, v4
	v_fma_f32 v4, v89, v89, v4
	v_fma_f32 v4, v90, v90, v4
	v_fma_f32 v4, v91, v91, v4
	v_fma_f32 v4, v92, v92, v4
	v_fma_f32 v4, v93, v93, v4
	v_fma_f32 v4, v94, v94, v4
	v_fma_f32 v4, v95, v95, v4
	s_nop 1
	v_add_f32_dpp v5, v4, v4 quad_perm:[1,0,3,2] row_mask:0xf bank_mask:0xf
	s_nop 1
	v_add_f32_dpp v4, v5, v5 quad_perm:[2,3,0,1] row_mask:0xf bank_mask:0xf
	s_nop 1
	v_add_f32_dpp v5, v4, v4 row_half_mirror row_mask:0xf bank_mask:0xf
	s_nop 1
	v_add_f32_dpp v4, v5, v5 row_mirror row_mask:0xf bank_mask:0xf
	s_nop 1
	v_readlane_b32 s98, v4, 0
	v_readlane_b32 s99, v4, 16
	s_nop 3
	v_mov_b32_e32 v5, s98
	v_add_f32_e32 v5, s99, v5
	v_readlane_b32 s98, v4, 32
	v_readlane_b32 s99, v4, 48
	s_nop 3
	v_add_f32_e32 v5, s98, v5
	v_add_f32_e32 v5, s99, v5
	v_mul_f32_e32 v5, 0x3a800000, v5
	v_add_f32_e32 v5, 0x358637bd, v5
	v_rsq_f32_e32 v6, v5
	s_nop 0
	s_add_u32 s98, s97, 10
	v_pk_mul_f32 v[80:81], v[80:81], v[6:7] op_sel_hi:[1,0]
	v_pk_mul_f32 v[82:83], v[82:83], v[6:7] op_sel_hi:[1,0]
	v_pk_mul_f32 v[84:85], v[84:85], v[6:7] op_sel_hi:[1,0]
	v_pk_mul_f32 v[86:87], v[86:87], v[6:7] op_sel_hi:[1,0]
	v_pk_mul_f32 v[88:89], v[88:89], v[6:7] op_sel_hi:[1,0]
	v_pk_mul_f32 v[90:91], v[90:91], v[6:7] op_sel_hi:[1,0]
	v_pk_mul_f32 v[92:93], v[92:93], v[6:7] op_sel_hi:[1,0]
	v_pk_mul_f32 v[94:95], v[94:95], v[6:7] op_sel_hi:[1,0]
	v_pk_mul_f32 v[80:81], v[80:81], v[112:113]
	v_pk_mul_f32 v[82:83], v[82:83], v[114:115]
	v_pk_mul_f32 v[84:85], v[84:85], v[116:117]
	v_pk_mul_f32 v[86:87], v[86:87], v[118:119]
	v_pk_mul_f32 v[88:89], v[88:89], v[120:121]
	v_pk_mul_f32 v[90:91], v[90:91], v[122:123]
	v_pk_mul_f32 v[92:93], v[92:93], v[124:125]
	v_pk_mul_f32 v[94:95], v[94:95], v[126:127]
	v_pk_fma_f32 v[80:81], v[80:81], v[128:129], v[144:145]
	v_pk_fma_f32 v[82:83], v[82:83], v[130:131], v[146:147]
	v_pk_fma_f32 v[84:85], v[84:85], v[132:133], v[148:149]
	v_pk_fma_f32 v[86:87], v[86:87], v[134:135], v[150:151]
	v_pk_fma_f32 v[88:89], v[88:89], v[136:137], v[152:153]
	v_pk_fma_f32 v[90:91], v[90:91], v[138:139], v[154:155]
	v_pk_fma_f32 v[92:93], v[92:93], v[140:141], v[156:157]
	v_pk_fma_f32 v[94:95], v[94:95], v[142:143], v[158:159]
	v_cvt_pk_bf16_f32 v80, v80, v81
	v_cvt_pk_bf16_f32 v81, v82, v83
	v_cvt_pk_bf16_f32 v82, v84, v85
	v_cvt_pk_bf16_f32 v83, v86, v87
	v_cvt_pk_bf16_f32 v84, v88, v89
	v_cvt_pk_bf16_f32 v85, v90, v91
	v_cvt_pk_bf16_f32 v86, v92, v93
	v_cvt_pk_bf16_f32 v87, v94, v95
	s_lshl_b32 s99, s98, 11
	v_lshl_add_u32 v8, v0, 3, s99
	global_store_dwordx2 v8, v[80:81], s[94:95]
	global_store_dwordx2 v8, v[82:83], s[94:95] offset:512
	global_store_dwordx2 v8, v[84:85], s[94:95] offset:1024
	global_store_dwordx2 v8, v[86:87], s[94:95] offset:1536
	s_lshl_b32 s99, s98, 2
	v_mov_b32_e32 v9, s99
	v_mov_b32_e32 v10, 0
	v_cmp_eq_u32_e32 vcc, 0, v0
	s_and_saveexec_b64 s[98:99], vcc
	global_store_dword v9, v10, s[90:91]
	global_store_dword v9, v10, s[92:93]
	s_or_b64 exec, exec, s[98:99]
	s_waitcnt vmcnt(46)
	v_mul_f32_e32 v4, v96, v96
	v_fma_f32 v4, v97, v97, v4
	v_fma_f32 v4, v98, v98, v4
	v_fma_f32 v4, v99, v99, v4
	v_fma_f32 v4, v100, v100, v4
	v_fma_f32 v4, v101, v101, v4
	v_fma_f32 v4, v102, v102, v4
	v_fma_f32 v4, v103, v103, v4
	v_fma_f32 v4, v104, v104, v4
	v_fma_f32 v4, v105, v105, v4
	v_fma_f32 v4, v106, v106, v4
	v_fma_f32 v4, v107, v107, v4
	v_fma_f32 v4, v108, v108, v4
	v_fma_f32 v4, v109, v109, v4
	v_fma_f32 v4, v110, v110, v4
	v_fma_f32 v4, v111, v111, v4
	s_nop 1
	v_add_f32_dpp v5, v4, v4 quad_perm:[1,0,3,2] row_mask:0xf bank_mask:0xf
	s_nop 1
	v_add_f32_dpp v4, v5, v5 quad_perm:[2,3,0,1] row_mask:0xf bank_mask:0xf
	s_nop 1
	v_add_f32_dpp v5, v4, v4 row_half_mirror row_mask:0xf bank_mask:0xf
	s_nop 1
	v_add_f32_dpp v4, v5, v5 row_mirror row_mask:0xf bank_mask:0xf
	s_nop 1
	v_readlane_b32 s98, v4, 0
	v_readlane_b32 s99, v4, 16
	s_nop 3
	v_mov_b32_e32 v5, s98
	v_add_f32_e32 v5, s99, v5
	v_readlane_b32 s98, v4, 32
	v_readlane_b32 s99, v4, 48
	s_nop 3
	v_add_f32_e32 v5, s98, v5
	v_add_f32_e32 v5, s99, v5
	v_mul_f32_e32 v5, 0x3a800000, v5
	v_add_f32_e32 v5, 0x358637bd, v5
	v_rsq_f32_e32 v6, v5
	s_nop 0
	s_add_u32 s98, s97, 11
	v_pk_mul_f32 v[96:97], v[96:97], v[6:7] op_sel_hi:[1,0]
	v_pk_mul_f32 v[98:99], v[98:99], v[6:7] op_sel_hi:[1,0]
	v_pk_mul_f32 v[100:101], v[100:101], v[6:7] op_sel_hi:[1,0]
	v_pk_mul_f32 v[102:103], v[102:103], v[6:7] op_sel_hi:[1,0]
	v_pk_mul_f32 v[104:105], v[104:105], v[6:7] op_sel_hi:[1,0]
	v_pk_mul_f32 v[106:107], v[106:107], v[6:7] op_sel_hi:[1,0]
	v_pk_mul_f32 v[108:109], v[108:109], v[6:7] op_sel_hi:[1,0]
	v_pk_mul_f32 v[110:111], v[110:111], v[6:7] op_sel_hi:[1,0]
	v_pk_mul_f32 v[96:97], v[96:97], v[112:113]
	v_pk_mul_f32 v[98:99], v[98:99], v[114:115]
	v_pk_mul_f32 v[100:101], v[100:101], v[116:117]
	v_pk_mul_f32 v[102:103], v[102:103], v[118:119]
	v_pk_mul_f32 v[104:105], v[104:105], v[120:121]
	v_pk_mul_f32 v[106:107], v[106:107], v[122:123]
	v_pk_mul_f32 v[108:109], v[108:109], v[124:125]
	v_pk_mul_f32 v[110:111], v[110:111], v[126:127]
	v_pk_fma_f32 v[96:97], v[96:97], v[128:129], v[144:145]
	v_pk_fma_f32 v[98:99], v[98:99], v[130:131], v[146:147]
	v_pk_fma_f32 v[100:101], v[100:101], v[132:133], v[148:149]
	v_pk_fma_f32 v[102:103], v[102:103], v[134:135], v[150:151]
	v_pk_fma_f32 v[104:105], v[104:105], v[136:137], v[152:153]
	v_pk_fma_f32 v[106:107], v[106:107], v[138:139], v[154:155]
	v_pk_fma_f32 v[108:109], v[108:109], v[140:141], v[156:157]
	v_pk_fma_f32 v[110:111], v[110:111], v[142:143], v[158:159]
	v_cvt_pk_bf16_f32 v96, v96, v97
	v_cvt_pk_bf16_f32 v97, v98, v99
	v_cvt_pk_bf16_f32 v98, v100, v101
	v_cvt_pk_bf16_f32 v99, v102, v103
	v_cvt_pk_bf16_f32 v100, v104, v105
	v_cvt_pk_bf16_f32 v101, v106, v107
	v_cvt_pk_bf16_f32 v102, v108, v109
	v_cvt_pk_bf16_f32 v103, v110, v111
	s_lshl_b32 s99, s98, 11
	v_lshl_add_u32 v8, v0, 3, s99
	global_store_dwordx2 v8, v[96:97], s[94:95]
	global_store_dwordx2 v8, v[98:99], s[94:95] offset:512
	global_store_dwordx2 v8, v[100:101], s[94:95] offset:1024
	global_store_dwordx2 v8, v[102:103], s[94:95] offset:1536
	s_lshl_b32 s99, s98, 2
	v_mov_b32_e32 v9, s99
	v_mov_b32_e32 v10, 0
	v_cmp_eq_u32_e32 vcc, 0, v0
	s_and_saveexec_b64 s[98:99], vcc
	global_store_dword v9, v10, s[90:91]
	global_store_dword v9, v10, s[92:93]
	s_or_b64 exec, exec, s[98:99]
	s_waitcnt vmcnt(42)
	v_mul_f32_e32 v4, v16, v16
	v_fma_f32 v4, v17, v17, v4
	v_fma_f32 v4, v18, v18, v4
	v_fma_f32 v4, v19, v19, v4
	v_fma_f32 v4, v20, v20, v4
	v_fma_f32 v4, v21, v21, v4
	v_fma_f32 v4, v22, v22, v4
	v_fma_f32 v4, v23, v23, v4
	v_fma_f32 v4, v24, v24, v4
	v_fma_f32 v4, v25, v25, v4
	v_fma_f32 v4, v26, v26, v4
	v_fma_f32 v4, v27, v27, v4
	v_fma_f32 v4, v28, v28, v4
	v_fma_f32 v4, v29, v29, v4
	v_fma_f32 v4, v30, v30, v4
	v_fma_f32 v4, v31, v31, v4
	s_nop 1
	v_add_f32_dpp v5, v4, v4 quad_perm:[1,0,3,2] row_mask:0xf bank_mask:0xf
	s_nop 1
	v_add_f32_dpp v4, v5, v5 quad_perm:[2,3,0,1] row_mask:0xf bank_mask:0xf
	s_nop 1
	v_add_f32_dpp v5, v4, v4 row_half_mirror row_mask:0xf bank_mask:0xf
	s_nop 1
	v_add_f32_dpp v4, v5, v5 row_mirror row_mask:0xf bank_mask:0xf
	s_nop 1
	v_readlane_b32 s98, v4, 0
	v_readlane_b32 s99, v4, 16
	s_nop 3
	v_mov_b32_e32 v5, s98
	v_add_f32_e32 v5, s99, v5
	v_readlane_b32 s98, v4, 32
	v_readlane_b32 s99, v4, 48
	s_nop 3
	v_add_f32_e32 v5, s98, v5
	v_add_f32_e32 v5, s99, v5
	v_mul_f32_e32 v5, 0x3a800000, v5
	v_add_f32_e32 v5, 0x358637bd, v5
	v_rsq_f32_e32 v6, v5
	s_nop 0
	s_add_u32 s98, s97, 12
	v_pk_mul_f32 v[16:17], v[16:17], v[6:7] op_sel_hi:[1,0]
	v_pk_mul_f32 v[18:19], v[18:19], v[6:7] op_sel_hi:[1,0]
	v_pk_mul_f32 v[20:21], v[20:21], v[6:7] op_sel_hi:[1,0]
	v_pk_mul_f32 v[22:23], v[22:23], v[6:7] op_sel_hi:[1,0]
	v_pk_mul_f32 v[24:25], v[24:25], v[6:7] op_sel_hi:[1,0]
	v_pk_mul_f32 v[26:27], v[26:27], v[6:7] op_sel_hi:[1,0]
	v_pk_mul_f32 v[28:29], v[28:29], v[6:7] op_sel_hi:[1,0]
	v_pk_mul_f32 v[30:31], v[30:31], v[6:7] op_sel_hi:[1,0]
	v_pk_mul_f32 v[16:17], v[16:17], v[112:113]
	v_pk_mul_f32 v[18:19], v[18:19], v[114:115]
	v_pk_mul_f32 v[20:21], v[20:21], v[116:117]
	v_pk_mul_f32 v[22:23], v[22:23], v[118:119]
	v_pk_mul_f32 v[24:25], v[24:25], v[120:121]
	v_pk_mul_f32 v[26:27], v[26:27], v[122:123]
	v_pk_mul_f32 v[28:29], v[28:29], v[124:125]
	v_pk_mul_f32 v[30:31], v[30:31], v[126:127]
	v_pk_fma_f32 v[16:17], v[16:17], v[128:129], v[144:145]
	v_pk_fma_f32 v[18:19], v[18:19], v[130:131], v[146:147]
	v_pk_fma_f32 v[20:21], v[20:21], v[132:133], v[148:149]
	v_pk_fma_f32 v[22:23], v[22:23], v[134:135], v[150:151]
	v_pk_fma_f32 v[24:25], v[24:25], v[136:137], v[152:153]
	v_pk_fma_f32 v[26:27], v[26:27], v[138:139], v[154:155]
	v_pk_fma_f32 v[28:29], v[28:29], v[140:141], v[156:157]
	v_pk_fma_f32 v[30:31], v[30:31], v[142:143], v[158:159]
	v_cvt_pk_bf16_f32 v16, v16, v17
	v_cvt_pk_bf16_f32 v17, v18, v19
	v_cvt_pk_bf16_f32 v18, v20, v21
	v_cvt_pk_bf16_f32 v19, v22, v23
	v_cvt_pk_bf16_f32 v20, v24, v25
	v_cvt_pk_bf16_f32 v21, v26, v27
	v_cvt_pk_bf16_f32 v22, v28, v29
	v_cvt_pk_bf16_f32 v23, v30, v31
	s_lshl_b32 s99, s98, 11
	v_lshl_add_u32 v8, v0, 3, s99
	global_store_dwordx2 v8, v[16:17], s[94:95]
	global_store_dwordx2 v8, v[18:19], s[94:95] offset:512
	global_store_dwordx2 v8, v[20:21], s[94:95] offset:1024
	global_store_dwordx2 v8, v[22:23], s[94:95] offset:1536
	s_lshl_b32 s99, s98, 2
	v_mov_b32_e32 v9, s99
	v_mov_b32_e32 v10, 0
	v_cmp_eq_u32_e32 vcc, 0, v0
	s_and_saveexec_b64 s[98:99], vcc
	global_store_dword v9, v10, s[90:91]
	global_store_dword v9, v10, s[92:93]
	s_or_b64 exec, exec, s[98:99]
	s_waitcnt vmcnt(38)
	v_mul_f32_e32 v4, v32, v32
	v_fma_f32 v4, v33, v33, v4
	v_fma_f32 v4, v34, v34, v4
	v_fma_f32 v4, v35, v35, v4
	v_fma_f32 v4, v36, v36, v4
	v_fma_f32 v4, v37, v37, v4
	v_fma_f32 v4, v38, v38, v4
	v_fma_f32 v4, v39, v39, v4
	v_fma_f32 v4, v40, v40, v4
	v_fma_f32 v4, v41, v41, v4
	v_fma_f32 v4, v42, v42, v4
	v_fma_f32 v4, v43, v43, v4
	v_fma_f32 v4, v44, v44, v4
	v_fma_f32 v4, v45, v45, v4
	v_fma_f32 v4, v46, v46, v4
	v_fma_f32 v4, v47, v47, v4
	s_nop 1
	v_add_f32_dpp v5, v4, v4 quad_perm:[1,0,3,2] row_mask:0xf bank_mask:0xf
	s_nop 1
	v_add_f32_dpp v4, v5, v5 quad_perm:[2,3,0,1] row_mask:0xf bank_mask:0xf
	s_nop 1
	v_add_f32_dpp v5, v4, v4 row_half_mirror row_mask:0xf bank_mask:0xf
	s_nop 1
	v_add_f32_dpp v4, v5, v5 row_mirror row_mask:0xf bank_mask:0xf
	s_nop 1
	v_readlane_b32 s98, v4, 0
	v_readlane_b32 s99, v4, 16
	s_nop 3
	v_mov_b32_e32 v5, s98
	v_add_f32_e32 v5, s99, v5
	v_readlane_b32 s98, v4, 32
	v_readlane_b32 s99, v4, 48
	s_nop 3
	v_add_f32_e32 v5, s98, v5
	v_add_f32_e32 v5, s99, v5
	v_mul_f32_e32 v5, 0x3a800000, v5
	v_add_f32_e32 v5, 0x358637bd, v5
	v_rsq_f32_e32 v6, v5
	s_nop 0
	s_add_u32 s98, s97, 13
	v_pk_mul_f32 v[32:33], v[32:33], v[6:7] op_sel_hi:[1,0]
	v_pk_mul_f32 v[34:35], v[34:35], v[6:7] op_sel_hi:[1,0]
	v_pk_mul_f32 v[36:37], v[36:37], v[6:7] op_sel_hi:[1,0]
	v_pk_mul_f32 v[38:39], v[38:39], v[6:7] op_sel_hi:[1,0]
	v_pk_mul_f32 v[40:41], v[40:41], v[6:7] op_sel_hi:[1,0]
	v_pk_mul_f32 v[42:43], v[42:43], v[6:7] op_sel_hi:[1,0]
	v_pk_mul_f32 v[44:45], v[44:45], v[6:7] op_sel_hi:[1,0]
	v_pk_mul_f32 v[46:47], v[46:47], v[6:7] op_sel_hi:[1,0]
	v_pk_mul_f32 v[32:33], v[32:33], v[112:113]
	v_pk_mul_f32 v[34:35], v[34:35], v[114:115]
	v_pk_mul_f32 v[36:37], v[36:37], v[116:117]
	v_pk_mul_f32 v[38:39], v[38:39], v[118:119]
	v_pk_mul_f32 v[40:41], v[40:41], v[120:121]
	v_pk_mul_f32 v[42:43], v[42:43], v[122:123]
	v_pk_mul_f32 v[44:45], v[44:45], v[124:125]
	v_pk_mul_f32 v[46:47], v[46:47], v[126:127]
	v_pk_fma_f32 v[32:33], v[32:33], v[128:129], v[144:145]
	v_pk_fma_f32 v[34:35], v[34:35], v[130:131], v[146:147]
	v_pk_fma_f32 v[36:37], v[36:37], v[132:133], v[148:149]
	v_pk_fma_f32 v[38:39], v[38:39], v[134:135], v[150:151]
	v_pk_fma_f32 v[40:41], v[40:41], v[136:137], v[152:153]
	v_pk_fma_f32 v[42:43], v[42:43], v[138:139], v[154:155]
	v_pk_fma_f32 v[44:45], v[44:45], v[140:141], v[156:157]
	v_pk_fma_f32 v[46:47], v[46:47], v[142:143], v[158:159]
	v_cvt_pk_bf16_f32 v32, v32, v33
	v_cvt_pk_bf16_f32 v33, v34, v35
	v_cvt_pk_bf16_f32 v34, v36, v37
	v_cvt_pk_bf16_f32 v35, v38, v39
	v_cvt_pk_bf16_f32 v36, v40, v41
	v_cvt_pk_bf16_f32 v37, v42, v43
	v_cvt_pk_bf16_f32 v38, v44, v45
	v_cvt_pk_bf16_f32 v39, v46, v47
	s_lshl_b32 s99, s98, 11
	v_lshl_add_u32 v8, v0, 3, s99
	global_store_dwordx2 v8, v[32:33], s[94:95]
	global_store_dwordx2 v8, v[34:35], s[94:95] offset:512
	global_store_dwordx2 v8, v[36:37], s[94:95] offset:1024
	global_store_dwordx2 v8, v[38:39], s[94:95] offset:1536
	s_lshl_b32 s99, s98, 2
	v_mov_b32_e32 v9, s99
	v_mov_b32_e32 v10, 0
	v_cmp_eq_u32_e32 vcc, 0, v0
	s_and_saveexec_b64 s[98:99], vcc
	global_store_dword v9, v10, s[90:91]
	global_store_dword v9, v10, s[92:93]
	s_or_b64 exec, exec, s[98:99]
	s_waitcnt vmcnt(34)
	v_mul_f32_e32 v4, v48, v48
	v_fma_f32 v4, v49, v49, v4
	v_fma_f32 v4, v50, v50, v4
	v_fma_f32 v4, v51, v51, v4
	v_fma_f32 v4, v52, v52, v4
	v_fma_f32 v4, v53, v53, v4
	v_fma_f32 v4, v54, v54, v4
	v_fma_f32 v4, v55, v55, v4
	v_fma_f32 v4, v56, v56, v4
	v_fma_f32 v4, v57, v57, v4
	v_fma_f32 v4, v58, v58, v4
	v_fma_f32 v4, v59, v59, v4
	v_fma_f32 v4, v60, v60, v4
	v_fma_f32 v4, v61, v61, v4
	v_fma_f32 v4, v62, v62, v4
	v_fma_f32 v4, v63, v63, v4
	s_nop 1
	v_add_f32_dpp v5, v4, v4 quad_perm:[1,0,3,2] row_mask:0xf bank_mask:0xf
	s_nop 1
	v_add_f32_dpp v4, v5, v5 quad_perm:[2,3,0,1] row_mask:0xf bank_mask:0xf
	s_nop 1
	v_add_f32_dpp v5, v4, v4 row_half_mirror row_mask:0xf bank_mask:0xf
	s_nop 1
	v_add_f32_dpp v4, v5, v5 row_mirror row_mask:0xf bank_mask:0xf
	s_nop 1
	v_readlane_b32 s98, v4, 0
	v_readlane_b32 s99, v4, 16
	s_nop 3
	v_mov_b32_e32 v5, s98
	v_add_f32_e32 v5, s99, v5
	v_readlane_b32 s98, v4, 32
	v_readlane_b32 s99, v4, 48
	s_nop 3
	v_add_f32_e32 v5, s98, v5
	v_add_f32_e32 v5, s99, v5
	v_mul_f32_e32 v5, 0x3a800000, v5
	v_add_f32_e32 v5, 0x358637bd, v5
	v_rsq_f32_e32 v6, v5
	s_nop 0
	s_add_u32 s98, s97, 14
	v_pk_mul_f32 v[48:49], v[48:49], v[6:7] op_sel_hi:[1,0]
	v_pk_mul_f32 v[50:51], v[50:51], v[6:7] op_sel_hi:[1,0]
	v_pk_mul_f32 v[52:53], v[52:53], v[6:7] op_sel_hi:[1,0]
	v_pk_mul_f32 v[54:55], v[54:55], v[6:7] op_sel_hi:[1,0]
	v_pk_mul_f32 v[56:57], v[56:57], v[6:7] op_sel_hi:[1,0]
	v_pk_mul_f32 v[58:59], v[58:59], v[6:7] op_sel_hi:[1,0]
	v_pk_mul_f32 v[60:61], v[60:61], v[6:7] op_sel_hi:[1,0]
	v_pk_mul_f32 v[62:63], v[62:63], v[6:7] op_sel_hi:[1,0]
	v_pk_mul_f32 v[48:49], v[48:49], v[112:113]
	v_pk_mul_f32 v[50:51], v[50:51], v[114:115]
	v_pk_mul_f32 v[52:53], v[52:53], v[116:117]
	v_pk_mul_f32 v[54:55], v[54:55], v[118:119]
	v_pk_mul_f32 v[56:57], v[56:57], v[120:121]
	v_pk_mul_f32 v[58:59], v[58:59], v[122:123]
	v_pk_mul_f32 v[60:61], v[60:61], v[124:125]
	v_pk_mul_f32 v[62:63], v[62:63], v[126:127]
	v_pk_fma_f32 v[48:49], v[48:49], v[128:129], v[144:145]
	v_pk_fma_f32 v[50:51], v[50:51], v[130:131], v[146:147]
	v_pk_fma_f32 v[52:53], v[52:53], v[132:133], v[148:149]
	v_pk_fma_f32 v[54:55], v[54:55], v[134:135], v[150:151]
	v_pk_fma_f32 v[56:57], v[56:57], v[136:137], v[152:153]
	v_pk_fma_f32 v[58:59], v[58:59], v[138:139], v[154:155]
	v_pk_fma_f32 v[60:61], v[60:61], v[140:141], v[156:157]
	v_pk_fma_f32 v[62:63], v[62:63], v[142:143], v[158:159]
	v_cvt_pk_bf16_f32 v48, v48, v49
	v_cvt_pk_bf16_f32 v49, v50, v51
	v_cvt_pk_bf16_f32 v50, v52, v53
	v_cvt_pk_bf16_f32 v51, v54, v55
	v_cvt_pk_bf16_f32 v52, v56, v57
	v_cvt_pk_bf16_f32 v53, v58, v59
	v_cvt_pk_bf16_f32 v54, v60, v61
	v_cvt_pk_bf16_f32 v55, v62, v63
	s_lshl_b32 s99, s98, 11
	v_lshl_add_u32 v8, v0, 3, s99
	global_store_dwordx2 v8, v[48:49], s[94:95]
	global_store_dwordx2 v8, v[50:51], s[94:95] offset:512
	global_store_dwordx2 v8, v[52:53], s[94:95] offset:1024
	global_store_dwordx2 v8, v[54:55], s[94:95] offset:1536
	s_lshl_b32 s99, s98, 2
	v_mov_b32_e32 v9, s99
	v_mov_b32_e32 v10, 0
	v_cmp_eq_u32_e32 vcc, 0, v0
	s_and_saveexec_b64 s[98:99], vcc
	global_store_dword v9, v10, s[90:91]
	global_store_dword v9, v10, s[92:93]
	s_or_b64 exec, exec, s[98:99]
	s_waitcnt vmcnt(30)
	v_mul_f32_e32 v4, v64, v64
	v_fma_f32 v4, v65, v65, v4
	v_fma_f32 v4, v66, v66, v4
	v_fma_f32 v4, v67, v67, v4
	v_fma_f32 v4, v68, v68, v4
	v_fma_f32 v4, v69, v69, v4
	v_fma_f32 v4, v70, v70, v4
	v_fma_f32 v4, v71, v71, v4
	v_fma_f32 v4, v72, v72, v4
	v_fma_f32 v4, v73, v73, v4
	v_fma_f32 v4, v74, v74, v4
	v_fma_f32 v4, v75, v75, v4
	v_fma_f32 v4, v76, v76, v4
	v_fma_f32 v4, v77, v77, v4
	v_fma_f32 v4, v78, v78, v4
	v_fma_f32 v4, v79, v79, v4
	s_nop 1
	v_add_f32_dpp v5, v4, v4 quad_perm:[1,0,3,2] row_mask:0xf bank_mask:0xf
	s_nop 1
	v_add_f32_dpp v4, v5, v5 quad_perm:[2,3,0,1] row_mask:0xf bank_mask:0xf
	s_nop 1
	v_add_f32_dpp v5, v4, v4 row_half_mirror row_mask:0xf bank_mask:0xf
	s_nop 1
	v_add_f32_dpp v4, v5, v5 row_mirror row_mask:0xf bank_mask:0xf
	s_nop 1
	v_readlane_b32 s98, v4, 0
	v_readlane_b32 s99, v4, 16
	s_nop 3
	v_mov_b32_e32 v5, s98
	v_add_f32_e32 v5, s99, v5
	v_readlane_b32 s98, v4, 32
	v_readlane_b32 s99, v4, 48
	s_nop 3
	v_add_f32_e32 v5, s98, v5
	v_add_f32_e32 v5, s99, v5
	v_mul_f32_e32 v5, 0x3a800000, v5
	v_add_f32_e32 v5, 0x358637bd, v5
	v_rsq_f32_e32 v6, v5
	s_nop 0
	s_add_u32 s98, s97, 15
	v_pk_mul_f32 v[64:65], v[64:65], v[6:7] op_sel_hi:[1,0]
	v_pk_mul_f32 v[66:67], v[66:67], v[6:7] op_sel_hi:[1,0]
	v_pk_mul_f32 v[68:69], v[68:69], v[6:7] op_sel_hi:[1,0]
	v_pk_mul_f32 v[70:71], v[70:71], v[6:7] op_sel_hi:[1,0]
	v_pk_mul_f32 v[72:73], v[72:73], v[6:7] op_sel_hi:[1,0]
	v_pk_mul_f32 v[74:75], v[74:75], v[6:7] op_sel_hi:[1,0]
	v_pk_mul_f32 v[76:77], v[76:77], v[6:7] op_sel_hi:[1,0]
	v_pk_mul_f32 v[78:79], v[78:79], v[6:7] op_sel_hi:[1,0]
	v_pk_mul_f32 v[64:65], v[64:65], v[112:113]
	v_pk_mul_f32 v[66:67], v[66:67], v[114:115]
	v_pk_mul_f32 v[68:69], v[68:69], v[116:117]
	v_pk_mul_f32 v[70:71], v[70:71], v[118:119]
	v_pk_mul_f32 v[72:73], v[72:73], v[120:121]
	v_pk_mul_f32 v[74:75], v[74:75], v[122:123]
	v_pk_mul_f32 v[76:77], v[76:77], v[124:125]
	v_pk_mul_f32 v[78:79], v[78:79], v[126:127]
	v_pk_fma_f32 v[64:65], v[64:65], v[128:129], v[144:145]
	v_pk_fma_f32 v[66:67], v[66:67], v[130:131], v[146:147]
	v_pk_fma_f32 v[68:69], v[68:69], v[132:133], v[148:149]
	v_pk_fma_f32 v[70:71], v[70:71], v[134:135], v[150:151]
	v_pk_fma_f32 v[72:73], v[72:73], v[136:137], v[152:153]
	v_pk_fma_f32 v[74:75], v[74:75], v[138:139], v[154:155]
	v_pk_fma_f32 v[76:77], v[76:77], v[140:141], v[156:157]
	v_pk_fma_f32 v[78:79], v[78:79], v[142:143], v[158:159]
	v_cvt_pk_bf16_f32 v64, v64, v65
	v_cvt_pk_bf16_f32 v65, v66, v67
	v_cvt_pk_bf16_f32 v66, v68, v69
	v_cvt_pk_bf16_f32 v67, v70, v71
	v_cvt_pk_bf16_f32 v68, v72, v73
	v_cvt_pk_bf16_f32 v69, v74, v75
	v_cvt_pk_bf16_f32 v70, v76, v77
	v_cvt_pk_bf16_f32 v71, v78, v79
	s_lshl_b32 s99, s98, 11
	v_lshl_add_u32 v8, v0, 3, s99
	global_store_dwordx2 v8, v[64:65], s[94:95]
	global_store_dwordx2 v8, v[66:67], s[94:95] offset:512
	global_store_dwordx2 v8, v[68:69], s[94:95] offset:1024
	global_store_dwordx2 v8, v[70:71], s[94:95] offset:1536
	s_lshl_b32 s99, s98, 2
	v_mov_b32_e32 v9, s99
	v_mov_b32_e32 v10, 0
	v_cmp_eq_u32_e32 vcc, 0, v0
	s_and_saveexec_b64 s[98:99], vcc
	global_store_dword v9, v10, s[90:91]
	global_store_dword v9, v10, s[92:93]
	s_or_b64 exec, exec, s[98:99]
	s_waitcnt vmcnt(0)

.LBB0_2341:
	s_cmp_gt_i32 s44, 10
	s_waitcnt lgkmcnt(0)
	s_cselect_b64 s[2:3], -1, 0
	s_cmp_lt_i32 s45, 11
	s_cselect_b64 s[4:5], -1, 0
	s_or_b64 s[2:3], s[2:3], s[4:5]
	s_and_b64 vcc, exec, s[2:3]
	s_cbranch_vccnz .LBB0_2401
	s_lshl_b32 s96, s22, 3
	s_lshr_b32 s97, s70, 6
	s_add_u32 s96, s96, s97
	s_lshl_b32 s97, s96, 4
	s_cmpk_ge_u32 s97, 0x8000
	s_cbranch_scc1 .Lnp10_done
	s_load_dwordx2 s[88:89], s[0:1], 0xb8
	s_load_dwordx2 s[90:91], s[0:1], 0x18
	s_load_dwordx2 s[92:93], s[0:1], 0x140
	s_load_dwordx2 s[94:95], s[0:1], 0x158
	v_mbcnt_hi_u32_b32 v0, -1, v210
	v_lshlrev_b32_e32 v1, 4, v0
	s_waitcnt lgkmcnt(0)
	s_add_u32 s90, s90, 8192
	s_addc_u32 s91, s91, 0
	global_load_dwordx4 v[112:115], v1, s[90:91] nt
	global_load_dwordx4 v[116:119], v1, s[90:91] offset:1024 nt
	global_load_dwordx4 v[120:123], v1, s[90:91] offset:2048 nt
	global_load_dwordx4 v[124:127], v1, s[90:91] offset:3072 nt
	s_lshr_b32 s98, s97, 12
	s_add_u32 s98, s98, 16
	s_mul_i32 s98, s98, 0x3000
	s_add_u32 s92, s92, s98
	s_addc_u32 s93, s93, 0
	global_load_dwordx4 v[144:147], v1, s[92:93] nt
	global_load_dwordx4 v[148:151], v1, s[92:93] offset:1024 nt
	global_load_dwordx4 v[152:155], v1, s[92:93] offset:2048 nt
	global_load_dwordx4 v[156:159], v1, s[92:93] offset:3072 nt
	s_add_u32 s92, s92, 0x1000
	s_addc_u32 s93, s93, 0
	global_load_dwordx4 v[128:131], v1, s[92:93] nt
	global_load_dwordx4 v[132:135], v1, s[92:93] offset:1024 nt
	global_load_dwordx4 v[136:139], v1, s[92:93] offset:2048 nt
	global_load_dwordx4 v[140:143], v1, s[92:93] offset:3072 nt
	s_load_dwordx2 s[90:91], s[0:1], 0x210
	s_load_dwordx2 s[92:93], s[0:1], 0x218
	s_add_u32 s98, s97, 0
	s_lshl_b32 s98, s98, 12
	v_add_u32_e32 v3, s98, v1
	global_load_dwordx4 v[16:19], v3, s[88:89] nt
	global_load_dwordx4 v[20:23], v3, s[88:89] offset:1024 nt
	global_load_dwordx4 v[24:27], v3, s[88:89] offset:2048 nt
	global_load_dwordx4 v[28:31], v3, s[88:89] offset:3072 nt
	s_add_u32 s98, s97, 1
	s_lshl_b32 s98, s98, 12
	v_add_u32_e32 v3, s98, v1
	global_load_dwordx4 v[32:35], v3, s[88:89] nt
	global_load_dwordx4 v[36:39], v3, s[88:89] offset:1024 nt
	global_load_dwordx4 v[40:43], v3, s[88:89] offset:2048 nt
	global_load_dwordx4 v[44:47], v3, s[88:89] offset:3072 nt
	s_add_u32 s98, s97, 2
	s_lshl_b32 s98, s98, 12
	v_add_u32_e32 v3, s98, v1
	global_load_dwordx4 v[48:51], v3, s[88:89] nt
	global_load_dwordx4 v[52:55], v3, s[88:89] offset:1024 nt
	global_load_dwordx4 v[56:59], v3, s[88:89] offset:2048 nt
	global_load_dwordx4 v[60:63], v3, s[88:89] offset:3072 nt
	s_add_u32 s98, s97, 3
	s_lshl_b32 s98, s98, 12
	v_add_u32_e32 v3, s98, v1
	global_load_dwordx4 v[64:67], v3, s[88:89] nt
	global_load_dwordx4 v[68:71], v3, s[88:89] offset:1024 nt
	global_load_dwordx4 v[72:75], v3, s[88:89] offset:2048 nt
	global_load_dwordx4 v[76:79], v3, s[88:89] offset:3072 nt
	s_add_u32 s98, s97, 4
	s_lshl_b32 s98, s98, 12
	v_add_u32_e32 v3, s98, v1
	global_load_dwordx4 v[80:83], v3, s[88:89] nt
	global_load_dwordx4 v[84:87], v3, s[88:89] offset:1024 nt
	global_load_dwordx4 v[88:91], v3, s[88:89] offset:2048 nt
	global_load_dwordx4 v[92:95], v3, s[88:89] offset:3072 nt
	s_waitcnt vmcnt(0) lgkmcnt(0)
	v_pk_add_f32 v[128:129], v[128:129], 1.0 op_sel_hi:[1,0]
	v_pk_add_f32 v[130:131], v[130:131], 1.0 op_sel_hi:[1,0]
	v_pk_add_f32 v[132:133], v[132:133], 1.0 op_sel_hi:[1,0]
	v_pk_add_f32 v[134:135], v[134:135], 1.0 op_sel_hi:[1,0]
	v_pk_add_f32 v[136:137], v[136:137], 1.0 op_sel_hi:[1,0]
	v_pk_add_f32 v[138:139], v[138:139], 1.0 op_sel_hi:[1,0]
	v_pk_add_f32 v[140:141], v[140:141], 1.0 op_sel_hi:[1,0]
	v_pk_add_f32 v[142:143], v[142:143], 1.0 op_sel_hi:[1,0]
	s_add_u32 s98, s97, 5
	s_lshl_b32 s98, s98, 12
	v_add_u32_e32 v3, s98, v1
	global_load_dwordx4 v[96:99], v3, s[88:89] nt
	global_load_dwordx4 v[100:103], v3, s[88:89] offset:1024 nt
	global_load_dwordx4 v[104:107], v3, s[88:89] offset:2048 nt
	global_load_dwordx4 v[108:111], v3, s[88:89] offset:3072 nt
	s_waitcnt vmcnt(20)
	v_mul_f32_e32 v4, v16, v16
	v_fma_f32 v4, v17, v17, v4
	v_fma_f32 v4, v18, v18, v4
	v_fma_f32 v4, v19, v19, v4
	v_fma_f32 v4, v20, v20, v4
	v_fma_f32 v4, v21, v21, v4
	v_fma_f32 v4, v22, v22, v4
	v_fma_f32 v4, v23, v23, v4
	v_fma_f32 v4, v24, v24, v4
	v_fma_f32 v4, v25, v25, v4
	v_fma_f32 v4, v26, v26, v4
	v_fma_f32 v4, v27, v27, v4
	v_fma_f32 v4, v28, v28, v4
	v_fma_f32 v4, v29, v29, v4
	v_fma_f32 v4, v30, v30, v4
	v_fma_f32 v4, v31, v31, v4
	s_nop 1
	v_add_f32_dpp v5, v4, v4 quad_perm:[1,0,3,2] row_mask:0xf bank_mask:0xf
	s_nop 1
	v_add_f32_dpp v4, v5, v5 quad_perm:[2,3,0,1] row_mask:0xf bank_mask:0xf
	s_nop 1
	v_add_f32_dpp v5, v4, v4 row_half_mirror row_mask:0xf bank_mask:0xf
	s_nop 1
	v_add_f32_dpp v4, v5, v5 row_mirror row_mask:0xf bank_mask:0xf
	s_nop 1
	v_readlane_b32 s98, v4, 0
	v_readlane_b32 s99, v4, 16
	s_nop 3
	v_mov_b32_e32 v5, s98
	v_add_f32_e32 v5, s99, v5
	v_readlane_b32 s98, v4, 32
	v_readlane_b32 s99, v4, 48
	s_nop 3
	v_add_f32_e32 v5, s98, v5
	v_add_f32_e32 v5, s99, v5
	v_mul_f32_e32 v5, 0x3a800000, v5
	v_add_f32_e32 v5, 0x358637bd, v5
	v_rsq_f32_e32 v6, v5
	s_nop 0
	s_add_u32 s98, s97, 0
	v_pk_mul_f32 v[16:17], v[16:17], v[6:7] op_sel_hi:[1,0]
	v_pk_mul_f32 v[18:19], v[18:19], v[6:7] op_sel_hi:[1,0]
	v_pk_mul_f32 v[20:21], v[20:21], v[6:7] op_sel_hi:[1,0]
	v_pk_mul_f32 v[22:23], v[22:23], v[6:7] op_sel_hi:[1,0]
	v_pk_mul_f32 v[24:25], v[24:25], v[6:7] op_sel_hi:[1,0]
	v_pk_mul_f32 v[26:27], v[26:27], v[6:7] op_sel_hi:[1,0]
	v_pk_mul_f32 v[28:29], v[28:29], v[6:7] op_sel_hi:[1,0]
	v_pk_mul_f32 v[30:31], v[30:31], v[6:7] op_sel_hi:[1,0]
	v_pk_mul_f32 v[16:17], v[16:17], v[112:113]
	v_pk_mul_f32 v[18:19], v[18:19], v[114:115]
	v_pk_mul_f32 v[20:21], v[20:21], v[116:117]
	v_pk_mul_f32 v[22:23], v[22:23], v[118:119]
	v_pk_mul_f32 v[24:25], v[24:25], v[120:121]
	v_pk_mul_f32 v[26:27], v[26:27], v[122:123]
	v_pk_mul_f32 v[28:29], v[28:29], v[124:125]
	v_pk_mul_f32 v[30:31], v[30:31], v[126:127]
	v_pk_fma_f32 v[16:17], v[16:17], v[128:129], v[144:145]
	v_pk_fma_f32 v[18:19], v[18:19], v[130:131], v[146:147]
	v_pk_fma_f32 v[20:21], v[20:21], v[132:133], v[148:149]
	v_pk_fma_f32 v[22:23], v[22:23], v[134:135], v[150:151]
	v_pk_fma_f32 v[24:25], v[24:25], v[136:137], v[152:153]
	v_pk_fma_f32 v[26:27], v[26:27], v[138:139], v[154:155]
	v_pk_fma_f32 v[28:29], v[28:29], v[140:141], v[156:157]
	v_pk_fma_f32 v[30:31], v[30:31], v[142:143], v[158:159]
	v_cvt_pk_bf16_f32 v16, v16, v17
	v_cvt_pk_bf16_f32 v17, v18, v19
	v_cvt_pk_bf16_f32 v18, v20, v21
	v_cvt_pk_bf16_f32 v19, v22, v23
	v_cvt_pk_bf16_f32 v20, v24, v25
	v_cvt_pk_bf16_f32 v21, v26, v27
	v_cvt_pk_bf16_f32 v22, v28, v29
	v_cvt_pk_bf16_f32 v23, v30, v31
	s_lshl_b32 s99, s98, 11
	v_lshl_add_u32 v8, v0, 3, s99
	global_store_dwordx2 v8, v[16:17], s[94:95]
	global_store_dwordx2 v8, v[18:19], s[94:95] offset:512
	global_store_dwordx2 v8, v[20:21], s[94:95] offset:1024
	global_store_dwordx2 v8, v[22:23], s[94:95] offset:1536
	s_lshl_b32 s99, s98, 2
	v_mov_b32_e32 v9, s99
	v_mov_b32_e32 v10, 0
	v_cmp_eq_u32_e32 vcc, 0, v0
	s_and_saveexec_b64 s[98:99], vcc
	global_store_dword v9, v10, s[90:91]
	global_store_dword v9, v10, s[92:93]
	s_or_b64 exec, exec, s[98:99]
	s_add_u32 s98, s97, 6
	s_lshl_b32 s98, s98, 12
	v_add_u32_e32 v3, s98, v1
	global_load_dwordx4 v[16:19], v3, s[88:89] nt
	global_load_dwordx4 v[20:23], v3, s[88:89] offset:1024 nt
	global_load_dwordx4 v[24:27], v3, s[88:89] offset:2048 nt
	global_load_dwordx4 v[28:31], v3, s[88:89] offset:3072 nt
	s_waitcnt vmcnt(26)
	v_mul_f32_e32 v4, v32, v32
	v_fma_f32 v4, v33, v33, v4
	v_fma_f32 v4, v34, v34, v4
	v_fma_f32 v4, v35, v35, v4
	v_fma_f32 v4, v36, v36, v4
	v_fma_f32 v4, v37, v37, v4
	v_fma_f32 v4, v38, v38, v4
	v_fma_f32 v4, v39, v39, v4
	v_fma_f32 v4, v40, v40, v4
	v_fma_f32 v4, v41, v41, v4
	v_fma_f32 v4, v42, v42, v4
	v_fma_f32 v4, v43, v43, v4
	v_fma_f32 v4, v44, v44, v4
	v_fma_f32 v4, v45, v45, v4
	v_fma_f32 v4, v46, v46, v4
	v_fma_f32 v4, v47, v47, v4
	s_nop 1
	v_add_f32_dpp v5, v4, v4 quad_perm:[1,0,3,2] row_mask:0xf bank_mask:0xf
	s_nop 1
	v_add_f32_dpp v4, v5, v5 quad_perm:[2,3,0,1] row_mask:0xf bank_mask:0xf
	s_nop 1
	v_add_f32_dpp v5, v4, v4 row_half_mirror row_mask:0xf bank_mask:0xf
	s_nop 1
	v_add_f32_dpp v4, v5, v5 row_mirror row_mask:0xf bank_mask:0xf
	s_nop 1
	v_readlane_b32 s98, v4, 0
	v_readlane_b32 s99, v4, 16
	s_nop 3
	v_mov_b32_e32 v5, s98
	v_add_f32_e32 v5, s99, v5
	v_readlane_b32 s98, v4, 32
	v_readlane_b32 s99, v4, 48
	s_nop 3
	v_add_f32_e32 v5, s98, v5
	v_add_f32_e32 v5, s99, v5
	v_mul_f32_e32 v5, 0x3a800000, v5
	v_add_f32_e32 v5, 0x358637bd, v5
	v_rsq_f32_e32 v6, v5
	s_nop 0
	s_add_u32 s98, s97, 1
	v_pk_mul_f32 v[32:33], v[32:33], v[6:7] op_sel_hi:[1,0]
	v_pk_mul_f32 v[34:35], v[34:35], v[6:7] op_sel_hi:[1,0]
	v_pk_mul_f32 v[36:37], v[36:37], v[6:7] op_sel_hi:[1,0]
	v_pk_mul_f32 v[38:39], v[38:39], v[6:7] op_sel_hi:[1,0]
	v_pk_mul_f32 v[40:41], v[40:41], v[6:7] op_sel_hi:[1,0]
	v_pk_mul_f32 v[42:43], v[42:43], v[6:7] op_sel_hi:[1,0]
	v_pk_mul_f32 v[44:45], v[44:45], v[6:7] op_sel_hi:[1,0]
	v_pk_mul_f32 v[46:47], v[46:47], v[6:7] op_sel_hi:[1,0]
	v_pk_mul_f32 v[32:33], v[32:33], v[112:113]
	v_pk_mul_f32 v[34:35], v[34:35], v[114:115]
	v_pk_mul_f32 v[36:37], v[36:37], v[116:117]
	v_pk_mul_f32 v[38:39], v[38:39], v[118:119]
	v_pk_mul_f32 v[40:41], v[40:41], v[120:121]
	v_pk_mul_f32 v[42:43], v[42:43], v[122:123]
	v_pk_mul_f32 v[44:45], v[44:45], v[124:125]
	v_pk_mul_f32 v[46:47], v[46:47], v[126:127]
	v_pk_fma_f32 v[32:33], v[32:33], v[128:129], v[144:145]
	v_pk_fma_f32 v[34:35], v[34:35], v[130:131], v[146:147]
	v_pk_fma_f32 v[36:37], v[36:37], v[132:133], v[148:149]
	v_pk_fma_f32 v[38:39], v[38:39], v[134:135], v[150:151]
	v_pk_fma_f32 v[40:41], v[40:41], v[136:137], v[152:153]
	v_pk_fma_f32 v[42:43], v[42:43], v[138:139], v[154:155]
	v_pk_fma_f32 v[44:45], v[44:45], v[140:141], v[156:157]
	v_pk_fma_f32 v[46:47], v[46:47], v[142:143], v[158:159]
	v_cvt_pk_bf16_f32 v32, v32, v33
	v_cvt_pk_bf16_f32 v33, v34, v35
	v_cvt_pk_bf16_f32 v34, v36, v37
	v_cvt_pk_bf16_f32 v35, v38, v39
	v_cvt_pk_bf16_f32 v36, v40, v41
	v_cvt_pk_bf16_f32 v37, v42, v43
	v_cvt_pk_bf16_f32 v38, v44, v45
	v_cvt_pk_bf16_f32 v39, v46, v47
	s_lshl_b32 s99, s98, 11
	v_lshl_add_u32 v8, v0, 3, s99
	global_store_dwordx2 v8, v[32:33], s[94:95]
	global_store_dwordx2 v8, v[34:35], s[94:95] offset:512
	global_store_dwordx2 v8, v[36:37], s[94:95] offset:1024
	global_store_dwordx2 v8, v[38:39], s[94:95] offset:1536
	s_lshl_b32 s99, s98, 2
	v_mov_b32_e32 v9, s99
	v_mov_b32_e32 v10, 0
	v_cmp_eq_u32_e32 vcc, 0, v0
	s_and_saveexec_b64 s[98:99], vcc
	global_store_dword v9, v10, s[90:91]
	global_store_dword v9, v10, s[92:93]
	s_or_b64 exec, exec, s[98:99]
	s_add_u32 s98, s97, 7
	s_lshl_b32 s98, s98, 12
	v_add_u32_e32 v3, s98, v1
	global_load_dwordx4 v[32:35], v3, s[88:89] nt
	global_load_dwordx4 v[36:39], v3, s[88:89] offset:1024 nt
	global_load_dwordx4 v[40:43], v3, s[88:89] offset:2048 nt
	global_load_dwordx4 v[44:47], v3, s[88:89] offset:3072 nt
	s_waitcnt vmcnt(32)
	v_mul_f32_e32 v4, v48, v48
	v_fma_f32 v4, v49, v49, v4
	v_fma_f32 v4, v50, v50, v4
	v_fma_f32 v4, v51, v51, v4
	v_fma_f32 v4, v52, v52, v4
	v_fma_f32 v4, v53, v53, v4
	v_fma_f32 v4, v54, v54, v4
	v_fma_f32 v4, v55, v55, v4
	v_fma_f32 v4, v56, v56, v4
	v_fma_f32 v4, v57, v57, v4
	v_fma_f32 v4, v58, v58, v4
	v_fma_f32 v4, v59, v59, v4
	v_fma_f32 v4, v60, v60, v4
	v_fma_f32 v4, v61, v61, v4
	v_fma_f32 v4, v62, v62, v4
	v_fma_f32 v4, v63, v63, v4
	s_nop 1
	v_add_f32_dpp v5, v4, v4 quad_perm:[1,0,3,2] row_mask:0xf bank_mask:0xf
	s_nop 1
	v_add_f32_dpp v4, v5, v5 quad_perm:[2,3,0,1] row_mask:0xf bank_mask:0xf
	s_nop 1
	v_add_f32_dpp v5, v4, v4 row_half_mirror row_mask:0xf bank_mask:0xf
	s_nop 1
	v_add_f32_dpp v4, v5, v5 row_mirror row_mask:0xf bank_mask:0xf
	s_nop 1
	v_readlane_b32 s98, v4, 0
	v_readlane_b32 s99, v4, 16
	s_nop 3
	v_mov_b32_e32 v5, s98
	v_add_f32_e32 v5, s99, v5
	v_readlane_b32 s98, v4, 32
	v_readlane_b32 s99, v4, 48
	s_nop 3
	v_add_f32_e32 v5, s98, v5
	v_add_f32_e32 v5, s99, v5
	v_mul_f32_e32 v5, 0x3a800000, v5
	v_add_f32_e32 v5, 0x358637bd, v5
	v_rsq_f32_e32 v6, v5
	s_nop 0
	s_add_u32 s98, s97, 2
	v_pk_mul_f32 v[48:49], v[48:49], v[6:7] op_sel_hi:[1,0]
	v_pk_mul_f32 v[50:51], v[50:51], v[6:7] op_sel_hi:[1,0]
	v_pk_mul_f32 v[52:53], v[52:53], v[6:7] op_sel_hi:[1,0]
	v_pk_mul_f32 v[54:55], v[54:55], v[6:7] op_sel_hi:[1,0]
	v_pk_mul_f32 v[56:57], v[56:57], v[6:7] op_sel_hi:[1,0]
	v_pk_mul_f32 v[58:59], v[58:59], v[6:7] op_sel_hi:[1,0]
	v_pk_mul_f32 v[60:61], v[60:61], v[6:7] op_sel_hi:[1,0]
	v_pk_mul_f32 v[62:63], v[62:63], v[6:7] op_sel_hi:[1,0]
	v_pk_mul_f32 v[48:49], v[48:49], v[112:113]
	v_pk_mul_f32 v[50:51], v[50:51], v[114:115]
	v_pk_mul_f32 v[52:53], v[52:53], v[116:117]
	v_pk_mul_f32 v[54:55], v[54:55], v[118:119]
	v_pk_mul_f32 v[56:57], v[56:57], v[120:121]
	v_pk_mul_f32 v[58:59], v[58:59], v[122:123]
	v_pk_mul_f32 v[60:61], v[60:61], v[124:125]
	v_pk_mul_f32 v[62:63], v[62:63], v[126:127]
	v_pk_fma_f32 v[48:49], v[48:49], v[128:129], v[144:145]
	v_pk_fma_f32 v[50:51], v[50:51], v[130:131], v[146:147]
	v_pk_fma_f32 v[52:53], v[52:53], v[132:133], v[148:149]
	v_pk_fma_f32 v[54:55], v[54:55], v[134:135], v[150:151]
	v_pk_fma_f32 v[56:57], v[56:57], v[136:137], v[152:153]
	v_pk_fma_f32 v[58:59], v[58:59], v[138:139], v[154:155]
	v_pk_fma_f32 v[60:61], v[60:61], v[140:141], v[156:157]
	v_pk_fma_f32 v[62:63], v[62:63], v[142:143], v[158:159]
	v_cvt_pk_bf16_f32 v48, v48, v49
	v_cvt_pk_bf16_f32 v49, v50, v51
	v_cvt_pk_bf16_f32 v50, v52, v53
	v_cvt_pk_bf16_f32 v51, v54, v55
	v_cvt_pk_bf16_f32 v52, v56, v57
	v_cvt_pk_bf16_f32 v53, v58, v59
	v_cvt_pk_bf16_f32 v54, v60, v61
	v_cvt_pk_bf16_f32 v55, v62, v63
	s_lshl_b32 s99, s98, 11
	v_lshl_add_u32 v8, v0, 3, s99
	global_store_dwordx2 v8, v[48:49], s[94:95]
	global_store_dwordx2 v8, v[50:51], s[94:95] offset:512
	global_store_dwordx2 v8, v[52:53], s[94:95] offset:1024
	global_store_dwordx2 v8, v[54:55], s[94:95] offset:1536
	s_lshl_b32 s99, s98, 2
	v_mov_b32_e32 v9, s99
	v_mov_b32_e32 v10, 0
	v_cmp_eq_u32_e32 vcc, 0, v0
	s_and_saveexec_b64 s[98:99], vcc
	global_store_dword v9, v10, s[90:91]
	global_store_dword v9, v10, s[92:93]
	s_or_b64 exec, exec, s[98:99]
	s_add_u32 s98, s97, 8
	s_lshl_b32 s98, s98, 12
	v_add_u32_e32 v3, s98, v1
	global_load_dwordx4 v[48:51], v3, s[88:89] nt
	global_load_dwordx4 v[52:55], v3, s[88:89] offset:1024 nt
	global_load_dwordx4 v[56:59], v3, s[88:89] offset:2048 nt
	global_load_dwordx4 v[60:63], v3, s[88:89] offset:3072 nt
	s_waitcnt vmcnt(38)
	v_mul_f32_e32 v4, v64, v64
	v_fma_f32 v4, v65, v65, v4
	v_fma_f32 v4, v66, v66, v4
	v_fma_f32 v4, v67, v67, v4
	v_fma_f32 v4, v68, v68, v4
	v_fma_f32 v4, v69, v69, v4
	v_fma_f32 v4, v70, v70, v4
	v_fma_f32 v4, v71, v71, v4
	v_fma_f32 v4, v72, v72, v4
	v_fma_f32 v4, v73, v73, v4
	v_fma_f32 v4, v74, v74, v4
	v_fma_f32 v4, v75, v75, v4
	v_fma_f32 v4, v76, v76, v4
	v_fma_f32 v4, v77, v77, v4
	v_fma_f32 v4, v78, v78, v4
	v_fma_f32 v4, v79, v79, v4
	s_nop 1
	v_add_f32_dpp v5, v4, v4 quad_perm:[1,0,3,2] row_mask:0xf bank_mask:0xf
	s_nop 1
	v_add_f32_dpp v4, v5, v5 quad_perm:[2,3,0,1] row_mask:0xf bank_mask:0xf
	s_nop 1
	v_add_f32_dpp v5, v4, v4 row_half_mirror row_mask:0xf bank_mask:0xf
	s_nop 1
	v_add_f32_dpp v4, v5, v5 row_mirror row_mask:0xf bank_mask:0xf
	s_nop 1
	v_readlane_b32 s98, v4, 0
	v_readlane_b32 s99, v4, 16
	s_nop 3
	v_mov_b32_e32 v5, s98
	v_add_f32_e32 v5, s99, v5
	v_readlane_b32 s98, v4, 32
	v_readlane_b32 s99, v4, 48
	s_nop 3
	v_add_f32_e32 v5, s98, v5
	v_add_f32_e32 v5, s99, v5
	v_mul_f32_e32 v5, 0x3a800000, v5
	v_add_f32_e32 v5, 0x358637bd, v5
	v_rsq_f32_e32 v6, v5
	s_nop 0
	s_add_u32 s98, s97, 3
	v_pk_mul_f32 v[64:65], v[64:65], v[6:7] op_sel_hi:[1,0]
	v_pk_mul_f32 v[66:67], v[66:67], v[6:7] op_sel_hi:[1,0]
	v_pk_mul_f32 v[68:69], v[68:69], v[6:7] op_sel_hi:[1,0]
	v_pk_mul_f32 v[70:71], v[70:71], v[6:7] op_sel_hi:[1,0]
	v_pk_mul_f32 v[72:73], v[72:73], v[6:7] op_sel_hi:[1,0]
	v_pk_mul_f32 v[74:75], v[74:75], v[6:7] op_sel_hi:[1,0]
	v_pk_mul_f32 v[76:77], v[76:77], v[6:7] op_sel_hi:[1,0]
	v_pk_mul_f32 v[78:79], v[78:79], v[6:7] op_sel_hi:[1,0]
	v_pk_mul_f32 v[64:65], v[64:65], v[112:113]
	v_pk_mul_f32 v[66:67], v[66:67], v[114:115]
	v_pk_mul_f32 v[68:69], v[68:69], v[116:117]
	v_pk_mul_f32 v[70:71], v[70:71], v[118:119]
	v_pk_mul_f32 v[72:73], v[72:73], v[120:121]
	v_pk_mul_f32 v[74:75], v[74:75], v[122:123]
	v_pk_mul_f32 v[76:77], v[76:77], v[124:125]
	v_pk_mul_f32 v[78:79], v[78:79], v[126:127]
	v_pk_fma_f32 v[64:65], v[64:65], v[128:129], v[144:145]
	v_pk_fma_f32 v[66:67], v[66:67], v[130:131], v[146:147]
	v_pk_fma_f32 v[68:69], v[68:69], v[132:133], v[148:149]
	v_pk_fma_f32 v[70:71], v[70:71], v[134:135], v[150:151]
	v_pk_fma_f32 v[72:73], v[72:73], v[136:137], v[152:153]
	v_pk_fma_f32 v[74:75], v[74:75], v[138:139], v[154:155]
	v_pk_fma_f32 v[76:77], v[76:77], v[140:141], v[156:157]
	v_pk_fma_f32 v[78:79], v[78:79], v[142:143], v[158:159]
	v_cvt_pk_bf16_f32 v64, v64, v65
	v_cvt_pk_bf16_f32 v65, v66, v67
	v_cvt_pk_bf16_f32 v66, v68, v69
	v_cvt_pk_bf16_f32 v67, v70, v71
	v_cvt_pk_bf16_f32 v68, v72, v73
	v_cvt_pk_bf16_f32 v69, v74, v75
	v_cvt_pk_bf16_f32 v70, v76, v77
	v_cvt_pk_bf16_f32 v71, v78, v79
	s_lshl_b32 s99, s98, 11
	v_lshl_add_u32 v8, v0, 3, s99
	global_store_dwordx2 v8, v[64:65], s[94:95]
	global_store_dwordx2 v8, v[66:67], s[94:95] offset:512
	global_store_dwordx2 v8, v[68:69], s[94:95] offset:1024
	global_store_dwordx2 v8, v[70:71], s[94:95] offset:1536
	s_lshl_b32 s99, s98, 2
	v_mov_b32_e32 v9, s99
	v_mov_b32_e32 v10, 0
	v_cmp_eq_u32_e32 vcc, 0, v0
	s_and_saveexec_b64 s[98:99], vcc
	global_store_dword v9, v10, s[90:91]
	global_store_dword v9, v10, s[92:93]
	s_or_b64 exec, exec, s[98:99]
	s_add_u32 s98, s97, 9
	s_lshl_b32 s98, s98, 12
	v_add_u32_e32 v3, s98, v1
	global_load_dwordx4 v[64:67], v3, s[88:89] nt
	global_load_dwordx4 v[68:71], v3, s[88:89] offset:1024 nt
	global_load_dwordx4 v[72:75], v3, s[88:89] offset:2048 nt
	global_load_dwordx4 v[76:79], v3, s[88:89] offset:3072 nt
	s_waitcnt vmcnt(44)
	v_mul_f32_e32 v4, v80, v80
	v_fma_f32 v4, v81, v81, v4
	v_fma_f32 v4, v82, v82, v4
	v_fma_f32 v4, v83, v83, v4
	v_fma_f32 v4, v84, v84, v4
	v_fma_f32 v4, v85, v85, v4
	v_fma_f32 v4, v86, v86, v4
	v_fma_f32 v4, v87, v87, v4
	v_fma_f32 v4, v88, v88, v4
	v_fma_f32 v4, v89, v89, v4
	v_fma_f32 v4, v90, v90, v4
	v_fma_f32 v4, v91, v91, v4
	v_fma_f32 v4, v92, v92, v4
	v_fma_f32 v4, v93, v93, v4
	v_fma_f32 v4, v94, v94, v4
	v_fma_f32 v4, v95, v95, v4
	s_nop 1
	v_add_f32_dpp v5, v4, v4 quad_perm:[1,0,3,2] row_mask:0xf bank_mask:0xf
	s_nop 1
	v_add_f32_dpp v4, v5, v5 quad_perm:[2,3,0,1] row_mask:0xf bank_mask:0xf
	s_nop 1
	v_add_f32_dpp v5, v4, v4 row_half_mirror row_mask:0xf bank_mask:0xf
	s_nop 1
	v_add_f32_dpp v4, v5, v5 row_mirror row_mask:0xf bank_mask:0xf
	s_nop 1
	v_readlane_b32 s98, v4, 0
	v_readlane_b32 s99, v4, 16
	s_nop 3
	v_mov_b32_e32 v5, s98
	v_add_f32_e32 v5, s99, v5
	v_readlane_b32 s98, v4, 32
	v_readlane_b32 s99, v4, 48
	s_nop 3
	v_add_f32_e32 v5, s98, v5
	v_add_f32_e32 v5, s99, v5
	v_mul_f32_e32 v5, 0x3a800000, v5
	v_add_f32_e32 v5, 0x358637bd, v5
	v_rsq_f32_e32 v6, v5
	s_nop 0
	s_add_u32 s98, s97, 4
	v_pk_mul_f32 v[80:81], v[80:81], v[6:7] op_sel_hi:[1,0]
	v_pk_mul_f32 v[82:83], v[82:83], v[6:7] op_sel_hi:[1,0]
	v_pk_mul_f32 v[84:85], v[84:85], v[6:7] op_sel_hi:[1,0]
	v_pk_mul_f32 v[86:87], v[86:87], v[6:7] op_sel_hi:[1,0]
	v_pk_mul_f32 v[88:89], v[88:89], v[6:7] op_sel_hi:[1,0]
	v_pk_mul_f32 v[90:91], v[90:91], v[6:7] op_sel_hi:[1,0]
	v_pk_mul_f32 v[92:93], v[92:93], v[6:7] op_sel_hi:[1,0]
	v_pk_mul_f32 v[94:95], v[94:95], v[6:7] op_sel_hi:[1,0]
	v_pk_mul_f32 v[80:81], v[80:81], v[112:113]
	v_pk_mul_f32 v[82:83], v[82:83], v[114:115]
	v_pk_mul_f32 v[84:85], v[84:85], v[116:117]
	v_pk_mul_f32 v[86:87], v[86:87], v[118:119]
	v_pk_mul_f32 v[88:89], v[88:89], v[120:121]
	v_pk_mul_f32 v[90:91], v[90:91], v[122:123]
	v_pk_mul_f32 v[92:93], v[92:93], v[124:125]
	v_pk_mul_f32 v[94:95], v[94:95], v[126:127]
	v_pk_fma_f32 v[80:81], v[80:81], v[128:129], v[144:145]
	v_pk_fma_f32 v[82:83], v[82:83], v[130:131], v[146:147]
	v_pk_fma_f32 v[84:85], v[84:85], v[132:133], v[148:149]
	v_pk_fma_f32 v[86:87], v[86:87], v[134:135], v[150:151]
	v_pk_fma_f32 v[88:89], v[88:89], v[136:137], v[152:153]
	v_pk_fma_f32 v[90:91], v[90:91], v[138:139], v[154:155]
	v_pk_fma_f32 v[92:93], v[92:93], v[140:141], v[156:157]
	v_pk_fma_f32 v[94:95], v[94:95], v[142:143], v[158:159]
	v_cvt_pk_bf16_f32 v80, v80, v81
	v_cvt_pk_bf16_f32 v81, v82, v83
	v_cvt_pk_bf16_f32 v82, v84, v85
	v_cvt_pk_bf16_f32 v83, v86, v87
	v_cvt_pk_bf16_f32 v84, v88, v89
	v_cvt_pk_bf16_f32 v85, v90, v91
	v_cvt_pk_bf16_f32 v86, v92, v93
	v_cvt_pk_bf16_f32 v87, v94, v95
	s_lshl_b32 s99, s98, 11
	v_lshl_add_u32 v8, v0, 3, s99
	global_store_dwordx2 v8, v[80:81], s[94:95]
	global_store_dwordx2 v8, v[82:83], s[94:95] offset:512
	global_store_dwordx2 v8, v[84:85], s[94:95] offset:1024
	global_store_dwordx2 v8, v[86:87], s[94:95] offset:1536
	s_lshl_b32 s99, s98, 2
	v_mov_b32_e32 v9, s99
	v_mov_b32_e32 v10, 0
	v_cmp_eq_u32_e32 vcc, 0, v0
	s_and_saveexec_b64 s[98:99], vcc
	global_store_dword v9, v10, s[90:91]
	global_store_dword v9, v10, s[92:93]
	s_or_b64 exec, exec, s[98:99]
	s_add_u32 s98, s97, 10
	s_lshl_b32 s98, s98, 12
	v_add_u32_e32 v3, s98, v1
	global_load_dwordx4 v[80:83], v3, s[88:89] nt
	global_load_dwordx4 v[84:87], v3, s[88:89] offset:1024 nt
	global_load_dwordx4 v[88:91], v3, s[88:89] offset:2048 nt
	global_load_dwordx4 v[92:95], v3, s[88:89] offset:3072 nt
	s_waitcnt vmcnt(50)
	v_mul_f32_e32 v4, v96, v96
	v_fma_f32 v4, v97, v97, v4
	v_fma_f32 v4, v98, v98, v4
	v_fma_f32 v4, v99, v99, v4
	v_fma_f32 v4, v100, v100, v4
	v_fma_f32 v4, v101, v101, v4
	v_fma_f32 v4, v102, v102, v4
	v_fma_f32 v4, v103, v103, v4
	v_fma_f32 v4, v104, v104, v4
	v_fma_f32 v4, v105, v105, v4
	v_fma_f32 v4, v106, v106, v4
	v_fma_f32 v4, v107, v107, v4
	v_fma_f32 v4, v108, v108, v4
	v_fma_f32 v4, v109, v109, v4
	v_fma_f32 v4, v110, v110, v4
	v_fma_f32 v4, v111, v111, v4
	s_nop 1
	v_add_f32_dpp v5, v4, v4 quad_perm:[1,0,3,2] row_mask:0xf bank_mask:0xf
	s_nop 1
	v_add_f32_dpp v4, v5, v5 quad_perm:[2,3,0,1] row_mask:0xf bank_mask:0xf
	s_nop 1
	v_add_f32_dpp v5, v4, v4 row_half_mirror row_mask:0xf bank_mask:0xf
	s_nop 1
	v_add_f32_dpp v4, v5, v5 row_mirror row_mask:0xf bank_mask:0xf
	s_nop 1
	v_readlane_b32 s98, v4, 0
	v_readlane_b32 s99, v4, 16
	s_nop 3
	v_mov_b32_e32 v5, s98
	v_add_f32_e32 v5, s99, v5
	v_readlane_b32 s98, v4, 32
	v_readlane_b32 s99, v4, 48
	s_nop 3
	v_add_f32_e32 v5, s98, v5
	v_add_f32_e32 v5, s99, v5
	v_mul_f32_e32 v5, 0x3a800000, v5
	v_add_f32_e32 v5, 0x358637bd, v5
	v_rsq_f32_e32 v6, v5
	s_nop 0
	s_add_u32 s98, s97, 5
	v_pk_mul_f32 v[96:97], v[96:97], v[6:7] op_sel_hi:[1,0]
	v_pk_mul_f32 v[98:99], v[98:99], v[6:7] op_sel_hi:[1,0]
	v_pk_mul_f32 v[100:101], v[100:101], v[6:7] op_sel_hi:[1,0]
	v_pk_mul_f32 v[102:103], v[102:103], v[6:7] op_sel_hi:[1,0]
	v_pk_mul_f32 v[104:105], v[104:105], v[6:7] op_sel_hi:[1,0]
	v_pk_mul_f32 v[106:107], v[106:107], v[6:7] op_sel_hi:[1,0]
	v_pk_mul_f32 v[108:109], v[108:109], v[6:7] op_sel_hi:[1,0]
	v_pk_mul_f32 v[110:111], v[110:111], v[6:7] op_sel_hi:[1,0]
	v_pk_mul_f32 v[96:97], v[96:97], v[112:113]
	v_pk_mul_f32 v[98:99], v[98:99], v[114:115]
	v_pk_mul_f32 v[100:101], v[100:101], v[116:117]
	v_pk_mul_f32 v[102:103], v[102:103], v[118:119]
	v_pk_mul_f32 v[104:105], v[104:105], v[120:121]
	v_pk_mul_f32 v[106:107], v[106:107], v[122:123]
	v_pk_mul_f32 v[108:109], v[108:109], v[124:125]
	v_pk_mul_f32 v[110:111], v[110:111], v[126:127]
	v_pk_fma_f32 v[96:97], v[96:97], v[128:129], v[144:145]
	v_pk_fma_f32 v[98:99], v[98:99], v[130:131], v[146:147]
	v_pk_fma_f32 v[100:101], v[100:101], v[132:133], v[148:149]
	v_pk_fma_f32 v[102:103], v[102:103], v[134:135], v[150:151]
	v_pk_fma_f32 v[104:105], v[104:105], v[136:137], v[152:153]
	v_pk_fma_f32 v[106:107], v[106:107], v[138:139], v[154:155]
	v_pk_fma_f32 v[108:109], v[108:109], v[140:141], v[156:157]
	v_pk_fma_f32 v[110:111], v[110:111], v[142:143], v[158:159]
	v_cvt_pk_bf16_f32 v96, v96, v97
	v_cvt_pk_bf16_f32 v97, v98, v99
	v_cvt_pk_bf16_f32 v98, v100, v101
	v_cvt_pk_bf16_f32 v99, v102, v103
	v_cvt_pk_bf16_f32 v100, v104, v105
	v_cvt_pk_bf16_f32 v101, v106, v107
	v_cvt_pk_bf16_f32 v102, v108, v109
	v_cvt_pk_bf16_f32 v103, v110, v111
	s_lshl_b32 s99, s98, 11
	v_lshl_add_u32 v8, v0, 3, s99
	global_store_dwordx2 v8, v[96:97], s[94:95]
	global_store_dwordx2 v8, v[98:99], s[94:95] offset:512
	global_store_dwordx2 v8, v[100:101], s[94:95] offset:1024
	global_store_dwordx2 v8, v[102:103], s[94:95] offset:1536
	s_lshl_b32 s99, s98, 2
	v_mov_b32_e32 v9, s99
	v_mov_b32_e32 v10, 0
	v_cmp_eq_u32_e32 vcc, 0, v0
	s_and_saveexec_b64 s[98:99], vcc
	global_store_dword v9, v10, s[90:91]
	global_store_dword v9, v10, s[92:93]
	s_or_b64 exec, exec, s[98:99]
	s_add_u32 s98, s97, 11
	s_lshl_b32 s98, s98, 12
	v_add_u32_e32 v3, s98, v1
	global_load_dwordx4 v[96:99], v3, s[88:89] nt
	global_load_dwordx4 v[100:103], v3, s[88:89] offset:1024 nt
	global_load_dwordx4 v[104:107], v3, s[88:89] offset:2048 nt
	global_load_dwordx4 v[108:111], v3, s[88:89] offset:3072 nt
	s_waitcnt vmcnt(50)
	v_mul_f32_e32 v4, v16, v16
	v_fma_f32 v4, v17, v17, v4
	v_fma_f32 v4, v18, v18, v4
	v_fma_f32 v4, v19, v19, v4
	v_fma_f32 v4, v20, v20, v4
	v_fma_f32 v4, v21, v21, v4
	v_fma_f32 v4, v22, v22, v4
	v_fma_f32 v4, v23, v23, v4
	v_fma_f32 v4, v24, v24, v4
	v_fma_f32 v4, v25, v25, v4
	v_fma_f32 v4, v26, v26, v4
	v_fma_f32 v4, v27, v27, v4
	v_fma_f32 v4, v28, v28, v4
	v_fma_f32 v4, v29, v29, v4
	v_fma_f32 v4, v30, v30, v4
	v_fma_f32 v4, v31, v31, v4
	s_nop 1
	v_add_f32_dpp v5, v4, v4 quad_perm:[1,0,3,2] row_mask:0xf bank_mask:0xf
	s_nop 1
	v_add_f32_dpp v4, v5, v5 quad_perm:[2,3,0,1] row_mask:0xf bank_mask:0xf
	s_nop 1
	v_add_f32_dpp v5, v4, v4 row_half_mirror row_mask:0xf bank_mask:0xf
	s_nop 1
	v_add_f32_dpp v4, v5, v5 row_mirror row_mask:0xf bank_mask:0xf
	s_nop 1
	v_readlane_b32 s98, v4, 0
	v_readlane_b32 s99, v4, 16
	s_nop 3
	v_mov_b32_e32 v5, s98
	v_add_f32_e32 v5, s99, v5
	v_readlane_b32 s98, v4, 32
	v_readlane_b32 s99, v4, 48
	s_nop 3
	v_add_f32_e32 v5, s98, v5
	v_add_f32_e32 v5, s99, v5
	v_mul_f32_e32 v5, 0x3a800000, v5
	v_add_f32_e32 v5, 0x358637bd, v5
	v_rsq_f32_e32 v6, v5
	s_nop 0
	s_add_u32 s98, s97, 6
	v_pk_mul_f32 v[16:17], v[16:17], v[6:7] op_sel_hi:[1,0]
	v_pk_mul_f32 v[18:19], v[18:19], v[6:7] op_sel_hi:[1,0]
	v_pk_mul_f32 v[20:21], v[20:21], v[6:7] op_sel_hi:[1,0]
	v_pk_mul_f32 v[22:23], v[22:23], v[6:7] op_sel_hi:[1,0]
	v_pk_mul_f32 v[24:25], v[24:25], v[6:7] op_sel_hi:[1,0]
	v_pk_mul_f32 v[26:27], v[26:27], v[6:7] op_sel_hi:[1,0]
	v_pk_mul_f32 v[28:29], v[28:29], v[6:7] op_sel_hi:[1,0]
	v_pk_mul_f32 v[30:31], v[30:31], v[6:7] op_sel_hi:[1,0]
	v_pk_mul_f32 v[16:17], v[16:17], v[112:113]
	v_pk_mul_f32 v[18:19], v[18:19], v[114:115]
	v_pk_mul_f32 v[20:21], v[20:21], v[116:117]
	v_pk_mul_f32 v[22:23], v[22:23], v[118:119]
	v_pk_mul_f32 v[24:25], v[24:25], v[120:121]
	v_pk_mul_f32 v[26:27], v[26:27], v[122:123]
	v_pk_mul_f32 v[28:29], v[28:29], v[124:125]
	v_pk_mul_f32 v[30:31], v[30:31], v[126:127]
	v_pk_fma_f32 v[16:17], v[16:17], v[128:129], v[144:145]
	v_pk_fma_f32 v[18:19], v[18:19], v[130:131], v[146:147]
	v_pk_fma_f32 v[20:21], v[20:21], v[132:133], v[148:149]
	v_pk_fma_f32 v[22:23], v[22:23], v[134:135], v[150:151]
	v_pk_fma_f32 v[24:25], v[24:25], v[136:137], v[152:153]
	v_pk_fma_f32 v[26:27], v[26:27], v[138:139], v[154:155]
	v_pk_fma_f32 v[28:29], v[28:29], v[140:141], v[156:157]
	v_pk_fma_f32 v[30:31], v[30:31], v[142:143], v[158:159]
	v_cvt_pk_bf16_f32 v16, v16, v17
	v_cvt_pk_bf16_f32 v17, v18, v19
	v_cvt_pk_bf16_f32 v18, v20, v21
	v_cvt_pk_bf16_f32 v19, v22, v23
	v_cvt_pk_bf16_f32 v20, v24, v25
	v_cvt_pk_bf16_f32 v21, v26, v27
	v_cvt_pk_bf16_f32 v22, v28, v29
	v_cvt_pk_bf16_f32 v23, v30, v31
	s_lshl_b32 s99, s98, 11
	v_lshl_add_u32 v8, v0, 3, s99
	global_store_dwordx2 v8, v[16:17], s[94:95]
	global_store_dwordx2 v8, v[18:19], s[94:95] offset:512
	global_store_dwordx2 v8, v[20:21], s[94:95] offset:1024
	global_store_dwordx2 v8, v[22:23], s[94:95] offset:1536
	s_lshl_b32 s99, s98, 2
	v_mov_b32_e32 v9, s99
	v_mov_b32_e32 v10, 0
	v_cmp_eq_u32_e32 vcc, 0, v0
	s_and_saveexec_b64 s[98:99], vcc
	global_store_dword v9, v10, s[90:91]
	global_store_dword v9, v10, s[92:93]
	s_or_b64 exec, exec, s[98:99]
	s_add_u32 s98, s97, 12
	s_lshl_b32 s98, s98, 12
	v_add_u32_e32 v3, s98, v1
	global_load_dwordx4 v[16:19], v3, s[88:89] nt
	global_load_dwordx4 v[20:23], v3, s[88:89] offset:1024 nt
	global_load_dwordx4 v[24:27], v3, s[88:89] offset:2048 nt
	global_load_dwordx4 v[28:31], v3, s[88:89] offset:3072 nt
	s_waitcnt vmcnt(50)
	v_mul_f32_e32 v4, v32, v32
	v_fma_f32 v4, v33, v33, v4
	v_fma_f32 v4, v34, v34, v4
	v_fma_f32 v4, v35, v35, v4
	v_fma_f32 v4, v36, v36, v4
	v_fma_f32 v4, v37, v37, v4
	v_fma_f32 v4, v38, v38, v4
	v_fma_f32 v4, v39, v39, v4
	v_fma_f32 v4, v40, v40, v4
	v_fma_f32 v4, v41, v41, v4
	v_fma_f32 v4, v42, v42, v4
	v_fma_f32 v4, v43, v43, v4
	v_fma_f32 v4, v44, v44, v4
	v_fma_f32 v4, v45, v45, v4
	v_fma_f32 v4, v46, v46, v4
	v_fma_f32 v4, v47, v47, v4
	s_nop 1
	v_add_f32_dpp v5, v4, v4 quad_perm:[1,0,3,2] row_mask:0xf bank_mask:0xf
	s_nop 1
	v_add_f32_dpp v4, v5, v5 quad_perm:[2,3,0,1] row_mask:0xf bank_mask:0xf
	s_nop 1
	v_add_f32_dpp v5, v4, v4 row_half_mirror row_mask:0xf bank_mask:0xf
	s_nop 1
	v_add_f32_dpp v4, v5, v5 row_mirror row_mask:0xf bank_mask:0xf
	s_nop 1
	v_readlane_b32 s98, v4, 0
	v_readlane_b32 s99, v4, 16
	s_nop 3
	v_mov_b32_e32 v5, s98
	v_add_f32_e32 v5, s99, v5
	v_readlane_b32 s98, v4, 32
	v_readlane_b32 s99, v4, 48
	s_nop 3
	v_add_f32_e32 v5, s98, v5
	v_add_f32_e32 v5, s99, v5
	v_mul_f32_e32 v5, 0x3a800000, v5
	v_add_f32_e32 v5, 0x358637bd, v5
	v_rsq_f32_e32 v6, v5
	s_nop 0
	s_add_u32 s98, s97, 7
	v_pk_mul_f32 v[32:33], v[32:33], v[6:7] op_sel_hi:[1,0]
	v_pk_mul_f32 v[34:35], v[34:35], v[6:7] op_sel_hi:[1,0]
	v_pk_mul_f32 v[36:37], v[36:37], v[6:7] op_sel_hi:[1,0]
	v_pk_mul_f32 v[38:39], v[38:39], v[6:7] op_sel_hi:[1,0]
	v_pk_mul_f32 v[40:41], v[40:41], v[6:7] op_sel_hi:[1,0]
	v_pk_mul_f32 v[42:43], v[42:43], v[6:7] op_sel_hi:[1,0]
	v_pk_mul_f32 v[44:45], v[44:45], v[6:7] op_sel_hi:[1,0]
	v_pk_mul_f32 v[46:47], v[46:47], v[6:7] op_sel_hi:[1,0]
	v_pk_mul_f32 v[32:33], v[32:33], v[112:113]
	v_pk_mul_f32 v[34:35], v[34:35], v[114:115]
	v_pk_mul_f32 v[36:37], v[36:37], v[116:117]
	v_pk_mul_f32 v[38:39], v[38:39], v[118:119]
	v_pk_mul_f32 v[40:41], v[40:41], v[120:121]
	v_pk_mul_f32 v[42:43], v[42:43], v[122:123]
	v_pk_mul_f32 v[44:45], v[44:45], v[124:125]
	v_pk_mul_f32 v[46:47], v[46:47], v[126:127]
	v_pk_fma_f32 v[32:33], v[32:33], v[128:129], v[144:145]
	v_pk_fma_f32 v[34:35], v[34:35], v[130:131], v[146:147]
	v_pk_fma_f32 v[36:37], v[36:37], v[132:133], v[148:149]
	v_pk_fma_f32 v[38:39], v[38:39], v[134:135], v[150:151]
	v_pk_fma_f32 v[40:41], v[40:41], v[136:137], v[152:153]
	v_pk_fma_f32 v[42:43], v[42:43], v[138:139], v[154:155]
	v_pk_fma_f32 v[44:45], v[44:45], v[140:141], v[156:157]
	v_pk_fma_f32 v[46:47], v[46:47], v[142:143], v[158:159]
	v_cvt_pk_bf16_f32 v32, v32, v33
	v_cvt_pk_bf16_f32 v33, v34, v35
	v_cvt_pk_bf16_f32 v34, v36, v37
	v_cvt_pk_bf16_f32 v35, v38, v39
	v_cvt_pk_bf16_f32 v36, v40, v41
	v_cvt_pk_bf16_f32 v37, v42, v43
	v_cvt_pk_bf16_f32 v38, v44, v45
	v_cvt_pk_bf16_f32 v39, v46, v47
	s_lshl_b32 s99, s98, 11
	v_lshl_add_u32 v8, v0, 3, s99
	global_store_dwordx2 v8, v[32:33], s[94:95]
	global_store_dwordx2 v8, v[34:35], s[94:95] offset:512
	global_store_dwordx2 v8, v[36:37], s[94:95] offset:1024
	global_store_dwordx2 v8, v[38:39], s[94:95] offset:1536
	s_lshl_b32 s99, s98, 2
	v_mov_b32_e32 v9, s99
	v_mov_b32_e32 v10, 0
	v_cmp_eq_u32_e32 vcc, 0, v0
	s_and_saveexec_b64 s[98:99], vcc
	global_store_dword v9, v10, s[90:91]
	global_store_dword v9, v10, s[92:93]
	s_or_b64 exec, exec, s[98:99]
	s_add_u32 s98, s97, 13
	s_lshl_b32 s98, s98, 12
	v_add_u32_e32 v3, s98, v1
	global_load_dwordx4 v[32:35], v3, s[88:89] nt
	global_load_dwordx4 v[36:39], v3, s[88:89] offset:1024 nt
	global_load_dwordx4 v[40:43], v3, s[88:89] offset:2048 nt
	global_load_dwordx4 v[44:47], v3, s[88:89] offset:3072 nt
	s_waitcnt vmcnt(50)
	v_mul_f32_e32 v4, v48, v48
	v_fma_f32 v4, v49, v49, v4
	v_fma_f32 v4, v50, v50, v4
	v_fma_f32 v4, v51, v51, v4
	v_fma_f32 v4, v52, v52, v4
	v_fma_f32 v4, v53, v53, v4
	v_fma_f32 v4, v54, v54, v4
	v_fma_f32 v4, v55, v55, v4
	v_fma_f32 v4, v56, v56, v4
	v_fma_f32 v4, v57, v57, v4
	v_fma_f32 v4, v58, v58, v4
	v_fma_f32 v4, v59, v59, v4
	v_fma_f32 v4, v60, v60, v4
	v_fma_f32 v4, v61, v61, v4
	v_fma_f32 v4, v62, v62, v4
	v_fma_f32 v4, v63, v63, v4
	s_nop 1
	v_add_f32_dpp v5, v4, v4 quad_perm:[1,0,3,2] row_mask:0xf bank_mask:0xf
	s_nop 1
	v_add_f32_dpp v4, v5, v5 quad_perm:[2,3,0,1] row_mask:0xf bank_mask:0xf
	s_nop 1
	v_add_f32_dpp v5, v4, v4 row_half_mirror row_mask:0xf bank_mask:0xf
	s_nop 1
	v_add_f32_dpp v4, v5, v5 row_mirror row_mask:0xf bank_mask:0xf
	s_nop 1
	v_readlane_b32 s98, v4, 0
	v_readlane_b32 s99, v4, 16
	s_nop 3
	v_mov_b32_e32 v5, s98
	v_add_f32_e32 v5, s99, v5
	v_readlane_b32 s98, v4, 32
	v_readlane_b32 s99, v4, 48
	s_nop 3
	v_add_f32_e32 v5, s98, v5
	v_add_f32_e32 v5, s99, v5
	v_mul_f32_e32 v5, 0x3a800000, v5
	v_add_f32_e32 v5, 0x358637bd, v5
	v_rsq_f32_e32 v6, v5
	s_nop 0
	s_add_u32 s98, s97, 8
	v_pk_mul_f32 v[48:49], v[48:49], v[6:7] op_sel_hi:[1,0]
	v_pk_mul_f32 v[50:51], v[50:51], v[6:7] op_sel_hi:[1,0]
	v_pk_mul_f32 v[52:53], v[52:53], v[6:7] op_sel_hi:[1,0]
	v_pk_mul_f32 v[54:55], v[54:55], v[6:7] op_sel_hi:[1,0]
	v_pk_mul_f32 v[56:57], v[56:57], v[6:7] op_sel_hi:[1,0]
	v_pk_mul_f32 v[58:59], v[58:59], v[6:7] op_sel_hi:[1,0]
	v_pk_mul_f32 v[60:61], v[60:61], v[6:7] op_sel_hi:[1,0]
	v_pk_mul_f32 v[62:63], v[62:63], v[6:7] op_sel_hi:[1,0]
	v_pk_mul_f32 v[48:49], v[48:49], v[112:113]
	v_pk_mul_f32 v[50:51], v[50:51], v[114:115]
	v_pk_mul_f32 v[52:53], v[52:53], v[116:117]
	v_pk_mul_f32 v[54:55], v[54:55], v[118:119]
	v_pk_mul_f32 v[56:57], v[56:57], v[120:121]
	v_pk_mul_f32 v[58:59], v[58:59], v[122:123]
	v_pk_mul_f32 v[60:61], v[60:61], v[124:125]
	v_pk_mul_f32 v[62:63], v[62:63], v[126:127]
	v_pk_fma_f32 v[48:49], v[48:49], v[128:129], v[144:145]
	v_pk_fma_f32 v[50:51], v[50:51], v[130:131], v[146:147]
	v_pk_fma_f32 v[52:53], v[52:53], v[132:133], v[148:149]
	v_pk_fma_f32 v[54:55], v[54:55], v[134:135], v[150:151]
	v_pk_fma_f32 v[56:57], v[56:57], v[136:137], v[152:153]
	v_pk_fma_f32 v[58:59], v[58:59], v[138:139], v[154:155]
	v_pk_fma_f32 v[60:61], v[60:61], v[140:141], v[156:157]
	v_pk_fma_f32 v[62:63], v[62:63], v[142:143], v[158:159]
	v_cvt_pk_bf16_f32 v48, v48, v49
	v_cvt_pk_bf16_f32 v49, v50, v51
	v_cvt_pk_bf16_f32 v50, v52, v53
	v_cvt_pk_bf16_f32 v51, v54, v55
	v_cvt_pk_bf16_f32 v52, v56, v57
	v_cvt_pk_bf16_f32 v53, v58, v59
	v_cvt_pk_bf16_f32 v54, v60, v61
	v_cvt_pk_bf16_f32 v55, v62, v63
	s_lshl_b32 s99, s98, 11
	v_lshl_add_u32 v8, v0, 3, s99
	global_store_dwordx2 v8, v[48:49], s[94:95]
	global_store_dwordx2 v8, v[50:51], s[94:95] offset:512
	global_store_dwordx2 v8, v[52:53], s[94:95] offset:1024
	global_store_dwordx2 v8, v[54:55], s[94:95] offset:1536
	s_lshl_b32 s99, s98, 2
	v_mov_b32_e32 v9, s99
	v_mov_b32_e32 v10, 0
	v_cmp_eq_u32_e32 vcc, 0, v0
	s_and_saveexec_b64 s[98:99], vcc
	global_store_dword v9, v10, s[90:91]
	global_store_dword v9, v10, s[92:93]
	s_or_b64 exec, exec, s[98:99]
	s_add_u32 s98, s97, 14
	s_lshl_b32 s98, s98, 12
	v_add_u32_e32 v3, s98, v1
	global_load_dwordx4 v[48:51], v3, s[88:89] nt
	global_load_dwordx4 v[52:55], v3, s[88:89] offset:1024 nt
	global_load_dwordx4 v[56:59], v3, s[88:89] offset:2048 nt
	global_load_dwordx4 v[60:63], v3, s[88:89] offset:3072 nt
	s_waitcnt vmcnt(50)
	v_mul_f32_e32 v4, v64, v64
	v_fma_f32 v4, v65, v65, v4
	v_fma_f32 v4, v66, v66, v4
	v_fma_f32 v4, v67, v67, v4
	v_fma_f32 v4, v68, v68, v4
	v_fma_f32 v4, v69, v69, v4
	v_fma_f32 v4, v70, v70, v4
	v_fma_f32 v4, v71, v71, v4
	v_fma_f32 v4, v72, v72, v4
	v_fma_f32 v4, v73, v73, v4
	v_fma_f32 v4, v74, v74, v4
	v_fma_f32 v4, v75, v75, v4
	v_fma_f32 v4, v76, v76, v4
	v_fma_f32 v4, v77, v77, v4
	v_fma_f32 v4, v78, v78, v4
	v_fma_f32 v4, v79, v79, v4
	s_nop 1
	v_add_f32_dpp v5, v4, v4 quad_perm:[1,0,3,2] row_mask:0xf bank_mask:0xf
	s_nop 1
	v_add_f32_dpp v4, v5, v5 quad_perm:[2,3,0,1] row_mask:0xf bank_mask:0xf
	s_nop 1
	v_add_f32_dpp v5, v4, v4 row_half_mirror row_mask:0xf bank_mask:0xf
	s_nop 1
	v_add_f32_dpp v4, v5, v5 row_mirror row_mask:0xf bank_mask:0xf
	s_nop 1
	v_readlane_b32 s98, v4, 0
	v_readlane_b32 s99, v4, 16
	s_nop 3
	v_mov_b32_e32 v5, s98
	v_add_f32_e32 v5, s99, v5
	v_readlane_b32 s98, v4, 32
	v_readlane_b32 s99, v4, 48
	s_nop 3
	v_add_f32_e32 v5, s98, v5
	v_add_f32_e32 v5, s99, v5
	v_mul_f32_e32 v5, 0x3a800000, v5
	v_add_f32_e32 v5, 0x358637bd, v5
	v_rsq_f32_e32 v6, v5
	s_nop 0
	s_add_u32 s98, s97, 9
	v_pk_mul_f32 v[64:65], v[64:65], v[6:7] op_sel_hi:[1,0]
	v_pk_mul_f32 v[66:67], v[66:67], v[6:7] op_sel_hi:[1,0]
	v_pk_mul_f32 v[68:69], v[68:69], v[6:7] op_sel_hi:[1,0]
	v_pk_mul_f32 v[70:71], v[70:71], v[6:7] op_sel_hi:[1,0]
	v_pk_mul_f32 v[72:73], v[72:73], v[6:7] op_sel_hi:[1,0]
	v_pk_mul_f32 v[74:75], v[74:75], v[6:7] op_sel_hi:[1,0]
	v_pk_mul_f32 v[76:77], v[76:77], v[6:7] op_sel_hi:[1,0]
	v_pk_mul_f32 v[78:79], v[78:79], v[6:7] op_sel_hi:[1,0]
	v_pk_mul_f32 v[64:65], v[64:65], v[112:113]
	v_pk_mul_f32 v[66:67], v[66:67], v[114:115]
	v_pk_mul_f32 v[68:69], v[68:69], v[116:117]
	v_pk_mul_f32 v[70:71], v[70:71], v[118:119]
	v_pk_mul_f32 v[72:73], v[72:73], v[120:121]
	v_pk_mul_f32 v[74:75], v[74:75], v[122:123]
	v_pk_mul_f32 v[76:77], v[76:77], v[124:125]
	v_pk_mul_f32 v[78:79], v[78:79], v[126:127]
	v_pk_fma_f32 v[64:65], v[64:65], v[128:129], v[144:145]
	v_pk_fma_f32 v[66:67], v[66:67], v[130:131], v[146:147]
	v_pk_fma_f32 v[68:69], v[68:69], v[132:133], v[148:149]
	v_pk_fma_f32 v[70:71], v[70:71], v[134:135], v[150:151]
	v_pk_fma_f32 v[72:73], v[72:73], v[136:137], v[152:153]
	v_pk_fma_f32 v[74:75], v[74:75], v[138:139], v[154:155]
	v_pk_fma_f32 v[76:77], v[76:77], v[140:141], v[156:157]
	v_pk_fma_f32 v[78:79], v[78:79], v[142:143], v[158:159]
	v_cvt_pk_bf16_f32 v64, v64, v65
	v_cvt_pk_bf16_f32 v65, v66, v67
	v_cvt_pk_bf16_f32 v66, v68, v69
	v_cvt_pk_bf16_f32 v67, v70, v71
	v_cvt_pk_bf16_f32 v68, v72, v73
	v_cvt_pk_bf16_f32 v69, v74, v75
	v_cvt_pk_bf16_f32 v70, v76, v77
	v_cvt_pk_bf16_f32 v71, v78, v79
	s_lshl_b32 s99, s98, 11
	v_lshl_add_u32 v8, v0, 3, s99
	global_store_dwordx2 v8, v[64:65], s[94:95]
	global_store_dwordx2 v8, v[66:67], s[94:95] offset:512
	global_store_dwordx2 v8, v[68:69], s[94:95] offset:1024
	global_store_dwordx2 v8, v[70:71], s[94:95] offset:1536
	s_lshl_b32 s99, s98, 2
	v_mov_b32_e32 v9, s99
	v_mov_b32_e32 v10, 0
	v_cmp_eq_u32_e32 vcc, 0, v0
	s_and_saveexec_b64 s[98:99], vcc
	global_store_dword v9, v10, s[90:91]
	global_store_dword v9, v10, s[92:93]
	s_or_b64 exec, exec, s[98:99]
	s_add_u32 s98, s97, 15
	s_lshl_b32 s98, s98, 12
	v_add_u32_e32 v3, s98, v1
	global_load_dwordx4 v[64:67], v3, s[88:89] nt
	global_load_dwordx4 v[68:71], v3, s[88:89] offset:1024 nt
	global_load_dwordx4 v[72:75], v3, s[88:89] offset:2048 nt
	global_load_dwordx4 v[76:79], v3, s[88:89] offset:3072 nt
	s_waitcnt vmcnt(50)
	v_mul_f32_e32 v4, v80, v80
	v_fma_f32 v4, v81, v81, v4
	v_fma_f32 v4, v82, v82, v4
	v_fma_f32 v4, v83, v83, v4
	v_fma_f32 v4, v84, v84, v4
	v_fma_f32 v4, v85, v85, v4
	v_fma_f32 v4, v86, v86, v4
	v_fma_f32 v4, v87, v87, v4
	v_fma_f32 v4, v88, v88, v4
	v_fma_f32 v4, v89, v89, v4
	v_fma_f32 v4, v90, v90, v4
	v_fma_f32 v4, v91, v91, v4
	v_fma_f32 v4, v92, v92, v4
	v_fma_f32 v4, v93, v93, v4
	v_fma_f32 v4, v94, v94, v4
	v_fma_f32 v4, v95, v95, v4
	s_nop 1
	v_add_f32_dpp v5, v4, v4 quad_perm:[1,0,3,2] row_mask:0xf bank_mask:0xf
	s_nop 1
	v_add_f32_dpp v4, v5, v5 quad_perm:[2,3,0,1] row_mask:0xf bank_mask:0xf
	s_nop 1
	v_add_f32_dpp v5, v4, v4 row_half_mirror row_mask:0xf bank_mask:0xf
	s_nop 1
	v_add_f32_dpp v4, v5, v5 row_mirror row_mask:0xf bank_mask:0xf
	s_nop 1
	v_readlane_b32 s98, v4, 0
	v_readlane_b32 s99, v4, 16
	s_nop 3
	v_mov_b32_e32 v5, s98
	v_add_f32_e32 v5, s99, v5
	v_readlane_b32 s98, v4, 32
	v_readlane_b32 s99, v4, 48
	s_nop 3
	v_add_f32_e32 v5, s98, v5
	v_add_f32_e32 v5, s99, v5
	v_mul_f32_e32 v5, 0x3a800000, v5
	v_add_f32_e32 v5, 0x358637bd, v5
	v_rsq_f32_e32 v6, v5
	s_nop 0
	s_add_u32 s98, s97, 10
	v_pk_mul_f32 v[80:81], v[80:81], v[6:7] op_sel_hi:[1,0]
	v_pk_mul_f32 v[82:83], v[82:83], v[6:7] op_sel_hi:[1,0]
	v_pk_mul_f32 v[84:85], v[84:85], v[6:7] op_sel_hi:[1,0]
	v_pk_mul_f32 v[86:87], v[86:87], v[6:7] op_sel_hi:[1,0]
	v_pk_mul_f32 v[88:89], v[88:89], v[6:7] op_sel_hi:[1,0]
	v_pk_mul_f32 v[90:91], v[90:91], v[6:7] op_sel_hi:[1,0]
	v_pk_mul_f32 v[92:93], v[92:93], v[6:7] op_sel_hi:[1,0]
	v_pk_mul_f32 v[94:95], v[94:95], v[6:7] op_sel_hi:[1,0]
	v_pk_mul_f32 v[80:81], v[80:81], v[112:113]
	v_pk_mul_f32 v[82:83], v[82:83], v[114:115]
	v_pk_mul_f32 v[84:85], v[84:85], v[116:117]
	v_pk_mul_f32 v[86:87], v[86:87], v[118:119]
	v_pk_mul_f32 v[88:89], v[88:89], v[120:121]
	v_pk_mul_f32 v[90:91], v[90:91], v[122:123]
	v_pk_mul_f32 v[92:93], v[92:93], v[124:125]
	v_pk_mul_f32 v[94:95], v[94:95], v[126:127]
	v_pk_fma_f32 v[80:81], v[80:81], v[128:129], v[144:145]
	v_pk_fma_f32 v[82:83], v[82:83], v[130:131], v[146:147]
	v_pk_fma_f32 v[84:85], v[84:85], v[132:133], v[148:149]
	v_pk_fma_f32 v[86:87], v[86:87], v[134:135], v[150:151]
	v_pk_fma_f32 v[88:89], v[88:89], v[136:137], v[152:153]
	v_pk_fma_f32 v[90:91], v[90:91], v[138:139], v[154:155]
	v_pk_fma_f32 v[92:93], v[92:93], v[140:141], v[156:157]
	v_pk_fma_f32 v[94:95], v[94:95], v[142:143], v[158:159]
	v_cvt_pk_bf16_f32 v80, v80, v81
	v_cvt_pk_bf16_f32 v81, v82, v83
	v_cvt_pk_bf16_f32 v82, v84, v85
	v_cvt_pk_bf16_f32 v83, v86, v87
	v_cvt_pk_bf16_f32 v84, v88, v89
	v_cvt_pk_bf16_f32 v85, v90, v91
	v_cvt_pk_bf16_f32 v86, v92, v93
	v_cvt_pk_bf16_f32 v87, v94, v95
	s_lshl_b32 s99, s98, 11
	v_lshl_add_u32 v8, v0, 3, s99
	global_store_dwordx2 v8, v[80:81], s[94:95]
	global_store_dwordx2 v8, v[82:83], s[94:95] offset:512
	global_store_dwordx2 v8, v[84:85], s[94:95] offset:1024
	global_store_dwordx2 v8, v[86:87], s[94:95] offset:1536
	s_lshl_b32 s99, s98, 2
	v_mov_b32_e32 v9, s99
	v_mov_b32_e32 v10, 0
	v_cmp_eq_u32_e32 vcc, 0, v0
	s_and_saveexec_b64 s[98:99], vcc
	global_store_dword v9, v10, s[90:91]
	global_store_dword v9, v10, s[92:93]
	s_or_b64 exec, exec, s[98:99]
	s_waitcnt vmcnt(46)
	v_mul_f32_e32 v4, v96, v96
	v_fma_f32 v4, v97, v97, v4
	v_fma_f32 v4, v98, v98, v4
	v_fma_f32 v4, v99, v99, v4
	v_fma_f32 v4, v100, v100, v4
	v_fma_f32 v4, v101, v101, v4
	v_fma_f32 v4, v102, v102, v4
	v_fma_f32 v4, v103, v103, v4
	v_fma_f32 v4, v104, v104, v4
	v_fma_f32 v4, v105, v105, v4
	v_fma_f32 v4, v106, v106, v4
	v_fma_f32 v4, v107, v107, v4
	v_fma_f32 v4, v108, v108, v4
	v_fma_f32 v4, v109, v109, v4
	v_fma_f32 v4, v110, v110, v4
	v_fma_f32 v4, v111, v111, v4
	s_nop 1
	v_add_f32_dpp v5, v4, v4 quad_perm:[1,0,3,2] row_mask:0xf bank_mask:0xf
	s_nop 1
	v_add_f32_dpp v4, v5, v5 quad_perm:[2,3,0,1] row_mask:0xf bank_mask:0xf
	s_nop 1
	v_add_f32_dpp v5, v4, v4 row_half_mirror row_mask:0xf bank_mask:0xf
	s_nop 1
	v_add_f32_dpp v4, v5, v5 row_mirror row_mask:0xf bank_mask:0xf
	s_nop 1
	v_readlane_b32 s98, v4, 0
	v_readlane_b32 s99, v4, 16
	s_nop 3
	v_mov_b32_e32 v5, s98
	v_add_f32_e32 v5, s99, v5
	v_readlane_b32 s98, v4, 32
	v_readlane_b32 s99, v4, 48
	s_nop 3
	v_add_f32_e32 v5, s98, v5
	v_add_f32_e32 v5, s99, v5
	v_mul_f32_e32 v5, 0x3a800000, v5
	v_add_f32_e32 v5, 0x358637bd, v5
	v_rsq_f32_e32 v6, v5
	s_nop 0
	s_add_u32 s98, s97, 11
	v_pk_mul_f32 v[96:97], v[96:97], v[6:7] op_sel_hi:[1,0]
	v_pk_mul_f32 v[98:99], v[98:99], v[6:7] op_sel_hi:[1,0]
	v_pk_mul_f32 v[100:101], v[100:101], v[6:7] op_sel_hi:[1,0]
	v_pk_mul_f32 v[102:103], v[102:103], v[6:7] op_sel_hi:[1,0]
	v_pk_mul_f32 v[104:105], v[104:105], v[6:7] op_sel_hi:[1,0]
	v_pk_mul_f32 v[106:107], v[106:107], v[6:7] op_sel_hi:[1,0]
	v_pk_mul_f32 v[108:109], v[108:109], v[6:7] op_sel_hi:[1,0]
	v_pk_mul_f32 v[110:111], v[110:111], v[6:7] op_sel_hi:[1,0]
	v_pk_mul_f32 v[96:97], v[96:97], v[112:113]
	v_pk_mul_f32 v[98:99], v[98:99], v[114:115]
	v_pk_mul_f32 v[100:101], v[100:101], v[116:117]
	v_pk_mul_f32 v[102:103], v[102:103], v[118:119]
	v_pk_mul_f32 v[104:105], v[104:105], v[120:121]
	v_pk_mul_f32 v[106:107], v[106:107], v[122:123]
	v_pk_mul_f32 v[108:109], v[108:109], v[124:125]
	v_pk_mul_f32 v[110:111], v[110:111], v[126:127]
	v_pk_fma_f32 v[96:97], v[96:97], v[128:129], v[144:145]
	v_pk_fma_f32 v[98:99], v[98:99], v[130:131], v[146:147]
	v_pk_fma_f32 v[100:101], v[100:101], v[132:133], v[148:149]
	v_pk_fma_f32 v[102:103], v[102:103], v[134:135], v[150:151]
	v_pk_fma_f32 v[104:105], v[104:105], v[136:137], v[152:153]
	v_pk_fma_f32 v[106:107], v[106:107], v[138:139], v[154:155]
	v_pk_fma_f32 v[108:109], v[108:109], v[140:141], v[156:157]
	v_pk_fma_f32 v[110:111], v[110:111], v[142:143], v[158:159]
	v_cvt_pk_bf16_f32 v96, v96, v97
	v_cvt_pk_bf16_f32 v97, v98, v99
	v_cvt_pk_bf16_f32 v98, v100, v101
	v_cvt_pk_bf16_f32 v99, v102, v103
	v_cvt_pk_bf16_f32 v100, v104, v105
	v_cvt_pk_bf16_f32 v101, v106, v107
	v_cvt_pk_bf16_f32 v102, v108, v109
	v_cvt_pk_bf16_f32 v103, v110, v111
	s_lshl_b32 s99, s98, 11
	v_lshl_add_u32 v8, v0, 3, s99
	global_store_dwordx2 v8, v[96:97], s[94:95]
	global_store_dwordx2 v8, v[98:99], s[94:95] offset:512
	global_store_dwordx2 v8, v[100:101], s[94:95] offset:1024
	global_store_dwordx2 v8, v[102:103], s[94:95] offset:1536
	s_lshl_b32 s99, s98, 2
	v_mov_b32_e32 v9, s99
	v_mov_b32_e32 v10, 0
	v_cmp_eq_u32_e32 vcc, 0, v0
	s_and_saveexec_b64 s[98:99], vcc
	global_store_dword v9, v10, s[90:91]
	global_store_dword v9, v10, s[92:93]
	s_or_b64 exec, exec, s[98:99]
	s_waitcnt vmcnt(42)
	v_mul_f32_e32 v4, v16, v16
	v_fma_f32 v4, v17, v17, v4
	v_fma_f32 v4, v18, v18, v4
	v_fma_f32 v4, v19, v19, v4
	v_fma_f32 v4, v20, v20, v4
	v_fma_f32 v4, v21, v21, v4
	v_fma_f32 v4, v22, v22, v4
	v_fma_f32 v4, v23, v23, v4
	v_fma_f32 v4, v24, v24, v4
	v_fma_f32 v4, v25, v25, v4
	v_fma_f32 v4, v26, v26, v4
	v_fma_f32 v4, v27, v27, v4
	v_fma_f32 v4, v28, v28, v4
	v_fma_f32 v4, v29, v29, v4
	v_fma_f32 v4, v30, v30, v4
	v_fma_f32 v4, v31, v31, v4
	s_nop 1
	v_add_f32_dpp v5, v4, v4 quad_perm:[1,0,3,2] row_mask:0xf bank_mask:0xf
	s_nop 1
	v_add_f32_dpp v4, v5, v5 quad_perm:[2,3,0,1] row_mask:0xf bank_mask:0xf
	s_nop 1
	v_add_f32_dpp v5, v4, v4 row_half_mirror row_mask:0xf bank_mask:0xf
	s_nop 1
	v_add_f32_dpp v4, v5, v5 row_mirror row_mask:0xf bank_mask:0xf
	s_nop 1
	v_readlane_b32 s98, v4, 0
	v_readlane_b32 s99, v4, 16
	s_nop 3
	v_mov_b32_e32 v5, s98
	v_add_f32_e32 v5, s99, v5
	v_readlane_b32 s98, v4, 32
	v_readlane_b32 s99, v4, 48
	s_nop 3
	v_add_f32_e32 v5, s98, v5
	v_add_f32_e32 v5, s99, v5
	v_mul_f32_e32 v5, 0x3a800000, v5
	v_add_f32_e32 v5, 0x358637bd, v5
	v_rsq_f32_e32 v6, v5
	s_nop 0
	s_add_u32 s98, s97, 12
	v_pk_mul_f32 v[16:17], v[16:17], v[6:7] op_sel_hi:[1,0]
	v_pk_mul_f32 v[18:19], v[18:19], v[6:7] op_sel_hi:[1,0]
	v_pk_mul_f32 v[20:21], v[20:21], v[6:7] op_sel_hi:[1,0]
	v_pk_mul_f32 v[22:23], v[22:23], v[6:7] op_sel_hi:[1,0]
	v_pk_mul_f32 v[24:25], v[24:25], v[6:7] op_sel_hi:[1,0]
	v_pk_mul_f32 v[26:27], v[26:27], v[6:7] op_sel_hi:[1,0]
	v_pk_mul_f32 v[28:29], v[28:29], v[6:7] op_sel_hi:[1,0]
	v_pk_mul_f32 v[30:31], v[30:31], v[6:7] op_sel_hi:[1,0]
	v_pk_mul_f32 v[16:17], v[16:17], v[112:113]
	v_pk_mul_f32 v[18:19], v[18:19], v[114:115]
	v_pk_mul_f32 v[20:21], v[20:21], v[116:117]
	v_pk_mul_f32 v[22:23], v[22:23], v[118:119]
	v_pk_mul_f32 v[24:25], v[24:25], v[120:121]
	v_pk_mul_f32 v[26:27], v[26:27], v[122:123]
	v_pk_mul_f32 v[28:29], v[28:29], v[124:125]
	v_pk_mul_f32 v[30:31], v[30:31], v[126:127]
	v_pk_fma_f32 v[16:17], v[16:17], v[128:129], v[144:145]
	v_pk_fma_f32 v[18:19], v[18:19], v[130:131], v[146:147]
	v_pk_fma_f32 v[20:21], v[20:21], v[132:133], v[148:149]
	v_pk_fma_f32 v[22:23], v[22:23], v[134:135], v[150:151]
	v_pk_fma_f32 v[24:25], v[24:25], v[136:137], v[152:153]
	v_pk_fma_f32 v[26:27], v[26:27], v[138:139], v[154:155]
	v_pk_fma_f32 v[28:29], v[28:29], v[140:141], v[156:157]
	v_pk_fma_f32 v[30:31], v[30:31], v[142:143], v[158:159]
	v_cvt_pk_bf16_f32 v16, v16, v17
	v_cvt_pk_bf16_f32 v17, v18, v19
	v_cvt_pk_bf16_f32 v18, v20, v21
	v_cvt_pk_bf16_f32 v19, v22, v23
	v_cvt_pk_bf16_f32 v20, v24, v25
	v_cvt_pk_bf16_f32 v21, v26, v27
	v_cvt_pk_bf16_f32 v22, v28, v29
	v_cvt_pk_bf16_f32 v23, v30, v31
	s_lshl_b32 s99, s98, 11
	v_lshl_add_u32 v8, v0, 3, s99
	global_store_dwordx2 v8, v[16:17], s[94:95]
	global_store_dwordx2 v8, v[18:19], s[94:95] offset:512
	global_store_dwordx2 v8, v[20:21], s[94:95] offset:1024
	global_store_dwordx2 v8, v[22:23], s[94:95] offset:1536
	s_lshl_b32 s99, s98, 2
	v_mov_b32_e32 v9, s99
	v_mov_b32_e32 v10, 0
	v_cmp_eq_u32_e32 vcc, 0, v0
	s_and_saveexec_b64 s[98:99], vcc
	global_store_dword v9, v10, s[90:91]
	global_store_dword v9, v10, s[92:93]
	s_or_b64 exec, exec, s[98:99]
	s_waitcnt vmcnt(38)
	v_mul_f32_e32 v4, v32, v32
	v_fma_f32 v4, v33, v33, v4
	v_fma_f32 v4, v34, v34, v4
	v_fma_f32 v4, v35, v35, v4
	v_fma_f32 v4, v36, v36, v4
	v_fma_f32 v4, v37, v37, v4
	v_fma_f32 v4, v38, v38, v4
	v_fma_f32 v4, v39, v39, v4
	v_fma_f32 v4, v40, v40, v4
	v_fma_f32 v4, v41, v41, v4
	v_fma_f32 v4, v42, v42, v4
	v_fma_f32 v4, v43, v43, v4
	v_fma_f32 v4, v44, v44, v4
	v_fma_f32 v4, v45, v45, v4
	v_fma_f32 v4, v46, v46, v4
	v_fma_f32 v4, v47, v47, v4
	s_nop 1
	v_add_f32_dpp v5, v4, v4 quad_perm:[1,0,3,2] row_mask:0xf bank_mask:0xf
	s_nop 1
	v_add_f32_dpp v4, v5, v5 quad_perm:[2,3,0,1] row_mask:0xf bank_mask:0xf
	s_nop 1
	v_add_f32_dpp v5, v4, v4 row_half_mirror row_mask:0xf bank_mask:0xf
	s_nop 1
	v_add_f32_dpp v4, v5, v5 row_mirror row_mask:0xf bank_mask:0xf
	s_nop 1
	v_readlane_b32 s98, v4, 0
	v_readlane_b32 s99, v4, 16
	s_nop 3
	v_mov_b32_e32 v5, s98
	v_add_f32_e32 v5, s99, v5
	v_readlane_b32 s98, v4, 32
	v_readlane_b32 s99, v4, 48
	s_nop 3
	v_add_f32_e32 v5, s98, v5
	v_add_f32_e32 v5, s99, v5
	v_mul_f32_e32 v5, 0x3a800000, v5
	v_add_f32_e32 v5, 0x358637bd, v5
	v_rsq_f32_e32 v6, v5
	s_nop 0
	s_add_u32 s98, s97, 13
	v_pk_mul_f32 v[32:33], v[32:33], v[6:7] op_sel_hi:[1,0]
	v_pk_mul_f32 v[34:35], v[34:35], v[6:7] op_sel_hi:[1,0]
	v_pk_mul_f32 v[36:37], v[36:37], v[6:7] op_sel_hi:[1,0]
	v_pk_mul_f32 v[38:39], v[38:39], v[6:7] op_sel_hi:[1,0]
	v_pk_mul_f32 v[40:41], v[40:41], v[6:7] op_sel_hi:[1,0]
	v_pk_mul_f32 v[42:43], v[42:43], v[6:7] op_sel_hi:[1,0]
	v_pk_mul_f32 v[44:45], v[44:45], v[6:7] op_sel_hi:[1,0]
	v_pk_mul_f32 v[46:47], v[46:47], v[6:7] op_sel_hi:[1,0]
	v_pk_mul_f32 v[32:33], v[32:33], v[112:113]
	v_pk_mul_f32 v[34:35], v[34:35], v[114:115]
	v_pk_mul_f32 v[36:37], v[36:37], v[116:117]
	v_pk_mul_f32 v[38:39], v[38:39], v[118:119]
	v_pk_mul_f32 v[40:41], v[40:41], v[120:121]
	v_pk_mul_f32 v[42:43], v[42:43], v[122:123]
	v_pk_mul_f32 v[44:45], v[44:45], v[124:125]
	v_pk_mul_f32 v[46:47], v[46:47], v[126:127]
	v_pk_fma_f32 v[32:33], v[32:33], v[128:129], v[144:145]
	v_pk_fma_f32 v[34:35], v[34:35], v[130:131], v[146:147]
	v_pk_fma_f32 v[36:37], v[36:37], v[132:133], v[148:149]
	v_pk_fma_f32 v[38:39], v[38:39], v[134:135], v[150:151]
	v_pk_fma_f32 v[40:41], v[40:41], v[136:137], v[152:153]
	v_pk_fma_f32 v[42:43], v[42:43], v[138:139], v[154:155]
	v_pk_fma_f32 v[44:45], v[44:45], v[140:141], v[156:157]
	v_pk_fma_f32 v[46:47], v[46:47], v[142:143], v[158:159]
	v_cvt_pk_bf16_f32 v32, v32, v33
	v_cvt_pk_bf16_f32 v33, v34, v35
	v_cvt_pk_bf16_f32 v34, v36, v37
	v_cvt_pk_bf16_f32 v35, v38, v39
	v_cvt_pk_bf16_f32 v36, v40, v41
	v_cvt_pk_bf16_f32 v37, v42, v43
	v_cvt_pk_bf16_f32 v38, v44, v45
	v_cvt_pk_bf16_f32 v39, v46, v47
	s_lshl_b32 s99, s98, 11
	v_lshl_add_u32 v8, v0, 3, s99
	global_store_dwordx2 v8, v[32:33], s[94:95]
	global_store_dwordx2 v8, v[34:35], s[94:95] offset:512
	global_store_dwordx2 v8, v[36:37], s[94:95] offset:1024
	global_store_dwordx2 v8, v[38:39], s[94:95] offset:1536
	s_lshl_b32 s99, s98, 2
	v_mov_b32_e32 v9, s99
	v_mov_b32_e32 v10, 0
	v_cmp_eq_u32_e32 vcc, 0, v0
	s_and_saveexec_b64 s[98:99], vcc
	global_store_dword v9, v10, s[90:91]
	global_store_dword v9, v10, s[92:93]
	s_or_b64 exec, exec, s[98:99]
	s_waitcnt vmcnt(34)
	v_mul_f32_e32 v4, v48, v48
	v_fma_f32 v4, v49, v49, v4
	v_fma_f32 v4, v50, v50, v4
	v_fma_f32 v4, v51, v51, v4
	v_fma_f32 v4, v52, v52, v4
	v_fma_f32 v4, v53, v53, v4
	v_fma_f32 v4, v54, v54, v4
	v_fma_f32 v4, v55, v55, v4
	v_fma_f32 v4, v56, v56, v4
	v_fma_f32 v4, v57, v57, v4
	v_fma_f32 v4, v58, v58, v4
	v_fma_f32 v4, v59, v59, v4
	v_fma_f32 v4, v60, v60, v4
	v_fma_f32 v4, v61, v61, v4
	v_fma_f32 v4, v62, v62, v4
	v_fma_f32 v4, v63, v63, v4
	s_nop 1
	v_add_f32_dpp v5, v4, v4 quad_perm:[1,0,3,2] row_mask:0xf bank_mask:0xf
	s_nop 1
	v_add_f32_dpp v4, v5, v5 quad_perm:[2,3,0,1] row_mask:0xf bank_mask:0xf
	s_nop 1
	v_add_f32_dpp v5, v4, v4 row_half_mirror row_mask:0xf bank_mask:0xf
	s_nop 1
	v_add_f32_dpp v4, v5, v5 row_mirror row_mask:0xf bank_mask:0xf
	s_nop 1
	v_readlane_b32 s98, v4, 0
	v_readlane_b32 s99, v4, 16
	s_nop 3
	v_mov_b32_e32 v5, s98
	v_add_f32_e32 v5, s99, v5
	v_readlane_b32 s98, v4, 32
	v_readlane_b32 s99, v4, 48
	s_nop 3
	v_add_f32_e32 v5, s98, v5
	v_add_f32_e32 v5, s99, v5
	v_mul_f32_e32 v5, 0x3a800000, v5
	v_add_f32_e32 v5, 0x358637bd, v5
	v_rsq_f32_e32 v6, v5
	s_nop 0
	s_add_u32 s98, s97, 14
	v_pk_mul_f32 v[48:49], v[48:49], v[6:7] op_sel_hi:[1,0]
	v_pk_mul_f32 v[50:51], v[50:51], v[6:7] op_sel_hi:[1,0]
	v_pk_mul_f32 v[52:53], v[52:53], v[6:7] op_sel_hi:[1,0]
	v_pk_mul_f32 v[54:55], v[54:55], v[6:7] op_sel_hi:[1,0]
	v_pk_mul_f32 v[56:57], v[56:57], v[6:7] op_sel_hi:[1,0]
	v_pk_mul_f32 v[58:59], v[58:59], v[6:7] op_sel_hi:[1,0]
	v_pk_mul_f32 v[60:61], v[60:61], v[6:7] op_sel_hi:[1,0]
	v_pk_mul_f32 v[62:63], v[62:63], v[6:7] op_sel_hi:[1,0]
	v_pk_mul_f32 v[48:49], v[48:49], v[112:113]
	v_pk_mul_f32 v[50:51], v[50:51], v[114:115]
	v_pk_mul_f32 v[52:53], v[52:53], v[116:117]
	v_pk_mul_f32 v[54:55], v[54:55], v[118:119]
	v_pk_mul_f32 v[56:57], v[56:57], v[120:121]
	v_pk_mul_f32 v[58:59], v[58:59], v[122:123]
	v_pk_mul_f32 v[60:61], v[60:61], v[124:125]
	v_pk_mul_f32 v[62:63], v[62:63], v[126:127]
	v_pk_fma_f32 v[48:49], v[48:49], v[128:129], v[144:145]
	v_pk_fma_f32 v[50:51], v[50:51], v[130:131], v[146:147]
	v_pk_fma_f32 v[52:53], v[52:53], v[132:133], v[148:149]
	v_pk_fma_f32 v[54:55], v[54:55], v[134:135], v[150:151]
	v_pk_fma_f32 v[56:57], v[56:57], v[136:137], v[152:153]
	v_pk_fma_f32 v[58:59], v[58:59], v[138:139], v[154:155]
	v_pk_fma_f32 v[60:61], v[60:61], v[140:141], v[156:157]
	v_pk_fma_f32 v[62:63], v[62:63], v[142:143], v[158:159]
	v_cvt_pk_bf16_f32 v48, v48, v49
	v_cvt_pk_bf16_f32 v49, v50, v51
	v_cvt_pk_bf16_f32 v50, v52, v53
	v_cvt_pk_bf16_f32 v51, v54, v55
	v_cvt_pk_bf16_f32 v52, v56, v57
	v_cvt_pk_bf16_f32 v53, v58, v59
	v_cvt_pk_bf16_f32 v54, v60, v61
	v_cvt_pk_bf16_f32 v55, v62, v63
	s_lshl_b32 s99, s98, 11
	v_lshl_add_u32 v8, v0, 3, s99
	global_store_dwordx2 v8, v[48:49], s[94:95]
	global_store_dwordx2 v8, v[50:51], s[94:95] offset:512
	global_store_dwordx2 v8, v[52:53], s[94:95] offset:1024
	global_store_dwordx2 v8, v[54:55], s[94:95] offset:1536
	s_lshl_b32 s99, s98, 2
	v_mov_b32_e32 v9, s99
	v_mov_b32_e32 v10, 0
	v_cmp_eq_u32_e32 vcc, 0, v0
	s_and_saveexec_b64 s[98:99], vcc
	global_store_dword v9, v10, s[90:91]
	global_store_dword v9, v10, s[92:93]
	s_or_b64 exec, exec, s[98:99]
	s_waitcnt vmcnt(30)
	v_mul_f32_e32 v4, v64, v64
	v_fma_f32 v4, v65, v65, v4
	v_fma_f32 v4, v66, v66, v4
	v_fma_f32 v4, v67, v67, v4
	v_fma_f32 v4, v68, v68, v4
	v_fma_f32 v4, v69, v69, v4
	v_fma_f32 v4, v70, v70, v4
	v_fma_f32 v4, v71, v71, v4
	v_fma_f32 v4, v72, v72, v4
	v_fma_f32 v4, v73, v73, v4
	v_fma_f32 v4, v74, v74, v4
	v_fma_f32 v4, v75, v75, v4
	v_fma_f32 v4, v76, v76, v4
	v_fma_f32 v4, v77, v77, v4
	v_fma_f32 v4, v78, v78, v4
	v_fma_f32 v4, v79, v79, v4
	s_nop 1
	v_add_f32_dpp v5, v4, v4 quad_perm:[1,0,3,2] row_mask:0xf bank_mask:0xf
	s_nop 1
	v_add_f32_dpp v4, v5, v5 quad_perm:[2,3,0,1] row_mask:0xf bank_mask:0xf
	s_nop 1
	v_add_f32_dpp v5, v4, v4 row_half_mirror row_mask:0xf bank_mask:0xf
	s_nop 1
	v_add_f32_dpp v4, v5, v5 row_mirror row_mask:0xf bank_mask:0xf
	s_nop 1
	v_readlane_b32 s98, v4, 0
	v_readlane_b32 s99, v4, 16
	s_nop 3
	v_mov_b32_e32 v5, s98
	v_add_f32_e32 v5, s99, v5
	v_readlane_b32 s98, v4, 32
	v_readlane_b32 s99, v4, 48
	s_nop 3
	v_add_f32_e32 v5, s98, v5
	v_add_f32_e32 v5, s99, v5
	v_mul_f32_e32 v5, 0x3a800000, v5
	v_add_f32_e32 v5, 0x358637bd, v5
	v_rsq_f32_e32 v6, v5
	s_nop 0
	s_add_u32 s98, s97, 15
	v_pk_mul_f32 v[64:65], v[64:65], v[6:7] op_sel_hi:[1,0]
	v_pk_mul_f32 v[66:67], v[66:67], v[6:7] op_sel_hi:[1,0]
	v_pk_mul_f32 v[68:69], v[68:69], v[6:7] op_sel_hi:[1,0]
	v_pk_mul_f32 v[70:71], v[70:71], v[6:7] op_sel_hi:[1,0]
	v_pk_mul_f32 v[72:73], v[72:73], v[6:7] op_sel_hi:[1,0]
	v_pk_mul_f32 v[74:75], v[74:75], v[6:7] op_sel_hi:[1,0]
	v_pk_mul_f32 v[76:77], v[76:77], v[6:7] op_sel_hi:[1,0]
	v_pk_mul_f32 v[78:79], v[78:79], v[6:7] op_sel_hi:[1,0]
	v_pk_mul_f32 v[64:65], v[64:65], v[112:113]
	v_pk_mul_f32 v[66:67], v[66:67], v[114:115]
	v_pk_mul_f32 v[68:69], v[68:69], v[116:117]
	v_pk_mul_f32 v[70:71], v[70:71], v[118:119]
	v_pk_mul_f32 v[72:73], v[72:73], v[120:121]
	v_pk_mul_f32 v[74:75], v[74:75], v[122:123]
	v_pk_mul_f32 v[76:77], v[76:77], v[124:125]
	v_pk_mul_f32 v[78:79], v[78:79], v[126:127]
	v_pk_fma_f32 v[64:65], v[64:65], v[128:129], v[144:145]
	v_pk_fma_f32 v[66:67], v[66:67], v[130:131], v[146:147]
	v_pk_fma_f32 v[68:69], v[68:69], v[132:133], v[148:149]
	v_pk_fma_f32 v[70:71], v[70:71], v[134:135], v[150:151]
	v_pk_fma_f32 v[72:73], v[72:73], v[136:137], v[152:153]
	v_pk_fma_f32 v[74:75], v[74:75], v[138:139], v[154:155]
	v_pk_fma_f32 v[76:77], v[76:77], v[140:141], v[156:157]
	v_pk_fma_f32 v[78:79], v[78:79], v[142:143], v[158:159]
	v_cvt_pk_bf16_f32 v64, v64, v65
	v_cvt_pk_bf16_f32 v65, v66, v67
	v_cvt_pk_bf16_f32 v66, v68, v69
	v_cvt_pk_bf16_f32 v67, v70, v71
	v_cvt_pk_bf16_f32 v68, v72, v73
	v_cvt_pk_bf16_f32 v69, v74, v75
	v_cvt_pk_bf16_f32 v70, v76, v77
	v_cvt_pk_bf16_f32 v71, v78, v79
	s_lshl_b32 s99, s98, 11
	v_lshl_add_u32 v8, v0, 3, s99
	global_store_dwordx2 v8, v[64:65], s[94:95]
	global_store_dwordx2 v8, v[66:67], s[94:95] offset:512
	global_store_dwordx2 v8, v[68:69], s[94:95] offset:1024
	global_store_dwordx2 v8, v[70:71], s[94:95] offset:1536
	s_lshl_b32 s99, s98, 2
	v_mov_b32_e32 v9, s99
	v_mov_b32_e32 v10, 0
	v_cmp_eq_u32_e32 vcc, 0, v0
	s_and_saveexec_b64 s[98:99], vcc
	global_store_dword v9, v10, s[90:91]
	global_store_dword v9, v10, s[92:93]
	s_or_b64 exec, exec, s[98:99]
	s_waitcnt vmcnt(0)

.LBB0_4600:
	s_cmp_gt_i32 s44, 17
	s_cselect_b64 s[2:3], -1, 0
	s_cmp_lt_i32 s45, 18
	s_cselect_b64 s[4:5], -1, 0
	s_or_b64 s[2:3], s[2:3], s[4:5]
	s_and_b64 vcc, exec, s[2:3]
	s_cbranch_vccnz .LBB0_4660
	s_lshl_b32 s96, s22, 3
	s_lshr_b32 s97, s70, 6
	s_add_u32 s96, s96, s97
	s_lshl_b32 s97, s96, 4
	s_cmpk_ge_u32 s97, 0x8000
	s_cbranch_scc1 .Lnp17_done
	s_load_dwordx2 s[88:89], s[0:1], 0xb8
	s_load_dwordx2 s[90:91], s[0:1], 0x18
	s_load_dwordx2 s[92:93], s[0:1], 0x140
	s_load_dwordx2 s[94:95], s[0:1], 0x158
	v_mbcnt_hi_u32_b32 v0, -1, v210
	v_lshlrev_b32_e32 v1, 4, v0
	s_waitcnt lgkmcnt(0)
	s_add_u32 s90, s90, 12288
	s_addc_u32 s91, s91, 0
	global_load_dwordx4 v[112:115], v1, s[90:91] nt
	global_load_dwordx4 v[116:119], v1, s[90:91] offset:1024 nt
	global_load_dwordx4 v[120:123], v1, s[90:91] offset:2048 nt
	global_load_dwordx4 v[124:127], v1, s[90:91] offset:3072 nt
	s_lshr_b32 s98, s97, 12
	s_add_u32 s98, s98, 24
	s_mul_i32 s98, s98, 0x3000
	s_add_u32 s92, s92, s98
	s_addc_u32 s93, s93, 0
	global_load_dwordx4 v[144:147], v1, s[92:93] nt
	global_load_dwordx4 v[148:151], v1, s[92:93] offset:1024 nt
	global_load_dwordx4 v[152:155], v1, s[92:93] offset:2048 nt
	global_load_dwordx4 v[156:159], v1, s[92:93] offset:3072 nt
	s_add_u32 s92, s92, 0x1000
	s_addc_u32 s93, s93, 0
	global_load_dwordx4 v[128:131], v1, s[92:93] nt
	global_load_dwordx4 v[132:135], v1, s[92:93] offset:1024 nt
	global_load_dwordx4 v[136:139], v1, s[92:93] offset:2048 nt
	global_load_dwordx4 v[140:143], v1, s[92:93] offset:3072 nt
	s_load_dwordx2 s[90:91], s[0:1], 0x210
	s_load_dwordx2 s[92:93], s[0:1], 0x218
	s_add_u32 s98, s97, 0
	s_lshl_b32 s98, s98, 12
	v_add_u32_e32 v3, s98, v1
	global_load_dwordx4 v[16:19], v3, s[88:89] nt
	global_load_dwordx4 v[20:23], v3, s[88:89] offset:1024 nt
	global_load_dwordx4 v[24:27], v3, s[88:89] offset:2048 nt
	global_load_dwordx4 v[28:31], v3, s[88:89] offset:3072 nt
	s_add_u32 s98, s97, 1
	s_lshl_b32 s98, s98, 12
	v_add_u32_e32 v3, s98, v1
	global_load_dwordx4 v[32:35], v3, s[88:89] nt
	global_load_dwordx4 v[36:39], v3, s[88:89] offset:1024 nt
	global_load_dwordx4 v[40:43], v3, s[88:89] offset:2048 nt
	global_load_dwordx4 v[44:47], v3, s[88:89] offset:3072 nt
	s_add_u32 s98, s97, 2
	s_lshl_b32 s98, s98, 12
	v_add_u32_e32 v3, s98, v1
	global_load_dwordx4 v[48:51], v3, s[88:89] nt
	global_load_dwordx4 v[52:55], v3, s[88:89] offset:1024 nt
	global_load_dwordx4 v[56:59], v3, s[88:89] offset:2048 nt
	global_load_dwordx4 v[60:63], v3, s[88:89] offset:3072 nt
	s_add_u32 s98, s97, 3
	s_lshl_b32 s98, s98, 12
	v_add_u32_e32 v3, s98, v1
	global_load_dwordx4 v[64:67], v3, s[88:89] nt
	global_load_dwordx4 v[68:71], v3, s[88:89] offset:1024 nt
	global_load_dwordx4 v[72:75], v3, s[88:89] offset:2048 nt
	global_load_dwordx4 v[76:79], v3, s[88:89] offset:3072 nt
	s_add_u32 s98, s97, 4
	s_lshl_b32 s98, s98, 12
	v_add_u32_e32 v3, s98, v1
	global_load_dwordx4 v[80:83], v3, s[88:89] nt
	global_load_dwordx4 v[84:87], v3, s[88:89] offset:1024 nt
	global_load_dwordx4 v[88:91], v3, s[88:89] offset:2048 nt
	global_load_dwordx4 v[92:95], v3, s[88:89] offset:3072 nt
	s_waitcnt vmcnt(0) lgkmcnt(0)
	v_pk_add_f32 v[128:129], v[128:129], 1.0 op_sel_hi:[1,0]
	v_pk_add_f32 v[130:131], v[130:131], 1.0 op_sel_hi:[1,0]
	v_pk_add_f32 v[132:133], v[132:133], 1.0 op_sel_hi:[1,0]
	v_pk_add_f32 v[134:135], v[134:135], 1.0 op_sel_hi:[1,0]
	v_pk_add_f32 v[136:137], v[136:137], 1.0 op_sel_hi:[1,0]
	v_pk_add_f32 v[138:139], v[138:139], 1.0 op_sel_hi:[1,0]
	v_pk_add_f32 v[140:141], v[140:141], 1.0 op_sel_hi:[1,0]
	v_pk_add_f32 v[142:143], v[142:143], 1.0 op_sel_hi:[1,0]
	s_add_u32 s98, s97, 5
	s_lshl_b32 s98, s98, 12
	v_add_u32_e32 v3, s98, v1
	global_load_dwordx4 v[96:99], v3, s[88:89] nt
	global_load_dwordx4 v[100:103], v3, s[88:89] offset:1024 nt
	global_load_dwordx4 v[104:107], v3, s[88:89] offset:2048 nt
	global_load_dwordx4 v[108:111], v3, s[88:89] offset:3072 nt
	s_waitcnt vmcnt(20)
	v_mul_f32_e32 v4, v16, v16
	v_fma_f32 v4, v17, v17, v4
	v_fma_f32 v4, v18, v18, v4
	v_fma_f32 v4, v19, v19, v4
	v_fma_f32 v4, v20, v20, v4
	v_fma_f32 v4, v21, v21, v4
	v_fma_f32 v4, v22, v22, v4
	v_fma_f32 v4, v23, v23, v4
	v_fma_f32 v4, v24, v24, v4
	v_fma_f32 v4, v25, v25, v4
	v_fma_f32 v4, v26, v26, v4
	v_fma_f32 v4, v27, v27, v4
	v_fma_f32 v4, v28, v28, v4
	v_fma_f32 v4, v29, v29, v4
	v_fma_f32 v4, v30, v30, v4
	v_fma_f32 v4, v31, v31, v4
	s_nop 1
	v_add_f32_dpp v5, v4, v4 quad_perm:[1,0,3,2] row_mask:0xf bank_mask:0xf
	s_nop 1
	v_add_f32_dpp v4, v5, v5 quad_perm:[2,3,0,1] row_mask:0xf bank_mask:0xf
	s_nop 1
	v_add_f32_dpp v5, v4, v4 row_half_mirror row_mask:0xf bank_mask:0xf
	s_nop 1
	v_add_f32_dpp v4, v5, v5 row_mirror row_mask:0xf bank_mask:0xf
	s_nop 1
	v_readlane_b32 s98, v4, 0
	v_readlane_b32 s99, v4, 16
	s_nop 3
	v_mov_b32_e32 v5, s98
	v_add_f32_e32 v5, s99, v5
	v_readlane_b32 s98, v4, 32
	v_readlane_b32 s99, v4, 48
	s_nop 3
	v_add_f32_e32 v5, s98, v5
	v_add_f32_e32 v5, s99, v5
	v_mul_f32_e32 v5, 0x3a800000, v5
	v_add_f32_e32 v5, 0x358637bd, v5
	v_rsq_f32_e32 v6, v5
	s_nop 0
	s_add_u32 s98, s97, 0
	v_pk_mul_f32 v[16:17], v[16:17], v[6:7] op_sel_hi:[1,0]
	v_pk_mul_f32 v[18:19], v[18:19], v[6:7] op_sel_hi:[1,0]
	v_pk_mul_f32 v[20:21], v[20:21], v[6:7] op_sel_hi:[1,0]
	v_pk_mul_f32 v[22:23], v[22:23], v[6:7] op_sel_hi:[1,0]
	v_pk_mul_f32 v[24:25], v[24:25], v[6:7] op_sel_hi:[1,0]
	v_pk_mul_f32 v[26:27], v[26:27], v[6:7] op_sel_hi:[1,0]
	v_pk_mul_f32 v[28:29], v[28:29], v[6:7] op_sel_hi:[1,0]
	v_pk_mul_f32 v[30:31], v[30:31], v[6:7] op_sel_hi:[1,0]
	v_pk_mul_f32 v[16:17], v[16:17], v[112:113]
	v_pk_mul_f32 v[18:19], v[18:19], v[114:115]
	v_pk_mul_f32 v[20:21], v[20:21], v[116:117]
	v_pk_mul_f32 v[22:23], v[22:23], v[118:119]
	v_pk_mul_f32 v[24:25], v[24:25], v[120:121]
	v_pk_mul_f32 v[26:27], v[26:27], v[122:123]
	v_pk_mul_f32 v[28:29], v[28:29], v[124:125]
	v_pk_mul_f32 v[30:31], v[30:31], v[126:127]
	v_pk_fma_f32 v[16:17], v[16:17], v[128:129], v[144:145]
	v_pk_fma_f32 v[18:19], v[18:19], v[130:131], v[146:147]
	v_pk_fma_f32 v[20:21], v[20:21], v[132:133], v[148:149]
	v_pk_fma_f32 v[22:23], v[22:23], v[134:135], v[150:151]
	v_pk_fma_f32 v[24:25], v[24:25], v[136:137], v[152:153]
	v_pk_fma_f32 v[26:27], v[26:27], v[138:139], v[154:155]
	v_pk_fma_f32 v[28:29], v[28:29], v[140:141], v[156:157]
	v_pk_fma_f32 v[30:31], v[30:31], v[142:143], v[158:159]
	v_cvt_pk_bf16_f32 v16, v16, v17
	v_cvt_pk_bf16_f32 v17, v18, v19
	v_cvt_pk_bf16_f32 v18, v20, v21
	v_cvt_pk_bf16_f32 v19, v22, v23
	v_cvt_pk_bf16_f32 v20, v24, v25
	v_cvt_pk_bf16_f32 v21, v26, v27
	v_cvt_pk_bf16_f32 v22, v28, v29
	v_cvt_pk_bf16_f32 v23, v30, v31
	s_lshl_b32 s99, s98, 11
	v_lshl_add_u32 v8, v0, 3, s99
	global_store_dwordx2 v8, v[16:17], s[94:95]
	global_store_dwordx2 v8, v[18:19], s[94:95] offset:512
	global_store_dwordx2 v8, v[20:21], s[94:95] offset:1024
	global_store_dwordx2 v8, v[22:23], s[94:95] offset:1536
	s_lshl_b32 s99, s98, 2
	v_mov_b32_e32 v9, s99
	v_mov_b32_e32 v10, 0
	v_cmp_eq_u32_e32 vcc, 0, v0
	s_and_saveexec_b64 s[98:99], vcc
	global_store_dword v9, v10, s[90:91]
	global_store_dword v9, v10, s[92:93]
	s_or_b64 exec, exec, s[98:99]
	s_add_u32 s98, s97, 6
	s_lshl_b32 s98, s98, 12
	v_add_u32_e32 v3, s98, v1
	global_load_dwordx4 v[16:19], v3, s[88:89] nt
	global_load_dwordx4 v[20:23], v3, s[88:89] offset:1024 nt
	global_load_dwordx4 v[24:27], v3, s[88:89] offset:2048 nt
	global_load_dwordx4 v[28:31], v3, s[88:89] offset:3072 nt
	s_waitcnt vmcnt(26)
	v_mul_f32_e32 v4, v32, v32
	v_fma_f32 v4, v33, v33, v4
	v_fma_f32 v4, v34, v34, v4
	v_fma_f32 v4, v35, v35, v4
	v_fma_f32 v4, v36, v36, v4
	v_fma_f32 v4, v37, v37, v4
	v_fma_f32 v4, v38, v38, v4
	v_fma_f32 v4, v39, v39, v4
	v_fma_f32 v4, v40, v40, v4
	v_fma_f32 v4, v41, v41, v4
	v_fma_f32 v4, v42, v42, v4
	v_fma_f32 v4, v43, v43, v4
	v_fma_f32 v4, v44, v44, v4
	v_fma_f32 v4, v45, v45, v4
	v_fma_f32 v4, v46, v46, v4
	v_fma_f32 v4, v47, v47, v4
	s_nop 1
	v_add_f32_dpp v5, v4, v4 quad_perm:[1,0,3,2] row_mask:0xf bank_mask:0xf
	s_nop 1
	v_add_f32_dpp v4, v5, v5 quad_perm:[2,3,0,1] row_mask:0xf bank_mask:0xf
	s_nop 1
	v_add_f32_dpp v5, v4, v4 row_half_mirror row_mask:0xf bank_mask:0xf
	s_nop 1
	v_add_f32_dpp v4, v5, v5 row_mirror row_mask:0xf bank_mask:0xf
	s_nop 1
	v_readlane_b32 s98, v4, 0
	v_readlane_b32 s99, v4, 16
	s_nop 3
	v_mov_b32_e32 v5, s98
	v_add_f32_e32 v5, s99, v5
	v_readlane_b32 s98, v4, 32
	v_readlane_b32 s99, v4, 48
	s_nop 3
	v_add_f32_e32 v5, s98, v5
	v_add_f32_e32 v5, s99, v5
	v_mul_f32_e32 v5, 0x3a800000, v5
	v_add_f32_e32 v5, 0x358637bd, v5
	v_rsq_f32_e32 v6, v5
	s_nop 0
	s_add_u32 s98, s97, 1
	v_pk_mul_f32 v[32:33], v[32:33], v[6:7] op_sel_hi:[1,0]
	v_pk_mul_f32 v[34:35], v[34:35], v[6:7] op_sel_hi:[1,0]
	v_pk_mul_f32 v[36:37], v[36:37], v[6:7] op_sel_hi:[1,0]
	v_pk_mul_f32 v[38:39], v[38:39], v[6:7] op_sel_hi:[1,0]
	v_pk_mul_f32 v[40:41], v[40:41], v[6:7] op_sel_hi:[1,0]
	v_pk_mul_f32 v[42:43], v[42:43], v[6:7] op_sel_hi:[1,0]
	v_pk_mul_f32 v[44:45], v[44:45], v[6:7] op_sel_hi:[1,0]
	v_pk_mul_f32 v[46:47], v[46:47], v[6:7] op_sel_hi:[1,0]
	v_pk_mul_f32 v[32:33], v[32:33], v[112:113]
	v_pk_mul_f32 v[34:35], v[34:35], v[114:115]
	v_pk_mul_f32 v[36:37], v[36:37], v[116:117]
	v_pk_mul_f32 v[38:39], v[38:39], v[118:119]
	v_pk_mul_f32 v[40:41], v[40:41], v[120:121]
	v_pk_mul_f32 v[42:43], v[42:43], v[122:123]
	v_pk_mul_f32 v[44:45], v[44:45], v[124:125]
	v_pk_mul_f32 v[46:47], v[46:47], v[126:127]
	v_pk_fma_f32 v[32:33], v[32:33], v[128:129], v[144:145]
	v_pk_fma_f32 v[34:35], v[34:35], v[130:131], v[146:147]
	v_pk_fma_f32 v[36:37], v[36:37], v[132:133], v[148:149]
	v_pk_fma_f32 v[38:39], v[38:39], v[134:135], v[150:151]
	v_pk_fma_f32 v[40:41], v[40:41], v[136:137], v[152:153]
	v_pk_fma_f32 v[42:43], v[42:43], v[138:139], v[154:155]
	v_pk_fma_f32 v[44:45], v[44:45], v[140:141], v[156:157]
	v_pk_fma_f32 v[46:47], v[46:47], v[142:143], v[158:159]
	v_cvt_pk_bf16_f32 v32, v32, v33
	v_cvt_pk_bf16_f32 v33, v34, v35
	v_cvt_pk_bf16_f32 v34, v36, v37
	v_cvt_pk_bf16_f32 v35, v38, v39
	v_cvt_pk_bf16_f32 v36, v40, v41
	v_cvt_pk_bf16_f32 v37, v42, v43
	v_cvt_pk_bf16_f32 v38, v44, v45
	v_cvt_pk_bf16_f32 v39, v46, v47
	s_lshl_b32 s99, s98, 11
	v_lshl_add_u32 v8, v0, 3, s99
	global_store_dwordx2 v8, v[32:33], s[94:95]
	global_store_dwordx2 v8, v[34:35], s[94:95] offset:512
	global_store_dwordx2 v8, v[36:37], s[94:95] offset:1024
	global_store_dwordx2 v8, v[38:39], s[94:95] offset:1536
	s_lshl_b32 s99, s98, 2
	v_mov_b32_e32 v9, s99
	v_mov_b32_e32 v10, 0
	v_cmp_eq_u32_e32 vcc, 0, v0
	s_and_saveexec_b64 s[98:99], vcc
	global_store_dword v9, v10, s[90:91]
	global_store_dword v9, v10, s[92:93]
	s_or_b64 exec, exec, s[98:99]
	s_add_u32 s98, s97, 7
	s_lshl_b32 s98, s98, 12
	v_add_u32_e32 v3, s98, v1
	global_load_dwordx4 v[32:35], v3, s[88:89] nt
	global_load_dwordx4 v[36:39], v3, s[88:89] offset:1024 nt
	global_load_dwordx4 v[40:43], v3, s[88:89] offset:2048 nt
	global_load_dwordx4 v[44:47], v3, s[88:89] offset:3072 nt
	s_waitcnt vmcnt(32)
	v_mul_f32_e32 v4, v48, v48
	v_fma_f32 v4, v49, v49, v4
	v_fma_f32 v4, v50, v50, v4
	v_fma_f32 v4, v51, v51, v4
	v_fma_f32 v4, v52, v52, v4
	v_fma_f32 v4, v53, v53, v4
	v_fma_f32 v4, v54, v54, v4
	v_fma_f32 v4, v55, v55, v4
	v_fma_f32 v4, v56, v56, v4
	v_fma_f32 v4, v57, v57, v4
	v_fma_f32 v4, v58, v58, v4
	v_fma_f32 v4, v59, v59, v4
	v_fma_f32 v4, v60, v60, v4
	v_fma_f32 v4, v61, v61, v4
	v_fma_f32 v4, v62, v62, v4
	v_fma_f32 v4, v63, v63, v4
	s_nop 1
	v_add_f32_dpp v5, v4, v4 quad_perm:[1,0,3,2] row_mask:0xf bank_mask:0xf
	s_nop 1
	v_add_f32_dpp v4, v5, v5 quad_perm:[2,3,0,1] row_mask:0xf bank_mask:0xf
	s_nop 1
	v_add_f32_dpp v5, v4, v4 row_half_mirror row_mask:0xf bank_mask:0xf
	s_nop 1
	v_add_f32_dpp v4, v5, v5 row_mirror row_mask:0xf bank_mask:0xf
	s_nop 1
	v_readlane_b32 s98, v4, 0
	v_readlane_b32 s99, v4, 16
	s_nop 3
	v_mov_b32_e32 v5, s98
	v_add_f32_e32 v5, s99, v5
	v_readlane_b32 s98, v4, 32
	v_readlane_b32 s99, v4, 48
	s_nop 3
	v_add_f32_e32 v5, s98, v5
	v_add_f32_e32 v5, s99, v5
	v_mul_f32_e32 v5, 0x3a800000, v5
	v_add_f32_e32 v5, 0x358637bd, v5
	v_rsq_f32_e32 v6, v5
	s_nop 0
	s_add_u32 s98, s97, 2
	v_pk_mul_f32 v[48:49], v[48:49], v[6:7] op_sel_hi:[1,0]
	v_pk_mul_f32 v[50:51], v[50:51], v[6:7] op_sel_hi:[1,0]
	v_pk_mul_f32 v[52:53], v[52:53], v[6:7] op_sel_hi:[1,0]
	v_pk_mul_f32 v[54:55], v[54:55], v[6:7] op_sel_hi:[1,0]
	v_pk_mul_f32 v[56:57], v[56:57], v[6:7] op_sel_hi:[1,0]
	v_pk_mul_f32 v[58:59], v[58:59], v[6:7] op_sel_hi:[1,0]
	v_pk_mul_f32 v[60:61], v[60:61], v[6:7] op_sel_hi:[1,0]
	v_pk_mul_f32 v[62:63], v[62:63], v[6:7] op_sel_hi:[1,0]
	v_pk_mul_f32 v[48:49], v[48:49], v[112:113]
	v_pk_mul_f32 v[50:51], v[50:51], v[114:115]
	v_pk_mul_f32 v[52:53], v[52:53], v[116:117]
	v_pk_mul_f32 v[54:55], v[54:55], v[118:119]
	v_pk_mul_f32 v[56:57], v[56:57], v[120:121]
	v_pk_mul_f32 v[58:59], v[58:59], v[122:123]
	v_pk_mul_f32 v[60:61], v[60:61], v[124:125]
	v_pk_mul_f32 v[62:63], v[62:63], v[126:127]
	v_pk_fma_f32 v[48:49], v[48:49], v[128:129], v[144:145]
	v_pk_fma_f32 v[50:51], v[50:51], v[130:131], v[146:147]
	v_pk_fma_f32 v[52:53], v[52:53], v[132:133], v[148:149]
	v_pk_fma_f32 v[54:55], v[54:55], v[134:135], v[150:151]
	v_pk_fma_f32 v[56:57], v[56:57], v[136:137], v[152:153]
	v_pk_fma_f32 v[58:59], v[58:59], v[138:139], v[154:155]
	v_pk_fma_f32 v[60:61], v[60:61], v[140:141], v[156:157]
	v_pk_fma_f32 v[62:63], v[62:63], v[142:143], v[158:159]
	v_cvt_pk_bf16_f32 v48, v48, v49
	v_cvt_pk_bf16_f32 v49, v50, v51
	v_cvt_pk_bf16_f32 v50, v52, v53
	v_cvt_pk_bf16_f32 v51, v54, v55
	v_cvt_pk_bf16_f32 v52, v56, v57
	v_cvt_pk_bf16_f32 v53, v58, v59
	v_cvt_pk_bf16_f32 v54, v60, v61
	v_cvt_pk_bf16_f32 v55, v62, v63
	s_lshl_b32 s99, s98, 11
	v_lshl_add_u32 v8, v0, 3, s99
	global_store_dwordx2 v8, v[48:49], s[94:95]
	global_store_dwordx2 v8, v[50:51], s[94:95] offset:512
	global_store_dwordx2 v8, v[52:53], s[94:95] offset:1024
	global_store_dwordx2 v8, v[54:55], s[94:95] offset:1536
	s_lshl_b32 s99, s98, 2
	v_mov_b32_e32 v9, s99
	v_mov_b32_e32 v10, 0
	v_cmp_eq_u32_e32 vcc, 0, v0
	s_and_saveexec_b64 s[98:99], vcc
	global_store_dword v9, v10, s[90:91]
	global_store_dword v9, v10, s[92:93]
	s_or_b64 exec, exec, s[98:99]
	s_add_u32 s98, s97, 8
	s_lshl_b32 s98, s98, 12
	v_add_u32_e32 v3, s98, v1
	global_load_dwordx4 v[48:51], v3, s[88:89] nt
	global_load_dwordx4 v[52:55], v3, s[88:89] offset:1024 nt
	global_load_dwordx4 v[56:59], v3, s[88:89] offset:2048 nt
	global_load_dwordx4 v[60:63], v3, s[88:89] offset:3072 nt
	s_waitcnt vmcnt(38)
	v_mul_f32_e32 v4, v64, v64
	v_fma_f32 v4, v65, v65, v4
	v_fma_f32 v4, v66, v66, v4
	v_fma_f32 v4, v67, v67, v4
	v_fma_f32 v4, v68, v68, v4
	v_fma_f32 v4, v69, v69, v4
	v_fma_f32 v4, v70, v70, v4
	v_fma_f32 v4, v71, v71, v4
	v_fma_f32 v4, v72, v72, v4
	v_fma_f32 v4, v73, v73, v4
	v_fma_f32 v4, v74, v74, v4
	v_fma_f32 v4, v75, v75, v4
	v_fma_f32 v4, v76, v76, v4
	v_fma_f32 v4, v77, v77, v4
	v_fma_f32 v4, v78, v78, v4
	v_fma_f32 v4, v79, v79, v4
	s_nop 1
	v_add_f32_dpp v5, v4, v4 quad_perm:[1,0,3,2] row_mask:0xf bank_mask:0xf
	s_nop 1
	v_add_f32_dpp v4, v5, v5 quad_perm:[2,3,0,1] row_mask:0xf bank_mask:0xf
	s_nop 1
	v_add_f32_dpp v5, v4, v4 row_half_mirror row_mask:0xf bank_mask:0xf
	s_nop 1
	v_add_f32_dpp v4, v5, v5 row_mirror row_mask:0xf bank_mask:0xf
	s_nop 1
	v_readlane_b32 s98, v4, 0
	v_readlane_b32 s99, v4, 16
	s_nop 3
	v_mov_b32_e32 v5, s98
	v_add_f32_e32 v5, s99, v5
	v_readlane_b32 s98, v4, 32
	v_readlane_b32 s99, v4, 48
	s_nop 3
	v_add_f32_e32 v5, s98, v5
	v_add_f32_e32 v5, s99, v5
	v_mul_f32_e32 v5, 0x3a800000, v5
	v_add_f32_e32 v5, 0x358637bd, v5
	v_rsq_f32_e32 v6, v5
	s_nop 0
	s_add_u32 s98, s97, 3
	v_pk_mul_f32 v[64:65], v[64:65], v[6:7] op_sel_hi:[1,0]
	v_pk_mul_f32 v[66:67], v[66:67], v[6:7] op_sel_hi:[1,0]
	v_pk_mul_f32 v[68:69], v[68:69], v[6:7] op_sel_hi:[1,0]
	v_pk_mul_f32 v[70:71], v[70:71], v[6:7] op_sel_hi:[1,0]
	v_pk_mul_f32 v[72:73], v[72:73], v[6:7] op_sel_hi:[1,0]
	v_pk_mul_f32 v[74:75], v[74:75], v[6:7] op_sel_hi:[1,0]
	v_pk_mul_f32 v[76:77], v[76:77], v[6:7] op_sel_hi:[1,0]
	v_pk_mul_f32 v[78:79], v[78:79], v[6:7] op_sel_hi:[1,0]
	v_pk_mul_f32 v[64:65], v[64:65], v[112:113]
	v_pk_mul_f32 v[66:67], v[66:67], v[114:115]
	v_pk_mul_f32 v[68:69], v[68:69], v[116:117]
	v_pk_mul_f32 v[70:71], v[70:71], v[118:119]
	v_pk_mul_f32 v[72:73], v[72:73], v[120:121]
	v_pk_mul_f32 v[74:75], v[74:75], v[122:123]
	v_pk_mul_f32 v[76:77], v[76:77], v[124:125]
	v_pk_mul_f32 v[78:79], v[78:79], v[126:127]
	v_pk_fma_f32 v[64:65], v[64:65], v[128:129], v[144:145]
	v_pk_fma_f32 v[66:67], v[66:67], v[130:131], v[146:147]
	v_pk_fma_f32 v[68:69], v[68:69], v[132:133], v[148:149]
	v_pk_fma_f32 v[70:71], v[70:71], v[134:135], v[150:151]
	v_pk_fma_f32 v[72:73], v[72:73], v[136:137], v[152:153]
	v_pk_fma_f32 v[74:75], v[74:75], v[138:139], v[154:155]
	v_pk_fma_f32 v[76:77], v[76:77], v[140:141], v[156:157]
	v_pk_fma_f32 v[78:79], v[78:79], v[142:143], v[158:159]
	v_cvt_pk_bf16_f32 v64, v64, v65
	v_cvt_pk_bf16_f32 v65, v66, v67
	v_cvt_pk_bf16_f32 v66, v68, v69
	v_cvt_pk_bf16_f32 v67, v70, v71
	v_cvt_pk_bf16_f32 v68, v72, v73
	v_cvt_pk_bf16_f32 v69, v74, v75
	v_cvt_pk_bf16_f32 v70, v76, v77
	v_cvt_pk_bf16_f32 v71, v78, v79
	s_lshl_b32 s99, s98, 11
	v_lshl_add_u32 v8, v0, 3, s99
	global_store_dwordx2 v8, v[64:65], s[94:95]
	global_store_dwordx2 v8, v[66:67], s[94:95] offset:512
	global_store_dwordx2 v8, v[68:69], s[94:95] offset:1024
	global_store_dwordx2 v8, v[70:71], s[94:95] offset:1536
	s_lshl_b32 s99, s98, 2
	v_mov_b32_e32 v9, s99
	v_mov_b32_e32 v10, 0
	v_cmp_eq_u32_e32 vcc, 0, v0
	s_and_saveexec_b64 s[98:99], vcc
	global_store_dword v9, v10, s[90:91]
	global_store_dword v9, v10, s[92:93]
	s_or_b64 exec, exec, s[98:99]
	s_add_u32 s98, s97, 9
	s_lshl_b32 s98, s98, 12
	v_add_u32_e32 v3, s98, v1
	global_load_dwordx4 v[64:67], v3, s[88:89] nt
	global_load_dwordx4 v[68:71], v3, s[88:89] offset:1024 nt
	global_load_dwordx4 v[72:75], v3, s[88:89] offset:2048 nt
	global_load_dwordx4 v[76:79], v3, s[88:89] offset:3072 nt
	s_waitcnt vmcnt(44)
	v_mul_f32_e32 v4, v80, v80
	v_fma_f32 v4, v81, v81, v4
	v_fma_f32 v4, v82, v82, v4
	v_fma_f32 v4, v83, v83, v4
	v_fma_f32 v4, v84, v84, v4
	v_fma_f32 v4, v85, v85, v4
	v_fma_f32 v4, v86, v86, v4
	v_fma_f32 v4, v87, v87, v4
	v_fma_f32 v4, v88, v88, v4
	v_fma_f32 v4, v89, v89, v4
	v_fma_f32 v4, v90, v90, v4
	v_fma_f32 v4, v91, v91, v4
	v_fma_f32 v4, v92, v92, v4
	v_fma_f32 v4, v93, v93, v4
	v_fma_f32 v4, v94, v94, v4
	v_fma_f32 v4, v95, v95, v4
	s_nop 1
	v_add_f32_dpp v5, v4, v4 quad_perm:[1,0,3,2] row_mask:0xf bank_mask:0xf
	s_nop 1
	v_add_f32_dpp v4, v5, v5 quad_perm:[2,3,0,1] row_mask:0xf bank_mask:0xf
	s_nop 1
	v_add_f32_dpp v5, v4, v4 row_half_mirror row_mask:0xf bank_mask:0xf
	s_nop 1
	v_add_f32_dpp v4, v5, v5 row_mirror row_mask:0xf bank_mask:0xf
	s_nop 1
	v_readlane_b32 s98, v4, 0
	v_readlane_b32 s99, v4, 16
	s_nop 3
	v_mov_b32_e32 v5, s98
	v_add_f32_e32 v5, s99, v5
	v_readlane_b32 s98, v4, 32
	v_readlane_b32 s99, v4, 48
	s_nop 3
	v_add_f32_e32 v5, s98, v5
	v_add_f32_e32 v5, s99, v5
	v_mul_f32_e32 v5, 0x3a800000, v5
	v_add_f32_e32 v5, 0x358637bd, v5
	v_rsq_f32_e32 v6, v5
	s_nop 0
	s_add_u32 s98, s97, 4
	v_pk_mul_f32 v[80:81], v[80:81], v[6:7] op_sel_hi:[1,0]
	v_pk_mul_f32 v[82:83], v[82:83], v[6:7] op_sel_hi:[1,0]
	v_pk_mul_f32 v[84:85], v[84:85], v[6:7] op_sel_hi:[1,0]
	v_pk_mul_f32 v[86:87], v[86:87], v[6:7] op_sel_hi:[1,0]
	v_pk_mul_f32 v[88:89], v[88:89], v[6:7] op_sel_hi:[1,0]
	v_pk_mul_f32 v[90:91], v[90:91], v[6:7] op_sel_hi:[1,0]
	v_pk_mul_f32 v[92:93], v[92:93], v[6:7] op_sel_hi:[1,0]
	v_pk_mul_f32 v[94:95], v[94:95], v[6:7] op_sel_hi:[1,0]
	v_pk_mul_f32 v[80:81], v[80:81], v[112:113]
	v_pk_mul_f32 v[82:83], v[82:83], v[114:115]
	v_pk_mul_f32 v[84:85], v[84:85], v[116:117]
	v_pk_mul_f32 v[86:87], v[86:87], v[118:119]
	v_pk_mul_f32 v[88:89], v[88:89], v[120:121]
	v_pk_mul_f32 v[90:91], v[90:91], v[122:123]
	v_pk_mul_f32 v[92:93], v[92:93], v[124:125]
	v_pk_mul_f32 v[94:95], v[94:95], v[126:127]
	v_pk_fma_f32 v[80:81], v[80:81], v[128:129], v[144:145]
	v_pk_fma_f32 v[82:83], v[82:83], v[130:131], v[146:147]
	v_pk_fma_f32 v[84:85], v[84:85], v[132:133], v[148:149]
	v_pk_fma_f32 v[86:87], v[86:87], v[134:135], v[150:151]
	v_pk_fma_f32 v[88:89], v[88:89], v[136:137], v[152:153]
	v_pk_fma_f32 v[90:91], v[90:91], v[138:139], v[154:155]
	v_pk_fma_f32 v[92:93], v[92:93], v[140:141], v[156:157]
	v_pk_fma_f32 v[94:95], v[94:95], v[142:143], v[158:159]
	v_cvt_pk_bf16_f32 v80, v80, v81
	v_cvt_pk_bf16_f32 v81, v82, v83
	v_cvt_pk_bf16_f32 v82, v84, v85
	v_cvt_pk_bf16_f32 v83, v86, v87
	v_cvt_pk_bf16_f32 v84, v88, v89
	v_cvt_pk_bf16_f32 v85, v90, v91
	v_cvt_pk_bf16_f32 v86, v92, v93
	v_cvt_pk_bf16_f32 v87, v94, v95
	s_lshl_b32 s99, s98, 11
	v_lshl_add_u32 v8, v0, 3, s99
	global_store_dwordx2 v8, v[80:81], s[94:95]
	global_store_dwordx2 v8, v[82:83], s[94:95] offset:512
	global_store_dwordx2 v8, v[84:85], s[94:95] offset:1024
	global_store_dwordx2 v8, v[86:87], s[94:95] offset:1536
	s_lshl_b32 s99, s98, 2
	v_mov_b32_e32 v9, s99
	v_mov_b32_e32 v10, 0
	v_cmp_eq_u32_e32 vcc, 0, v0
	s_and_saveexec_b64 s[98:99], vcc
	global_store_dword v9, v10, s[90:91]
	global_store_dword v9, v10, s[92:93]
	s_or_b64 exec, exec, s[98:99]
	s_add_u32 s98, s97, 10
	s_lshl_b32 s98, s98, 12
	v_add_u32_e32 v3, s98, v1
	global_load_dwordx4 v[80:83], v3, s[88:89] nt
	global_load_dwordx4 v[84:87], v3, s[88:89] offset:1024 nt
	global_load_dwordx4 v[88:91], v3, s[88:89] offset:2048 nt
	global_load_dwordx4 v[92:95], v3, s[88:89] offset:3072 nt
	s_waitcnt vmcnt(50)
	v_mul_f32_e32 v4, v96, v96
	v_fma_f32 v4, v97, v97, v4
	v_fma_f32 v4, v98, v98, v4
	v_fma_f32 v4, v99, v99, v4
	v_fma_f32 v4, v100, v100, v4
	v_fma_f32 v4, v101, v101, v4
	v_fma_f32 v4, v102, v102, v4
	v_fma_f32 v4, v103, v103, v4
	v_fma_f32 v4, v104, v104, v4
	v_fma_f32 v4, v105, v105, v4
	v_fma_f32 v4, v106, v106, v4
	v_fma_f32 v4, v107, v107, v4
	v_fma_f32 v4, v108, v108, v4
	v_fma_f32 v4, v109, v109, v4
	v_fma_f32 v4, v110, v110, v4
	v_fma_f32 v4, v111, v111, v4
	s_nop 1
	v_add_f32_dpp v5, v4, v4 quad_perm:[1,0,3,2] row_mask:0xf bank_mask:0xf
	s_nop 1
	v_add_f32_dpp v4, v5, v5 quad_perm:[2,3,0,1] row_mask:0xf bank_mask:0xf
	s_nop 1
	v_add_f32_dpp v5, v4, v4 row_half_mirror row_mask:0xf bank_mask:0xf
	s_nop 1
	v_add_f32_dpp v4, v5, v5 row_mirror row_mask:0xf bank_mask:0xf
	s_nop 1
	v_readlane_b32 s98, v4, 0
	v_readlane_b32 s99, v4, 16
	s_nop 3
	v_mov_b32_e32 v5, s98
	v_add_f32_e32 v5, s99, v5
	v_readlane_b32 s98, v4, 32
	v_readlane_b32 s99, v4, 48
	s_nop 3
	v_add_f32_e32 v5, s98, v5
	v_add_f32_e32 v5, s99, v5
	v_mul_f32_e32 v5, 0x3a800000, v5
	v_add_f32_e32 v5, 0x358637bd, v5
	v_rsq_f32_e32 v6, v5
	s_nop 0
	s_add_u32 s98, s97, 5
	v_pk_mul_f32 v[96:97], v[96:97], v[6:7] op_sel_hi:[1,0]
	v_pk_mul_f32 v[98:99], v[98:99], v[6:7] op_sel_hi:[1,0]
	v_pk_mul_f32 v[100:101], v[100:101], v[6:7] op_sel_hi:[1,0]
	v_pk_mul_f32 v[102:103], v[102:103], v[6:7] op_sel_hi:[1,0]
	v_pk_mul_f32 v[104:105], v[104:105], v[6:7] op_sel_hi:[1,0]
	v_pk_mul_f32 v[106:107], v[106:107], v[6:7] op_sel_hi:[1,0]
	v_pk_mul_f32 v[108:109], v[108:109], v[6:7] op_sel_hi:[1,0]
	v_pk_mul_f32 v[110:111], v[110:111], v[6:7] op_sel_hi:[1,0]
	v_pk_mul_f32 v[96:97], v[96:97], v[112:113]
	v_pk_mul_f32 v[98:99], v[98:99], v[114:115]
	v_pk_mul_f32 v[100:101], v[100:101], v[116:117]
	v_pk_mul_f32 v[102:103], v[102:103], v[118:119]
	v_pk_mul_f32 v[104:105], v[104:105], v[120:121]
	v_pk_mul_f32 v[106:107], v[106:107], v[122:123]
	v_pk_mul_f32 v[108:109], v[108:109], v[124:125]
	v_pk_mul_f32 v[110:111], v[110:111], v[126:127]
	v_pk_fma_f32 v[96:97], v[96:97], v[128:129], v[144:145]
	v_pk_fma_f32 v[98:99], v[98:99], v[130:131], v[146:147]
	v_pk_fma_f32 v[100:101], v[100:101], v[132:133], v[148:149]
	v_pk_fma_f32 v[102:103], v[102:103], v[134:135], v[150:151]
	v_pk_fma_f32 v[104:105], v[104:105], v[136:137], v[152:153]
	v_pk_fma_f32 v[106:107], v[106:107], v[138:139], v[154:155]
	v_pk_fma_f32 v[108:109], v[108:109], v[140:141], v[156:157]
	v_pk_fma_f32 v[110:111], v[110:111], v[142:143], v[158:159]
	v_cvt_pk_bf16_f32 v96, v96, v97
	v_cvt_pk_bf16_f32 v97, v98, v99
	v_cvt_pk_bf16_f32 v98, v100, v101
	v_cvt_pk_bf16_f32 v99, v102, v103
	v_cvt_pk_bf16_f32 v100, v104, v105
	v_cvt_pk_bf16_f32 v101, v106, v107
	v_cvt_pk_bf16_f32 v102, v108, v109
	v_cvt_pk_bf16_f32 v103, v110, v111
	s_lshl_b32 s99, s98, 11
	v_lshl_add_u32 v8, v0, 3, s99
	global_store_dwordx2 v8, v[96:97], s[94:95]
	global_store_dwordx2 v8, v[98:99], s[94:95] offset:512
	global_store_dwordx2 v8, v[100:101], s[94:95] offset:1024
	global_store_dwordx2 v8, v[102:103], s[94:95] offset:1536
	s_lshl_b32 s99, s98, 2
	v_mov_b32_e32 v9, s99
	v_mov_b32_e32 v10, 0
	v_cmp_eq_u32_e32 vcc, 0, v0
	s_and_saveexec_b64 s[98:99], vcc
	global_store_dword v9, v10, s[90:91]
	global_store_dword v9, v10, s[92:93]
	s_or_b64 exec, exec, s[98:99]
	s_add_u32 s98, s97, 11
	s_lshl_b32 s98, s98, 12
	v_add_u32_e32 v3, s98, v1
	global_load_dwordx4 v[96:99], v3, s[88:89] nt
	global_load_dwordx4 v[100:103], v3, s[88:89] offset:1024 nt
	global_load_dwordx4 v[104:107], v3, s[88:89] offset:2048 nt
	global_load_dwordx4 v[108:111], v3, s[88:89] offset:3072 nt
	s_waitcnt vmcnt(50)
	v_mul_f32_e32 v4, v16, v16
	v_fma_f32 v4, v17, v17, v4
	v_fma_f32 v4, v18, v18, v4
	v_fma_f32 v4, v19, v19, v4
	v_fma_f32 v4, v20, v20, v4
	v_fma_f32 v4, v21, v21, v4
	v_fma_f32 v4, v22, v22, v4
	v_fma_f32 v4, v23, v23, v4
	v_fma_f32 v4, v24, v24, v4
	v_fma_f32 v4, v25, v25, v4
	v_fma_f32 v4, v26, v26, v4
	v_fma_f32 v4, v27, v27, v4
	v_fma_f32 v4, v28, v28, v4
	v_fma_f32 v4, v29, v29, v4
	v_fma_f32 v4, v30, v30, v4
	v_fma_f32 v4, v31, v31, v4
	s_nop 1
	v_add_f32_dpp v5, v4, v4 quad_perm:[1,0,3,2] row_mask:0xf bank_mask:0xf
	s_nop 1
	v_add_f32_dpp v4, v5, v5 quad_perm:[2,3,0,1] row_mask:0xf bank_mask:0xf
	s_nop 1
	v_add_f32_dpp v5, v4, v4 row_half_mirror row_mask:0xf bank_mask:0xf
	s_nop 1
	v_add_f32_dpp v4, v5, v5 row_mirror row_mask:0xf bank_mask:0xf
	s_nop 1
	v_readlane_b32 s98, v4, 0
	v_readlane_b32 s99, v4, 16
	s_nop 3
	v_mov_b32_e32 v5, s98
	v_add_f32_e32 v5, s99, v5
	v_readlane_b32 s98, v4, 32
	v_readlane_b32 s99, v4, 48
	s_nop 3
	v_add_f32_e32 v5, s98, v5
	v_add_f32_e32 v5, s99, v5
	v_mul_f32_e32 v5, 0x3a800000, v5
	v_add_f32_e32 v5, 0x358637bd, v5
	v_rsq_f32_e32 v6, v5
	s_nop 0
	s_add_u32 s98, s97, 6
	v_pk_mul_f32 v[16:17], v[16:17], v[6:7] op_sel_hi:[1,0]
	v_pk_mul_f32 v[18:19], v[18:19], v[6:7] op_sel_hi:[1,0]
	v_pk_mul_f32 v[20:21], v[20:21], v[6:7] op_sel_hi:[1,0]
	v_pk_mul_f32 v[22:23], v[22:23], v[6:7] op_sel_hi:[1,0]
	v_pk_mul_f32 v[24:25], v[24:25], v[6:7] op_sel_hi:[1,0]
	v_pk_mul_f32 v[26:27], v[26:27], v[6:7] op_sel_hi:[1,0]
	v_pk_mul_f32 v[28:29], v[28:29], v[6:7] op_sel_hi:[1,0]
	v_pk_mul_f32 v[30:31], v[30:31], v[6:7] op_sel_hi:[1,0]
	v_pk_mul_f32 v[16:17], v[16:17], v[112:113]
	v_pk_mul_f32 v[18:19], v[18:19], v[114:115]
	v_pk_mul_f32 v[20:21], v[20:21], v[116:117]
	v_pk_mul_f32 v[22:23], v[22:23], v[118:119]
	v_pk_mul_f32 v[24:25], v[24:25], v[120:121]
	v_pk_mul_f32 v[26:27], v[26:27], v[122:123]
	v_pk_mul_f32 v[28:29], v[28:29], v[124:125]
	v_pk_mul_f32 v[30:31], v[30:31], v[126:127]
	v_pk_fma_f32 v[16:17], v[16:17], v[128:129], v[144:145]
	v_pk_fma_f32 v[18:19], v[18:19], v[130:131], v[146:147]
	v_pk_fma_f32 v[20:21], v[20:21], v[132:133], v[148:149]
	v_pk_fma_f32 v[22:23], v[22:23], v[134:135], v[150:151]
	v_pk_fma_f32 v[24:25], v[24:25], v[136:137], v[152:153]
	v_pk_fma_f32 v[26:27], v[26:27], v[138:139], v[154:155]
	v_pk_fma_f32 v[28:29], v[28:29], v[140:141], v[156:157]
	v_pk_fma_f32 v[30:31], v[30:31], v[142:143], v[158:159]
	v_cvt_pk_bf16_f32 v16, v16, v17
	v_cvt_pk_bf16_f32 v17, v18, v19
	v_cvt_pk_bf16_f32 v18, v20, v21
	v_cvt_pk_bf16_f32 v19, v22, v23
	v_cvt_pk_bf16_f32 v20, v24, v25
	v_cvt_pk_bf16_f32 v21, v26, v27
	v_cvt_pk_bf16_f32 v22, v28, v29
	v_cvt_pk_bf16_f32 v23, v30, v31
	s_lshl_b32 s99, s98, 11
	v_lshl_add_u32 v8, v0, 3, s99
	global_store_dwordx2 v8, v[16:17], s[94:95]
	global_store_dwordx2 v8, v[18:19], s[94:95] offset:512
	global_store_dwordx2 v8, v[20:21], s[94:95] offset:1024
	global_store_dwordx2 v8, v[22:23], s[94:95] offset:1536
	s_lshl_b32 s99, s98, 2
	v_mov_b32_e32 v9, s99
	v_mov_b32_e32 v10, 0
	v_cmp_eq_u32_e32 vcc, 0, v0
	s_and_saveexec_b64 s[98:99], vcc
	global_store_dword v9, v10, s[90:91]
	global_store_dword v9, v10, s[92:93]
	s_or_b64 exec, exec, s[98:99]
	s_add_u32 s98, s97, 12
	s_lshl_b32 s98, s98, 12
	v_add_u32_e32 v3, s98, v1
	global_load_dwordx4 v[16:19], v3, s[88:89] nt
	global_load_dwordx4 v[20:23], v3, s[88:89] offset:1024 nt
	global_load_dwordx4 v[24:27], v3, s[88:89] offset:2048 nt
	global_load_dwordx4 v[28:31], v3, s[88:89] offset:3072 nt
	s_waitcnt vmcnt(50)
	v_mul_f32_e32 v4, v32, v32
	v_fma_f32 v4, v33, v33, v4
	v_fma_f32 v4, v34, v34, v4
	v_fma_f32 v4, v35, v35, v4
	v_fma_f32 v4, v36, v36, v4
	v_fma_f32 v4, v37, v37, v4
	v_fma_f32 v4, v38, v38, v4
	v_fma_f32 v4, v39, v39, v4
	v_fma_f32 v4, v40, v40, v4
	v_fma_f32 v4, v41, v41, v4
	v_fma_f32 v4, v42, v42, v4
	v_fma_f32 v4, v43, v43, v4
	v_fma_f32 v4, v44, v44, v4
	v_fma_f32 v4, v45, v45, v4
	v_fma_f32 v4, v46, v46, v4
	v_fma_f32 v4, v47, v47, v4
	s_nop 1
	v_add_f32_dpp v5, v4, v4 quad_perm:[1,0,3,2] row_mask:0xf bank_mask:0xf
	s_nop 1
	v_add_f32_dpp v4, v5, v5 quad_perm:[2,3,0,1] row_mask:0xf bank_mask:0xf
	s_nop 1
	v_add_f32_dpp v5, v4, v4 row_half_mirror row_mask:0xf bank_mask:0xf
	s_nop 1
	v_add_f32_dpp v4, v5, v5 row_mirror row_mask:0xf bank_mask:0xf
	s_nop 1
	v_readlane_b32 s98, v4, 0
	v_readlane_b32 s99, v4, 16
	s_nop 3
	v_mov_b32_e32 v5, s98
	v_add_f32_e32 v5, s99, v5
	v_readlane_b32 s98, v4, 32
	v_readlane_b32 s99, v4, 48
	s_nop 3
	v_add_f32_e32 v5, s98, v5
	v_add_f32_e32 v5, s99, v5
	v_mul_f32_e32 v5, 0x3a800000, v5
	v_add_f32_e32 v5, 0x358637bd, v5
	v_rsq_f32_e32 v6, v5
	s_nop 0
	s_add_u32 s98, s97, 7
	v_pk_mul_f32 v[32:33], v[32:33], v[6:7] op_sel_hi:[1,0]
	v_pk_mul_f32 v[34:35], v[34:35], v[6:7] op_sel_hi:[1,0]
	v_pk_mul_f32 v[36:37], v[36:37], v[6:7] op_sel_hi:[1,0]
	v_pk_mul_f32 v[38:39], v[38:39], v[6:7] op_sel_hi:[1,0]
	v_pk_mul_f32 v[40:41], v[40:41], v[6:7] op_sel_hi:[1,0]
	v_pk_mul_f32 v[42:43], v[42:43], v[6:7] op_sel_hi:[1,0]
	v_pk_mul_f32 v[44:45], v[44:45], v[6:7] op_sel_hi:[1,0]
	v_pk_mul_f32 v[46:47], v[46:47], v[6:7] op_sel_hi:[1,0]
	v_pk_mul_f32 v[32:33], v[32:33], v[112:113]
	v_pk_mul_f32 v[34:35], v[34:35], v[114:115]
	v_pk_mul_f32 v[36:37], v[36:37], v[116:117]
	v_pk_mul_f32 v[38:39], v[38:39], v[118:119]
	v_pk_mul_f32 v[40:41], v[40:41], v[120:121]
	v_pk_mul_f32 v[42:43], v[42:43], v[122:123]
	v_pk_mul_f32 v[44:45], v[44:45], v[124:125]
	v_pk_mul_f32 v[46:47], v[46:47], v[126:127]
	v_pk_fma_f32 v[32:33], v[32:33], v[128:129], v[144:145]
	v_pk_fma_f32 v[34:35], v[34:35], v[130:131], v[146:147]
	v_pk_fma_f32 v[36:37], v[36:37], v[132:133], v[148:149]
	v_pk_fma_f32 v[38:39], v[38:39], v[134:135], v[150:151]
	v_pk_fma_f32 v[40:41], v[40:41], v[136:137], v[152:153]
	v_pk_fma_f32 v[42:43], v[42:43], v[138:139], v[154:155]
	v_pk_fma_f32 v[44:45], v[44:45], v[140:141], v[156:157]
	v_pk_fma_f32 v[46:47], v[46:47], v[142:143], v[158:159]
	v_cvt_pk_bf16_f32 v32, v32, v33
	v_cvt_pk_bf16_f32 v33, v34, v35
	v_cvt_pk_bf16_f32 v34, v36, v37
	v_cvt_pk_bf16_f32 v35, v38, v39
	v_cvt_pk_bf16_f32 v36, v40, v41
	v_cvt_pk_bf16_f32 v37, v42, v43
	v_cvt_pk_bf16_f32 v38, v44, v45
	v_cvt_pk_bf16_f32 v39, v46, v47
	s_lshl_b32 s99, s98, 11
	v_lshl_add_u32 v8, v0, 3, s99
	global_store_dwordx2 v8, v[32:33], s[94:95]
	global_store_dwordx2 v8, v[34:35], s[94:95] offset:512
	global_store_dwordx2 v8, v[36:37], s[94:95] offset:1024
	global_store_dwordx2 v8, v[38:39], s[94:95] offset:1536
	s_lshl_b32 s99, s98, 2
	v_mov_b32_e32 v9, s99
	v_mov_b32_e32 v10, 0
	v_cmp_eq_u32_e32 vcc, 0, v0
	s_and_saveexec_b64 s[98:99], vcc
	global_store_dword v9, v10, s[90:91]
	global_store_dword v9, v10, s[92:93]
	s_or_b64 exec, exec, s[98:99]
	s_add_u32 s98, s97, 13
	s_lshl_b32 s98, s98, 12
	v_add_u32_e32 v3, s98, v1
	global_load_dwordx4 v[32:35], v3, s[88:89] nt
	global_load_dwordx4 v[36:39], v3, s[88:89] offset:1024 nt
	global_load_dwordx4 v[40:43], v3, s[88:89] offset:2048 nt
	global_load_dwordx4 v[44:47], v3, s[88:89] offset:3072 nt
	s_waitcnt vmcnt(50)
	v_mul_f32_e32 v4, v48, v48
	v_fma_f32 v4, v49, v49, v4
	v_fma_f32 v4, v50, v50, v4
	v_fma_f32 v4, v51, v51, v4
	v_fma_f32 v4, v52, v52, v4
	v_fma_f32 v4, v53, v53, v4
	v_fma_f32 v4, v54, v54, v4
	v_fma_f32 v4, v55, v55, v4
	v_fma_f32 v4, v56, v56, v4
	v_fma_f32 v4, v57, v57, v4
	v_fma_f32 v4, v58, v58, v4
	v_fma_f32 v4, v59, v59, v4
	v_fma_f32 v4, v60, v60, v4
	v_fma_f32 v4, v61, v61, v4
	v_fma_f32 v4, v62, v62, v4
	v_fma_f32 v4, v63, v63, v4
	s_nop 1
	v_add_f32_dpp v5, v4, v4 quad_perm:[1,0,3,2] row_mask:0xf bank_mask:0xf
	s_nop 1
	v_add_f32_dpp v4, v5, v5 quad_perm:[2,3,0,1] row_mask:0xf bank_mask:0xf
	s_nop 1
	v_add_f32_dpp v5, v4, v4 row_half_mirror row_mask:0xf bank_mask:0xf
	s_nop 1
	v_add_f32_dpp v4, v5, v5 row_mirror row_mask:0xf bank_mask:0xf
	s_nop 1
	v_readlane_b32 s98, v4, 0
	v_readlane_b32 s99, v4, 16
	s_nop 3
	v_mov_b32_e32 v5, s98
	v_add_f32_e32 v5, s99, v5
	v_readlane_b32 s98, v4, 32
	v_readlane_b32 s99, v4, 48
	s_nop 3
	v_add_f32_e32 v5, s98, v5
	v_add_f32_e32 v5, s99, v5
	v_mul_f32_e32 v5, 0x3a800000, v5
	v_add_f32_e32 v5, 0x358637bd, v5
	v_rsq_f32_e32 v6, v5
	s_nop 0
	s_add_u32 s98, s97, 8
	v_pk_mul_f32 v[48:49], v[48:49], v[6:7] op_sel_hi:[1,0]
	v_pk_mul_f32 v[50:51], v[50:51], v[6:7] op_sel_hi:[1,0]
	v_pk_mul_f32 v[52:53], v[52:53], v[6:7] op_sel_hi:[1,0]
	v_pk_mul_f32 v[54:55], v[54:55], v[6:7] op_sel_hi:[1,0]
	v_pk_mul_f32 v[56:57], v[56:57], v[6:7] op_sel_hi:[1,0]
	v_pk_mul_f32 v[58:59], v[58:59], v[6:7] op_sel_hi:[1,0]
	v_pk_mul_f32 v[60:61], v[60:61], v[6:7] op_sel_hi:[1,0]
	v_pk_mul_f32 v[62:63], v[62:63], v[6:7] op_sel_hi:[1,0]
	v_pk_mul_f32 v[48:49], v[48:49], v[112:113]
	v_pk_mul_f32 v[50:51], v[50:51], v[114:115]
	v_pk_mul_f32 v[52:53], v[52:53], v[116:117]
	v_pk_mul_f32 v[54:55], v[54:55], v[118:119]
	v_pk_mul_f32 v[56:57], v[56:57], v[120:121]
	v_pk_mul_f32 v[58:59], v[58:59], v[122:123]
	v_pk_mul_f32 v[60:61], v[60:61], v[124:125]
	v_pk_mul_f32 v[62:63], v[62:63], v[126:127]
	v_pk_fma_f32 v[48:49], v[48:49], v[128:129], v[144:145]
	v_pk_fma_f32 v[50:51], v[50:51], v[130:131], v[146:147]
	v_pk_fma_f32 v[52:53], v[52:53], v[132:133], v[148:149]
	v_pk_fma_f32 v[54:55], v[54:55], v[134:135], v[150:151]
	v_pk_fma_f32 v[56:57], v[56:57], v[136:137], v[152:153]
	v_pk_fma_f32 v[58:59], v[58:59], v[138:139], v[154:155]
	v_pk_fma_f32 v[60:61], v[60:61], v[140:141], v[156:157]
	v_pk_fma_f32 v[62:63], v[62:63], v[142:143], v[158:159]
	v_cvt_pk_bf16_f32 v48, v48, v49
	v_cvt_pk_bf16_f32 v49, v50, v51
	v_cvt_pk_bf16_f32 v50, v52, v53
	v_cvt_pk_bf16_f32 v51, v54, v55
	v_cvt_pk_bf16_f32 v52, v56, v57
	v_cvt_pk_bf16_f32 v53, v58, v59
	v_cvt_pk_bf16_f32 v54, v60, v61
	v_cvt_pk_bf16_f32 v55, v62, v63
	s_lshl_b32 s99, s98, 11
	v_lshl_add_u32 v8, v0, 3, s99
	global_store_dwordx2 v8, v[48:49], s[94:95]
	global_store_dwordx2 v8, v[50:51], s[94:95] offset:512
	global_store_dwordx2 v8, v[52:53], s[94:95] offset:1024
	global_store_dwordx2 v8, v[54:55], s[94:95] offset:1536
	s_lshl_b32 s99, s98, 2
	v_mov_b32_e32 v9, s99
	v_mov_b32_e32 v10, 0
	v_cmp_eq_u32_e32 vcc, 0, v0
	s_and_saveexec_b64 s[98:99], vcc
	global_store_dword v9, v10, s[90:91]
	global_store_dword v9, v10, s[92:93]
	s_or_b64 exec, exec, s[98:99]
	s_add_u32 s98, s97, 14
	s_lshl_b32 s98, s98, 12
	v_add_u32_e32 v3, s98, v1
	global_load_dwordx4 v[48:51], v3, s[88:89] nt
	global_load_dwordx4 v[52:55], v3, s[88:89] offset:1024 nt
	global_load_dwordx4 v[56:59], v3, s[88:89] offset:2048 nt
	global_load_dwordx4 v[60:63], v3, s[88:89] offset:3072 nt
	s_waitcnt vmcnt(50)
	v_mul_f32_e32 v4, v64, v64
	v_fma_f32 v4, v65, v65, v4
	v_fma_f32 v4, v66, v66, v4
	v_fma_f32 v4, v67, v67, v4
	v_fma_f32 v4, v68, v68, v4
	v_fma_f32 v4, v69, v69, v4
	v_fma_f32 v4, v70, v70, v4
	v_fma_f32 v4, v71, v71, v4
	v_fma_f32 v4, v72, v72, v4
	v_fma_f32 v4, v73, v73, v4
	v_fma_f32 v4, v74, v74, v4
	v_fma_f32 v4, v75, v75, v4
	v_fma_f32 v4, v76, v76, v4
	v_fma_f32 v4, v77, v77, v4
	v_fma_f32 v4, v78, v78, v4
	v_fma_f32 v4, v79, v79, v4
	s_nop 1
	v_add_f32_dpp v5, v4, v4 quad_perm:[1,0,3,2] row_mask:0xf bank_mask:0xf
	s_nop 1
	v_add_f32_dpp v4, v5, v5 quad_perm:[2,3,0,1] row_mask:0xf bank_mask:0xf
	s_nop 1
	v_add_f32_dpp v5, v4, v4 row_half_mirror row_mask:0xf bank_mask:0xf
	s_nop 1
	v_add_f32_dpp v4, v5, v5 row_mirror row_mask:0xf bank_mask:0xf
	s_nop 1
	v_readlane_b32 s98, v4, 0
	v_readlane_b32 s99, v4, 16
	s_nop 3
	v_mov_b32_e32 v5, s98
	v_add_f32_e32 v5, s99, v5
	v_readlane_b32 s98, v4, 32
	v_readlane_b32 s99, v4, 48
	s_nop 3
	v_add_f32_e32 v5, s98, v5
	v_add_f32_e32 v5, s99, v5
	v_mul_f32_e32 v5, 0x3a800000, v5
	v_add_f32_e32 v5, 0x358637bd, v5
	v_rsq_f32_e32 v6, v5
	s_nop 0
	s_add_u32 s98, s97, 9
	v_pk_mul_f32 v[64:65], v[64:65], v[6:7] op_sel_hi:[1,0]
	v_pk_mul_f32 v[66:67], v[66:67], v[6:7] op_sel_hi:[1,0]
	v_pk_mul_f32 v[68:69], v[68:69], v[6:7] op_sel_hi:[1,0]
	v_pk_mul_f32 v[70:71], v[70:71], v[6:7] op_sel_hi:[1,0]
	v_pk_mul_f32 v[72:73], v[72:73], v[6:7] op_sel_hi:[1,0]
	v_pk_mul_f32 v[74:75], v[74:75], v[6:7] op_sel_hi:[1,0]
	v_pk_mul_f32 v[76:77], v[76:77], v[6:7] op_sel_hi:[1,0]
	v_pk_mul_f32 v[78:79], v[78:79], v[6:7] op_sel_hi:[1,0]
	v_pk_mul_f32 v[64:65], v[64:65], v[112:113]
	v_pk_mul_f32 v[66:67], v[66:67], v[114:115]
	v_pk_mul_f32 v[68:69], v[68:69], v[116:117]
	v_pk_mul_f32 v[70:71], v[70:71], v[118:119]
	v_pk_mul_f32 v[72:73], v[72:73], v[120:121]
	v_pk_mul_f32 v[74:75], v[74:75], v[122:123]
	v_pk_mul_f32 v[76:77], v[76:77], v[124:125]
	v_pk_mul_f32 v[78:79], v[78:79], v[126:127]
	v_pk_fma_f32 v[64:65], v[64:65], v[128:129], v[144:145]
	v_pk_fma_f32 v[66:67], v[66:67], v[130:131], v[146:147]
	v_pk_fma_f32 v[68:69], v[68:69], v[132:133], v[148:149]
	v_pk_fma_f32 v[70:71], v[70:71], v[134:135], v[150:151]
	v_pk_fma_f32 v[72:73], v[72:73], v[136:137], v[152:153]
	v_pk_fma_f32 v[74:75], v[74:75], v[138:139], v[154:155]
	v_pk_fma_f32 v[76:77], v[76:77], v[140:141], v[156:157]
	v_pk_fma_f32 v[78:79], v[78:79], v[142:143], v[158:159]
	v_cvt_pk_bf16_f32 v64, v64, v65
	v_cvt_pk_bf16_f32 v65, v66, v67
	v_cvt_pk_bf16_f32 v66, v68, v69
	v_cvt_pk_bf16_f32 v67, v70, v71
	v_cvt_pk_bf16_f32 v68, v72, v73
	v_cvt_pk_bf16_f32 v69, v74, v75
	v_cvt_pk_bf16_f32 v70, v76, v77
	v_cvt_pk_bf16_f32 v71, v78, v79
	s_lshl_b32 s99, s98, 11
	v_lshl_add_u32 v8, v0, 3, s99
	global_store_dwordx2 v8, v[64:65], s[94:95]
	global_store_dwordx2 v8, v[66:67], s[94:95] offset:512
	global_store_dwordx2 v8, v[68:69], s[94:95] offset:1024
	global_store_dwordx2 v8, v[70:71], s[94:95] offset:1536
	s_lshl_b32 s99, s98, 2
	v_mov_b32_e32 v9, s99
	v_mov_b32_e32 v10, 0
	v_cmp_eq_u32_e32 vcc, 0, v0
	s_and_saveexec_b64 s[98:99], vcc
	global_store_dword v9, v10, s[90:91]
	global_store_dword v9, v10, s[92:93]
	s_or_b64 exec, exec, s[98:99]
	s_add_u32 s98, s97, 15
	s_lshl_b32 s98, s98, 12
	v_add_u32_e32 v3, s98, v1
	global_load_dwordx4 v[64:67], v3, s[88:89] nt
	global_load_dwordx4 v[68:71], v3, s[88:89] offset:1024 nt
	global_load_dwordx4 v[72:75], v3, s[88:89] offset:2048 nt
	global_load_dwordx4 v[76:79], v3, s[88:89] offset:3072 nt
	s_waitcnt vmcnt(50)
	v_mul_f32_e32 v4, v80, v80
	v_fma_f32 v4, v81, v81, v4
	v_fma_f32 v4, v82, v82, v4
	v_fma_f32 v4, v83, v83, v4
	v_fma_f32 v4, v84, v84, v4
	v_fma_f32 v4, v85, v85, v4
	v_fma_f32 v4, v86, v86, v4
	v_fma_f32 v4, v87, v87, v4
	v_fma_f32 v4, v88, v88, v4
	v_fma_f32 v4, v89, v89, v4
	v_fma_f32 v4, v90, v90, v4
	v_fma_f32 v4, v91, v91, v4
	v_fma_f32 v4, v92, v92, v4
	v_fma_f32 v4, v93, v93, v4
	v_fma_f32 v4, v94, v94, v4
	v_fma_f32 v4, v95, v95, v4
	s_nop 1
	v_add_f32_dpp v5, v4, v4 quad_perm:[1,0,3,2] row_mask:0xf bank_mask:0xf
	s_nop 1
	v_add_f32_dpp v4, v5, v5 quad_perm:[2,3,0,1] row_mask:0xf bank_mask:0xf
	s_nop 1
	v_add_f32_dpp v5, v4, v4 row_half_mirror row_mask:0xf bank_mask:0xf
	s_nop 1
	v_add_f32_dpp v4, v5, v5 row_mirror row_mask:0xf bank_mask:0xf
	s_nop 1
	v_readlane_b32 s98, v4, 0
	v_readlane_b32 s99, v4, 16
	s_nop 3
	v_mov_b32_e32 v5, s98
	v_add_f32_e32 v5, s99, v5
	v_readlane_b32 s98, v4, 32
	v_readlane_b32 s99, v4, 48
	s_nop 3
	v_add_f32_e32 v5, s98, v5
	v_add_f32_e32 v5, s99, v5
	v_mul_f32_e32 v5, 0x3a800000, v5
	v_add_f32_e32 v5, 0x358637bd, v5
	v_rsq_f32_e32 v6, v5
	s_nop 0
	s_add_u32 s98, s97, 10
	v_pk_mul_f32 v[80:81], v[80:81], v[6:7] op_sel_hi:[1,0]
	v_pk_mul_f32 v[82:83], v[82:83], v[6:7] op_sel_hi:[1,0]
	v_pk_mul_f32 v[84:85], v[84:85], v[6:7] op_sel_hi:[1,0]
	v_pk_mul_f32 v[86:87], v[86:87], v[6:7] op_sel_hi:[1,0]
	v_pk_mul_f32 v[88:89], v[88:89], v[6:7] op_sel_hi:[1,0]
	v_pk_mul_f32 v[90:91], v[90:91], v[6:7] op_sel_hi:[1,0]
	v_pk_mul_f32 v[92:93], v[92:93], v[6:7] op_sel_hi:[1,0]
	v_pk_mul_f32 v[94:95], v[94:95], v[6:7] op_sel_hi:[1,0]
	v_pk_mul_f32 v[80:81], v[80:81], v[112:113]
	v_pk_mul_f32 v[82:83], v[82:83], v[114:115]
	v_pk_mul_f32 v[84:85], v[84:85], v[116:117]
	v_pk_mul_f32 v[86:87], v[86:87], v[118:119]
	v_pk_mul_f32 v[88:89], v[88:89], v[120:121]
	v_pk_mul_f32 v[90:91], v[90:91], v[122:123]
	v_pk_mul_f32 v[92:93], v[92:93], v[124:125]
	v_pk_mul_f32 v[94:95], v[94:95], v[126:127]
	v_pk_fma_f32 v[80:81], v[80:81], v[128:129], v[144:145]
	v_pk_fma_f32 v[82:83], v[82:83], v[130:131], v[146:147]
	v_pk_fma_f32 v[84:85], v[84:85], v[132:133], v[148:149]
	v_pk_fma_f32 v[86:87], v[86:87], v[134:135], v[150:151]
	v_pk_fma_f32 v[88:89], v[88:89], v[136:137], v[152:153]
	v_pk_fma_f32 v[90:91], v[90:91], v[138:139], v[154:155]
	v_pk_fma_f32 v[92:93], v[92:93], v[140:141], v[156:157]
	v_pk_fma_f32 v[94:95], v[94:95], v[142:143], v[158:159]
	v_cvt_pk_bf16_f32 v80, v80, v81
	v_cvt_pk_bf16_f32 v81, v82, v83
	v_cvt_pk_bf16_f32 v82, v84, v85
	v_cvt_pk_bf16_f32 v83, v86, v87
	v_cvt_pk_bf16_f32 v84, v88, v89
	v_cvt_pk_bf16_f32 v85, v90, v91
	v_cvt_pk_bf16_f32 v86, v92, v93
	v_cvt_pk_bf16_f32 v87, v94, v95
	s_lshl_b32 s99, s98, 11
	v_lshl_add_u32 v8, v0, 3, s99
	global_store_dwordx2 v8, v[80:81], s[94:95]
	global_store_dwordx2 v8, v[82:83], s[94:95] offset:512
	global_store_dwordx2 v8, v[84:85], s[94:95] offset:1024
	global_store_dwordx2 v8, v[86:87], s[94:95] offset:1536
	s_lshl_b32 s99, s98, 2
	v_mov_b32_e32 v9, s99
	v_mov_b32_e32 v10, 0
	v_cmp_eq_u32_e32 vcc, 0, v0
	s_and_saveexec_b64 s[98:99], vcc
	global_store_dword v9, v10, s[90:91]
	global_store_dword v9, v10, s[92:93]
	s_or_b64 exec, exec, s[98:99]
	s_waitcnt vmcnt(46)
	v_mul_f32_e32 v4, v96, v96
	v_fma_f32 v4, v97, v97, v4
	v_fma_f32 v4, v98, v98, v4
	v_fma_f32 v4, v99, v99, v4
	v_fma_f32 v4, v100, v100, v4
	v_fma_f32 v4, v101, v101, v4
	v_fma_f32 v4, v102, v102, v4
	v_fma_f32 v4, v103, v103, v4
	v_fma_f32 v4, v104, v104, v4
	v_fma_f32 v4, v105, v105, v4
	v_fma_f32 v4, v106, v106, v4
	v_fma_f32 v4, v107, v107, v4
	v_fma_f32 v4, v108, v108, v4
	v_fma_f32 v4, v109, v109, v4
	v_fma_f32 v4, v110, v110, v4
	v_fma_f32 v4, v111, v111, v4
	s_nop 1
	v_add_f32_dpp v5, v4, v4 quad_perm:[1,0,3,2] row_mask:0xf bank_mask:0xf
	s_nop 1
	v_add_f32_dpp v4, v5, v5 quad_perm:[2,3,0,1] row_mask:0xf bank_mask:0xf
	s_nop 1
	v_add_f32_dpp v5, v4, v4 row_half_mirror row_mask:0xf bank_mask:0xf
	s_nop 1
	v_add_f32_dpp v4, v5, v5 row_mirror row_mask:0xf bank_mask:0xf
	s_nop 1
	v_readlane_b32 s98, v4, 0
	v_readlane_b32 s99, v4, 16
	s_nop 3
	v_mov_b32_e32 v5, s98
	v_add_f32_e32 v5, s99, v5
	v_readlane_b32 s98, v4, 32
	v_readlane_b32 s99, v4, 48
	s_nop 3
	v_add_f32_e32 v5, s98, v5
	v_add_f32_e32 v5, s99, v5
	v_mul_f32_e32 v5, 0x3a800000, v5
	v_add_f32_e32 v5, 0x358637bd, v5
	v_rsq_f32_e32 v6, v5
	s_nop 0
	s_add_u32 s98, s97, 11
	v_pk_mul_f32 v[96:97], v[96:97], v[6:7] op_sel_hi:[1,0]
	v_pk_mul_f32 v[98:99], v[98:99], v[6:7] op_sel_hi:[1,0]
	v_pk_mul_f32 v[100:101], v[100:101], v[6:7] op_sel_hi:[1,0]
	v_pk_mul_f32 v[102:103], v[102:103], v[6:7] op_sel_hi:[1,0]
	v_pk_mul_f32 v[104:105], v[104:105], v[6:7] op_sel_hi:[1,0]
	v_pk_mul_f32 v[106:107], v[106:107], v[6:7] op_sel_hi:[1,0]
	v_pk_mul_f32 v[108:109], v[108:109], v[6:7] op_sel_hi:[1,0]
	v_pk_mul_f32 v[110:111], v[110:111], v[6:7] op_sel_hi:[1,0]
	v_pk_mul_f32 v[96:97], v[96:97], v[112:113]
	v_pk_mul_f32 v[98:99], v[98:99], v[114:115]
	v_pk_mul_f32 v[100:101], v[100:101], v[116:117]
	v_pk_mul_f32 v[102:103], v[102:103], v[118:119]
	v_pk_mul_f32 v[104:105], v[104:105], v[120:121]
	v_pk_mul_f32 v[106:107], v[106:107], v[122:123]
	v_pk_mul_f32 v[108:109], v[108:109], v[124:125]
	v_pk_mul_f32 v[110:111], v[110:111], v[126:127]
	v_pk_fma_f32 v[96:97], v[96:97], v[128:129], v[144:145]
	v_pk_fma_f32 v[98:99], v[98:99], v[130:131], v[146:147]
	v_pk_fma_f32 v[100:101], v[100:101], v[132:133], v[148:149]
	v_pk_fma_f32 v[102:103], v[102:103], v[134:135], v[150:151]
	v_pk_fma_f32 v[104:105], v[104:105], v[136:137], v[152:153]
	v_pk_fma_f32 v[106:107], v[106:107], v[138:139], v[154:155]
	v_pk_fma_f32 v[108:109], v[108:109], v[140:141], v[156:157]
	v_pk_fma_f32 v[110:111], v[110:111], v[142:143], v[158:159]
	v_cvt_pk_bf16_f32 v96, v96, v97
	v_cvt_pk_bf16_f32 v97, v98, v99
	v_cvt_pk_bf16_f32 v98, v100, v101
	v_cvt_pk_bf16_f32 v99, v102, v103
	v_cvt_pk_bf16_f32 v100, v104, v105
	v_cvt_pk_bf16_f32 v101, v106, v107
	v_cvt_pk_bf16_f32 v102, v108, v109
	v_cvt_pk_bf16_f32 v103, v110, v111
	s_lshl_b32 s99, s98, 11
	v_lshl_add_u32 v8, v0, 3, s99
	global_store_dwordx2 v8, v[96:97], s[94:95]
	global_store_dwordx2 v8, v[98:99], s[94:95] offset:512
	global_store_dwordx2 v8, v[100:101], s[94:95] offset:1024
	global_store_dwordx2 v8, v[102:103], s[94:95] offset:1536
	s_lshl_b32 s99, s98, 2
	v_mov_b32_e32 v9, s99
	v_mov_b32_e32 v10, 0
	v_cmp_eq_u32_e32 vcc, 0, v0
	s_and_saveexec_b64 s[98:99], vcc
	global_store_dword v9, v10, s[90:91]
	global_store_dword v9, v10, s[92:93]
	s_or_b64 exec, exec, s[98:99]
	s_waitcnt vmcnt(42)
	v_mul_f32_e32 v4, v16, v16
	v_fma_f32 v4, v17, v17, v4
	v_fma_f32 v4, v18, v18, v4
	v_fma_f32 v4, v19, v19, v4
	v_fma_f32 v4, v20, v20, v4
	v_fma_f32 v4, v21, v21, v4
	v_fma_f32 v4, v22, v22, v4
	v_fma_f32 v4, v23, v23, v4
	v_fma_f32 v4, v24, v24, v4
	v_fma_f32 v4, v25, v25, v4
	v_fma_f32 v4, v26, v26, v4
	v_fma_f32 v4, v27, v27, v4
	v_fma_f32 v4, v28, v28, v4
	v_fma_f32 v4, v29, v29, v4
	v_fma_f32 v4, v30, v30, v4
	v_fma_f32 v4, v31, v31, v4
	s_nop 1
	v_add_f32_dpp v5, v4, v4 quad_perm:[1,0,3,2] row_mask:0xf bank_mask:0xf
	s_nop 1
	v_add_f32_dpp v4, v5, v5 quad_perm:[2,3,0,1] row_mask:0xf bank_mask:0xf
	s_nop 1
	v_add_f32_dpp v5, v4, v4 row_half_mirror row_mask:0xf bank_mask:0xf
	s_nop 1
	v_add_f32_dpp v4, v5, v5 row_mirror row_mask:0xf bank_mask:0xf
	s_nop 1
	v_readlane_b32 s98, v4, 0
	v_readlane_b32 s99, v4, 16
	s_nop 3
	v_mov_b32_e32 v5, s98
	v_add_f32_e32 v5, s99, v5
	v_readlane_b32 s98, v4, 32
	v_readlane_b32 s99, v4, 48
	s_nop 3
	v_add_f32_e32 v5, s98, v5
	v_add_f32_e32 v5, s99, v5
	v_mul_f32_e32 v5, 0x3a800000, v5
	v_add_f32_e32 v5, 0x358637bd, v5
	v_rsq_f32_e32 v6, v5
	s_nop 0
	s_add_u32 s98, s97, 12
	v_pk_mul_f32 v[16:17], v[16:17], v[6:7] op_sel_hi:[1,0]
	v_pk_mul_f32 v[18:19], v[18:19], v[6:7] op_sel_hi:[1,0]
	v_pk_mul_f32 v[20:21], v[20:21], v[6:7] op_sel_hi:[1,0]
	v_pk_mul_f32 v[22:23], v[22:23], v[6:7] op_sel_hi:[1,0]
	v_pk_mul_f32 v[24:25], v[24:25], v[6:7] op_sel_hi:[1,0]
	v_pk_mul_f32 v[26:27], v[26:27], v[6:7] op_sel_hi:[1,0]
	v_pk_mul_f32 v[28:29], v[28:29], v[6:7] op_sel_hi:[1,0]
	v_pk_mul_f32 v[30:31], v[30:31], v[6:7] op_sel_hi:[1,0]
	v_pk_mul_f32 v[16:17], v[16:17], v[112:113]
	v_pk_mul_f32 v[18:19], v[18:19], v[114:115]
	v_pk_mul_f32 v[20:21], v[20:21], v[116:117]
	v_pk_mul_f32 v[22:23], v[22:23], v[118:119]
	v_pk_mul_f32 v[24:25], v[24:25], v[120:121]
	v_pk_mul_f32 v[26:27], v[26:27], v[122:123]
	v_pk_mul_f32 v[28:29], v[28:29], v[124:125]
	v_pk_mul_f32 v[30:31], v[30:31], v[126:127]
	v_pk_fma_f32 v[16:17], v[16:17], v[128:129], v[144:145]
	v_pk_fma_f32 v[18:19], v[18:19], v[130:131], v[146:147]
	v_pk_fma_f32 v[20:21], v[20:21], v[132:133], v[148:149]
	v_pk_fma_f32 v[22:23], v[22:23], v[134:135], v[150:151]
	v_pk_fma_f32 v[24:25], v[24:25], v[136:137], v[152:153]
	v_pk_fma_f32 v[26:27], v[26:27], v[138:139], v[154:155]
	v_pk_fma_f32 v[28:29], v[28:29], v[140:141], v[156:157]
	v_pk_fma_f32 v[30:31], v[30:31], v[142:143], v[158:159]
	v_cvt_pk_bf16_f32 v16, v16, v17
	v_cvt_pk_bf16_f32 v17, v18, v19
	v_cvt_pk_bf16_f32 v18, v20, v21
	v_cvt_pk_bf16_f32 v19, v22, v23
	v_cvt_pk_bf16_f32 v20, v24, v25
	v_cvt_pk_bf16_f32 v21, v26, v27
	v_cvt_pk_bf16_f32 v22, v28, v29
	v_cvt_pk_bf16_f32 v23, v30, v31
	s_lshl_b32 s99, s98, 11
	v_lshl_add_u32 v8, v0, 3, s99
	global_store_dwordx2 v8, v[16:17], s[94:95]
	global_store_dwordx2 v8, v[18:19], s[94:95] offset:512
	global_store_dwordx2 v8, v[20:21], s[94:95] offset:1024
	global_store_dwordx2 v8, v[22:23], s[94:95] offset:1536
	s_lshl_b32 s99, s98, 2
	v_mov_b32_e32 v9, s99
	v_mov_b32_e32 v10, 0
	v_cmp_eq_u32_e32 vcc, 0, v0
	s_and_saveexec_b64 s[98:99], vcc
	global_store_dword v9, v10, s[90:91]
	global_store_dword v9, v10, s[92:93]
	s_or_b64 exec, exec, s[98:99]
	s_waitcnt vmcnt(38)
	v_mul_f32_e32 v4, v32, v32
	v_fma_f32 v4, v33, v33, v4
	v_fma_f32 v4, v34, v34, v4
	v_fma_f32 v4, v35, v35, v4
	v_fma_f32 v4, v36, v36, v4
	v_fma_f32 v4, v37, v37, v4
	v_fma_f32 v4, v38, v38, v4
	v_fma_f32 v4, v39, v39, v4
	v_fma_f32 v4, v40, v40, v4
	v_fma_f32 v4, v41, v41, v4
	v_fma_f32 v4, v42, v42, v4
	v_fma_f32 v4, v43, v43, v4
	v_fma_f32 v4, v44, v44, v4
	v_fma_f32 v4, v45, v45, v4
	v_fma_f32 v4, v46, v46, v4
	v_fma_f32 v4, v47, v47, v4
	s_nop 1
	v_add_f32_dpp v5, v4, v4 quad_perm:[1,0,3,2] row_mask:0xf bank_mask:0xf
	s_nop 1
	v_add_f32_dpp v4, v5, v5 quad_perm:[2,3,0,1] row_mask:0xf bank_mask:0xf
	s_nop 1
	v_add_f32_dpp v5, v4, v4 row_half_mirror row_mask:0xf bank_mask:0xf
	s_nop 1
	v_add_f32_dpp v4, v5, v5 row_mirror row_mask:0xf bank_mask:0xf
	s_nop 1
	v_readlane_b32 s98, v4, 0
	v_readlane_b32 s99, v4, 16
	s_nop 3
	v_mov_b32_e32 v5, s98
	v_add_f32_e32 v5, s99, v5
	v_readlane_b32 s98, v4, 32
	v_readlane_b32 s99, v4, 48
	s_nop 3
	v_add_f32_e32 v5, s98, v5
	v_add_f32_e32 v5, s99, v5
	v_mul_f32_e32 v5, 0x3a800000, v5
	v_add_f32_e32 v5, 0x358637bd, v5
	v_rsq_f32_e32 v6, v5
	s_nop 0
	s_add_u32 s98, s97, 13
	v_pk_mul_f32 v[32:33], v[32:33], v[6:7] op_sel_hi:[1,0]
	v_pk_mul_f32 v[34:35], v[34:35], v[6:7] op_sel_hi:[1,0]
	v_pk_mul_f32 v[36:37], v[36:37], v[6:7] op_sel_hi:[1,0]
	v_pk_mul_f32 v[38:39], v[38:39], v[6:7] op_sel_hi:[1,0]
	v_pk_mul_f32 v[40:41], v[40:41], v[6:7] op_sel_hi:[1,0]
	v_pk_mul_f32 v[42:43], v[42:43], v[6:7] op_sel_hi:[1,0]
	v_pk_mul_f32 v[44:45], v[44:45], v[6:7] op_sel_hi:[1,0]
	v_pk_mul_f32 v[46:47], v[46:47], v[6:7] op_sel_hi:[1,0]
	v_pk_mul_f32 v[32:33], v[32:33], v[112:113]
	v_pk_mul_f32 v[34:35], v[34:35], v[114:115]
	v_pk_mul_f32 v[36:37], v[36:37], v[116:117]
	v_pk_mul_f32 v[38:39], v[38:39], v[118:119]
	v_pk_mul_f32 v[40:41], v[40:41], v[120:121]
	v_pk_mul_f32 v[42:43], v[42:43], v[122:123]
	v_pk_mul_f32 v[44:45], v[44:45], v[124:125]
	v_pk_mul_f32 v[46:47], v[46:47], v[126:127]
	v_pk_fma_f32 v[32:33], v[32:33], v[128:129], v[144:145]
	v_pk_fma_f32 v[34:35], v[34:35], v[130:131], v[146:147]
	v_pk_fma_f32 v[36:37], v[36:37], v[132:133], v[148:149]
	v_pk_fma_f32 v[38:39], v[38:39], v[134:135], v[150:151]
	v_pk_fma_f32 v[40:41], v[40:41], v[136:137], v[152:153]
	v_pk_fma_f32 v[42:43], v[42:43], v[138:139], v[154:155]
	v_pk_fma_f32 v[44:45], v[44:45], v[140:141], v[156:157]
	v_pk_fma_f32 v[46:47], v[46:47], v[142:143], v[158:159]
	v_cvt_pk_bf16_f32 v32, v32, v33
	v_cvt_pk_bf16_f32 v33, v34, v35
	v_cvt_pk_bf16_f32 v34, v36, v37
	v_cvt_pk_bf16_f32 v35, v38, v39
	v_cvt_pk_bf16_f32 v36, v40, v41
	v_cvt_pk_bf16_f32 v37, v42, v43
	v_cvt_pk_bf16_f32 v38, v44, v45
	v_cvt_pk_bf16_f32 v39, v46, v47
	s_lshl_b32 s99, s98, 11
	v_lshl_add_u32 v8, v0, 3, s99
	global_store_dwordx2 v8, v[32:33], s[94:95]
	global_store_dwordx2 v8, v[34:35], s[94:95] offset:512
	global_store_dwordx2 v8, v[36:37], s[94:95] offset:1024
	global_store_dwordx2 v8, v[38:39], s[94:95] offset:1536
	s_lshl_b32 s99, s98, 2
	v_mov_b32_e32 v9, s99
	v_mov_b32_e32 v10, 0
	v_cmp_eq_u32_e32 vcc, 0, v0
	s_and_saveexec_b64 s[98:99], vcc
	global_store_dword v9, v10, s[90:91]
	global_store_dword v9, v10, s[92:93]
	s_or_b64 exec, exec, s[98:99]
	s_waitcnt vmcnt(34)
	v_mul_f32_e32 v4, v48, v48
	v_fma_f32 v4, v49, v49, v4
	v_fma_f32 v4, v50, v50, v4
	v_fma_f32 v4, v51, v51, v4
	v_fma_f32 v4, v52, v52, v4
	v_fma_f32 v4, v53, v53, v4
	v_fma_f32 v4, v54, v54, v4
	v_fma_f32 v4, v55, v55, v4
	v_fma_f32 v4, v56, v56, v4
	v_fma_f32 v4, v57, v57, v4
	v_fma_f32 v4, v58, v58, v4
	v_fma_f32 v4, v59, v59, v4
	v_fma_f32 v4, v60, v60, v4
	v_fma_f32 v4, v61, v61, v4
	v_fma_f32 v4, v62, v62, v4
	v_fma_f32 v4, v63, v63, v4
	s_nop 1
	v_add_f32_dpp v5, v4, v4 quad_perm:[1,0,3,2] row_mask:0xf bank_mask:0xf
	s_nop 1
	v_add_f32_dpp v4, v5, v5 quad_perm:[2,3,0,1] row_mask:0xf bank_mask:0xf
	s_nop 1
	v_add_f32_dpp v5, v4, v4 row_half_mirror row_mask:0xf bank_mask:0xf
	s_nop 1
	v_add_f32_dpp v4, v5, v5 row_mirror row_mask:0xf bank_mask:0xf
	s_nop 1
	v_readlane_b32 s98, v4, 0
	v_readlane_b32 s99, v4, 16
	s_nop 3
	v_mov_b32_e32 v5, s98
	v_add_f32_e32 v5, s99, v5
	v_readlane_b32 s98, v4, 32
	v_readlane_b32 s99, v4, 48
	s_nop 3
	v_add_f32_e32 v5, s98, v5
	v_add_f32_e32 v5, s99, v5
	v_mul_f32_e32 v5, 0x3a800000, v5
	v_add_f32_e32 v5, 0x358637bd, v5
	v_rsq_f32_e32 v6, v5
	s_nop 0
	s_add_u32 s98, s97, 14
	v_pk_mul_f32 v[48:49], v[48:49], v[6:7] op_sel_hi:[1,0]
	v_pk_mul_f32 v[50:51], v[50:51], v[6:7] op_sel_hi:[1,0]
	v_pk_mul_f32 v[52:53], v[52:53], v[6:7] op_sel_hi:[1,0]
	v_pk_mul_f32 v[54:55], v[54:55], v[6:7] op_sel_hi:[1,0]
	v_pk_mul_f32 v[56:57], v[56:57], v[6:7] op_sel_hi:[1,0]
	v_pk_mul_f32 v[58:59], v[58:59], v[6:7] op_sel_hi:[1,0]
	v_pk_mul_f32 v[60:61], v[60:61], v[6:7] op_sel_hi:[1,0]
	v_pk_mul_f32 v[62:63], v[62:63], v[6:7] op_sel_hi:[1,0]
	v_pk_mul_f32 v[48:49], v[48:49], v[112:113]
	v_pk_mul_f32 v[50:51], v[50:51], v[114:115]
	v_pk_mul_f32 v[52:53], v[52:53], v[116:117]
	v_pk_mul_f32 v[54:55], v[54:55], v[118:119]
	v_pk_mul_f32 v[56:57], v[56:57], v[120:121]
	v_pk_mul_f32 v[58:59], v[58:59], v[122:123]
	v_pk_mul_f32 v[60:61], v[60:61], v[124:125]
	v_pk_mul_f32 v[62:63], v[62:63], v[126:127]
	v_pk_fma_f32 v[48:49], v[48:49], v[128:129], v[144:145]
	v_pk_fma_f32 v[50:51], v[50:51], v[130:131], v[146:147]
	v_pk_fma_f32 v[52:53], v[52:53], v[132:133], v[148:149]
	v_pk_fma_f32 v[54:55], v[54:55], v[134:135], v[150:151]
	v_pk_fma_f32 v[56:57], v[56:57], v[136:137], v[152:153]
	v_pk_fma_f32 v[58:59], v[58:59], v[138:139], v[154:155]
	v_pk_fma_f32 v[60:61], v[60:61], v[140:141], v[156:157]
	v_pk_fma_f32 v[62:63], v[62:63], v[142:143], v[158:159]
	v_cvt_pk_bf16_f32 v48, v48, v49
	v_cvt_pk_bf16_f32 v49, v50, v51
	v_cvt_pk_bf16_f32 v50, v52, v53
	v_cvt_pk_bf16_f32 v51, v54, v55
	v_cvt_pk_bf16_f32 v52, v56, v57
	v_cvt_pk_bf16_f32 v53, v58, v59
	v_cvt_pk_bf16_f32 v54, v60, v61
	v_cvt_pk_bf16_f32 v55, v62, v63
	s_lshl_b32 s99, s98, 11
	v_lshl_add_u32 v8, v0, 3, s99
	global_store_dwordx2 v8, v[48:49], s[94:95]
	global_store_dwordx2 v8, v[50:51], s[94:95] offset:512
	global_store_dwordx2 v8, v[52:53], s[94:95] offset:1024
	global_store_dwordx2 v8, v[54:55], s[94:95] offset:1536
	s_lshl_b32 s99, s98, 2
	v_mov_b32_e32 v9, s99
	v_mov_b32_e32 v10, 0
	v_cmp_eq_u32_e32 vcc, 0, v0
	s_and_saveexec_b64 s[98:99], vcc
	global_store_dword v9, v10, s[90:91]
	global_store_dword v9, v10, s[92:93]
	s_or_b64 exec, exec, s[98:99]
	s_waitcnt vmcnt(30)
	v_mul_f32_e32 v4, v64, v64
	v_fma_f32 v4, v65, v65, v4
	v_fma_f32 v4, v66, v66, v4
	v_fma_f32 v4, v67, v67, v4
	v_fma_f32 v4, v68, v68, v4
	v_fma_f32 v4, v69, v69, v4
	v_fma_f32 v4, v70, v70, v4
	v_fma_f32 v4, v71, v71, v4
	v_fma_f32 v4, v72, v72, v4
	v_fma_f32 v4, v73, v73, v4
	v_fma_f32 v4, v74, v74, v4
	v_fma_f32 v4, v75, v75, v4
	v_fma_f32 v4, v76, v76, v4
	v_fma_f32 v4, v77, v77, v4
	v_fma_f32 v4, v78, v78, v4
	v_fma_f32 v4, v79, v79, v4
	s_nop 1
	v_add_f32_dpp v5, v4, v4 quad_perm:[1,0,3,2] row_mask:0xf bank_mask:0xf
	s_nop 1
	v_add_f32_dpp v4, v5, v5 quad_perm:[2,3,0,1] row_mask:0xf bank_mask:0xf
	s_nop 1
	v_add_f32_dpp v5, v4, v4 row_half_mirror row_mask:0xf bank_mask:0xf
	s_nop 1
	v_add_f32_dpp v4, v5, v5 row_mirror row_mask:0xf bank_mask:0xf
	s_nop 1
	v_readlane_b32 s98, v4, 0
	v_readlane_b32 s99, v4, 16
	s_nop 3
	v_mov_b32_e32 v5, s98
	v_add_f32_e32 v5, s99, v5
	v_readlane_b32 s98, v4, 32
	v_readlane_b32 s99, v4, 48
	s_nop 3
	v_add_f32_e32 v5, s98, v5
	v_add_f32_e32 v5, s99, v5
	v_mul_f32_e32 v5, 0x3a800000, v5
	v_add_f32_e32 v5, 0x358637bd, v5
	v_rsq_f32_e32 v6, v5
	s_nop 0
	s_add_u32 s98, s97, 15
	v_pk_mul_f32 v[64:65], v[64:65], v[6:7] op_sel_hi:[1,0]
	v_pk_mul_f32 v[66:67], v[66:67], v[6:7] op_sel_hi:[1,0]
	v_pk_mul_f32 v[68:69], v[68:69], v[6:7] op_sel_hi:[1,0]
	v_pk_mul_f32 v[70:71], v[70:71], v[6:7] op_sel_hi:[1,0]
	v_pk_mul_f32 v[72:73], v[72:73], v[6:7] op_sel_hi:[1,0]
	v_pk_mul_f32 v[74:75], v[74:75], v[6:7] op_sel_hi:[1,0]
	v_pk_mul_f32 v[76:77], v[76:77], v[6:7] op_sel_hi:[1,0]
	v_pk_mul_f32 v[78:79], v[78:79], v[6:7] op_sel_hi:[1,0]
	v_pk_mul_f32 v[64:65], v[64:65], v[112:113]
	v_pk_mul_f32 v[66:67], v[66:67], v[114:115]
	v_pk_mul_f32 v[68:69], v[68:69], v[116:117]
	v_pk_mul_f32 v[70:71], v[70:71], v[118:119]
	v_pk_mul_f32 v[72:73], v[72:73], v[120:121]
	v_pk_mul_f32 v[74:75], v[74:75], v[122:123]
	v_pk_mul_f32 v[76:77], v[76:77], v[124:125]
	v_pk_mul_f32 v[78:79], v[78:79], v[126:127]
	v_pk_fma_f32 v[64:65], v[64:65], v[128:129], v[144:145]
	v_pk_fma_f32 v[66:67], v[66:67], v[130:131], v[146:147]
	v_pk_fma_f32 v[68:69], v[68:69], v[132:133], v[148:149]
	v_pk_fma_f32 v[70:71], v[70:71], v[134:135], v[150:151]
	v_pk_fma_f32 v[72:73], v[72:73], v[136:137], v[152:153]
	v_pk_fma_f32 v[74:75], v[74:75], v[138:139], v[154:155]
	v_pk_fma_f32 v[76:77], v[76:77], v[140:141], v[156:157]
	v_pk_fma_f32 v[78:79], v[78:79], v[142:143], v[158:159]
	v_cvt_pk_bf16_f32 v64, v64, v65
	v_cvt_pk_bf16_f32 v65, v66, v67
	v_cvt_pk_bf16_f32 v66, v68, v69
	v_cvt_pk_bf16_f32 v67, v70, v71
	v_cvt_pk_bf16_f32 v68, v72, v73
	v_cvt_pk_bf16_f32 v69, v74, v75
	v_cvt_pk_bf16_f32 v70, v76, v77
	v_cvt_pk_bf16_f32 v71, v78, v79
	s_lshl_b32 s99, s98, 11
	v_lshl_add_u32 v8, v0, 3, s99
	global_store_dwordx2 v8, v[64:65], s[94:95]
	global_store_dwordx2 v8, v[66:67], s[94:95] offset:512
	global_store_dwordx2 v8, v[68:69], s[94:95] offset:1024
	global_store_dwordx2 v8, v[70:71], s[94:95] offset:1536
	s_lshl_b32 s99, s98, 2
	v_mov_b32_e32 v9, s99
	v_mov_b32_e32 v10, 0
	v_cmp_eq_u32_e32 vcc, 0, v0
	s_and_saveexec_b64 s[98:99], vcc
	global_store_dword v9, v10, s[90:91]
	global_store_dword v9, v10, s[92:93]
	s_or_b64 exec, exec, s[98:99]
	s_waitcnt vmcnt(0)

.LBB0_5762:
	s_cmp_gt_i32 s44, 22
	s_waitcnt lgkmcnt(0)
	s_cselect_b64 s[2:3], -1, 0
	s_cmp_lt_i32 s45, 23
	s_cselect_b64 s[4:5], -1, 0
	s_or_b64 s[2:3], s[2:3], s[4:5]
	s_and_b64 vcc, exec, s[2:3]
	s_cbranch_vccnz .LBB0_5820
	s_lshl_b32 s96, s22, 3
	s_lshr_b32 s97, s70, 6
	s_add_u32 s96, s96, s97
	s_lshl_b32 s97, s96, 4
	s_cmpk_ge_u32 s97, 0x8000
	s_cbranch_scc1 .Lnp22_done
	s_load_dwordx2 s[88:89], s[0:1], 0xb8
	s_load_dwordx2 s[90:91], s[0:1], 0xb0
	v_mbcnt_hi_u32_b32 v0, -1, v210
	v_lshlrev_b32_e32 v1, 4, v0
	s_waitcnt lgkmcnt(0)
	global_load_dwordx4 v[112:115], v1, s[90:91] nt
	global_load_dwordx4 v[116:119], v1, s[90:91] offset:1024 nt
	global_load_dwordx4 v[120:123], v1, s[90:91] offset:2048 nt
	global_load_dwordx4 v[124:127], v1, s[90:91] offset:3072 nt
	s_add_u32 s98, s97, 0
	s_lshl_b32 s98, s98, 12
	v_add_u32_e32 v3, s98, v1
	global_load_dwordx4 v[16:19], v3, s[88:89] nt
	global_load_dwordx4 v[20:23], v3, s[88:89] offset:1024 nt
	global_load_dwordx4 v[24:27], v3, s[88:89] offset:2048 nt
	global_load_dwordx4 v[28:31], v3, s[88:89] offset:3072 nt
	s_add_u32 s98, s97, 1
	s_lshl_b32 s98, s98, 12
	v_add_u32_e32 v3, s98, v1
	global_load_dwordx4 v[32:35], v3, s[88:89] nt
	global_load_dwordx4 v[36:39], v3, s[88:89] offset:1024 nt
	global_load_dwordx4 v[40:43], v3, s[88:89] offset:2048 nt
	global_load_dwordx4 v[44:47], v3, s[88:89] offset:3072 nt
	s_add_u32 s98, s97, 2
	s_lshl_b32 s98, s98, 12
	v_add_u32_e32 v3, s98, v1
	global_load_dwordx4 v[48:51], v3, s[88:89] nt
	global_load_dwordx4 v[52:55], v3, s[88:89] offset:1024 nt
	global_load_dwordx4 v[56:59], v3, s[88:89] offset:2048 nt
	global_load_dwordx4 v[60:63], v3, s[88:89] offset:3072 nt
	s_add_u32 s98, s97, 3
	s_lshl_b32 s98, s98, 12
	v_add_u32_e32 v3, s98, v1
	global_load_dwordx4 v[64:67], v3, s[88:89] nt
	global_load_dwordx4 v[68:71], v3, s[88:89] offset:1024 nt
	global_load_dwordx4 v[72:75], v3, s[88:89] offset:2048 nt
	global_load_dwordx4 v[76:79], v3, s[88:89] offset:3072 nt
	s_add_u32 s98, s97, 4
	s_lshl_b32 s98, s98, 12
	v_add_u32_e32 v3, s98, v1
	global_load_dwordx4 v[80:83], v3, s[88:89] nt
	global_load_dwordx4 v[84:87], v3, s[88:89] offset:1024 nt
	global_load_dwordx4 v[88:91], v3, s[88:89] offset:2048 nt
	global_load_dwordx4 v[92:95], v3, s[88:89] offset:3072 nt
	s_waitcnt vmcnt(0) lgkmcnt(0)
	s_add_u32 s98, s97, 5
	s_lshl_b32 s98, s98, 12
	v_add_u32_e32 v3, s98, v1
	global_load_dwordx4 v[96:99], v3, s[88:89] nt
	global_load_dwordx4 v[100:103], v3, s[88:89] offset:1024 nt
	global_load_dwordx4 v[104:107], v3, s[88:89] offset:2048 nt
	global_load_dwordx4 v[108:111], v3, s[88:89] offset:3072 nt
	s_waitcnt vmcnt(20)
	v_mul_f32_e32 v4, v16, v16
	v_fma_f32 v4, v17, v17, v4
	v_fma_f32 v4, v18, v18, v4
	v_fma_f32 v4, v19, v19, v4
	v_fma_f32 v4, v20, v20, v4
	v_fma_f32 v4, v21, v21, v4
	v_fma_f32 v4, v22, v22, v4
	v_fma_f32 v4, v23, v23, v4
	v_fma_f32 v4, v24, v24, v4
	v_fma_f32 v4, v25, v25, v4
	v_fma_f32 v4, v26, v26, v4
	v_fma_f32 v4, v27, v27, v4
	v_fma_f32 v4, v28, v28, v4
	v_fma_f32 v4, v29, v29, v4
	v_fma_f32 v4, v30, v30, v4
	v_fma_f32 v4, v31, v31, v4
	s_nop 1
	v_add_f32_dpp v5, v4, v4 quad_perm:[1,0,3,2] row_mask:0xf bank_mask:0xf
	s_nop 1
	v_add_f32_dpp v4, v5, v5 quad_perm:[2,3,0,1] row_mask:0xf bank_mask:0xf
	s_nop 1
	v_add_f32_dpp v5, v4, v4 row_half_mirror row_mask:0xf bank_mask:0xf
	s_nop 1
	v_add_f32_dpp v4, v5, v5 row_mirror row_mask:0xf bank_mask:0xf
	s_nop 1
	v_readlane_b32 s98, v4, 0
	v_readlane_b32 s99, v4, 16
	s_nop 3
	v_mov_b32_e32 v5, s98
	v_add_f32_e32 v5, s99, v5
	v_readlane_b32 s98, v4, 32
	v_readlane_b32 s99, v4, 48
	s_nop 3
	v_add_f32_e32 v5, s98, v5
	v_add_f32_e32 v5, s99, v5
	v_mul_f32_e32 v5, 0x3a800000, v5
	v_add_f32_e32 v5, 0x358637bd, v5
	v_rsq_f32_e32 v6, v5
	s_nop 0
	s_add_u32 s98, s97, 0
	v_pk_mul_f32 v[16:17], v[16:17], v[6:7] op_sel_hi:[1,0]
	v_pk_mul_f32 v[18:19], v[18:19], v[6:7] op_sel_hi:[1,0]
	v_pk_mul_f32 v[20:21], v[20:21], v[6:7] op_sel_hi:[1,0]
	v_pk_mul_f32 v[22:23], v[22:23], v[6:7] op_sel_hi:[1,0]
	v_pk_mul_f32 v[24:25], v[24:25], v[6:7] op_sel_hi:[1,0]
	v_pk_mul_f32 v[26:27], v[26:27], v[6:7] op_sel_hi:[1,0]
	v_pk_mul_f32 v[28:29], v[28:29], v[6:7] op_sel_hi:[1,0]
	v_pk_mul_f32 v[30:31], v[30:31], v[6:7] op_sel_hi:[1,0]
	v_pk_mul_f32 v[16:17], v[16:17], v[112:113]
	v_pk_mul_f32 v[18:19], v[18:19], v[114:115]
	v_pk_mul_f32 v[20:21], v[20:21], v[116:117]
	v_pk_mul_f32 v[22:23], v[22:23], v[118:119]
	v_pk_mul_f32 v[24:25], v[24:25], v[120:121]
	v_pk_mul_f32 v[26:27], v[26:27], v[122:123]
	v_pk_mul_f32 v[28:29], v[28:29], v[124:125]
	v_pk_mul_f32 v[30:31], v[30:31], v[126:127]
	s_lshl_b32 s99, s98, 12
	v_add_u32_e32 v8, s99, v1
	global_store_dwordx4 v8, v[16:19], s[88:89] nt
	global_store_dwordx4 v8, v[20:23], s[88:89] offset:1024 nt
	global_store_dwordx4 v8, v[24:27], s[88:89] offset:2048 nt
	global_store_dwordx4 v8, v[28:31], s[88:89] offset:3072 nt
	s_add_u32 s98, s97, 6
	s_lshl_b32 s98, s98, 12
	v_add_u32_e32 v3, s98, v1
	global_load_dwordx4 v[16:19], v3, s[88:89] nt
	global_load_dwordx4 v[20:23], v3, s[88:89] offset:1024 nt
	global_load_dwordx4 v[24:27], v3, s[88:89] offset:2048 nt
	global_load_dwordx4 v[28:31], v3, s[88:89] offset:3072 nt
	s_waitcnt vmcnt(24)
	v_mul_f32_e32 v4, v32, v32
	v_fma_f32 v4, v33, v33, v4
	v_fma_f32 v4, v34, v34, v4
	v_fma_f32 v4, v35, v35, v4
	v_fma_f32 v4, v36, v36, v4
	v_fma_f32 v4, v37, v37, v4
	v_fma_f32 v4, v38, v38, v4
	v_fma_f32 v4, v39, v39, v4
	v_fma_f32 v4, v40, v40, v4
	v_fma_f32 v4, v41, v41, v4
	v_fma_f32 v4, v42, v42, v4
	v_fma_f32 v4, v43, v43, v4
	v_fma_f32 v4, v44, v44, v4
	v_fma_f32 v4, v45, v45, v4
	v_fma_f32 v4, v46, v46, v4
	v_fma_f32 v4, v47, v47, v4
	s_nop 1
	v_add_f32_dpp v5, v4, v4 quad_perm:[1,0,3,2] row_mask:0xf bank_mask:0xf
	s_nop 1
	v_add_f32_dpp v4, v5, v5 quad_perm:[2,3,0,1] row_mask:0xf bank_mask:0xf
	s_nop 1
	v_add_f32_dpp v5, v4, v4 row_half_mirror row_mask:0xf bank_mask:0xf
	s_nop 1
	v_add_f32_dpp v4, v5, v5 row_mirror row_mask:0xf bank_mask:0xf
	s_nop 1
	v_readlane_b32 s98, v4, 0
	v_readlane_b32 s99, v4, 16
	s_nop 3
	v_mov_b32_e32 v5, s98
	v_add_f32_e32 v5, s99, v5
	v_readlane_b32 s98, v4, 32
	v_readlane_b32 s99, v4, 48
	s_nop 3
	v_add_f32_e32 v5, s98, v5
	v_add_f32_e32 v5, s99, v5
	v_mul_f32_e32 v5, 0x3a800000, v5
	v_add_f32_e32 v5, 0x358637bd, v5
	v_rsq_f32_e32 v6, v5
	s_nop 0
	s_add_u32 s98, s97, 1
	v_pk_mul_f32 v[32:33], v[32:33], v[6:7] op_sel_hi:[1,0]
	v_pk_mul_f32 v[34:35], v[34:35], v[6:7] op_sel_hi:[1,0]
	v_pk_mul_f32 v[36:37], v[36:37], v[6:7] op_sel_hi:[1,0]
	v_pk_mul_f32 v[38:39], v[38:39], v[6:7] op_sel_hi:[1,0]
	v_pk_mul_f32 v[40:41], v[40:41], v[6:7] op_sel_hi:[1,0]
	v_pk_mul_f32 v[42:43], v[42:43], v[6:7] op_sel_hi:[1,0]
	v_pk_mul_f32 v[44:45], v[44:45], v[6:7] op_sel_hi:[1,0]
	v_pk_mul_f32 v[46:47], v[46:47], v[6:7] op_sel_hi:[1,0]
	v_pk_mul_f32 v[32:33], v[32:33], v[112:113]
	v_pk_mul_f32 v[34:35], v[34:35], v[114:115]
	v_pk_mul_f32 v[36:37], v[36:37], v[116:117]
	v_pk_mul_f32 v[38:39], v[38:39], v[118:119]
	v_pk_mul_f32 v[40:41], v[40:41], v[120:121]
	v_pk_mul_f32 v[42:43], v[42:43], v[122:123]
	v_pk_mul_f32 v[44:45], v[44:45], v[124:125]
	v_pk_mul_f32 v[46:47], v[46:47], v[126:127]
	s_lshl_b32 s99, s98, 12
	v_add_u32_e32 v8, s99, v1
	global_store_dwordx4 v8, v[32:35], s[88:89] nt
	global_store_dwordx4 v8, v[36:39], s[88:89] offset:1024 nt
	global_store_dwordx4 v8, v[40:43], s[88:89] offset:2048 nt
	global_store_dwordx4 v8, v[44:47], s[88:89] offset:3072 nt
	s_add_u32 s98, s97, 7
	s_lshl_b32 s98, s98, 12
	v_add_u32_e32 v3, s98, v1
	global_load_dwordx4 v[32:35], v3, s[88:89] nt
	global_load_dwordx4 v[36:39], v3, s[88:89] offset:1024 nt
	global_load_dwordx4 v[40:43], v3, s[88:89] offset:2048 nt
	global_load_dwordx4 v[44:47], v3, s[88:89] offset:3072 nt
	s_waitcnt vmcnt(28)
	v_mul_f32_e32 v4, v48, v48
	v_fma_f32 v4, v49, v49, v4
	v_fma_f32 v4, v50, v50, v4
	v_fma_f32 v4, v51, v51, v4
	v_fma_f32 v4, v52, v52, v4
	v_fma_f32 v4, v53, v53, v4
	v_fma_f32 v4, v54, v54, v4
	v_fma_f32 v4, v55, v55, v4
	v_fma_f32 v4, v56, v56, v4
	v_fma_f32 v4, v57, v57, v4
	v_fma_f32 v4, v58, v58, v4
	v_fma_f32 v4, v59, v59, v4
	v_fma_f32 v4, v60, v60, v4
	v_fma_f32 v4, v61, v61, v4
	v_fma_f32 v4, v62, v62, v4
	v_fma_f32 v4, v63, v63, v4
	s_nop 1
	v_add_f32_dpp v5, v4, v4 quad_perm:[1,0,3,2] row_mask:0xf bank_mask:0xf
	s_nop 1
	v_add_f32_dpp v4, v5, v5 quad_perm:[2,3,0,1] row_mask:0xf bank_mask:0xf
	s_nop 1
	v_add_f32_dpp v5, v4, v4 row_half_mirror row_mask:0xf bank_mask:0xf
	s_nop 1
	v_add_f32_dpp v4, v5, v5 row_mirror row_mask:0xf bank_mask:0xf
	s_nop 1
	v_readlane_b32 s98, v4, 0
	v_readlane_b32 s99, v4, 16
	s_nop 3
	v_mov_b32_e32 v5, s98
	v_add_f32_e32 v5, s99, v5
	v_readlane_b32 s98, v4, 32
	v_readlane_b32 s99, v4, 48
	s_nop 3
	v_add_f32_e32 v5, s98, v5
	v_add_f32_e32 v5, s99, v5
	v_mul_f32_e32 v5, 0x3a800000, v5
	v_add_f32_e32 v5, 0x358637bd, v5
	v_rsq_f32_e32 v6, v5
	s_nop 0
	s_add_u32 s98, s97, 2
	v_pk_mul_f32 v[48:49], v[48:49], v[6:7] op_sel_hi:[1,0]
	v_pk_mul_f32 v[50:51], v[50:51], v[6:7] op_sel_hi:[1,0]
	v_pk_mul_f32 v[52:53], v[52:53], v[6:7] op_sel_hi:[1,0]
	v_pk_mul_f32 v[54:55], v[54:55], v[6:7] op_sel_hi:[1,0]
	v_pk_mul_f32 v[56:57], v[56:57], v[6:7] op_sel_hi:[1,0]
	v_pk_mul_f32 v[58:59], v[58:59], v[6:7] op_sel_hi:[1,0]
	v_pk_mul_f32 v[60:61], v[60:61], v[6:7] op_sel_hi:[1,0]
	v_pk_mul_f32 v[62:63], v[62:63], v[6:7] op_sel_hi:[1,0]
	v_pk_mul_f32 v[48:49], v[48:49], v[112:113]
	v_pk_mul_f32 v[50:51], v[50:51], v[114:115]
	v_pk_mul_f32 v[52:53], v[52:53], v[116:117]
	v_pk_mul_f32 v[54:55], v[54:55], v[118:119]
	v_pk_mul_f32 v[56:57], v[56:57], v[120:121]
	v_pk_mul_f32 v[58:59], v[58:59], v[122:123]
	v_pk_mul_f32 v[60:61], v[60:61], v[124:125]
	v_pk_mul_f32 v[62:63], v[62:63], v[126:127]
	s_lshl_b32 s99, s98, 12
	v_add_u32_e32 v8, s99, v1
	global_store_dwordx4 v8, v[48:51], s[88:89] nt
	global_store_dwordx4 v8, v[52:55], s[88:89] offset:1024 nt
	global_store_dwordx4 v8, v[56:59], s[88:89] offset:2048 nt
	global_store_dwordx4 v8, v[60:63], s[88:89] offset:3072 nt
	s_add_u32 s98, s97, 8
	s_lshl_b32 s98, s98, 12
	v_add_u32_e32 v3, s98, v1
	global_load_dwordx4 v[48:51], v3, s[88:89] nt
	global_load_dwordx4 v[52:55], v3, s[88:89] offset:1024 nt
	global_load_dwordx4 v[56:59], v3, s[88:89] offset:2048 nt
	global_load_dwordx4 v[60:63], v3, s[88:89] offset:3072 nt
	s_waitcnt vmcnt(32)
	v_mul_f32_e32 v4, v64, v64
	v_fma_f32 v4, v65, v65, v4
	v_fma_f32 v4, v66, v66, v4
	v_fma_f32 v4, v67, v67, v4
	v_fma_f32 v4, v68, v68, v4
	v_fma_f32 v4, v69, v69, v4
	v_fma_f32 v4, v70, v70, v4
	v_fma_f32 v4, v71, v71, v4
	v_fma_f32 v4, v72, v72, v4
	v_fma_f32 v4, v73, v73, v4
	v_fma_f32 v4, v74, v74, v4
	v_fma_f32 v4, v75, v75, v4
	v_fma_f32 v4, v76, v76, v4
	v_fma_f32 v4, v77, v77, v4
	v_fma_f32 v4, v78, v78, v4
	v_fma_f32 v4, v79, v79, v4
	s_nop 1
	v_add_f32_dpp v5, v4, v4 quad_perm:[1,0,3,2] row_mask:0xf bank_mask:0xf
	s_nop 1
	v_add_f32_dpp v4, v5, v5 quad_perm:[2,3,0,1] row_mask:0xf bank_mask:0xf
	s_nop 1
	v_add_f32_dpp v5, v4, v4 row_half_mirror row_mask:0xf bank_mask:0xf
	s_nop 1
	v_add_f32_dpp v4, v5, v5 row_mirror row_mask:0xf bank_mask:0xf
	s_nop 1
	v_readlane_b32 s98, v4, 0
	v_readlane_b32 s99, v4, 16
	s_nop 3
	v_mov_b32_e32 v5, s98
	v_add_f32_e32 v5, s99, v5
	v_readlane_b32 s98, v4, 32
	v_readlane_b32 s99, v4, 48
	s_nop 3
	v_add_f32_e32 v5, s98, v5
	v_add_f32_e32 v5, s99, v5
	v_mul_f32_e32 v5, 0x3a800000, v5
	v_add_f32_e32 v5, 0x358637bd, v5
	v_rsq_f32_e32 v6, v5
	s_nop 0
	s_add_u32 s98, s97, 3
	v_pk_mul_f32 v[64:65], v[64:65], v[6:7] op_sel_hi:[1,0]
	v_pk_mul_f32 v[66:67], v[66:67], v[6:7] op_sel_hi:[1,0]
	v_pk_mul_f32 v[68:69], v[68:69], v[6:7] op_sel_hi:[1,0]
	v_pk_mul_f32 v[70:71], v[70:71], v[6:7] op_sel_hi:[1,0]
	v_pk_mul_f32 v[72:73], v[72:73], v[6:7] op_sel_hi:[1,0]
	v_pk_mul_f32 v[74:75], v[74:75], v[6:7] op_sel_hi:[1,0]
	v_pk_mul_f32 v[76:77], v[76:77], v[6:7] op_sel_hi:[1,0]
	v_pk_mul_f32 v[78:79], v[78:79], v[6:7] op_sel_hi:[1,0]
	v_pk_mul_f32 v[64:65], v[64:65], v[112:113]
	v_pk_mul_f32 v[66:67], v[66:67], v[114:115]
	v_pk_mul_f32 v[68:69], v[68:69], v[116:117]
	v_pk_mul_f32 v[70:71], v[70:71], v[118:119]
	v_pk_mul_f32 v[72:73], v[72:73], v[120:121]
	v_pk_mul_f32 v[74:75], v[74:75], v[122:123]
	v_pk_mul_f32 v[76:77], v[76:77], v[124:125]
	v_pk_mul_f32 v[78:79], v[78:79], v[126:127]
	s_lshl_b32 s99, s98, 12
	v_add_u32_e32 v8, s99, v1
	global_store_dwordx4 v8, v[64:67], s[88:89] nt
	global_store_dwordx4 v8, v[68:71], s[88:89] offset:1024 nt
	global_store_dwordx4 v8, v[72:75], s[88:89] offset:2048 nt
	global_store_dwordx4 v8, v[76:79], s[88:89] offset:3072 nt
	s_add_u32 s98, s97, 9
	s_lshl_b32 s98, s98, 12
	v_add_u32_e32 v3, s98, v1
	global_load_dwordx4 v[64:67], v3, s[88:89] nt
	global_load_dwordx4 v[68:71], v3, s[88:89] offset:1024 nt
	global_load_dwordx4 v[72:75], v3, s[88:89] offset:2048 nt
	global_load_dwordx4 v[76:79], v3, s[88:89] offset:3072 nt
	s_waitcnt vmcnt(36)
	v_mul_f32_e32 v4, v80, v80
	v_fma_f32 v4, v81, v81, v4
	v_fma_f32 v4, v82, v82, v4
	v_fma_f32 v4, v83, v83, v4
	v_fma_f32 v4, v84, v84, v4
	v_fma_f32 v4, v85, v85, v4
	v_fma_f32 v4, v86, v86, v4
	v_fma_f32 v4, v87, v87, v4
	v_fma_f32 v4, v88, v88, v4
	v_fma_f32 v4, v89, v89, v4
	v_fma_f32 v4, v90, v90, v4
	v_fma_f32 v4, v91, v91, v4
	v_fma_f32 v4, v92, v92, v4
	v_fma_f32 v4, v93, v93, v4
	v_fma_f32 v4, v94, v94, v4
	v_fma_f32 v4, v95, v95, v4
	s_nop 1
	v_add_f32_dpp v5, v4, v4 quad_perm:[1,0,3,2] row_mask:0xf bank_mask:0xf
	s_nop 1
	v_add_f32_dpp v4, v5, v5 quad_perm:[2,3,0,1] row_mask:0xf bank_mask:0xf
	s_nop 1
	v_add_f32_dpp v5, v4, v4 row_half_mirror row_mask:0xf bank_mask:0xf
	s_nop 1
	v_add_f32_dpp v4, v5, v5 row_mirror row_mask:0xf bank_mask:0xf
	s_nop 1
	v_readlane_b32 s98, v4, 0
	v_readlane_b32 s99, v4, 16
	s_nop 3
	v_mov_b32_e32 v5, s98
	v_add_f32_e32 v5, s99, v5
	v_readlane_b32 s98, v4, 32
	v_readlane_b32 s99, v4, 48
	s_nop 3
	v_add_f32_e32 v5, s98, v5
	v_add_f32_e32 v5, s99, v5
	v_mul_f32_e32 v5, 0x3a800000, v5
	v_add_f32_e32 v5, 0x358637bd, v5
	v_rsq_f32_e32 v6, v5
	s_nop 0
	s_add_u32 s98, s97, 4
	v_pk_mul_f32 v[80:81], v[80:81], v[6:7] op_sel_hi:[1,0]
	v_pk_mul_f32 v[82:83], v[82:83], v[6:7] op_sel_hi:[1,0]
	v_pk_mul_f32 v[84:85], v[84:85], v[6:7] op_sel_hi:[1,0]
	v_pk_mul_f32 v[86:87], v[86:87], v[6:7] op_sel_hi:[1,0]
	v_pk_mul_f32 v[88:89], v[88:89], v[6:7] op_sel_hi:[1,0]
	v_pk_mul_f32 v[90:91], v[90:91], v[6:7] op_sel_hi:[1,0]
	v_pk_mul_f32 v[92:93], v[92:93], v[6:7] op_sel_hi:[1,0]
	v_pk_mul_f32 v[94:95], v[94:95], v[6:7] op_sel_hi:[1,0]
	v_pk_mul_f32 v[80:81], v[80:81], v[112:113]
	v_pk_mul_f32 v[82:83], v[82:83], v[114:115]
	v_pk_mul_f32 v[84:85], v[84:85], v[116:117]
	v_pk_mul_f32 v[86:87], v[86:87], v[118:119]
	v_pk_mul_f32 v[88:89], v[88:89], v[120:121]
	v_pk_mul_f32 v[90:91], v[90:91], v[122:123]
	v_pk_mul_f32 v[92:93], v[92:93], v[124:125]
	v_pk_mul_f32 v[94:95], v[94:95], v[126:127]
	s_lshl_b32 s99, s98, 12
	v_add_u32_e32 v8, s99, v1
	global_store_dwordx4 v8, v[80:83], s[88:89] nt
	global_store_dwordx4 v8, v[84:87], s[88:89] offset:1024 nt
	global_store_dwordx4 v8, v[88:91], s[88:89] offset:2048 nt
	global_store_dwordx4 v8, v[92:95], s[88:89] offset:3072 nt
	s_add_u32 s98, s97, 10
	s_lshl_b32 s98, s98, 12
	v_add_u32_e32 v3, s98, v1
	global_load_dwordx4 v[80:83], v3, s[88:89] nt
	global_load_dwordx4 v[84:87], v3, s[88:89] offset:1024 nt
	global_load_dwordx4 v[88:91], v3, s[88:89] offset:2048 nt
	global_load_dwordx4 v[92:95], v3, s[88:89] offset:3072 nt
	s_waitcnt vmcnt(40)
	v_mul_f32_e32 v4, v96, v96
	v_fma_f32 v4, v97, v97, v4
	v_fma_f32 v4, v98, v98, v4
	v_fma_f32 v4, v99, v99, v4
	v_fma_f32 v4, v100, v100, v4
	v_fma_f32 v4, v101, v101, v4
	v_fma_f32 v4, v102, v102, v4
	v_fma_f32 v4, v103, v103, v4
	v_fma_f32 v4, v104, v104, v4
	v_fma_f32 v4, v105, v105, v4
	v_fma_f32 v4, v106, v106, v4
	v_fma_f32 v4, v107, v107, v4
	v_fma_f32 v4, v108, v108, v4
	v_fma_f32 v4, v109, v109, v4
	v_fma_f32 v4, v110, v110, v4
	v_fma_f32 v4, v111, v111, v4
	s_nop 1
	v_add_f32_dpp v5, v4, v4 quad_perm:[1,0,3,2] row_mask:0xf bank_mask:0xf
	s_nop 1
	v_add_f32_dpp v4, v5, v5 quad_perm:[2,3,0,1] row_mask:0xf bank_mask:0xf
	s_nop 1
	v_add_f32_dpp v5, v4, v4 row_half_mirror row_mask:0xf bank_mask:0xf
	s_nop 1
	v_add_f32_dpp v4, v5, v5 row_mirror row_mask:0xf bank_mask:0xf
	s_nop 1
	v_readlane_b32 s98, v4, 0
	v_readlane_b32 s99, v4, 16
	s_nop 3
	v_mov_b32_e32 v5, s98
	v_add_f32_e32 v5, s99, v5
	v_readlane_b32 s98, v4, 32
	v_readlane_b32 s99, v4, 48
	s_nop 3
	v_add_f32_e32 v5, s98, v5
	v_add_f32_e32 v5, s99, v5
	v_mul_f32_e32 v5, 0x3a800000, v5
	v_add_f32_e32 v5, 0x358637bd, v5
	v_rsq_f32_e32 v6, v5
	s_nop 0
	s_add_u32 s98, s97, 5
	v_pk_mul_f32 v[96:97], v[96:97], v[6:7] op_sel_hi:[1,0]
	v_pk_mul_f32 v[98:99], v[98:99], v[6:7] op_sel_hi:[1,0]
	v_pk_mul_f32 v[100:101], v[100:101], v[6:7] op_sel_hi:[1,0]
	v_pk_mul_f32 v[102:103], v[102:103], v[6:7] op_sel_hi:[1,0]
	v_pk_mul_f32 v[104:105], v[104:105], v[6:7] op_sel_hi:[1,0]
	v_pk_mul_f32 v[106:107], v[106:107], v[6:7] op_sel_hi:[1,0]
	v_pk_mul_f32 v[108:109], v[108:109], v[6:7] op_sel_hi:[1,0]
	v_pk_mul_f32 v[110:111], v[110:111], v[6:7] op_sel_hi:[1,0]
	v_pk_mul_f32 v[96:97], v[96:97], v[112:113]
	v_pk_mul_f32 v[98:99], v[98:99], v[114:115]
	v_pk_mul_f32 v[100:101], v[100:101], v[116:117]
	v_pk_mul_f32 v[102:103], v[102:103], v[118:119]
	v_pk_mul_f32 v[104:105], v[104:105], v[120:121]
	v_pk_mul_f32 v[106:107], v[106:107], v[122:123]
	v_pk_mul_f32 v[108:109], v[108:109], v[124:125]
	v_pk_mul_f32 v[110:111], v[110:111], v[126:127]
	s_lshl_b32 s99, s98, 12
	v_add_u32_e32 v8, s99, v1
	global_store_dwordx4 v8, v[96:99], s[88:89] nt
	global_store_dwordx4 v8, v[100:103], s[88:89] offset:1024 nt
	global_store_dwordx4 v8, v[104:107], s[88:89] offset:2048 nt
	global_store_dwordx4 v8, v[108:111], s[88:89] offset:3072 nt
	s_add_u32 s98, s97, 11
	s_lshl_b32 s98, s98, 12
	v_add_u32_e32 v3, s98, v1
	global_load_dwordx4 v[96:99], v3, s[88:89] nt
	global_load_dwordx4 v[100:103], v3, s[88:89] offset:1024 nt
	global_load_dwordx4 v[104:107], v3, s[88:89] offset:2048 nt
	global_load_dwordx4 v[108:111], v3, s[88:89] offset:3072 nt
	s_waitcnt vmcnt(40)
	v_mul_f32_e32 v4, v16, v16
	v_fma_f32 v4, v17, v17, v4
	v_fma_f32 v4, v18, v18, v4
	v_fma_f32 v4, v19, v19, v4
	v_fma_f32 v4, v20, v20, v4
	v_fma_f32 v4, v21, v21, v4
	v_fma_f32 v4, v22, v22, v4
	v_fma_f32 v4, v23, v23, v4
	v_fma_f32 v4, v24, v24, v4
	v_fma_f32 v4, v25, v25, v4
	v_fma_f32 v4, v26, v26, v4
	v_fma_f32 v4, v27, v27, v4
	v_fma_f32 v4, v28, v28, v4
	v_fma_f32 v4, v29, v29, v4
	v_fma_f32 v4, v30, v30, v4
	v_fma_f32 v4, v31, v31, v4
	s_nop 1
	v_add_f32_dpp v5, v4, v4 quad_perm:[1,0,3,2] row_mask:0xf bank_mask:0xf
	s_nop 1
	v_add_f32_dpp v4, v5, v5 quad_perm:[2,3,0,1] row_mask:0xf bank_mask:0xf
	s_nop 1
	v_add_f32_dpp v5, v4, v4 row_half_mirror row_mask:0xf bank_mask:0xf
	s_nop 1
	v_add_f32_dpp v4, v5, v5 row_mirror row_mask:0xf bank_mask:0xf
	s_nop 1
	v_readlane_b32 s98, v4, 0
	v_readlane_b32 s99, v4, 16
	s_nop 3
	v_mov_b32_e32 v5, s98
	v_add_f32_e32 v5, s99, v5
	v_readlane_b32 s98, v4, 32
	v_readlane_b32 s99, v4, 48
	s_nop 3
	v_add_f32_e32 v5, s98, v5
	v_add_f32_e32 v5, s99, v5
	v_mul_f32_e32 v5, 0x3a800000, v5
	v_add_f32_e32 v5, 0x358637bd, v5
	v_rsq_f32_e32 v6, v5
	s_nop 0
	s_add_u32 s98, s97, 6
	v_pk_mul_f32 v[16:17], v[16:17], v[6:7] op_sel_hi:[1,0]
	v_pk_mul_f32 v[18:19], v[18:19], v[6:7] op_sel_hi:[1,0]
	v_pk_mul_f32 v[20:21], v[20:21], v[6:7] op_sel_hi:[1,0]
	v_pk_mul_f32 v[22:23], v[22:23], v[6:7] op_sel_hi:[1,0]
	v_pk_mul_f32 v[24:25], v[24:25], v[6:7] op_sel_hi:[1,0]
	v_pk_mul_f32 v[26:27], v[26:27], v[6:7] op_sel_hi:[1,0]
	v_pk_mul_f32 v[28:29], v[28:29], v[6:7] op_sel_hi:[1,0]
	v_pk_mul_f32 v[30:31], v[30:31], v[6:7] op_sel_hi:[1,0]
	v_pk_mul_f32 v[16:17], v[16:17], v[112:113]
	v_pk_mul_f32 v[18:19], v[18:19], v[114:115]
	v_pk_mul_f32 v[20:21], v[20:21], v[116:117]
	v_pk_mul_f32 v[22:23], v[22:23], v[118:119]
	v_pk_mul_f32 v[24:25], v[24:25], v[120:121]
	v_pk_mul_f32 v[26:27], v[26:27], v[122:123]
	v_pk_mul_f32 v[28:29], v[28:29], v[124:125]
	v_pk_mul_f32 v[30:31], v[30:31], v[126:127]
	s_lshl_b32 s99, s98, 12
	v_add_u32_e32 v8, s99, v1
	global_store_dwordx4 v8, v[16:19], s[88:89] nt
	global_store_dwordx4 v8, v[20:23], s[88:89] offset:1024 nt
	global_store_dwordx4 v8, v[24:27], s[88:89] offset:2048 nt
	global_store_dwordx4 v8, v[28:31], s[88:89] offset:3072 nt
	s_add_u32 s98, s97, 12
	s_lshl_b32 s98, s98, 12
	v_add_u32_e32 v3, s98, v1
	global_load_dwordx4 v[16:19], v3, s[88:89] nt
	global_load_dwordx4 v[20:23], v3, s[88:89] offset:1024 nt
	global_load_dwordx4 v[24:27], v3, s[88:89] offset:2048 nt
	global_load_dwordx4 v[28:31], v3, s[88:89] offset:3072 nt
	s_waitcnt vmcnt(40)
	v_mul_f32_e32 v4, v32, v32
	v_fma_f32 v4, v33, v33, v4
	v_fma_f32 v4, v34, v34, v4
	v_fma_f32 v4, v35, v35, v4
	v_fma_f32 v4, v36, v36, v4
	v_fma_f32 v4, v37, v37, v4
	v_fma_f32 v4, v38, v38, v4
	v_fma_f32 v4, v39, v39, v4
	v_fma_f32 v4, v40, v40, v4
	v_fma_f32 v4, v41, v41, v4
	v_fma_f32 v4, v42, v42, v4
	v_fma_f32 v4, v43, v43, v4
	v_fma_f32 v4, v44, v44, v4
	v_fma_f32 v4, v45, v45, v4
	v_fma_f32 v4, v46, v46, v4
	v_fma_f32 v4, v47, v47, v4
	s_nop 1
	v_add_f32_dpp v5, v4, v4 quad_perm:[1,0,3,2] row_mask:0xf bank_mask:0xf
	s_nop 1
	v_add_f32_dpp v4, v5, v5 quad_perm:[2,3,0,1] row_mask:0xf bank_mask:0xf
	s_nop 1
	v_add_f32_dpp v5, v4, v4 row_half_mirror row_mask:0xf bank_mask:0xf
	s_nop 1
	v_add_f32_dpp v4, v5, v5 row_mirror row_mask:0xf bank_mask:0xf
	s_nop 1
	v_readlane_b32 s98, v4, 0
	v_readlane_b32 s99, v4, 16
	s_nop 3
	v_mov_b32_e32 v5, s98
	v_add_f32_e32 v5, s99, v5
	v_readlane_b32 s98, v4, 32
	v_readlane_b32 s99, v4, 48
	s_nop 3
	v_add_f32_e32 v5, s98, v5
	v_add_f32_e32 v5, s99, v5
	v_mul_f32_e32 v5, 0x3a800000, v5
	v_add_f32_e32 v5, 0x358637bd, v5
	v_rsq_f32_e32 v6, v5
	s_nop 0
	s_add_u32 s98, s97, 7
	v_pk_mul_f32 v[32:33], v[32:33], v[6:7] op_sel_hi:[1,0]
	v_pk_mul_f32 v[34:35], v[34:35], v[6:7] op_sel_hi:[1,0]
	v_pk_mul_f32 v[36:37], v[36:37], v[6:7] op_sel_hi:[1,0]
	v_pk_mul_f32 v[38:39], v[38:39], v[6:7] op_sel_hi:[1,0]
	v_pk_mul_f32 v[40:41], v[40:41], v[6:7] op_sel_hi:[1,0]
	v_pk_mul_f32 v[42:43], v[42:43], v[6:7] op_sel_hi:[1,0]
	v_pk_mul_f32 v[44:45], v[44:45], v[6:7] op_sel_hi:[1,0]
	v_pk_mul_f32 v[46:47], v[46:47], v[6:7] op_sel_hi:[1,0]
	v_pk_mul_f32 v[32:33], v[32:33], v[112:113]
	v_pk_mul_f32 v[34:35], v[34:35], v[114:115]
	v_pk_mul_f32 v[36:37], v[36:37], v[116:117]
	v_pk_mul_f32 v[38:39], v[38:39], v[118:119]
	v_pk_mul_f32 v[40:41], v[40:41], v[120:121]
	v_pk_mul_f32 v[42:43], v[42:43], v[122:123]
	v_pk_mul_f32 v[44:45], v[44:45], v[124:125]
	v_pk_mul_f32 v[46:47], v[46:47], v[126:127]
	s_lshl_b32 s99, s98, 12
	v_add_u32_e32 v8, s99, v1
	global_store_dwordx4 v8, v[32:35], s[88:89] nt
	global_store_dwordx4 v8, v[36:39], s[88:89] offset:1024 nt
	global_store_dwordx4 v8, v[40:43], s[88:89] offset:2048 nt
	global_store_dwordx4 v8, v[44:47], s[88:89] offset:3072 nt
	s_add_u32 s98, s97, 13
	s_lshl_b32 s98, s98, 12
	v_add_u32_e32 v3, s98, v1
	global_load_dwordx4 v[32:35], v3, s[88:89] nt
	global_load_dwordx4 v[36:39], v3, s[88:89] offset:1024 nt
	global_load_dwordx4 v[40:43], v3, s[88:89] offset:2048 nt
	global_load_dwordx4 v[44:47], v3, s[88:89] offset:3072 nt
	s_waitcnt vmcnt(40)
	v_mul_f32_e32 v4, v48, v48
	v_fma_f32 v4, v49, v49, v4
	v_fma_f32 v4, v50, v50, v4
	v_fma_f32 v4, v51, v51, v4
	v_fma_f32 v4, v52, v52, v4
	v_fma_f32 v4, v53, v53, v4
	v_fma_f32 v4, v54, v54, v4
	v_fma_f32 v4, v55, v55, v4
	v_fma_f32 v4, v56, v56, v4
	v_fma_f32 v4, v57, v57, v4
	v_fma_f32 v4, v58, v58, v4
	v_fma_f32 v4, v59, v59, v4
	v_fma_f32 v4, v60, v60, v4
	v_fma_f32 v4, v61, v61, v4
	v_fma_f32 v4, v62, v62, v4
	v_fma_f32 v4, v63, v63, v4
	s_nop 1
	v_add_f32_dpp v5, v4, v4 quad_perm:[1,0,3,2] row_mask:0xf bank_mask:0xf
	s_nop 1
	v_add_f32_dpp v4, v5, v5 quad_perm:[2,3,0,1] row_mask:0xf bank_mask:0xf
	s_nop 1
	v_add_f32_dpp v5, v4, v4 row_half_mirror row_mask:0xf bank_mask:0xf
	s_nop 1
	v_add_f32_dpp v4, v5, v5 row_mirror row_mask:0xf bank_mask:0xf
	s_nop 1
	v_readlane_b32 s98, v4, 0
	v_readlane_b32 s99, v4, 16
	s_nop 3
	v_mov_b32_e32 v5, s98
	v_add_f32_e32 v5, s99, v5
	v_readlane_b32 s98, v4, 32
	v_readlane_b32 s99, v4, 48
	s_nop 3
	v_add_f32_e32 v5, s98, v5
	v_add_f32_e32 v5, s99, v5
	v_mul_f32_e32 v5, 0x3a800000, v5
	v_add_f32_e32 v5, 0x358637bd, v5
	v_rsq_f32_e32 v6, v5
	s_nop 0
	s_add_u32 s98, s97, 8
	v_pk_mul_f32 v[48:49], v[48:49], v[6:7] op_sel_hi:[1,0]
	v_pk_mul_f32 v[50:51], v[50:51], v[6:7] op_sel_hi:[1,0]
	v_pk_mul_f32 v[52:53], v[52:53], v[6:7] op_sel_hi:[1,0]
	v_pk_mul_f32 v[54:55], v[54:55], v[6:7] op_sel_hi:[1,0]
	v_pk_mul_f32 v[56:57], v[56:57], v[6:7] op_sel_hi:[1,0]
	v_pk_mul_f32 v[58:59], v[58:59], v[6:7] op_sel_hi:[1,0]
	v_pk_mul_f32 v[60:61], v[60:61], v[6:7] op_sel_hi:[1,0]
	v_pk_mul_f32 v[62:63], v[62:63], v[6:7] op_sel_hi:[1,0]
	v_pk_mul_f32 v[48:49], v[48:49], v[112:113]
	v_pk_mul_f32 v[50:51], v[50:51], v[114:115]
	v_pk_mul_f32 v[52:53], v[52:53], v[116:117]
	v_pk_mul_f32 v[54:55], v[54:55], v[118:119]
	v_pk_mul_f32 v[56:57], v[56:57], v[120:121]
	v_pk_mul_f32 v[58:59], v[58:59], v[122:123]
	v_pk_mul_f32 v[60:61], v[60:61], v[124:125]
	v_pk_mul_f32 v[62:63], v[62:63], v[126:127]
	s_lshl_b32 s99, s98, 12
	v_add_u32_e32 v8, s99, v1
	global_store_dwordx4 v8, v[48:51], s[88:89] nt
	global_store_dwordx4 v8, v[52:55], s[88:89] offset:1024 nt
	global_store_dwordx4 v8, v[56:59], s[88:89] offset:2048 nt
	global_store_dwordx4 v8, v[60:63], s[88:89] offset:3072 nt
	s_add_u32 s98, s97, 14
	s_lshl_b32 s98, s98, 12
	v_add_u32_e32 v3, s98, v1
	global_load_dwordx4 v[48:51], v3, s[88:89] nt
	global_load_dwordx4 v[52:55], v3, s[88:89] offset:1024 nt
	global_load_dwordx4 v[56:59], v3, s[88:89] offset:2048 nt
	global_load_dwordx4 v[60:63], v3, s[88:89] offset:3072 nt
	s_waitcnt vmcnt(40)
	v_mul_f32_e32 v4, v64, v64
	v_fma_f32 v4, v65, v65, v4
	v_fma_f32 v4, v66, v66, v4
	v_fma_f32 v4, v67, v67, v4
	v_fma_f32 v4, v68, v68, v4
	v_fma_f32 v4, v69, v69, v4
	v_fma_f32 v4, v70, v70, v4
	v_fma_f32 v4, v71, v71, v4
	v_fma_f32 v4, v72, v72, v4
	v_fma_f32 v4, v73, v73, v4
	v_fma_f32 v4, v74, v74, v4
	v_fma_f32 v4, v75, v75, v4
	v_fma_f32 v4, v76, v76, v4
	v_fma_f32 v4, v77, v77, v4
	v_fma_f32 v4, v78, v78, v4
	v_fma_f32 v4, v79, v79, v4
	s_nop 1
	v_add_f32_dpp v5, v4, v4 quad_perm:[1,0,3,2] row_mask:0xf bank_mask:0xf
	s_nop 1
	v_add_f32_dpp v4, v5, v5 quad_perm:[2,3,0,1] row_mask:0xf bank_mask:0xf
	s_nop 1
	v_add_f32_dpp v5, v4, v4 row_half_mirror row_mask:0xf bank_mask:0xf
	s_nop 1
	v_add_f32_dpp v4, v5, v5 row_mirror row_mask:0xf bank_mask:0xf
	s_nop 1
	v_readlane_b32 s98, v4, 0
	v_readlane_b32 s99, v4, 16
	s_nop 3
	v_mov_b32_e32 v5, s98
	v_add_f32_e32 v5, s99, v5
	v_readlane_b32 s98, v4, 32
	v_readlane_b32 s99, v4, 48
	s_nop 3
	v_add_f32_e32 v5, s98, v5
	v_add_f32_e32 v5, s99, v5
	v_mul_f32_e32 v5, 0x3a800000, v5
	v_add_f32_e32 v5, 0x358637bd, v5
	v_rsq_f32_e32 v6, v5
	s_nop 0
	s_add_u32 s98, s97, 9
	v_pk_mul_f32 v[64:65], v[64:65], v[6:7] op_sel_hi:[1,0]
	v_pk_mul_f32 v[66:67], v[66:67], v[6:7] op_sel_hi:[1,0]
	v_pk_mul_f32 v[68:69], v[68:69], v[6:7] op_sel_hi:[1,0]
	v_pk_mul_f32 v[70:71], v[70:71], v[6:7] op_sel_hi:[1,0]
	v_pk_mul_f32 v[72:73], v[72:73], v[6:7] op_sel_hi:[1,0]
	v_pk_mul_f32 v[74:75], v[74:75], v[6:7] op_sel_hi:[1,0]
	v_pk_mul_f32 v[76:77], v[76:77], v[6:7] op_sel_hi:[1,0]
	v_pk_mul_f32 v[78:79], v[78:79], v[6:7] op_sel_hi:[1,0]
	v_pk_mul_f32 v[64:65], v[64:65], v[112:113]
	v_pk_mul_f32 v[66:67], v[66:67], v[114:115]
	v_pk_mul_f32 v[68:69], v[68:69], v[116:117]
	v_pk_mul_f32 v[70:71], v[70:71], v[118:119]
	v_pk_mul_f32 v[72:73], v[72:73], v[120:121]
	v_pk_mul_f32 v[74:75], v[74:75], v[122:123]
	v_pk_mul_f32 v[76:77], v[76:77], v[124:125]
	v_pk_mul_f32 v[78:79], v[78:79], v[126:127]
	s_lshl_b32 s99, s98, 12
	v_add_u32_e32 v8, s99, v1
	global_store_dwordx4 v8, v[64:67], s[88:89] nt
	global_store_dwordx4 v8, v[68:71], s[88:89] offset:1024 nt
	global_store_dwordx4 v8, v[72:75], s[88:89] offset:2048 nt
	global_store_dwordx4 v8, v[76:79], s[88:89] offset:3072 nt
	s_add_u32 s98, s97, 15
	s_lshl_b32 s98, s98, 12
	v_add_u32_e32 v3, s98, v1
	global_load_dwordx4 v[64:67], v3, s[88:89] nt
	global_load_dwordx4 v[68:71], v3, s[88:89] offset:1024 nt
	global_load_dwordx4 v[72:75], v3, s[88:89] offset:2048 nt
	global_load_dwordx4 v[76:79], v3, s[88:89] offset:3072 nt
	s_waitcnt vmcnt(40)
	v_mul_f32_e32 v4, v80, v80
	v_fma_f32 v4, v81, v81, v4
	v_fma_f32 v4, v82, v82, v4
	v_fma_f32 v4, v83, v83, v4
	v_fma_f32 v4, v84, v84, v4
	v_fma_f32 v4, v85, v85, v4
	v_fma_f32 v4, v86, v86, v4
	v_fma_f32 v4, v87, v87, v4
	v_fma_f32 v4, v88, v88, v4
	v_fma_f32 v4, v89, v89, v4
	v_fma_f32 v4, v90, v90, v4
	v_fma_f32 v4, v91, v91, v4
	v_fma_f32 v4, v92, v92, v4
	v_fma_f32 v4, v93, v93, v4
	v_fma_f32 v4, v94, v94, v4
	v_fma_f32 v4, v95, v95, v4
	s_nop 1
	v_add_f32_dpp v5, v4, v4 quad_perm:[1,0,3,2] row_mask:0xf bank_mask:0xf
	s_nop 1
	v_add_f32_dpp v4, v5, v5 quad_perm:[2,3,0,1] row_mask:0xf bank_mask:0xf
	s_nop 1
	v_add_f32_dpp v5, v4, v4 row_half_mirror row_mask:0xf bank_mask:0xf
	s_nop 1
	v_add_f32_dpp v4, v5, v5 row_mirror row_mask:0xf bank_mask:0xf
	s_nop 1
	v_readlane_b32 s98, v4, 0
	v_readlane_b32 s99, v4, 16
	s_nop 3
	v_mov_b32_e32 v5, s98
	v_add_f32_e32 v5, s99, v5
	v_readlane_b32 s98, v4, 32
	v_readlane_b32 s99, v4, 48
	s_nop 3
	v_add_f32_e32 v5, s98, v5
	v_add_f32_e32 v5, s99, v5
	v_mul_f32_e32 v5, 0x3a800000, v5
	v_add_f32_e32 v5, 0x358637bd, v5
	v_rsq_f32_e32 v6, v5
	s_nop 0
	s_add_u32 s98, s97, 10
	v_pk_mul_f32 v[80:81], v[80:81], v[6:7] op_sel_hi:[1,0]
	v_pk_mul_f32 v[82:83], v[82:83], v[6:7] op_sel_hi:[1,0]
	v_pk_mul_f32 v[84:85], v[84:85], v[6:7] op_sel_hi:[1,0]
	v_pk_mul_f32 v[86:87], v[86:87], v[6:7] op_sel_hi:[1,0]
	v_pk_mul_f32 v[88:89], v[88:89], v[6:7] op_sel_hi:[1,0]
	v_pk_mul_f32 v[90:91], v[90:91], v[6:7] op_sel_hi:[1,0]
	v_pk_mul_f32 v[92:93], v[92:93], v[6:7] op_sel_hi:[1,0]
	v_pk_mul_f32 v[94:95], v[94:95], v[6:7] op_sel_hi:[1,0]
	v_pk_mul_f32 v[80:81], v[80:81], v[112:113]
	v_pk_mul_f32 v[82:83], v[82:83], v[114:115]
	v_pk_mul_f32 v[84:85], v[84:85], v[116:117]
	v_pk_mul_f32 v[86:87], v[86:87], v[118:119]
	v_pk_mul_f32 v[88:89], v[88:89], v[120:121]
	v_pk_mul_f32 v[90:91], v[90:91], v[122:123]
	v_pk_mul_f32 v[92:93], v[92:93], v[124:125]
	v_pk_mul_f32 v[94:95], v[94:95], v[126:127]
	s_lshl_b32 s99, s98, 12
	v_add_u32_e32 v8, s99, v1
	global_store_dwordx4 v8, v[80:83], s[88:89] nt
	global_store_dwordx4 v8, v[84:87], s[88:89] offset:1024 nt
	global_store_dwordx4 v8, v[88:91], s[88:89] offset:2048 nt
	global_store_dwordx4 v8, v[92:95], s[88:89] offset:3072 nt
	s_waitcnt vmcnt(36)
	v_mul_f32_e32 v4, v96, v96
	v_fma_f32 v4, v97, v97, v4
	v_fma_f32 v4, v98, v98, v4
	v_fma_f32 v4, v99, v99, v4
	v_fma_f32 v4, v100, v100, v4
	v_fma_f32 v4, v101, v101, v4
	v_fma_f32 v4, v102, v102, v4
	v_fma_f32 v4, v103, v103, v4
	v_fma_f32 v4, v104, v104, v4
	v_fma_f32 v4, v105, v105, v4
	v_fma_f32 v4, v106, v106, v4
	v_fma_f32 v4, v107, v107, v4
	v_fma_f32 v4, v108, v108, v4
	v_fma_f32 v4, v109, v109, v4
	v_fma_f32 v4, v110, v110, v4
	v_fma_f32 v4, v111, v111, v4
	s_nop 1
	v_add_f32_dpp v5, v4, v4 quad_perm:[1,0,3,2] row_mask:0xf bank_mask:0xf
	s_nop 1
	v_add_f32_dpp v4, v5, v5 quad_perm:[2,3,0,1] row_mask:0xf bank_mask:0xf
	s_nop 1
	v_add_f32_dpp v5, v4, v4 row_half_mirror row_mask:0xf bank_mask:0xf
	s_nop 1
	v_add_f32_dpp v4, v5, v5 row_mirror row_mask:0xf bank_mask:0xf
	s_nop 1
	v_readlane_b32 s98, v4, 0
	v_readlane_b32 s99, v4, 16
	s_nop 3
	v_mov_b32_e32 v5, s98
	v_add_f32_e32 v5, s99, v5
	v_readlane_b32 s98, v4, 32
	v_readlane_b32 s99, v4, 48
	s_nop 3
	v_add_f32_e32 v5, s98, v5
	v_add_f32_e32 v5, s99, v5
	v_mul_f32_e32 v5, 0x3a800000, v5
	v_add_f32_e32 v5, 0x358637bd, v5
	v_rsq_f32_e32 v6, v5
	s_nop 0
	s_add_u32 s98, s97, 11
	v_pk_mul_f32 v[96:97], v[96:97], v[6:7] op_sel_hi:[1,0]
	v_pk_mul_f32 v[98:99], v[98:99], v[6:7] op_sel_hi:[1,0]
	v_pk_mul_f32 v[100:101], v[100:101], v[6:7] op_sel_hi:[1,0]
	v_pk_mul_f32 v[102:103], v[102:103], v[6:7] op_sel_hi:[1,0]
	v_pk_mul_f32 v[104:105], v[104:105], v[6:7] op_sel_hi:[1,0]
	v_pk_mul_f32 v[106:107], v[106:107], v[6:7] op_sel_hi:[1,0]
	v_pk_mul_f32 v[108:109], v[108:109], v[6:7] op_sel_hi:[1,0]
	v_pk_mul_f32 v[110:111], v[110:111], v[6:7] op_sel_hi:[1,0]
	v_pk_mul_f32 v[96:97], v[96:97], v[112:113]
	v_pk_mul_f32 v[98:99], v[98:99], v[114:115]
	v_pk_mul_f32 v[100:101], v[100:101], v[116:117]
	v_pk_mul_f32 v[102:103], v[102:103], v[118:119]
	v_pk_mul_f32 v[104:105], v[104:105], v[120:121]
	v_pk_mul_f32 v[106:107], v[106:107], v[122:123]
	v_pk_mul_f32 v[108:109], v[108:109], v[124:125]
	v_pk_mul_f32 v[110:111], v[110:111], v[126:127]
	s_lshl_b32 s99, s98, 12
	v_add_u32_e32 v8, s99, v1
	global_store_dwordx4 v8, v[96:99], s[88:89] nt
	global_store_dwordx4 v8, v[100:103], s[88:89] offset:1024 nt
	global_store_dwordx4 v8, v[104:107], s[88:89] offset:2048 nt
	global_store_dwordx4 v8, v[108:111], s[88:89] offset:3072 nt
	s_waitcnt vmcnt(32)
	v_mul_f32_e32 v4, v16, v16
	v_fma_f32 v4, v17, v17, v4
	v_fma_f32 v4, v18, v18, v4
	v_fma_f32 v4, v19, v19, v4
	v_fma_f32 v4, v20, v20, v4
	v_fma_f32 v4, v21, v21, v4
	v_fma_f32 v4, v22, v22, v4
	v_fma_f32 v4, v23, v23, v4
	v_fma_f32 v4, v24, v24, v4
	v_fma_f32 v4, v25, v25, v4
	v_fma_f32 v4, v26, v26, v4
	v_fma_f32 v4, v27, v27, v4
	v_fma_f32 v4, v28, v28, v4
	v_fma_f32 v4, v29, v29, v4
	v_fma_f32 v4, v30, v30, v4
	v_fma_f32 v4, v31, v31, v4
	s_nop 1
	v_add_f32_dpp v5, v4, v4 quad_perm:[1,0,3,2] row_mask:0xf bank_mask:0xf
	s_nop 1
	v_add_f32_dpp v4, v5, v5 quad_perm:[2,3,0,1] row_mask:0xf bank_mask:0xf
	s_nop 1
	v_add_f32_dpp v5, v4, v4 row_half_mirror row_mask:0xf bank_mask:0xf
	s_nop 1
	v_add_f32_dpp v4, v5, v5 row_mirror row_mask:0xf bank_mask:0xf
	s_nop 1
	v_readlane_b32 s98, v4, 0
	v_readlane_b32 s99, v4, 16
	s_nop 3
	v_mov_b32_e32 v5, s98
	v_add_f32_e32 v5, s99, v5
	v_readlane_b32 s98, v4, 32
	v_readlane_b32 s99, v4, 48
	s_nop 3
	v_add_f32_e32 v5, s98, v5
	v_add_f32_e32 v5, s99, v5
	v_mul_f32_e32 v5, 0x3a800000, v5
	v_add_f32_e32 v5, 0x358637bd, v5
	v_rsq_f32_e32 v6, v5
	s_nop 0
	s_add_u32 s98, s97, 12
	v_pk_mul_f32 v[16:17], v[16:17], v[6:7] op_sel_hi:[1,0]
	v_pk_mul_f32 v[18:19], v[18:19], v[6:7] op_sel_hi:[1,0]
	v_pk_mul_f32 v[20:21], v[20:21], v[6:7] op_sel_hi:[1,0]
	v_pk_mul_f32 v[22:23], v[22:23], v[6:7] op_sel_hi:[1,0]
	v_pk_mul_f32 v[24:25], v[24:25], v[6:7] op_sel_hi:[1,0]
	v_pk_mul_f32 v[26:27], v[26:27], v[6:7] op_sel_hi:[1,0]
	v_pk_mul_f32 v[28:29], v[28:29], v[6:7] op_sel_hi:[1,0]
	v_pk_mul_f32 v[30:31], v[30:31], v[6:7] op_sel_hi:[1,0]
	v_pk_mul_f32 v[16:17], v[16:17], v[112:113]
	v_pk_mul_f32 v[18:19], v[18:19], v[114:115]
	v_pk_mul_f32 v[20:21], v[20:21], v[116:117]
	v_pk_mul_f32 v[22:23], v[22:23], v[118:119]
	v_pk_mul_f32 v[24:25], v[24:25], v[120:121]
	v_pk_mul_f32 v[26:27], v[26:27], v[122:123]
	v_pk_mul_f32 v[28:29], v[28:29], v[124:125]
	v_pk_mul_f32 v[30:31], v[30:31], v[126:127]
	s_lshl_b32 s99, s98, 12
	v_add_u32_e32 v8, s99, v1
	global_store_dwordx4 v8, v[16:19], s[88:89] nt
	global_store_dwordx4 v8, v[20:23], s[88:89] offset:1024 nt
	global_store_dwordx4 v8, v[24:27], s[88:89] offset:2048 nt
	global_store_dwordx4 v8, v[28:31], s[88:89] offset:3072 nt
	s_waitcnt vmcnt(28)
	v_mul_f32_e32 v4, v32, v32
	v_fma_f32 v4, v33, v33, v4
	v_fma_f32 v4, v34, v34, v4
	v_fma_f32 v4, v35, v35, v4
	v_fma_f32 v4, v36, v36, v4
	v_fma_f32 v4, v37, v37, v4
	v_fma_f32 v4, v38, v38, v4
	v_fma_f32 v4, v39, v39, v4
	v_fma_f32 v4, v40, v40, v4
	v_fma_f32 v4, v41, v41, v4
	v_fma_f32 v4, v42, v42, v4
	v_fma_f32 v4, v43, v43, v4
	v_fma_f32 v4, v44, v44, v4
	v_fma_f32 v4, v45, v45, v4
	v_fma_f32 v4, v46, v46, v4
	v_fma_f32 v4, v47, v47, v4
	s_nop 1
	v_add_f32_dpp v5, v4, v4 quad_perm:[1,0,3,2] row_mask:0xf bank_mask:0xf
	s_nop 1
	v_add_f32_dpp v4, v5, v5 quad_perm:[2,3,0,1] row_mask:0xf bank_mask:0xf
	s_nop 1
	v_add_f32_dpp v5, v4, v4 row_half_mirror row_mask:0xf bank_mask:0xf
	s_nop 1
	v_add_f32_dpp v4, v5, v5 row_mirror row_mask:0xf bank_mask:0xf
	s_nop 1
	v_readlane_b32 s98, v4, 0
	v_readlane_b32 s99, v4, 16
	s_nop 3
	v_mov_b32_e32 v5, s98
	v_add_f32_e32 v5, s99, v5
	v_readlane_b32 s98, v4, 32
	v_readlane_b32 s99, v4, 48
	s_nop 3
	v_add_f32_e32 v5, s98, v5
	v_add_f32_e32 v5, s99, v5
	v_mul_f32_e32 v5, 0x3a800000, v5
	v_add_f32_e32 v5, 0x358637bd, v5
	v_rsq_f32_e32 v6, v5
	s_nop 0
	s_add_u32 s98, s97, 13
	v_pk_mul_f32 v[32:33], v[32:33], v[6:7] op_sel_hi:[1,0]
	v_pk_mul_f32 v[34:35], v[34:35], v[6:7] op_sel_hi:[1,0]
	v_pk_mul_f32 v[36:37], v[36:37], v[6:7] op_sel_hi:[1,0]
	v_pk_mul_f32 v[38:39], v[38:39], v[6:7] op_sel_hi:[1,0]
	v_pk_mul_f32 v[40:41], v[40:41], v[6:7] op_sel_hi:[1,0]
	v_pk_mul_f32 v[42:43], v[42:43], v[6:7] op_sel_hi:[1,0]
	v_pk_mul_f32 v[44:45], v[44:45], v[6:7] op_sel_hi:[1,0]
	v_pk_mul_f32 v[46:47], v[46:47], v[6:7] op_sel_hi:[1,0]
	v_pk_mul_f32 v[32:33], v[32:33], v[112:113]
	v_pk_mul_f32 v[34:35], v[34:35], v[114:115]
	v_pk_mul_f32 v[36:37], v[36:37], v[116:117]
	v_pk_mul_f32 v[38:39], v[38:39], v[118:119]
	v_pk_mul_f32 v[40:41], v[40:41], v[120:121]
	v_pk_mul_f32 v[42:43], v[42:43], v[122:123]
	v_pk_mul_f32 v[44:45], v[44:45], v[124:125]
	v_pk_mul_f32 v[46:47], v[46:47], v[126:127]
	s_lshl_b32 s99, s98, 12
	v_add_u32_e32 v8, s99, v1
	global_store_dwordx4 v8, v[32:35], s[88:89] nt
	global_store_dwordx4 v8, v[36:39], s[88:89] offset:1024 nt
	global_store_dwordx4 v8, v[40:43], s[88:89] offset:2048 nt
	global_store_dwordx4 v8, v[44:47], s[88:89] offset:3072 nt
	s_waitcnt vmcnt(24)
	v_mul_f32_e32 v4, v48, v48
	v_fma_f32 v4, v49, v49, v4
	v_fma_f32 v4, v50, v50, v4
	v_fma_f32 v4, v51, v51, v4
	v_fma_f32 v4, v52, v52, v4
	v_fma_f32 v4, v53, v53, v4
	v_fma_f32 v4, v54, v54, v4
	v_fma_f32 v4, v55, v55, v4
	v_fma_f32 v4, v56, v56, v4
	v_fma_f32 v4, v57, v57, v4
	v_fma_f32 v4, v58, v58, v4
	v_fma_f32 v4, v59, v59, v4
	v_fma_f32 v4, v60, v60, v4
	v_fma_f32 v4, v61, v61, v4
	v_fma_f32 v4, v62, v62, v4
	v_fma_f32 v4, v63, v63, v4
	s_nop 1
	v_add_f32_dpp v5, v4, v4 quad_perm:[1,0,3,2] row_mask:0xf bank_mask:0xf
	s_nop 1
	v_add_f32_dpp v4, v5, v5 quad_perm:[2,3,0,1] row_mask:0xf bank_mask:0xf
	s_nop 1
	v_add_f32_dpp v5, v4, v4 row_half_mirror row_mask:0xf bank_mask:0xf
	s_nop 1
	v_add_f32_dpp v4, v5, v5 row_mirror row_mask:0xf bank_mask:0xf
	s_nop 1
	v_readlane_b32 s98, v4, 0
	v_readlane_b32 s99, v4, 16
	s_nop 3
	v_mov_b32_e32 v5, s98
	v_add_f32_e32 v5, s99, v5
	v_readlane_b32 s98, v4, 32
	v_readlane_b32 s99, v4, 48
	s_nop 3
	v_add_f32_e32 v5, s98, v5
	v_add_f32_e32 v5, s99, v5
	v_mul_f32_e32 v5, 0x3a800000, v5
	v_add_f32_e32 v5, 0x358637bd, v5
	v_rsq_f32_e32 v6, v5
	s_nop 0
	s_add_u32 s98, s97, 14
	v_pk_mul_f32 v[48:49], v[48:49], v[6:7] op_sel_hi:[1,0]
	v_pk_mul_f32 v[50:51], v[50:51], v[6:7] op_sel_hi:[1,0]
	v_pk_mul_f32 v[52:53], v[52:53], v[6:7] op_sel_hi:[1,0]
	v_pk_mul_f32 v[54:55], v[54:55], v[6:7] op_sel_hi:[1,0]
	v_pk_mul_f32 v[56:57], v[56:57], v[6:7] op_sel_hi:[1,0]
	v_pk_mul_f32 v[58:59], v[58:59], v[6:7] op_sel_hi:[1,0]
	v_pk_mul_f32 v[60:61], v[60:61], v[6:7] op_sel_hi:[1,0]
	v_pk_mul_f32 v[62:63], v[62:63], v[6:7] op_sel_hi:[1,0]
	v_pk_mul_f32 v[48:49], v[48:49], v[112:113]
	v_pk_mul_f32 v[50:51], v[50:51], v[114:115]
	v_pk_mul_f32 v[52:53], v[52:53], v[116:117]
	v_pk_mul_f32 v[54:55], v[54:55], v[118:119]
	v_pk_mul_f32 v[56:57], v[56:57], v[120:121]
	v_pk_mul_f32 v[58:59], v[58:59], v[122:123]
	v_pk_mul_f32 v[60:61], v[60:61], v[124:125]
	v_pk_mul_f32 v[62:63], v[62:63], v[126:127]
	s_lshl_b32 s99, s98, 12
	v_add_u32_e32 v8, s99, v1
	global_store_dwordx4 v8, v[48:51], s[88:89] nt
	global_store_dwordx4 v8, v[52:55], s[88:89] offset:1024 nt
	global_store_dwordx4 v8, v[56:59], s[88:89] offset:2048 nt
	global_store_dwordx4 v8, v[60:63], s[88:89] offset:3072 nt
	s_waitcnt vmcnt(20)
	v_mul_f32_e32 v4, v64, v64
	v_fma_f32 v4, v65, v65, v4
	v_fma_f32 v4, v66, v66, v4
	v_fma_f32 v4, v67, v67, v4
	v_fma_f32 v4, v68, v68, v4
	v_fma_f32 v4, v69, v69, v4
	v_fma_f32 v4, v70, v70, v4
	v_fma_f32 v4, v71, v71, v4
	v_fma_f32 v4, v72, v72, v4
	v_fma_f32 v4, v73, v73, v4
	v_fma_f32 v4, v74, v74, v4
	v_fma_f32 v4, v75, v75, v4
	v_fma_f32 v4, v76, v76, v4
	v_fma_f32 v4, v77, v77, v4
	v_fma_f32 v4, v78, v78, v4
	v_fma_f32 v4, v79, v79, v4
	s_nop 1
	v_add_f32_dpp v5, v4, v4 quad_perm:[1,0,3,2] row_mask:0xf bank_mask:0xf
	s_nop 1
	v_add_f32_dpp v4, v5, v5 quad_perm:[2,3,0,1] row_mask:0xf bank_mask:0xf
	s_nop 1
	v_add_f32_dpp v5, v4, v4 row_half_mirror row_mask:0xf bank_mask:0xf
	s_nop 1
	v_add_f32_dpp v4, v5, v5 row_mirror row_mask:0xf bank_mask:0xf
	s_nop 1
	v_readlane_b32 s98, v4, 0
	v_readlane_b32 s99, v4, 16
	s_nop 3
	v_mov_b32_e32 v5, s98
	v_add_f32_e32 v5, s99, v5
	v_readlane_b32 s98, v4, 32
	v_readlane_b32 s99, v4, 48
	s_nop 3
	v_add_f32_e32 v5, s98, v5
	v_add_f32_e32 v5, s99, v5
	v_mul_f32_e32 v5, 0x3a800000, v5
	v_add_f32_e32 v5, 0x358637bd, v5
	v_rsq_f32_e32 v6, v5
	s_nop 0
	s_add_u32 s98, s97, 15
	v_pk_mul_f32 v[64:65], v[64:65], v[6:7] op_sel_hi:[1,0]
	v_pk_mul_f32 v[66:67], v[66:67], v[6:7] op_sel_hi:[1,0]
	v_pk_mul_f32 v[68:69], v[68:69], v[6:7] op_sel_hi:[1,0]
	v_pk_mul_f32 v[70:71], v[70:71], v[6:7] op_sel_hi:[1,0]
	v_pk_mul_f32 v[72:73], v[72:73], v[6:7] op_sel_hi:[1,0]
	v_pk_mul_f32 v[74:75], v[74:75], v[6:7] op_sel_hi:[1,0]
	v_pk_mul_f32 v[76:77], v[76:77], v[6:7] op_sel_hi:[1,0]
	v_pk_mul_f32 v[78:79], v[78:79], v[6:7] op_sel_hi:[1,0]
	v_pk_mul_f32 v[64:65], v[64:65], v[112:113]
	v_pk_mul_f32 v[66:67], v[66:67], v[114:115]
	v_pk_mul_f32 v[68:69], v[68:69], v[116:117]
	v_pk_mul_f32 v[70:71], v[70:71], v[118:119]
	v_pk_mul_f32 v[72:73], v[72:73], v[120:121]
	v_pk_mul_f32 v[74:75], v[74:75], v[122:123]
	v_pk_mul_f32 v[76:77], v[76:77], v[124:125]
	v_pk_mul_f32 v[78:79], v[78:79], v[126:127]
	s_lshl_b32 s99, s98, 12
	v_add_u32_e32 v8, s99, v1
	global_store_dwordx4 v8, v[64:67], s[88:89] nt
	global_store_dwordx4 v8, v[68:71], s[88:89] offset:1024 nt
	global_store_dwordx4 v8, v[72:75], s[88:89] offset:2048 nt
	global_store_dwordx4 v8, v[76:79], s[88:89] offset:3072 nt
	s_waitcnt vmcnt(0)
